# stack2 but sc1 on ALL norm-pass stores (H / HQ / RS too)
# baseline (speedup 1.0000x reference)
.LBB0_309:
	v_lshlrev_b32_e32 v134, 16, v126
	v_and_b32_e32 v135, 0xffff0000, v126
	v_lshlrev_b32_e32 v126, 16, v127
	v_and_b32_e32 v127, 0xffff0000, v127
	v_pk_mul_f32 v[136:137], v[126:127], v[126:127]
	v_lshlrev_b32_e32 v138, 16, v128
	v_pk_fma_f32 v[136:137], v[134:135], v[134:135], v[136:137]
	v_and_b32_e32 v139, 0xffff0000, v128
	v_pk_fma_f32 v[136:137], v[138:139], v[138:139], v[136:137]
	v_lshlrev_b32_e32 v128, 16, v129
	v_and_b32_e32 v129, 0xffff0000, v129
	v_pk_fma_f32 v[136:137], v[128:129], v[128:129], v[136:137]
	v_lshlrev_b32_e32 v140, 16, v122
	v_and_b32_e32 v141, 0xffff0000, v122
	v_pk_fma_f32 v[136:137], v[140:141], v[140:141], v[136:137]
	v_lshlrev_b32_e32 v122, 16, v123
	v_and_b32_e32 v123, 0xffff0000, v123
	v_pk_fma_f32 v[136:137], v[122:123], v[122:123], v[136:137]
	v_lshlrev_b32_e32 v142, 16, v124
	v_and_b32_e32 v143, 0xffff0000, v124
	v_pk_fma_f32 v[136:137], v[142:143], v[142:143], v[136:137]
	v_lshlrev_b32_e32 v124, 16, v125
	v_and_b32_e32 v125, 0xffff0000, v125
	v_pk_fma_f32 v[136:137], v[124:125], v[124:125], v[136:137]
	v_lshlrev_b32_e32 v144, 16, v118
	v_and_b32_e32 v145, 0xffff0000, v118
	v_pk_fma_f32 v[136:137], v[144:145], v[144:145], v[136:137]
	v_lshlrev_b32_e32 v118, 16, v119
	v_and_b32_e32 v119, 0xffff0000, v119
	v_pk_fma_f32 v[136:137], v[118:119], v[118:119], v[136:137]
	v_lshlrev_b32_e32 v146, 16, v120
	v_and_b32_e32 v147, 0xffff0000, v120
	v_pk_fma_f32 v[136:137], v[146:147], v[146:147], v[136:137]
	v_lshlrev_b32_e32 v120, 16, v121
	v_and_b32_e32 v121, 0xffff0000, v121
	v_pk_fma_f32 v[136:137], v[120:121], v[120:121], v[136:137]
	v_lshlrev_b32_e32 v148, 16, v114
	v_and_b32_e32 v149, 0xffff0000, v114
	v_pk_fma_f32 v[136:137], v[148:149], v[148:149], v[136:137]
	v_lshlrev_b32_e32 v114, 16, v115
	v_and_b32_e32 v115, 0xffff0000, v115
	v_pk_fma_f32 v[136:137], v[114:115], v[114:115], v[136:137]
	v_lshlrev_b32_e32 v150, 16, v116
	v_and_b32_e32 v151, 0xffff0000, v116
	v_pk_fma_f32 v[136:137], v[150:151], v[150:151], v[136:137]
	v_lshlrev_b32_e32 v116, 16, v117
	v_and_b32_e32 v117, 0xffff0000, v117
	v_pk_fma_f32 v[136:137], v[116:117], v[116:117], v[136:137]
	v_cvt_f32_f16_sdwa v153, v110 dst_sel:DWORD dst_unused:UNUSED_PAD src0_sel:WORD_1
	v_add_f32_e32 v133, v136, v137
	v_mov_b32_e32 v136, 0
	v_cvt_f32_f16_e32 v152, v110
	v_add_f32_dpp v133, v133, v133 quad_perm:[1,0,3,2] row_mask:0xf bank_mask:0xf bound_ctrl:1
	v_cvt_f32_f16_sdwa v155, v111 dst_sel:DWORD dst_unused:UNUSED_PAD src0_sel:WORD_1
	v_cvt_f32_f16_e32 v154, v111
	v_add_f32_dpp v133, v133, v133 quad_perm:[2,3,0,1] row_mask:0xf bank_mask:0xf bound_ctrl:1
	v_pk_mul_f32 v[110:111], v[6:7], v[134:135]
	v_cvt_f32_f16_sdwa v135, v112 dst_sel:DWORD dst_unused:UNUSED_PAD src0_sel:WORD_1
	v_add_f32_dpp v133, v133, v133 row_half_mirror row_mask:0xf bank_mask:0xf bound_ctrl:1
	v_cvt_f32_f16_e32 v134, v112
	v_pk_mul_f32 v[122:123], v[16:17], v[122:123]
	v_add_f32_dpp v133, v133, v133 row_mirror row_mask:0xf bank_mask:0xf bound_ctrl:1
	v_pk_mul_f32 v[124:125], v[12:13], v[124:125]
	v_pk_mul_f32 v[126:127], v[8:9], v[126:127]
	v_mov_b32_dpp v136, v133 row_bcast:15 row_mask:0xa bank_mask:0xf
	v_add_f32_e32 v133, v133, v136
	v_mov_b32_e32 v136, 0
	v_pk_mul_f32 v[118:119], v[24:25], v[118:119]
	v_pk_mul_f32 v[128:129], v[4:5], v[128:129]
	v_mov_b32_dpp v136, v133 row_bcast:31 row_mask:0xc bank_mask:0xf
	v_add_f32_e32 v133, v133, v136
	v_pk_mul_f32 v[120:121], v[20:21], v[120:121]
	v_readlane_b32 s13, v133, 63
	s_nop 1
	v_fma_f32 v133, s13, v132, v1
	v_rsq_f32_e32 v133, v133
	s_nop 0
	v_mul_f32_e32 v136, 0.5, v133
	v_pk_fma_f32 v[110:111], v[110:111], v[136:137], v[152:153] op_sel_hi:[1,0,1]
	v_cvt_f32_f16_sdwa v153, v113 dst_sel:DWORD dst_unused:UNUSED_PAD src0_sel:WORD_1
	v_cvt_f32_f16_e32 v152, v113
	v_pk_mul_f32 v[112:113], v[2:3], v[138:139]
	v_cvt_f32_f16_sdwa v139, v107 dst_sel:DWORD dst_unused:UNUSED_PAD src0_sel:WORD_1
	v_pk_fma_f32 v[112:113], v[112:113], v[136:137], v[134:135] op_sel_hi:[1,0,1]
	v_cvt_f32_f16_sdwa v135, v106 dst_sel:DWORD dst_unused:UNUSED_PAD src0_sel:WORD_1
	v_cvt_f32_f16_e32 v134, v106
	v_cvt_f32_f16_e32 v138, v107
	v_pk_mul_f32 v[106:107], v[14:15], v[140:141]
	v_pk_fma_f32 v[126:127], v[126:127], v[136:137], v[154:155] op_sel_hi:[1,0,1]
	v_pk_fma_f32 v[106:107], v[106:107], v[136:137], v[134:135] op_sel_hi:[1,0,1]
	v_cvt_f32_f16_sdwa v135, v108 dst_sel:DWORD dst_unused:UNUSED_PAD src0_sel:WORD_1
	v_cvt_f32_f16_e32 v134, v108
	v_pk_fma_f32 v[122:123], v[122:123], v[136:137], v[138:139] op_sel_hi:[1,0,1]
	v_cvt_f32_f16_sdwa v139, v109 dst_sel:DWORD dst_unused:UNUSED_PAD src0_sel:WORD_1
	v_cvt_f32_f16_e32 v138, v109
	v_pk_mul_f32 v[108:109], v[10:11], v[142:143]
	v_pk_mul_f32 v[142:143], v[126:127], v[126:127]
	v_pk_fma_f32 v[108:109], v[108:109], v[136:137], v[134:135] op_sel_hi:[1,0,1]
	v_cvt_f32_f16_sdwa v135, v102 dst_sel:DWORD dst_unused:UNUSED_PAD src0_sel:WORD_1
	v_cvt_f32_f16_e32 v134, v102
	v_pk_fma_f32 v[124:125], v[124:125], v[136:137], v[138:139] op_sel_hi:[1,0,1]
	v_cvt_f32_f16_sdwa v139, v103 dst_sel:DWORD dst_unused:UNUSED_PAD src0_sel:WORD_1
	v_cvt_f32_f16_e32 v138, v103
	v_pk_mul_f32 v[102:103], v[22:23], v[144:145]
	v_pk_fma_f32 v[142:143], v[110:111], v[110:111], v[142:143]
	v_pk_fma_f32 v[102:103], v[102:103], v[136:137], v[134:135] op_sel_hi:[1,0,1]
	v_cvt_f32_f16_sdwa v135, v104 dst_sel:DWORD dst_unused:UNUSED_PAD src0_sel:WORD_1
	v_cvt_f32_f16_e32 v134, v104
	v_pk_fma_f32 v[118:119], v[118:119], v[136:137], v[138:139] op_sel_hi:[1,0,1]
	v_cvt_f32_f16_sdwa v139, v105 dst_sel:DWORD dst_unused:UNUSED_PAD src0_sel:WORD_1
	v_cvt_f32_f16_e32 v138, v105
	v_pk_fma_f32 v[128:129], v[128:129], v[136:137], v[152:153] op_sel_hi:[1,0,1]
	v_pk_fma_f32 v[142:143], v[112:113], v[112:113], v[142:143]
	v_pk_mul_f32 v[104:105], v[18:19], v[146:147]
	v_pk_fma_f32 v[142:143], v[128:129], v[128:129], v[142:143]
	v_pk_fma_f32 v[104:105], v[104:105], v[136:137], v[134:135] op_sel_hi:[1,0,1]
	v_cvt_f32_f16_sdwa v135, v98 dst_sel:DWORD dst_unused:UNUSED_PAD src0_sel:WORD_1
	v_cvt_f32_f16_e32 v134, v98
	v_pk_fma_f32 v[142:143], v[106:107], v[106:107], v[142:143]
	v_pk_fma_f32 v[120:121], v[120:121], v[136:137], v[138:139] op_sel_hi:[1,0,1]
	v_cvt_f32_f16_sdwa v139, v99 dst_sel:DWORD dst_unused:UNUSED_PAD src0_sel:WORD_1
	v_cvt_f32_f16_e32 v138, v99
	v_pk_fma_f32 v[142:143], v[122:123], v[122:123], v[142:143]
	v_pk_mul_f32 v[98:99], v[30:31], v[148:149]
	v_pk_fma_f32 v[142:143], v[108:109], v[108:109], v[142:143]
	v_pk_fma_f32 v[134:135], v[98:99], v[136:137], v[134:135] op_sel_hi:[1,0,1]
	v_pk_fma_f32 v[142:143], v[124:125], v[124:125], v[142:143]
	v_pk_mul_f32 v[98:99], v[32:33], v[114:115]
	v_pk_fma_f32 v[142:143], v[102:103], v[102:103], v[142:143]
	v_pk_fma_f32 v[114:115], v[98:99], v[136:137], v[138:139] op_sel_hi:[1,0,1]
	v_cvt_f32_f16_sdwa v99, v100 dst_sel:DWORD dst_unused:UNUSED_PAD src0_sel:WORD_1
	v_cvt_f32_f16_e32 v98, v100
	v_pk_fma_f32 v[142:143], v[118:119], v[118:119], v[142:143]
	v_cvt_f32_f16_sdwa v139, v101 dst_sel:DWORD dst_unused:UNUSED_PAD src0_sel:WORD_1
	v_cvt_f32_f16_e32 v138, v101
	v_pk_fma_f32 v[142:143], v[104:105], v[104:105], v[142:143]
	v_pk_mul_f32 v[100:101], v[26:27], v[150:151]
	v_pk_fma_f32 v[142:143], v[120:121], v[120:121], v[142:143]
	v_pk_fma_f32 v[140:141], v[100:101], v[136:137], v[98:99] op_sel_hi:[1,0,1]
	v_pk_fma_f32 v[142:143], v[134:135], v[134:135], v[142:143]
	v_pk_mul_f32 v[98:99], v[28:29], v[116:117]
	v_pk_fma_f32 v[142:143], v[114:115], v[114:115], v[142:143]
	v_pk_fma_f32 v[116:117], v[98:99], v[136:137], v[138:139] op_sel_hi:[1,0,1]
	v_pk_fma_f32 v[142:143], v[140:141], v[140:141], v[142:143]
	v_lshl_add_u64 v[136:137], s[14:15], 0, v[130:131]
	v_pk_fma_f32 v[142:143], v[116:117], v[116:117], v[142:143]
	v_add_co_u32_e32 v138, vcc, s11, v136
	v_add_f32_e32 v133, v142, v143
	v_mov_b32_e32 v142, 0
	v_cvt_pk_f16_f32 v98, v110, v111
	v_add_f32_dpp v133, v133, v133 quad_perm:[1,0,3,2] row_mask:0xf bank_mask:0xf bound_ctrl:1
	v_cvt_pk_f16_f32 v99, v126, v127
	v_cvt_pk_f16_f32 v100, v112, v113
	v_add_f32_dpp v133, v133, v133 quad_perm:[2,3,0,1] row_mask:0xf bank_mask:0xf bound_ctrl:1
	v_cvt_pk_f16_f32 v101, v128, v129
	v_addc_co_u32_e32 v139, vcc, 0, v137, vcc
	v_add_f32_dpp v133, v133, v133 row_half_mirror row_mask:0xf bank_mask:0xf bound_ctrl:1
	global_store_dwordx4 v[138:139], v[98:101], off offset:1024 sc1
	s_add_u32 s14, s14, s16
	v_add_f32_dpp v133, v133, v133 row_mirror row_mask:0xf bank_mask:0xf bound_ctrl:1
	v_cvt_pk_f16_f32 v98, v106, v107
	v_cvt_pk_f16_f32 v99, v122, v123
	v_mov_b32_dpp v142, v133 row_bcast:15 row_mask:0xa bank_mask:0xf
	v_add_f32_e32 v133, v133, v142
	v_mov_b32_e32 v142, 0
	v_cvt_pk_f16_f32 v100, v108, v109
	v_cvt_pk_f16_f32 v101, v124, v125
	v_mov_b32_dpp v142, v133 row_bcast:31 row_mask:0xc bank_mask:0xf
	v_add_f32_e32 v133, v133, v142
	global_store_dwordx4 v[138:139], v[98:101], off offset:2048 sc1
	v_readlane_b32 s13, v133, 63
	s_addc_u32 s15, s15, s17
	v_cvt_pk_f16_f32 v98, v102, v103
	v_fma_f32 v133, s13, v132, v1
	v_cvt_pk_f16_f32 v99, v118, v119
	v_cvt_pk_f16_f32 v100, v104, v105
	v_cvt_pk_f16_f32 v101, v120, v121
	v_rsq_f32_e32 v142, v133
	global_store_dwordx4 v[138:139], v[98:101], off offset:3072 sc1
	v_add_co_u32_e32 v138, vcc, s22, v136
	s_nop 0
	v_cvt_pk_f16_f32 v98, v134, v135
	v_cvt_pk_f16_f32 v99, v114, v115
	v_cvt_pk_f16_f32 v100, v140, v141
	v_cvt_pk_f16_f32 v101, v116, v117
	v_addc_co_u32_e32 v139, vcc, 0, v137, vcc
	global_store_dwordx4 v[138:139], v[98:101], off sc1
	s_add_u32 s18, s18, s16
	s_addc_u32 s19, s19, s17
	v_pk_mul_f32 v[98:99], v[40:41], v[126:127]
	s_nop 0
	v_pk_mul_f32 v[100:101], v[98:99], v[142:143] op_sel_hi:[1,0]
	v_pk_mul_f32 v[98:99], v[38:39], v[110:111]
	v_pk_mul_f32 v[110:111], v[36:37], v[128:129]
	v_pk_mul_f32 v[98:99], v[98:99], v[142:143] op_sel_hi:[1,0]
	v_pk_mul_f32 v[110:111], v[110:111], v[142:143] op_sel_hi:[1,0]
	v_cvt_pk_bf16_f32 v98, v98, v99
	v_cvt_pk_bf16_f32 v99, v100, v101
	v_pk_mul_f32 v[100:101], v[34:35], v[112:113]
	s_waitcnt vmcnt(9)
	v_mov_b64_e32 v[128:129], v[76:77]
	v_pk_mul_f32 v[100:101], v[100:101], v[142:143] op_sel_hi:[1,0]
	v_mov_b64_e32 v[126:127], v[74:75]
	v_cvt_pk_bf16_f32 v100, v100, v101
	v_cvt_pk_bf16_f32 v101, v110, v111
	v_add_co_u32_e32 v110, vcc, s23, v136
	s_nop 1
	v_addc_co_u32_e32 v111, vcc, 0, v137, vcc
	global_store_dwordx4 v[110:111], v[98:101], off sc1
	s_andn2_b64 vcc, exec, s[20:21]
	s_nop 0
	v_pk_mul_f32 v[98:99], v[46:47], v[106:107]
	v_pk_mul_f32 v[100:101], v[48:49], v[122:123]
	v_pk_mul_f32 v[98:99], v[98:99], v[142:143] op_sel_hi:[1,0]
	v_pk_mul_f32 v[100:101], v[100:101], v[142:143] op_sel_hi:[1,0]
	v_cvt_pk_bf16_f32 v98, v98, v99
	v_pk_mul_f32 v[106:107], v[44:45], v[124:125]
	v_cvt_pk_bf16_f32 v99, v100, v101
	v_pk_mul_f32 v[100:101], v[42:43], v[108:109]
	v_pk_mul_f32 v[106:107], v[106:107], v[142:143] op_sel_hi:[1,0]
	v_pk_mul_f32 v[100:101], v[100:101], v[142:143] op_sel_hi:[1,0]
	s_waitcnt vmcnt(8)
	v_mov_b64_e32 v[124:125], v[84:85]
	v_cvt_pk_bf16_f32 v100, v100, v101
	v_cvt_pk_bf16_f32 v101, v106, v107
	global_store_dwordx4 v[110:111], v[98:101], off offset:1024 sc1
	v_mov_b64_e32 v[108:109], v[72:73]
	v_mov_b64_e32 v[122:123], v[82:83]
	v_pk_mul_f32 v[98:99], v[54:55], v[102:103]
	v_pk_mul_f32 v[100:101], v[56:57], v[118:119]
	v_pk_mul_f32 v[98:99], v[98:99], v[142:143] op_sel_hi:[1,0]
	v_pk_mul_f32 v[100:101], v[100:101], v[142:143] op_sel_hi:[1,0]
	v_cvt_pk_bf16_f32 v98, v98, v99
	v_pk_mul_f32 v[102:103], v[52:53], v[120:121]
	v_cvt_pk_bf16_f32 v99, v100, v101
	v_pk_mul_f32 v[100:101], v[50:51], v[104:105]
	v_pk_mul_f32 v[102:103], v[102:103], v[142:143] op_sel_hi:[1,0]
	v_pk_mul_f32 v[100:101], v[100:101], v[142:143] op_sel_hi:[1,0]
	s_waitcnt vmcnt(8)
	v_mov_b64_e32 v[120:121], v[88:89]
	v_cvt_pk_bf16_f32 v100, v100, v101
	v_cvt_pk_bf16_f32 v101, v102, v103
	global_store_dwordx4 v[110:111], v[98:101], off offset:2048 sc1
	s_waitcnt vmcnt(8)
	v_pk_mul_f32 v[102:103], v[60:61], v[116:117]
	v_mov_b64_e32 v[118:119], v[86:87]
	s_waitcnt vmcnt(7)
	v_pk_mul_f32 v[98:99], v[62:63], v[134:135]
	v_pk_mul_f32 v[100:101], v[64:65], v[114:115]
	v_pk_mul_f32 v[98:99], v[98:99], v[142:143] op_sel_hi:[1,0]
	v_pk_mul_f32 v[100:101], v[100:101], v[142:143] op_sel_hi:[1,0]
	v_cvt_pk_bf16_f32 v98, v98, v99
	v_pk_mul_f32 v[102:103], v[102:103], v[142:143] op_sel_hi:[1,0]
	v_cvt_pk_bf16_f32 v99, v100, v101
	v_pk_mul_f32 v[100:101], v[58:59], v[140:141]
	v_mov_b64_e32 v[116:117], v[92:93]
	v_pk_mul_f32 v[100:101], v[100:101], v[142:143] op_sel_hi:[1,0]
	v_mov_b64_e32 v[114:115], v[90:91]
	v_cvt_pk_bf16_f32 v100, v100, v101
	v_cvt_pk_bf16_f32 v101, v102, v103
	global_store_dwordx4 v[110:111], v[98:101], off offset:3072 sc1
	v_mov_b64_e32 v[112:113], v[68:69]
	v_mov_b64_e32 v[104:105], v[80:81]
	v_mov_b64_e32 v[100:101], v[96:97]
	v_mov_b64_e32 v[110:111], v[66:67]
	v_mov_b64_e32 v[106:107], v[70:71]
	v_mov_b64_e32 v[102:103], v[78:79]
	v_mov_b64_e32 v[98:99], v[94:95]
	s_cbranch_vccz .LBB0_312

.LBB0_315:
	s_cmp_gt_i32 s8, 31
	s_cbranch_scc1 .LBB0_317
	s_ashr_i32 s9, s8, 31
	s_lshl_b64 s[10:11], s[8:9], 13
	v_readlane_b32 s12, v254, 58
	v_readlane_b32 s13, v254, 59
	s_add_u32 s10, s12, s10
	s_addc_u32 s11, s13, s11
	s_add_u32 s12, s10, 0x40000
	s_addc_u32 s13, s11, 0
	v_lshlrev_b32_e32 v148, 4, v166
	s_add_u32 s14, s10, 0x80000
	v_or_b32_e32 v150, 0x400, v148
	v_or_b32_e32 v151, 0x800, v148
	v_or_b32_e32 v152, 0xc00, v148
	s_addc_u32 s15, s11, 0
	global_load_dwordx4 v[16:19], v148, s[10:11]
	global_load_dwordx4 v[20:23], v148, s[10:11] offset:1024
	global_load_dwordx4 v[28:31], v148, s[10:11] offset:2048
	global_load_dwordx4 v[32:35], v148, s[10:11] offset:3072
	v_or_b32_e32 v149, 0x1000, v148
	global_load_dwordx4 v[36:39], v148, s[12:13]
	global_load_dwordx4 v[40:43], v150, s[12:13]
	global_load_dwordx4 v[44:47], v151, s[12:13]
	global_load_dwordx4 v[48:51], v152, s[12:13]
	global_load_dwordx4 v[52:55], v149, s[10:11]
	global_load_dwordx4 v[56:59], v149, s[12:13]
	global_load_dwordx4 v[60:63], v148, s[14:15]
	s_add_u32 s16, s10, 0xc0000
	s_addc_u32 s17, s11, 0
	v_or_b32_e32 v153, 0x1400, v148
	v_or_b32_e32 v154, 0x1800, v148
	v_or_b32_e32 v155, 0x1c00, v148
	global_load_dwordx4 v[64:67], v148, s[16:17]
	global_load_dwordx4 v[68:71], v150, s[14:15]
	global_load_dwordx4 v[72:75], v150, s[16:17]
	global_load_dwordx4 v[76:79], v151, s[14:15]
	global_load_dwordx4 v[80:83], v151, s[16:17]
	global_load_dwordx4 v[84:87], v152, s[14:15]
	global_load_dwordx4 v[88:91], v152, s[16:17]
	global_load_dwordx4 v[92:95], v149, s[14:15]
	global_load_dwordx4 v[96:99], v149, s[16:17]
	global_load_dwordx4 v[100:103], v153, s[10:11]
	global_load_dwordx4 v[104:107], v153, s[12:13]
	global_load_dwordx4 v[108:111], v153, s[14:15]
	global_load_dwordx4 v[112:115], v153, s[16:17]
	global_load_dwordx4 v[116:119], v154, s[10:11]
	global_load_dwordx4 v[120:123], v154, s[12:13]
	global_load_dwordx4 v[124:127], v154, s[14:15]
	global_load_dwordx4 v[128:131], v154, s[16:17]
	global_load_dwordx4 v[132:135], v155, s[10:11]
	global_load_dwordx4 v[136:139], v155, s[12:13]
	global_load_dwordx4 v[140:143], v155, s[14:15]
	global_load_dwordx4 v[144:147], v155, s[16:17]
	s_lshl_b64 s[8:9], s[8:9], 12
	s_add_u32 s10, s8, 0x2000000
	s_addc_u32 s11, s9, 0
	v_readlane_b32 s8, v254, 54
	v_readlane_b32 s9, v254, 55
	s_add_u32 s8, s8, s10
	v_lshlrev_b32_e32 v1, 3, v166
	s_addc_u32 s9, s9, s11
	s_nop 1
	global_load_dwordx2 v[26:27], v1, s[8:9]
	global_load_dwordx2 v[14:15], v1, s[8:9] offset:512
	global_load_dwordx2 v[12:13], v1, s[8:9] offset:1024
	global_load_dwordx2 v[10:11], v1, s[8:9] offset:1536
	global_load_dwordx2 v[8:9], v1, s[8:9] offset:2048
	global_load_dwordx2 v[6:7], v1, s[8:9] offset:2560
	global_load_dwordx2 v[4:5], v1, s[8:9] offset:3072
	global_load_dwordx2 v[2:3], v1, s[8:9] offset:3584
	s_waitcnt vmcnt(35)
	v_pk_add_f32 v[18:19], v[18:19], v[38:39]
	s_waitcnt vmcnt(34)
	v_pk_add_f32 v[20:21], v[20:21], v[40:41]
	s_waitcnt vmcnt(33)
	v_pk_add_f32 v[30:31], v[30:31], v[46:47]
	v_pk_add_f32 v[28:29], v[28:29], v[44:45]
	s_waitcnt vmcnt(32)
	v_pk_add_f32 v[34:35], v[34:35], v[50:51]
	s_waitcnt vmcnt(30)
	v_pk_add_f32 v[40:41], v[52:53], v[56:57]
	s_waitcnt vmcnt(28)
	v_pk_add_f32 v[24:25], v[62:63], v[66:67]
	s_waitcnt vmcnt(26)
	v_pk_add_f32 v[44:45], v[68:69], v[72:73]
	s_waitcnt vmcnt(24)
	v_pk_add_f32 v[50:51], v[78:79], v[82:83]
	v_pk_add_f32 v[52:53], v[76:77], v[80:81]
	v_pk_add_f32 v[16:17], v[16:17], v[36:37]
	v_pk_add_f32 v[22:23], v[22:23], v[42:43]
	v_pk_add_f32 v[32:33], v[32:33], v[48:49]
	v_pk_add_f32 v[36:37], v[54:55], v[58:59]
	v_pk_add_f32 v[38:39], v[60:61], v[64:65]
	v_pk_add_f32 v[42:43], v[70:71], v[74:75]
	s_waitcnt vmcnt(22)
	v_pk_add_f32 v[54:55], v[86:87], v[90:91]
	v_pk_add_f32 v[56:57], v[84:85], v[88:89]
	v_pk_add_f32 v[46:47], v[18:19], v[24:25]
	v_pk_add_f32 v[24:25], v[20:21], v[44:45]
	v_pk_add_f32 v[18:19], v[30:31], v[50:51]
	v_pk_add_f32 v[20:21], v[28:29], v[52:53]
	global_load_dwordx4 v[50:53], v148, s[4:5]
	s_waitcnt vmcnt(21)
	v_pk_add_f32 v[58:59], v[94:95], v[98:99]
	v_pk_add_f32 v[48:49], v[16:17], v[38:39]
	v_pk_add_f32 v[22:23], v[22:23], v[42:43]
	v_pk_add_f32 v[16:17], v[34:35], v[54:55]
	v_pk_add_f32 v[38:39], v[32:33], v[56:57]
	s_waitcnt vmcnt(11)
	v_pk_add_f32 v[54:55], v[132:133], v[136:137]
	s_waitcnt vmcnt(9)
	v_pk_add_f32 v[56:57], v[140:141], v[144:145]
	v_pk_add_f32 v[30:31], v[36:37], v[58:59]
	v_pk_add_f32 v[58:59], v[54:55], v[56:57]
	v_mul_f32_e32 v54, v25, v25
	v_mul_f32_e32 v55, v23, v23
	v_pk_add_f32 v[60:61], v[92:93], v[96:97]
	v_fmac_f32_e32 v54, v24, v24
	v_fmac_f32_e32 v55, v22, v22
	v_pk_add_f32 v[32:33], v[40:41], v[60:61]
	v_add_f32_e32 v60, v54, v55
	global_load_dwordx4 v[54:57], v150, s[4:5]
	v_mul_f32_e32 v61, v21, v21
	v_mul_f32_e32 v62, v19, v19
	v_fmac_f32_e32 v61, v20, v20
	v_fmac_f32_e32 v62, v18, v18
	v_add_f32_e32 v61, v61, v62
	v_mul_f32_e32 v66, v39, v39
	v_mul_f32_e32 v67, v17, v17
	global_load_dwordx4 v[62:65], v151, s[4:5]
	v_fmac_f32_e32 v66, v38, v38
	v_fmac_f32_e32 v67, v16, v16
	v_add_f32_e32 v86, v66, v67
	v_mul_f32_e32 v66, v33, v33
	v_mul_f32_e32 v67, v31, v31
	v_fmac_f32_e32 v66, v32, v32
	v_fmac_f32_e32 v67, v30, v30
	v_pk_add_f32 v[28:29], v[102:103], v[106:107]
	v_pk_add_f32 v[36:37], v[100:101], v[104:105]
	v_pk_add_f32 v[34:35], v[110:111], v[114:115]
	v_pk_add_f32 v[40:41], v[108:109], v[112:113]
	v_add_f32_e32 v87, v66, v67
	global_load_dwordx4 v[66:69], v152, s[4:5]
	v_pk_add_f32 v[34:35], v[28:29], v[34:35]
	v_pk_add_f32 v[36:37], v[36:37], v[40:41]
	v_mul_f32_e32 v71, v35, v35
	v_mul_f32_e32 v70, v37, v37
	v_fmac_f32_e32 v70, v36, v36
	v_fmac_f32_e32 v71, v34, v34
	v_pk_add_f32 v[28:29], v[118:119], v[122:123]
	v_pk_add_f32 v[42:43], v[116:117], v[120:121]
	v_pk_add_f32 v[40:41], v[126:127], v[130:131]
	v_pk_add_f32 v[44:45], v[124:125], v[128:129]
	v_add_f32_e32 v88, v70, v71
	global_load_dwordx4 v[70:73], v149, s[4:5]
	v_pk_add_f32 v[40:41], v[28:29], v[40:41]
	v_pk_add_f32 v[42:43], v[42:43], v[44:45]
	v_pk_add_f32 v[28:29], v[134:135], v[138:139]
	v_pk_add_f32 v[44:45], v[142:143], v[146:147]
	v_mul_f32_e32 v74, v43, v43
	v_mul_f32_e32 v75, v41, v41
	v_pk_add_f32 v[44:45], v[28:29], v[44:45]
	v_fmac_f32_e32 v74, v42, v42
	v_fmac_f32_e32 v75, v40, v40
	v_add_f32_e32 v89, v74, v75
	v_mul_f32_e32 v74, v59, v59
	v_mul_f32_e32 v75, v45, v45
	v_fmac_f32_e32 v74, v58, v58
	v_fmac_f32_e32 v75, v44, v44
	v_add_f32_e32 v90, v74, v75
	global_load_dwordx4 v[74:77], v153, s[4:5]
	global_load_dwordx4 v[78:81], v154, s[4:5]
	global_load_dwordx4 v[82:85], v155, s[4:5]
	v_mul_f32_e32 v28, v49, v49
	v_mul_f32_e32 v29, v47, v47
	v_fmac_f32_e32 v29, v46, v46
	v_fmac_f32_e32 v28, v48, v48
	v_add_f32_e32 v28, v28, v29
	v_add_f32_e32 v28, v28, v60
	v_add_f32_e32 v28, v28, v61
	v_add_f32_e32 v28, v28, v86
	v_add_f32_e32 v28, v28, v87
	v_add_f32_e32 v28, v28, v88
	v_add_f32_e32 v28, v28, v89
	v_add_f32_e32 v28, v28, v90
	v_mov_b32_e32 v29, 0
	v_mov_b32_e32 v91, 0x358637bd
	v_add_f32_dpp v28, v28, v28 quad_perm:[1,0,3,2] row_mask:0xf bank_mask:0xf bound_ctrl:1
	v_mov_b32_e32 v98, 0x3a000000
	s_waitcnt vmcnt(15)
	v_cvt_f32_f16_e32 v60, v27
	v_add_f32_dpp v28, v28, v28 quad_perm:[2,3,0,1] row_mask:0xf bank_mask:0xf bound_ctrl:1
	v_cvt_f32_f16_sdwa v61, v27 dst_sel:DWORD dst_unused:UNUSED_PAD src0_sel:WORD_1
	s_waitcnt vmcnt(7)
	v_pk_mul_f32 v[46:47], v[46:47], v[52:53]
	v_add_f32_dpp v28, v28, v28 row_half_mirror row_mask:0xf bank_mask:0xf bound_ctrl:1
	v_cvt_f32_f16_e32 v86, v26
	v_cvt_f32_f16_sdwa v87, v26 dst_sel:DWORD dst_unused:UNUSED_PAD src0_sel:WORD_1
	v_add_f32_dpp v28, v28, v28 row_mirror row_mask:0xf bank_mask:0xf bound_ctrl:1
	v_pk_mul_f32 v[48:49], v[48:49], v[50:51]
	v_mov_b32_e32 v99, 0
	v_mov_b32_dpp v29, v28 row_bcast:15 row_mask:0xa bank_mask:0xf
	v_add_f32_e32 v28, v28, v29
	v_mov_b32_e32 v29, 0
	s_waitcnt vmcnt(6)
	v_pk_mul_f32 v[22:23], v[22:23], v[56:57]
	v_mov_b32_dpp v29, v28 row_bcast:31 row_mask:0xc bank_mask:0xf
	v_add_f32_e32 v28, v28, v29
	v_pk_mul_f32 v[24:25], v[24:25], v[54:55]
	v_readlane_b32 s12, v28, 63
	s_waitcnt vmcnt(5)
	v_pk_mul_f32 v[18:19], v[18:19], v[64:65]
	v_fma_f32 v28, s12, v98, v91
	v_rsq_f32_e32 v28, v28
	v_pk_mul_f32 v[20:21], v[20:21], v[62:63]
	v_mul_f32_e32 v90, 0.5, v28
	v_pk_fma_f32 v[60:61], v[46:47], v[90:91], v[60:61] op_sel_hi:[1,0,1]
	v_cvt_f32_f16_e32 v46, v14
	v_cvt_f32_f16_sdwa v47, v14 dst_sel:DWORD dst_unused:UNUSED_PAD src0_sel:WORD_1
	v_cvt_f32_f16_e32 v14, v15
	v_cvt_f32_f16_sdwa v15, v15 dst_sel:DWORD dst_unused:UNUSED_PAD src0_sel:WORD_1
	v_pk_fma_f32 v[92:93], v[48:49], v[90:91], v[86:87] op_sel_hi:[1,0,1]
	global_load_dwordx4 v[26:29], v148, s[6:7]
	v_pk_fma_f32 v[96:97], v[24:25], v[90:91], v[46:47] op_sel_hi:[1,0,1]
	v_pk_fma_f32 v[94:95], v[22:23], v[90:91], v[14:15] op_sel_hi:[1,0,1]
	v_cvt_f32_f16_e32 v14, v12
	v_cvt_f32_f16_sdwa v15, v12 dst_sel:DWORD dst_unused:UNUSED_PAD src0_sel:WORD_1
	v_cvt_f32_f16_e32 v12, v13
	v_cvt_f32_f16_sdwa v13, v13 dst_sel:DWORD dst_unused:UNUSED_PAD src0_sel:WORD_1
	global_load_dwordx4 v[86:89], v150, s[6:7]
	global_load_dwordx4 v[22:25], v151, s[6:7]
	v_pk_fma_f32 v[62:63], v[20:21], v[90:91], v[14:15] op_sel_hi:[1,0,1]
	v_pk_fma_f32 v[56:57], v[18:19], v[90:91], v[12:13] op_sel_hi:[1,0,1]
	v_cvt_f32_f16_e32 v12, v10
	v_cvt_f32_f16_sdwa v13, v10 dst_sel:DWORD dst_unused:UNUSED_PAD src0_sel:WORD_1
	v_cvt_f32_f16_e32 v10, v11
	v_cvt_f32_f16_sdwa v11, v11 dst_sel:DWORD dst_unused:UNUSED_PAD src0_sel:WORD_1
	s_waitcnt vmcnt(7)
	v_pk_mul_f32 v[14:15], v[16:17], v[68:69]
	v_pk_mul_f32 v[16:17], v[38:39], v[66:67]
	global_load_dwordx4 v[18:21], v152, s[6:7]
	v_pk_fma_f32 v[52:53], v[14:15], v[90:91], v[10:11] op_sel_hi:[1,0,1]
	v_cvt_f32_f16_e32 v10, v8
	v_cvt_f32_f16_sdwa v11, v8 dst_sel:DWORD dst_unused:UNUSED_PAD src0_sel:WORD_1
	v_cvt_f32_f16_e32 v8, v9
	v_cvt_f32_f16_sdwa v9, v9 dst_sel:DWORD dst_unused:UNUSED_PAD src0_sel:WORD_1
	v_pk_fma_f32 v[54:55], v[16:17], v[90:91], v[12:13] op_sel_hi:[1,0,1]
	s_waitcnt vmcnt(7)
	v_pk_mul_f32 v[12:13], v[30:31], v[72:73]
	v_pk_mul_f32 v[30:31], v[32:33], v[70:71]
	v_pk_fma_f32 v[48:49], v[12:13], v[90:91], v[8:9] op_sel_hi:[1,0,1]
	v_cvt_f32_f16_e32 v8, v6
	v_cvt_f32_f16_sdwa v9, v6 dst_sel:DWORD dst_unused:UNUSED_PAD src0_sel:WORD_1
	v_cvt_f32_f16_e32 v6, v7
	v_cvt_f32_f16_sdwa v7, v7 dst_sel:DWORD dst_unused:UNUSED_PAD src0_sel:WORD_1
	v_pk_fma_f32 v[50:51], v[30:31], v[90:91], v[10:11] op_sel_hi:[1,0,1]
	s_waitcnt vmcnt(6)
	v_pk_mul_f32 v[30:31], v[34:35], v[76:77]
	v_pk_mul_f32 v[32:33], v[36:37], v[74:75]
	v_pk_fma_f32 v[38:39], v[30:31], v[90:91], v[6:7] op_sel_hi:[1,0,1]
	v_cvt_f32_f16_e32 v30, v4
	v_cvt_f32_f16_sdwa v31, v4 dst_sel:DWORD dst_unused:UNUSED_PAD src0_sel:WORD_1
	v_cvt_f32_f16_e32 v4, v5
	v_cvt_f32_f16_sdwa v5, v5 dst_sel:DWORD dst_unused:UNUSED_PAD src0_sel:WORD_1
	v_pk_fma_f32 v[46:47], v[32:33], v[90:91], v[8:9] op_sel_hi:[1,0,1]
	s_waitcnt vmcnt(5)
	v_pk_mul_f32 v[32:33], v[40:41], v[80:81]
	v_pk_mul_f32 v[34:35], v[42:43], v[78:79]
	global_load_dwordx4 v[14:17], v149, s[6:7]
	global_load_dwordx4 v[10:13], v153, s[6:7]
	global_load_dwordx4 v[6:9], v154, s[6:7]
	v_pk_fma_f32 v[32:33], v[32:33], v[90:91], v[4:5] op_sel_hi:[1,0,1]
	v_pk_fma_f32 v[36:37], v[34:35], v[90:91], v[30:31] op_sel_hi:[1,0,1]
	v_cvt_f32_f16_e32 v34, v2
	v_cvt_f32_f16_sdwa v35, v2 dst_sel:DWORD dst_unused:UNUSED_PAD src0_sel:WORD_1
	v_cvt_f32_f16_e32 v30, v3
	v_cvt_f32_f16_sdwa v31, v3 dst_sel:DWORD dst_unused:UNUSED_PAD src0_sel:WORD_1
	global_load_dwordx4 v[2:5], v155, s[6:7]
	s_waitcnt vmcnt(8)
	v_pk_mul_f32 v[40:41], v[44:45], v[84:85]
	v_cvt_f16_f32_e32 v44, v92
	v_cvt_f16_f32_sdwa v45, v93 dst_sel:WORD_1 dst_unused:UNUSED_PAD src0_sel:DWORD
	v_pk_mul_f32 v[42:43], v[58:59], v[82:83]
	v_pk_fma_f32 v[30:31], v[40:41], v[90:91], v[30:31] op_sel_hi:[1,0,1]
	v_pk_fma_f32 v[34:35], v[42:43], v[90:91], v[34:35] op_sel_hi:[1,0,1]
	v_cvt_f16_f32_e32 v41, v60
	v_cvt_f16_f32_sdwa v42, v61 dst_sel:WORD_1 dst_unused:UNUSED_PAD src0_sel:DWORD
	v_or_b32_e32 v40, v45, v44
	v_cvt_f16_f32_e32 v43, v96
	v_cvt_f16_f32_sdwa v44, v97 dst_sel:WORD_1 dst_unused:UNUSED_PAD src0_sel:DWORD
	v_cvt_f16_f32_e32 v45, v94
	v_cvt_f16_f32_sdwa v58, v95 dst_sel:WORD_1 dst_unused:UNUSED_PAD src0_sel:DWORD
	v_or_b32_e32 v41, v42, v41
	global_store_dwordx2 v1, v[40:41], s[8:9] sc1
	v_or_b32_e32 v40, v44, v43
	v_or_b32_e32 v41, v58, v45
	global_store_dwordx2 v1, v[40:41], s[8:9] offset:512 sc1
	v_cvt_f16_f32_e32 v40, v62
	v_cvt_f16_f32_sdwa v41, v63 dst_sel:WORD_1 dst_unused:UNUSED_PAD src0_sel:DWORD
	v_cvt_f16_f32_e32 v42, v56
	v_cvt_f16_f32_sdwa v43, v57 dst_sel:WORD_1 dst_unused:UNUSED_PAD src0_sel:DWORD
	v_cvt_f16_f32_e32 v44, v54
	v_cvt_f16_f32_sdwa v45, v55 dst_sel:WORD_1 dst_unused:UNUSED_PAD src0_sel:DWORD
	v_or_b32_e32 v40, v41, v40
	v_or_b32_e32 v41, v43, v42
	global_store_dwordx2 v1, v[40:41], s[8:9] offset:1024 sc1
	v_cvt_f16_f32_e32 v41, v52
	v_cvt_f16_f32_sdwa v42, v53 dst_sel:WORD_1 dst_unused:UNUSED_PAD src0_sel:DWORD
	v_or_b32_e32 v40, v45, v44
	v_cvt_f16_f32_e32 v43, v50
	v_cvt_f16_f32_sdwa v44, v51 dst_sel:WORD_1 dst_unused:UNUSED_PAD src0_sel:DWORD
	v_cvt_f16_f32_e32 v45, v48
	v_cvt_f16_f32_sdwa v58, v49 dst_sel:WORD_1 dst_unused:UNUSED_PAD src0_sel:DWORD
	v_or_b32_e32 v41, v42, v41
	global_store_dwordx2 v1, v[40:41], s[8:9] offset:1536 sc1
	v_or_b32_e32 v40, v44, v43
	v_or_b32_e32 v41, v58, v45
	global_store_dwordx2 v1, v[40:41], s[8:9] offset:2048 sc1
	v_cvt_f16_f32_e32 v40, v46
	v_cvt_f16_f32_sdwa v41, v47 dst_sel:WORD_1 dst_unused:UNUSED_PAD src0_sel:DWORD
	v_cvt_f16_f32_e32 v42, v38
	v_cvt_f16_f32_sdwa v43, v39 dst_sel:WORD_1 dst_unused:UNUSED_PAD src0_sel:DWORD
	v_cvt_f16_f32_e32 v44, v36
	v_cvt_f16_f32_sdwa v45, v37 dst_sel:WORD_1 dst_unused:UNUSED_PAD src0_sel:DWORD
	v_or_b32_e32 v40, v41, v40
	v_or_b32_e32 v41, v43, v42
	global_store_dwordx2 v1, v[40:41], s[8:9] offset:2560 sc1
	v_cvt_f16_f32_e32 v41, v32
	v_cvt_f16_f32_sdwa v42, v33 dst_sel:WORD_1 dst_unused:UNUSED_PAD src0_sel:DWORD
	v_or_b32_e32 v40, v45, v44
	v_cvt_f16_f32_e32 v43, v34
	v_cvt_f16_f32_sdwa v44, v35 dst_sel:WORD_1 dst_unused:UNUSED_PAD src0_sel:DWORD
	v_cvt_f16_f32_e32 v45, v30
	v_cvt_f16_f32_sdwa v58, v31 dst_sel:WORD_1 dst_unused:UNUSED_PAD src0_sel:DWORD
	v_or_b32_e32 v41, v42, v41
	global_store_dwordx2 v1, v[40:41], s[8:9] offset:3072 sc1
	v_or_b32_e32 v40, v44, v43
	v_or_b32_e32 v41, v58, v45
	v_mov_b32_e32 v42, v93
	v_mov_b32_e32 v43, v97
	global_store_dwordx2 v1, v[40:41], s[8:9] offset:3584 sc1
	v_mov_b32_e32 v40, v92
	v_mov_b32_e32 v41, v96
	v_pk_mul_f32 v[42:43], v[42:43], v[42:43]
	v_mov_b32_e32 v44, v61
	v_mov_b32_e32 v45, v95
	v_pk_fma_f32 v[40:41], v[40:41], v[40:41], v[42:43]
	v_mov_b32_e32 v42, v60
	v_mov_b32_e32 v43, v94
	v_pk_mul_f32 v[44:45], v[44:45], v[44:45]
	s_waitcnt vmcnt(15)
	v_pk_mul_f32 v[26:27], v[26:27], v[92:93]
	v_pk_fma_f32 v[42:43], v[42:43], v[42:43], v[44:45]
	v_pk_mul_f32 v[44:45], v[62:63], v[62:63]
	v_pk_add_f32 v[40:41], v[40:41], v[42:43]
	v_pk_mul_f32 v[42:43], v[56:57], v[56:57]
	v_pk_add_f32 v[40:41], v[40:41], v[40:41] op_sel_hi:[0,1]
	v_pk_mov_b32 v[58:59], v[44:45], v[42:43] op_sel:[1,0]
	v_mov_b32_e32 v45, v43
	v_mul_f32_e32 v40, v54, v54
	v_pk_add_f32 v[42:43], v[58:59], v[44:45]
	v_pk_fma_f32 v[44:45], v[54:55], v[54:55], v[40:41] op_sel_hi:[1,1,0]
	v_mul_f32_e32 v40, v52, v52
	v_pk_add_f32 v[42:43], v[42:43], v[42:43] op_sel_hi:[0,1]
	v_pk_fma_f32 v[58:59], v[52:53], v[52:53], v[40:41] op_sel_hi:[1,1,0]
	v_mul_f32_e32 v44, v50, v50
	v_mul_f32_e32 v58, v51, v51
	v_mul_f32_e32 v42, v48, v48
	v_mul_f32_e32 v40, v49, v49
	v_pk_add_f32 v[44:45], v[44:45], v[58:59]
	v_pk_add_f32 v[40:41], v[42:43], v[40:41]
	v_pk_mul_f32 v[42:43], v[38:39], v[38:39]
	v_pk_add_f32 v[40:41], v[44:45], v[40:41]
	v_pk_mul_f32 v[44:45], v[46:47], v[46:47]
	v_pk_add_f32 v[40:41], v[40:41], v[40:41] op_sel_hi:[0,1]
	v_pk_mov_b32 v[58:59], v[44:45], v[42:43] op_sel:[1,0]
	v_mov_b32_e32 v45, v43
	v_mul_f32_e32 v40, v36, v36
	v_pk_add_f32 v[42:43], v[58:59], v[44:45]
	v_pk_fma_f32 v[44:45], v[36:37], v[36:37], v[40:41] op_sel_hi:[1,1,0]
	v_mul_f32_e32 v40, v32, v32
	v_pk_add_f32 v[42:43], v[42:43], v[42:43] op_sel_hi:[0,1]
	v_pk_fma_f32 v[58:59], v[32:33], v[32:33], v[40:41] op_sel_hi:[1,1,0]
	v_mul_f32_e32 v44, v34, v34
	v_mul_f32_e32 v58, v35, v35
	v_mul_f32_e32 v42, v30, v30
	v_mul_f32_e32 v40, v31, v31
	v_pk_add_f32 v[44:45], v[44:45], v[58:59]
	v_pk_add_f32 v[40:41], v[42:43], v[40:41]
	v_pk_mul_f32 v[28:29], v[28:29], v[60:61]
	v_pk_add_f32 v[40:41], v[44:45], v[40:41]
	s_waitcnt vmcnt(13)
	v_pk_mul_f32 v[22:23], v[22:23], v[62:63]
	v_add_f32_e32 v40, v40, v41
	v_mov_b32_e32 v41, 0
	s_waitcnt vmcnt(12)
	v_pk_mul_f32 v[18:19], v[18:19], v[54:55]
	v_add_f32_dpp v40, v40, v40 quad_perm:[1,0,3,2] row_mask:0xf bank_mask:0xf bound_ctrl:1
	s_waitcnt vmcnt(11)
	v_pk_mul_f32 v[14:15], v[14:15], v[50:51]
	s_waitcnt vmcnt(10)
	v_pk_mul_f32 v[10:11], v[10:11], v[46:47]
	v_add_f32_dpp v40, v40, v40 quad_perm:[2,3,0,1] row_mask:0xf bank_mask:0xf bound_ctrl:1
	s_waitcnt vmcnt(9)
	v_pk_mul_f32 v[6:7], v[6:7], v[36:37]
	s_waitcnt vmcnt(8)
	v_pk_mul_f32 v[2:3], v[34:35], v[2:3]
	v_add_f32_dpp v40, v40, v40 row_half_mirror row_mask:0xf bank_mask:0xf bound_ctrl:1
	v_pk_mul_f32 v[42:43], v[86:87], v[96:97]
	v_pk_mul_f32 v[44:45], v[88:89], v[94:95]
	v_add_f32_dpp v40, v40, v40 row_mirror row_mask:0xf bank_mask:0xf bound_ctrl:1
	v_pk_mul_f32 v[24:25], v[24:25], v[56:57]
	v_pk_mul_f32 v[20:21], v[20:21], v[52:53]
	v_mov_b32_dpp v41, v40 row_bcast:15 row_mask:0xa bank_mask:0xf
	v_add_f32_e32 v40, v40, v41
	v_pk_mul_f32 v[16:17], v[16:17], v[48:49]
	v_pk_mul_f32 v[12:13], v[12:13], v[38:39]
	v_mov_b32_dpp v99, v40 row_bcast:31 row_mask:0xc bank_mask:0xf
	v_add_f32_e32 v40, v40, v99
	v_pk_mul_f32 v[8:9], v[8:9], v[32:33]
	v_readlane_b32 s8, v40, 63
	v_pk_mul_f32 v[4:5], v[30:31], v[4:5]
	s_nop 0
	v_fmac_f32_e32 v91, s8, v98
	v_rsq_f32_e32 v40, v91
	v_readlane_b32 s8, v254, 60
	v_readlane_b32 s9, v254, 61
	s_add_u32 s8, s8, s10
	v_pk_mul_f32 v[26:27], v[26:27], v[40:41] op_sel_hi:[1,0]
	s_addc_u32 s9, s9, s11
	v_pk_mul_f32 v[28:29], v[28:29], v[40:41] op_sel_hi:[1,0]
	v_cvt_pk_bf16_f32 v26, v26, v27
	v_pk_mul_f32 v[22:23], v[22:23], v[40:41] op_sel_hi:[1,0]
	v_cvt_pk_bf16_f32 v27, v28, v29
	v_pk_mul_f32 v[18:19], v[18:19], v[40:41] op_sel_hi:[1,0]
	v_pk_mul_f32 v[14:15], v[14:15], v[40:41] op_sel_hi:[1,0]
	v_pk_mul_f32 v[10:11], v[10:11], v[40:41] op_sel_hi:[1,0]
	v_pk_mul_f32 v[6:7], v[6:7], v[40:41] op_sel_hi:[1,0]
	v_pk_mul_f32 v[2:3], v[2:3], v[40:41] op_sel_hi:[1,0]
	v_pk_mul_f32 v[44:45], v[44:45], v[40:41] op_sel_hi:[1,0]
	v_pk_mul_f32 v[42:43], v[42:43], v[40:41] op_sel_hi:[1,0]
	global_store_dwordx2 v1, v[26:27], s[8:9] sc1
	v_cvt_pk_bf16_f32 v26, v42, v43
	v_cvt_pk_bf16_f32 v27, v44, v45
	global_store_dwordx2 v1, v[26:27], s[8:9] offset:512 sc1
	v_pk_mul_f32 v[24:25], v[24:25], v[40:41] op_sel_hi:[1,0]
	v_cvt_pk_bf16_f32 v22, v22, v23
	v_pk_mul_f32 v[20:21], v[20:21], v[40:41] op_sel_hi:[1,0]
	v_cvt_pk_bf16_f32 v23, v24, v25
	global_store_dwordx2 v1, v[22:23], s[8:9] offset:1024 sc1
	v_cvt_pk_bf16_f32 v18, v18, v19
	v_cvt_pk_bf16_f32 v19, v20, v21
	global_store_dwordx2 v1, v[18:19], s[8:9] offset:1536 sc1
	v_pk_mul_f32 v[16:17], v[16:17], v[40:41] op_sel_hi:[1,0]
	v_cvt_pk_bf16_f32 v14, v14, v15
	v_pk_mul_f32 v[12:13], v[12:13], v[40:41] op_sel_hi:[1,0]
	v_cvt_pk_bf16_f32 v15, v16, v17
	global_store_dwordx2 v1, v[14:15], s[8:9] offset:2048 sc1
	v_cvt_pk_bf16_f32 v10, v10, v11
	v_cvt_pk_bf16_f32 v11, v12, v13
	global_store_dwordx2 v1, v[10:11], s[8:9] offset:2560 sc1
	v_pk_mul_f32 v[8:9], v[8:9], v[40:41] op_sel_hi:[1,0]
	v_cvt_pk_bf16_f32 v6, v6, v7
	v_pk_mul_f32 v[4:5], v[4:5], v[40:41] op_sel_hi:[1,0]
	v_cvt_pk_bf16_f32 v7, v8, v9
	global_store_dwordx2 v1, v[6:7], s[8:9] offset:3072 sc1
	v_cvt_pk_bf16_f32 v2, v2, v3
	v_cvt_pk_bf16_f32 v3, v4, v5
	global_store_dwordx2 v1, v[2:3], s[8:9] offset:3584 sc1

.LBB0_318:
	s_cbranch_execz .LBB0_325
	s_ashr_i32 s9, s90, 5
	s_abs_i32 s8, s9
	v_cvt_f32_u32_e32 v1, s8
	s_sub_i32 s12, 0, s8
	s_abs_i32 s10, s62
	s_xor_b32 s11, s62, s9
	v_rcp_iflag_f32_e32 v1, v1
	s_ashr_i32 s11, s11, 31
	v_mul_f32_e32 v1, 0x4f7ffffe, v1
	v_cvt_u32_f32_e32 v1, v1
	s_nop 0
	v_readfirstlane_b32 s13, v1
	s_mul_i32 s12, s12, s13
	s_mul_hi_u32 s12, s13, s12
	s_add_i32 s13, s13, s12
	s_mul_hi_u32 s12, s10, s13
	s_mul_i32 s13, s12, s8
	s_sub_i32 s10, s10, s13
	s_add_i32 s14, s12, 1
	s_sub_i32 s13, s10, s8
	s_cmp_ge_u32 s10, s8
	s_cselect_b32 s12, s14, s12
	s_cselect_b32 s10, s13, s10
	s_add_i32 s13, s12, 1
	s_cmp_ge_u32 s10, s8
	s_cselect_b32 s8, s13, s12
	s_xor_b32 s8, s8, s11
	s_sub_i32 s8, s8, s11
	s_mul_i32 s9, s8, s9
	s_sub_i32 s9, s62, s9
	s_cmp_lg_u32 s9, 0
	s_cbranch_scc1 .LBB0_325
	s_ashr_i32 s9, s8, 31
	s_lshl_b64 s[10:11], s[8:9], 13
	v_readlane_b32 s12, v254, 58
	v_readlane_b32 s13, v254, 59
	s_add_u32 s10, s12, s10
	s_addc_u32 s11, s13, s11
	v_mov_b32_e32 v13, 0
	v_lshlrev_b32_e32 v12, 4, v0
	v_lshl_add_u64 v[2:3], s[10:11], 0, v[12:13]
	v_add_co_u32_e32 v4, vcc, 0x40000, v2
	s_waitcnt vmcnt(0)
	v_mov_b32_e32 v18, v186
	v_mov_b32_e32 v19, v187
	v_mov_b32_e32 v20, v188
	v_mov_b32_e32 v21, v189
	s_nop 0
	v_addc_co_u32_e32 v5, vcc, 0, v3, vcc
	v_add_co_u32_e32 v6, vcc, 0x80000, v2
	s_addk_i32 s8, 0x2000
	s_nop 0
	v_addc_co_u32_e32 v7, vcc, 0, v3, vcc
	v_add_co_u32_e32 v2, vcc, 0xc0000, v2
	v_mov_b32_e32 v22, v190
	v_mov_b32_e32 v23, v191
	v_mov_b32_e32 v24, v192
	v_mov_b32_e32 v25, v193
	v_mov_b32_e32 v26, v194
	v_mov_b32_e32 v27, v195
	v_mov_b32_e32 v28, v196
	v_mov_b32_e32 v29, v197
	v_addc_co_u32_e32 v3, vcc, 0, v3, vcc
	v_mov_b32_e32 v30, v198
	v_mov_b32_e32 v31, v199
	v_mov_b32_e32 v32, v200
	v_mov_b32_e32 v33, v201
	s_ashr_i32 s9, s8, 31
	s_lshl_b64 s[10:11], s[8:9], 12
	v_readlane_b32 s12, v254, 54
	v_readlane_b32 s13, v254, 55
	s_add_u32 s10, s12, s10
	s_addc_u32 s11, s13, s11
	v_lshlrev_b32_e32 v10, 3, v0
	v_mov_b32_e32 v6, v174
	v_mov_b32_e32 v7, v175
	v_mov_b32_e32 v8, v176
	v_mov_b32_e32 v9, v177
	v_mov_b32_e32 v2, v170
	v_mov_b32_e32 v3, v171
	v_mov_b32_e32 v4, v172
	v_mov_b32_e32 v5, v173
	v_mov_b32_e32 v14, v182
	v_mov_b32_e32 v15, v183
	v_mov_b32_e32 v11, v13
	v_lshl_add_u64 v[16:17], s[10:11], 0, v[10:11]
	v_mov_b32_e32 v1, v13
	v_mov_b32_e32 v12, v13
	v_cmp_eq_u32_e32 vcc, 0, v166
	s_waitcnt vmcnt(5)
	v_pk_add_f32 v[20:21], v[20:21], v[24:25]
	v_pk_add_f32 v[22:23], v[18:19], v[22:23]
	s_waitcnt vmcnt(3)
	v_pk_add_f32 v[18:19], v[28:29], v[32:33]
	v_pk_add_f32 v[24:25], v[26:27], v[30:31]
	v_pk_add_f32 v[18:19], v[20:21], v[18:19]
	v_pk_add_f32 v[20:21], v[22:23], v[24:25]
	v_mul_f32_e32 v22, v19, v19
	v_mul_f32_e32 v11, v21, v21
	v_fmac_f32_e32 v11, v20, v20
	v_fmac_f32_e32 v22, v18, v18
	v_add_f32_e32 v11, v11, v22
	s_nop 1
	v_add_f32_dpp v11, v11, v11 quad_perm:[1,0,3,2] row_mask:0xf bank_mask:0xf bound_ctrl:1
	s_nop 1
	v_add_f32_dpp v11, v11, v11 quad_perm:[2,3,0,1] row_mask:0xf bank_mask:0xf bound_ctrl:1
	s_nop 1
	v_add_f32_dpp v11, v11, v11 row_half_mirror row_mask:0xf bank_mask:0xf bound_ctrl:1
	s_nop 1
	v_add_f32_dpp v11, v11, v11 row_mirror row_mask:0xf bank_mask:0xf bound_ctrl:1
	s_nop 1
	v_mov_b32_dpp v1, v11 row_bcast:15 row_mask:0xa bank_mask:0xf
	v_add_f32_e32 v1, v11, v1
	s_nop 1
	v_mov_b32_dpp v12, v1 row_bcast:31 row_mask:0xc bank_mask:0xf
	v_add_f32_e32 v1, v1, v12
	s_nop 0
	v_readlane_b32 s6, v1, 63
	s_and_saveexec_b64 s[4:5], vcc
	s_lshl_b32 s7, s96, 2
	s_add_i32 s7, s7, 0
	v_mov_b32_e32 v1, s7
	v_mov_b32_e32 v11, s6
	ds_write_b32 v1, v11
	s_or_b64 exec, exec, s[4:5]
	s_waitcnt lgkmcnt(0)
	s_barrier
	ds_read_b128 v[22:25], v13
	ds_read_b128 v[26:29], v13 offset:16
	s_waitcnt vmcnt(2)
	v_pk_mul_f32 v[6:7], v[6:7], v[20:21]
	v_pk_mul_f32 v[8:9], v[8:9], v[18:19]
	s_lshl_b64 s[4:5], s[8:9], 11
	s_waitcnt lgkmcnt(1)
	v_add_f32_e32 v1, 0, v22
	v_add_f32_e32 v1, v1, v23
	v_add_f32_e32 v1, v1, v24
	v_add_f32_e32 v1, v1, v25
	s_waitcnt lgkmcnt(0)
	v_add_f32_e32 v1, v1, v26
	v_add_f32_e32 v1, v1, v27
	v_add_f32_e32 v1, v1, v28
	v_add_f32_e32 v11, v1, v29
	v_mov_b32_e32 v1, 0x358637bd
	v_fmamk_f32 v11, v11, 0x3a000000, v1
	v_rsq_f32_e32 v11, v11
	s_waitcnt vmcnt(0)
	v_cvt_f32_f16_sdwa v23, v14 dst_sel:DWORD dst_unused:UNUSED_PAD src0_sel:WORD_1
	v_cvt_f32_f16_e32 v22, v14
	v_cvt_f32_f16_sdwa v25, v15 dst_sel:DWORD dst_unused:UNUSED_PAD src0_sel:WORD_1
	v_cvt_f32_f16_e32 v24, v15
	v_mul_f32_e32 v12, 0.5, v11
	v_pk_fma_f32 v[6:7], v[6:7], v[12:13], v[22:23] op_sel_hi:[1,0,1]
	v_pk_fma_f32 v[8:9], v[8:9], v[12:13], v[24:25] op_sel_hi:[1,0,1]
	v_cvt_f16_f32_e32 v11, v6
	v_cvt_f16_f32_sdwa v12, v7 dst_sel:WORD_1 dst_unused:UNUSED_PAD src0_sel:DWORD
	v_cvt_f16_f32_e32 v15, v8
	v_cvt_f16_f32_sdwa v18, v9 dst_sel:WORD_1 dst_unused:UNUSED_PAD src0_sel:DWORD
	v_or_b32_e32 v14, v12, v11
	v_mul_f32_e32 v11, v7, v7
	v_mul_f32_e32 v12, v9, v9
	v_fmac_f32_e32 v11, v6, v6
	v_fmac_f32_e32 v12, v8, v8
	v_add_f32_e32 v11, v11, v12
	v_mov_b32_e32 v12, 0
	v_or_b32_e32 v15, v18, v15
	v_add_f32_dpp v11, v11, v11 quad_perm:[1,0,3,2] row_mask:0xf bank_mask:0xf bound_ctrl:1
	global_store_dwordx2 v[16:17], v[14:15], off sc1
	s_nop 0
	v_add_f32_dpp v11, v11, v11 quad_perm:[2,3,0,1] row_mask:0xf bank_mask:0xf bound_ctrl:1
	s_nop 1
	v_add_f32_dpp v11, v11, v11 row_half_mirror row_mask:0xf bank_mask:0xf bound_ctrl:1
	s_nop 1
	v_add_f32_dpp v11, v11, v11 row_mirror row_mask:0xf bank_mask:0xf bound_ctrl:1
	s_nop 1
	v_mov_b32_dpp v12, v11 row_bcast:15 row_mask:0xa bank_mask:0xf
	v_add_f32_e32 v11, v11, v12
	s_nop 1
	v_mov_b32_dpp v13, v11 row_bcast:31 row_mask:0xc bank_mask:0xf
	v_add_f32_e32 v11, v11, v13
	s_nop 0
	v_readlane_b32 s8, v11, 63
	s_and_saveexec_b64 s[6:7], vcc
	s_lshl_b32 s9, s96, 2
	s_add_i32 s9, s9, 0
	v_mov_b32_e32 v11, s9
	v_mov_b32_e32 v12, s8
	ds_write_b32 v11, v12 offset:32
	s_or_b64 exec, exec, s[6:7]
	v_mov_b32_e32 v11, 0
	s_waitcnt lgkmcnt(0)
	s_barrier
	ds_read_b128 v[12:15], v11 offset:32
	ds_read_b128 v[16:19], v11 offset:48
	s_lshl_b64 s[4:5], s[4:5], 1
	v_readlane_b32 s6, v254, 60
	v_pk_mul_f32 v[2:3], v[2:3], v[6:7]
	s_waitcnt lgkmcnt(1)
	v_add_f32_e32 v11, 0, v12
	v_add_f32_e32 v11, v11, v13
	v_add_f32_e32 v11, v11, v14
	v_add_f32_e32 v11, v11, v15
	s_waitcnt lgkmcnt(0)
	v_add_f32_e32 v11, v11, v16
	v_add_f32_e32 v11, v11, v17
	v_add_f32_e32 v11, v11, v18
	v_add_f32_e32 v11, v11, v19
	v_fmac_f32_e32 v1, 0x3a000000, v11
	v_rsq_f32_e32 v12, v1
	v_readlane_b32 s7, v254, 61
	s_add_u32 s4, s6, s4
	v_pk_mul_f32 v[4:5], v[4:5], v[8:9]
	v_pk_mul_f32 v[2:3], v[2:3], v[12:13] op_sel_hi:[1,0]
	s_addc_u32 s5, s7, s5
	v_pk_mul_f32 v[4:5], v[4:5], v[12:13] op_sel_hi:[1,0]
	v_cvt_pk_bf16_f32 v2, v2, v3
	s_nop 0
	v_cvt_pk_bf16_f32 v3, v4, v5
	global_store_dwordx2 v10, v[2:3], s[4:5] sc1
	s_barrier

.LBB0_638:
	s_or_b64 exec, exec, s[26:27]
	v_div_scale_f32 v140, s[26:27], s17, s17, v139
	v_rcp_f32_e32 v141, v140
	v_mov_b32_e32 v142, s17
	v_div_scale_f32 v142, vcc, s30, v142, s30
	v_fma_f32 v143, -v140, v141, 1.0
	v_fmac_f32_e32 v141, v143, v141
	v_mul_f32_e32 v143, v142, v141
	v_fma_f32 v144, -v140, v143, v142
	v_fmac_f32_e32 v143, v144, v141
	v_fma_f32 v140, -v140, v143, v142
	v_div_fmas_f32 v140, v140, v141, v143
	v_div_fixup_f32 v140, v140, s17, v139
	v_cndmask_b32_e64 v140, 0, v140, s[6:7]
	v_fmaak_f32 v128, v128, v140, 0x4b400000
	v_fmaak_f32 v129, v129, v140, 0x4b400000
	v_fmaak_f32 v122, v122, v140, 0x4b400000
	v_perm_b32 v128, v129, v128, s31
	v_fmaak_f32 v123, v123, v140, 0x4b400000
	v_perm_b32 v122, v122, v128, s34
	v_perm_b32 v122, v123, v122, s35
	v_fmaak_f32 v123, v124, v140, 0x4b400000
	v_fmaak_f32 v124, v125, v140, 0x4b400000
	v_fmaak_f32 v114, v114, v140, 0x4b400000
	v_fmaak_f32 v115, v115, v140, 0x4b400000
	v_fmaak_f32 v106, v106, v140, 0x4b400000
	v_fmaak_f32 v107, v107, v140, 0x4b400000
	v_fmaak_f32 v98, v98, v140, 0x4b400000
	v_fmaak_f32 v99, v99, v140, 0x4b400000
	v_fmaak_f32 v125, v126, v140, 0x4b400000
	v_perm_b32 v123, v124, v123, s31
	v_perm_b32 v114, v115, v114, s31
	v_fmaak_f32 v115, v116, v140, 0x4b400000
	v_fmaak_f32 v116, v117, v140, 0x4b400000
	v_perm_b32 v106, v107, v106, s31
	v_fmaak_f32 v107, v108, v140, 0x4b400000
	v_fmaak_f32 v108, v109, v140, 0x4b400000
	v_perm_b32 v98, v99, v98, s31
	v_fmaak_f32 v99, v100, v140, 0x4b400000
	v_fmaak_f32 v100, v101, v140, 0x4b400000
	v_perm_b32 v123, v125, v123, s34
	v_lshl_add_u64 v[124:125], s[94:95], 0, v[130:131]
	v_fmaak_f32 v118, v118, v140, 0x4b400000
	v_fmaak_f32 v117, v120, v140, 0x4b400000
	v_perm_b32 v115, v116, v115, s31
	v_fmaak_f32 v110, v110, v140, 0x4b400000
	v_fmaak_f32 v109, v112, v140, 0x4b400000
	v_perm_b32 v107, v108, v107, s31
	v_fmaak_f32 v102, v102, v140, 0x4b400000
	v_fmaak_f32 v101, v104, v140, 0x4b400000
	v_perm_b32 v99, v100, v99, s31
	v_fmaak_f32 v126, v127, v140, 0x4b400000
	v_add_co_u32_e32 v124, vcc, s36, v124
	v_fmaak_f32 v119, v119, v140, 0x4b400000
	v_perm_b32 v114, v118, v114, s34
	v_fmaak_f32 v118, v121, v140, 0x4b400000
	v_perm_b32 v115, v117, v115, s34
	v_fmaak_f32 v111, v111, v140, 0x4b400000
	v_perm_b32 v106, v110, v106, s34
	v_fmaak_f32 v110, v113, v140, 0x4b400000
	v_perm_b32 v107, v109, v107, s34
	v_fmaak_f32 v103, v103, v140, 0x4b400000
	v_perm_b32 v98, v102, v98, s34
	v_fmaak_f32 v102, v105, v140, 0x4b400000
	v_perm_b32 v99, v101, v99, s34
	v_perm_b32 v123, v126, v123, s35
	v_addc_co_u32_e32 v125, vcc, 0, v125, vcc
	v_perm_b32 v114, v119, v114, s35
	v_perm_b32 v115, v118, v115, s35
	v_perm_b32 v106, v111, v106, s35
	v_perm_b32 v107, v110, v107, s35
	v_perm_b32 v98, v103, v98, s35
	v_perm_b32 v99, v102, v99, s35
	global_store_dwordx2 v[124:125], v[122:123], off sc1
	global_store_dwordx2 v[124:125], v[114:115], off offset:512 sc1
	global_store_dwordx2 v[124:125], v[106:107], off offset:1024 sc1
	global_store_dwordx2 v[124:125], v[98:99], off offset:1536 sc1
	s_add_u32 s15, s15, s18
	v_mov_b64_e32 v[128:129], v[76:77]
	v_mov_b64_e32 v[124:125], v[84:85]
	v_mov_b64_e32 v[120:121], v[88:89]
	v_mov_b64_e32 v[116:117], v[92:93]
	v_mov_b64_e32 v[112:113], v[68:69]
	v_mov_b64_e32 v[108:109], v[72:73]
	v_mov_b64_e32 v[104:105], v[80:81]
	v_mov_b64_e32 v[100:101], v[96:97]
	s_addc_u32 s37, s37, s19
	v_lshl_add_u64 v[130:131], v[130:131], 0, s[20:21]
	v_lshl_add_u64 v[132:133], v[132:133], 0, s[22:23]
	v_lshl_add_u64 v[134:135], v[134:135], 0, s[22:23]
	s_andn2_b64 vcc, exec, s[24:25]
	v_mov_b64_e32 v[126:127], v[74:75]
	v_mov_b64_e32 v[122:123], v[82:83]
	v_mov_b64_e32 v[118:119], v[86:87]
	v_mov_b64_e32 v[114:115], v[90:91]
	v_mov_b64_e32 v[110:111], v[66:67]
	v_mov_b64_e32 v[106:107], v[70:71]
	v_mov_b64_e32 v[102:103], v[78:79]
	v_mov_b64_e32 v[98:99], v[94:95]
	s_cbranch_vccz .LBB0_643

.LBB0_646:
	s_cmp_gt_i32 s12, 31
	s_cbranch_scc1 .LBB0_650
	s_ashr_i32 s13, s12, 31
	s_lshl_b64 s[4:5], s[12:13], 13
	v_readlane_b32 s6, v254, 58
	v_readlane_b32 s7, v254, 59
	s_add_u32 s4, s6, s4
	s_addc_u32 s5, s7, s5
	s_add_u32 s6, s4, 0x40000
	s_addc_u32 s7, s5, 0
	v_lshlrev_b32_e32 v57, 4, v166
	s_add_u32 s14, s4, 0x80000
	v_or_b32_e32 v149, 0x400, v57
	v_or_b32_e32 v150, 0x800, v57
	v_or_b32_e32 v151, 0xc00, v57
	s_addc_u32 s15, s5, 0
	global_load_dwordx4 v[2:5], v57, s[4:5]
	global_load_dwordx4 v[6:9], v57, s[4:5] offset:1024
	global_load_dwordx4 v[24:27], v57, s[4:5] offset:2048
	global_load_dwordx4 v[28:31], v57, s[4:5] offset:3072
	v_or_b32_e32 v148, 0x1000, v57
	global_load_dwordx4 v[32:35], v57, s[6:7]
	global_load_dwordx4 v[36:39], v149, s[6:7]
	global_load_dwordx4 v[40:43], v150, s[6:7]
	global_load_dwordx4 v[44:47], v151, s[6:7]
	global_load_dwordx4 v[48:51], v148, s[4:5]
	global_load_dwordx4 v[52:55], v148, s[6:7]
	global_load_dwordx4 v[58:61], v57, s[14:15]
	s_add_u32 s16, s4, 0xc0000
	s_addc_u32 s17, s5, 0
	global_load_dwordx4 v[62:65], v57, s[16:17]
	global_load_dwordx4 v[66:69], v149, s[14:15]
	global_load_dwordx4 v[70:73], v149, s[16:17]
	global_load_dwordx4 v[74:77], v150, s[14:15]
	global_load_dwordx4 v[78:81], v150, s[16:17]
	global_load_dwordx4 v[82:85], v151, s[14:15]
	global_load_dwordx4 v[86:89], v151, s[16:17]
	global_load_dwordx4 v[90:93], v148, s[14:15]
	global_load_dwordx4 v[94:97], v148, s[16:17]
	v_or_b32_e32 v152, 0x1400, v57
	global_load_dwordx4 v[98:101], v152, s[4:5]
	global_load_dwordx4 v[102:105], v152, s[6:7]
	global_load_dwordx4 v[106:109], v152, s[14:15]
	global_load_dwordx4 v[110:113], v152, s[16:17]
	v_or_b32_e32 v153, 0x1800, v57
	global_load_dwordx4 v[114:117], v153, s[4:5]
	global_load_dwordx4 v[118:121], v153, s[6:7]
	global_load_dwordx4 v[122:125], v153, s[14:15]
	global_load_dwordx4 v[126:129], v153, s[16:17]
	v_or_b32_e32 v154, 0x1c00, v57
	global_load_dwordx4 v[130:133], v154, s[4:5]
	global_load_dwordx4 v[134:137], v154, s[6:7]
	global_load_dwordx4 v[138:141], v154, s[14:15]
	global_load_dwordx4 v[142:145], v154, s[16:17]
	s_add_i32 s6, s12, 0x2000
	s_ashr_i32 s7, s6, 31
	s_lshl_b64 s[4:5], s[6:7], 12
	v_readlane_b32 s12, v254, 54
	v_readlane_b32 s13, v254, 55
	s_add_u32 s4, s12, s4
	v_lshlrev_b32_e32 v56, 3, v166
	s_addc_u32 s5, s13, s5
	global_load_dwordx2 v[146:147], v56, s[4:5]
	global_load_dwordx2 v[22:23], v56, s[4:5] offset:512
	global_load_dwordx2 v[20:21], v56, s[4:5] offset:1024
	global_load_dwordx2 v[18:19], v56, s[4:5] offset:1536
	global_load_dwordx2 v[16:17], v56, s[4:5] offset:2048
	global_load_dwordx2 v[14:15], v56, s[4:5] offset:2560
	global_load_dwordx2 v[12:13], v56, s[4:5] offset:3072
	global_load_dwordx2 v[10:11], v56, s[4:5] offset:3584
	v_mov_b32_e32 v1, 0
	v_cmp_eq_u32_e32 vcc, 0, v166
	s_waitcnt vmcnt(35)
	v_pk_add_f32 v[4:5], v[4:5], v[34:35]
	v_pk_add_f32 v[2:3], v[2:3], v[32:33]
	s_waitcnt vmcnt(32)
	v_pk_add_f32 v[30:31], v[30:31], v[46:47]
	v_pk_add_f32 v[28:29], v[28:29], v[44:45]
	s_waitcnt vmcnt(28)
	v_pk_add_f32 v[32:33], v[60:61], v[64:65]
	v_pk_add_f32 v[34:35], v[58:59], v[62:63]
	s_waitcnt vmcnt(22)
	v_pk_add_f32 v[58:59], v[84:85], v[88:89]
	v_pk_add_f32 v[60:61], v[82:83], v[86:87]
	v_pk_add_f32 v[8:9], v[8:9], v[38:39]
	v_pk_add_f32 v[6:7], v[6:7], v[36:37]
	v_pk_add_f32 v[36:37], v[50:51], v[54:55]
	v_pk_add_f32 v[38:39], v[48:49], v[52:53]
	v_pk_add_f32 v[52:53], v[4:5], v[32:33]
	v_pk_add_f32 v[54:55], v[2:3], v[34:35]
	v_pk_add_f32 v[32:33], v[30:31], v[58:59]
	v_pk_add_f32 v[34:35], v[28:29], v[60:61]
	global_load_dwordx4 v[58:61], v57, s[8:9]
	v_pk_add_f32 v[26:27], v[26:27], v[42:43]
	v_pk_add_f32 v[24:25], v[24:25], v[40:41]
	v_pk_add_f32 v[42:43], v[66:67], v[70:71]
	v_pk_add_f32 v[46:47], v[74:75], v[78:79]
	s_waitcnt vmcnt(21)
	v_pk_add_f32 v[62:63], v[92:93], v[96:97]
	v_pk_add_f32 v[50:51], v[6:7], v[42:43]
	v_pk_add_f32 v[42:43], v[24:25], v[46:47]
	v_pk_add_f32 v[24:25], v[36:37], v[62:63]
	global_load_dwordx4 v[62:65], v149, s[8:9]
	v_pk_add_f32 v[40:41], v[68:69], v[72:73]
	v_pk_add_f32 v[44:45], v[76:77], v[80:81]
	v_pk_add_f32 v[2:3], v[90:91], v[94:95]
	v_pk_add_f32 v[48:49], v[8:9], v[40:41]
	v_pk_add_f32 v[40:41], v[26:27], v[44:45]
	v_pk_add_f32 v[26:27], v[38:39], v[2:3]
	s_waitcnt vmcnt(20)
	v_pk_add_f32 v[2:3], v[100:101], v[104:105]
	v_pk_add_f32 v[4:5], v[98:99], v[102:103]
	s_waitcnt vmcnt(18)
	v_pk_add_f32 v[6:7], v[108:109], v[112:113]
	v_pk_add_f32 v[8:9], v[106:107], v[110:111]
	v_pk_add_f32 v[28:29], v[2:3], v[6:7]
	v_pk_add_f32 v[30:31], v[4:5], v[8:9]
	s_waitcnt vmcnt(16)
	v_pk_add_f32 v[2:3], v[116:117], v[120:121]
	v_pk_add_f32 v[4:5], v[114:115], v[118:119]
	s_waitcnt vmcnt(14)
	v_pk_add_f32 v[6:7], v[124:125], v[128:129]
	v_pk_add_f32 v[8:9], v[122:123], v[126:127]
	v_pk_add_f32 v[36:37], v[2:3], v[6:7]
	v_pk_add_f32 v[38:39], v[4:5], v[8:9]
	s_waitcnt vmcnt(12)
	v_pk_add_f32 v[2:3], v[132:133], v[136:137]
	v_pk_add_f32 v[4:5], v[130:131], v[134:135]
	s_waitcnt vmcnt(10)
	v_pk_add_f32 v[6:7], v[140:141], v[144:145]
	v_pk_add_f32 v[8:9], v[138:139], v[142:143]
	v_pk_add_f32 v[46:47], v[2:3], v[6:7]
	v_pk_add_f32 v[44:45], v[4:5], v[8:9]
	v_pk_mul_f32 v[2:3], v[40:41], v[40:41]
	v_pk_mul_f32 v[4:5], v[42:43], v[42:43]
	v_mov_b32_e32 v90, v53
	v_pk_mov_b32 v[6:7], v[4:5], v[2:3] op_sel:[1,0]
	v_mov_b32_e32 v5, v3
	v_pk_add_f32 v[6:7], v[6:7], v[4:5]
	v_pk_mul_f32 v[2:3], v[28:29], v[28:29]
	v_pk_mul_f32 v[4:5], v[30:31], v[30:31]
	v_mov_b32_e32 v91, v49
	v_pk_mov_b32 v[8:9], v[4:5], v[2:3] op_sel:[1,0]
	v_mov_b32_e32 v5, v3
	v_pk_add_f32 v[8:9], v[8:9], v[4:5]
	global_load_dwordx4 v[66:69], v150, s[8:9]
	global_load_dwordx4 v[70:73], v151, s[8:9]
	global_load_dwordx4 v[74:77], v148, s[8:9]
	global_load_dwordx4 v[78:81], v152, s[8:9]
	global_load_dwordx4 v[82:85], v153, s[8:9]
	global_load_dwordx4 v[2:5], v154, s[8:9]
	v_mov_b32_e32 v86, v55
	v_mov_b32_e32 v87, v51
	v_mov_b32_e32 v88, v52
	v_mov_b32_e32 v89, v48
	v_pk_mul_f32 v[90:91], v[90:91], v[90:91]
	v_pk_mul_f32 v[86:87], v[86:87], v[86:87]
	v_pk_fma_f32 v[88:89], v[88:89], v[88:89], v[90:91]
	v_mov_b32_e32 v90, v54
	v_mov_b32_e32 v91, v50
	v_pk_fma_f32 v[86:87], v[90:91], v[90:91], v[86:87]
	v_mul_f32_e32 v90, v33, v33
	v_pk_add_f32 v[86:87], v[86:87], v[88:89]
	v_mul_f32_e32 v88, v35, v35
	v_mul_f32_e32 v92, v26, v26
	v_mul_f32_e32 v93, v27, v27
	v_mul_f32_e32 v94, v24, v24
	v_mul_f32_e32 v95, v25, v25
	v_pk_fma_f32 v[88:89], v[34:35], v[34:35], v[88:89] op_sel_hi:[1,1,0]
	v_pk_fma_f32 v[90:91], v[32:33], v[32:33], v[90:91] op_sel_hi:[1,1,0]
	v_pk_add_f32 v[86:87], v[86:87], v[86:87] op_sel:[0,1] op_sel_hi:[1,0]
	v_pk_add_f32 v[6:7], v[6:7], v[6:7] op_sel:[0,1] op_sel_hi:[1,0]
	v_mov_b32_e32 v89, v94
	v_mov_b32_e32 v91, v95
	v_mov_b32_e32 v87, v92
	v_mov_b32_e32 v7, v93
	v_pk_add_f32 v[88:89], v[88:89], v[90:91]
	v_pk_add_f32 v[6:7], v[86:87], v[6:7]
	v_mul_f32_e32 v86, v39, v39
	v_pk_add_f32 v[6:7], v[6:7], v[88:89]
	v_mul_f32_e32 v88, v37, v37
	v_mul_f32_e32 v96, v44, v44
	v_mul_f32_e32 v97, v45, v45
	v_mul_f32_e32 v98, v46, v46
	v_mul_f32_e32 v99, v47, v47
	v_pk_fma_f32 v[86:87], v[38:39], v[38:39], v[86:87] op_sel_hi:[1,1,0]
	v_pk_fma_f32 v[88:89], v[36:37], v[36:37], v[88:89] op_sel_hi:[1,1,0]
	v_pk_add_f32 v[6:7], v[6:7], v[6:7] op_sel:[0,1] op_sel_hi:[1,0]
	v_pk_add_f32 v[8:9], v[8:9], v[8:9] op_sel:[0,1] op_sel_hi:[1,0]
	v_mov_b32_e32 v87, v98
	v_mov_b32_e32 v89, v99
	v_mov_b32_e32 v7, v96
	v_mov_b32_e32 v9, v97
	v_pk_add_f32 v[86:87], v[86:87], v[88:89]
	v_pk_add_f32 v[6:7], v[6:7], v[8:9]
	v_mov_b32_e32 v96, 0x3a000000
	v_pk_add_f32 v[6:7], v[6:7], v[86:87]
	v_mov_b32_e32 v87, 0x358637bd
	v_add_f32_e32 v6, v6, v7
	v_mov_b32_e32 v7, 0
	s_waitcnt vmcnt(7)
	v_pk_mul_f32 v[54:55], v[54:55], v[58:59]
	v_add_f32_dpp v6, v6, v6 quad_perm:[1,0,3,2] row_mask:0xf bank_mask:0xf bound_ctrl:1
	v_cvt_f32_f16_e32 v58, v22
	v_cvt_f32_f16_sdwa v59, v22 dst_sel:DWORD dst_unused:UNUSED_PAD src0_sel:WORD_1
	v_add_f32_dpp v6, v6, v6 quad_perm:[2,3,0,1] row_mask:0xf bank_mask:0xf bound_ctrl:1
	v_cvt_f32_f16_e32 v22, v23
	v_cvt_f32_f16_sdwa v23, v23 dst_sel:DWORD dst_unused:UNUSED_PAD src0_sel:WORD_1
	v_add_f32_dpp v6, v6, v6 row_half_mirror row_mask:0xf bank_mask:0xf bound_ctrl:1
	s_waitcnt vmcnt(6)
	v_pk_mul_f32 v[48:49], v[48:49], v[64:65]
	v_cvt_f32_f16_e32 v88, v146
	v_add_f32_dpp v6, v6, v6 row_mirror row_mask:0xf bank_mask:0xf bound_ctrl:1
	v_cvt_f32_f16_sdwa v89, v146 dst_sel:DWORD dst_unused:UNUSED_PAD src0_sel:WORD_1
	v_cvt_f32_f16_e32 v90, v147
	v_mov_b32_dpp v7, v6 row_bcast:15 row_mask:0xa bank_mask:0xf
	v_add_f32_e32 v6, v6, v7
	v_mov_b32_e32 v7, 0
	v_cvt_f32_f16_sdwa v91, v147 dst_sel:DWORD dst_unused:UNUSED_PAD src0_sel:WORD_1
	v_pk_mul_f32 v[52:53], v[52:53], v[60:61]
	v_mov_b32_dpp v7, v6 row_bcast:31 row_mask:0xc bank_mask:0xf
	v_add_f32_e32 v6, v6, v7
	v_pk_mul_f32 v[50:51], v[50:51], v[62:63]
	v_readlane_b32 s12, v6, 63
	global_load_dwordx4 v[62:65], v153, s[10:11]
	s_waitcnt vmcnt(6)
	v_pk_mul_f32 v[42:43], v[42:43], v[66:67]
	v_fma_f32 v6, s12, v96, v87
	v_rsq_f32_e32 v86, v6
	global_load_dwordx4 v[6:9], v57, s[10:11]
	v_pk_mul_f32 v[40:41], v[40:41], v[68:69]
	s_waitcnt vmcnt(6)
	v_pk_mul_f32 v[32:33], v[32:33], v[72:73]
	v_pk_fma_f32 v[92:93], v[48:49], v[86:87], v[22:23] op_sel_hi:[1,0,1]
	v_cvt_f32_f16_e32 v48, v20
	v_cvt_f32_f16_sdwa v49, v20 dst_sel:DWORD dst_unused:UNUSED_PAD src0_sel:WORD_1
	v_pk_fma_f32 v[90:91], v[52:53], v[86:87], v[90:91] op_sel_hi:[1,0,1]
	v_pk_fma_f32 v[88:89], v[54:55], v[86:87], v[88:89] op_sel_hi:[1,0,1]
	global_load_dwordx4 v[52:55], v149, s[10:11]
	v_pk_fma_f32 v[68:69], v[42:43], v[86:87], v[48:49] op_sel_hi:[1,0,1]
	v_cvt_f32_f16_e32 v48, v18
	v_cvt_f32_f16_sdwa v49, v18 dst_sel:DWORD dst_unused:UNUSED_PAD src0_sel:WORD_1
	v_cvt_f32_f16_e32 v18, v19
	v_cvt_f32_f16_sdwa v19, v19 dst_sel:DWORD dst_unused:UNUSED_PAD src0_sel:WORD_1
	v_pk_fma_f32 v[94:95], v[50:51], v[86:87], v[58:59] op_sel_hi:[1,0,1]
	v_cvt_f32_f16_e32 v50, v21
	v_cvt_f32_f16_sdwa v51, v21 dst_sel:DWORD dst_unused:UNUSED_PAD src0_sel:WORD_1
	global_load_dwordx4 v[20:23], v150, s[10:11]
	v_pk_fma_f32 v[18:19], v[32:33], v[86:87], v[18:19] op_sel_hi:[1,0,1]
	v_cvt_f32_f16_e32 v32, v16
	v_cvt_f32_f16_sdwa v33, v16 dst_sel:DWORD dst_unused:UNUSED_PAD src0_sel:WORD_1
	v_cvt_f32_f16_e32 v16, v17
	v_cvt_f32_f16_sdwa v17, v17 dst_sel:DWORD dst_unused:UNUSED_PAD src0_sel:WORD_1
	v_pk_fma_f32 v[66:67], v[40:41], v[86:87], v[50:51] op_sel_hi:[1,0,1]
	global_load_dwordx4 v[40:43], v151, s[10:11]
	global_load_dwordx4 v[58:61], v152, s[10:11]
	v_pk_mul_f32 v[34:35], v[34:35], v[70:71]
	s_waitcnt vmcnt(9)
	v_pk_mul_f32 v[24:25], v[24:25], v[76:77]
	v_pk_fma_f32 v[70:71], v[34:35], v[86:87], v[48:49] op_sel_hi:[1,0,1]
	global_load_dwordx4 v[48:51], v148, s[10:11]
	v_pk_fma_f32 v[16:17], v[24:25], v[86:87], v[16:17] op_sel_hi:[1,0,1]
	v_cvt_f32_f16_e32 v24, v14
	v_cvt_f32_f16_sdwa v25, v14 dst_sel:DWORD dst_unused:UNUSED_PAD src0_sel:WORD_1
	v_cvt_f32_f16_e32 v14, v15
	v_cvt_f32_f16_sdwa v15, v15 dst_sel:DWORD dst_unused:UNUSED_PAD src0_sel:WORD_1
	v_pk_mul_f32 v[26:27], v[26:27], v[74:75]
	s_waitcnt vmcnt(7)
	v_pk_mul_f32 v[4:5], v[46:47], v[4:5]
	v_pk_fma_f32 v[72:73], v[26:27], v[86:87], v[32:33] op_sel_hi:[1,0,1]
	v_pk_mul_f32 v[26:27], v[28:29], v[80:81]
	v_pk_mul_f32 v[28:29], v[30:31], v[78:79]
	v_pk_fma_f32 v[74:75], v[26:27], v[86:87], v[14:15] op_sel_hi:[1,0,1]
	v_cvt_f32_f16_e32 v14, v12
	v_cvt_f32_f16_sdwa v15, v12 dst_sel:DWORD dst_unused:UNUSED_PAD src0_sel:WORD_1
	v_cvt_f32_f16_e32 v12, v13
	v_cvt_f32_f16_sdwa v13, v13 dst_sel:DWORD dst_unused:UNUSED_PAD src0_sel:WORD_1
	v_pk_fma_f32 v[76:77], v[28:29], v[86:87], v[24:25] op_sel_hi:[1,0,1]
	v_pk_mul_f32 v[24:25], v[36:37], v[84:85]
	global_load_dwordx4 v[34:37], v154, s[10:11]
	v_pk_mul_f32 v[26:27], v[38:39], v[82:83]
	v_pk_fma_f32 v[38:39], v[24:25], v[86:87], v[12:13] op_sel_hi:[1,0,1]
	v_cvt_f32_f16_e32 v12, v10
	v_cvt_f32_f16_sdwa v13, v10 dst_sel:DWORD dst_unused:UNUSED_PAD src0_sel:WORD_1
	v_cvt_f32_f16_e32 v10, v11
	v_cvt_f32_f16_sdwa v11, v11 dst_sel:DWORD dst_unused:UNUSED_PAD src0_sel:WORD_1
	v_pk_fma_f32 v[78:79], v[26:27], v[86:87], v[14:15] op_sel_hi:[1,0,1]
	v_cvt_f16_f32_e32 v14, v88
	v_cvt_f16_f32_sdwa v15, v89 dst_sel:WORD_1 dst_unused:UNUSED_PAD src0_sel:DWORD
	v_pk_mul_f32 v[2:3], v[44:45], v[2:3]
	v_pk_fma_f32 v[4:5], v[4:5], v[86:87], v[10:11] op_sel_hi:[1,0,1]
	v_pk_fma_f32 v[2:3], v[2:3], v[86:87], v[12:13] op_sel_hi:[1,0,1]
	v_cvt_f16_f32_e32 v11, v90
	v_cvt_f16_f32_sdwa v12, v91 dst_sel:WORD_1 dst_unused:UNUSED_PAD src0_sel:DWORD
	v_or_b32_e32 v10, v15, v14
	v_cvt_f16_f32_e32 v13, v94
	v_cvt_f16_f32_sdwa v14, v95 dst_sel:WORD_1 dst_unused:UNUSED_PAD src0_sel:DWORD
	v_cvt_f16_f32_e32 v15, v92
	v_cvt_f16_f32_sdwa v24, v93 dst_sel:WORD_1 dst_unused:UNUSED_PAD src0_sel:DWORD
	v_or_b32_e32 v11, v12, v11
	global_store_dwordx2 v56, v[10:11], s[4:5] sc1
	v_or_b32_e32 v10, v14, v13
	v_or_b32_e32 v11, v24, v15
	global_store_dwordx2 v56, v[10:11], s[4:5] offset:512 sc1
	v_cvt_f16_f32_e32 v10, v68
	v_cvt_f16_f32_sdwa v11, v69 dst_sel:WORD_1 dst_unused:UNUSED_PAD src0_sel:DWORD
	v_cvt_f16_f32_e32 v12, v66
	v_cvt_f16_f32_sdwa v13, v67 dst_sel:WORD_1 dst_unused:UNUSED_PAD src0_sel:DWORD
	v_cvt_f16_f32_e32 v14, v70
	v_cvt_f16_f32_sdwa v15, v71 dst_sel:WORD_1 dst_unused:UNUSED_PAD src0_sel:DWORD
	v_or_b32_e32 v10, v11, v10
	v_or_b32_e32 v11, v13, v12
	global_store_dwordx2 v56, v[10:11], s[4:5] offset:1024 sc1
	v_cvt_f16_f32_e32 v11, v18
	v_cvt_f16_f32_sdwa v12, v19 dst_sel:WORD_1 dst_unused:UNUSED_PAD src0_sel:DWORD
	v_or_b32_e32 v10, v15, v14
	v_cvt_f16_f32_e32 v13, v72
	v_cvt_f16_f32_sdwa v14, v73 dst_sel:WORD_1 dst_unused:UNUSED_PAD src0_sel:DWORD
	v_cvt_f16_f32_e32 v15, v16
	v_cvt_f16_f32_sdwa v24, v17 dst_sel:WORD_1 dst_unused:UNUSED_PAD src0_sel:DWORD
	v_or_b32_e32 v11, v12, v11
	global_store_dwordx2 v56, v[10:11], s[4:5] offset:1536 sc1
	v_or_b32_e32 v10, v14, v13
	v_or_b32_e32 v11, v24, v15
	global_store_dwordx2 v56, v[10:11], s[4:5] offset:2048 sc1
	v_cvt_f16_f32_e32 v10, v76
	v_cvt_f16_f32_sdwa v11, v77 dst_sel:WORD_1 dst_unused:UNUSED_PAD src0_sel:DWORD
	v_cvt_f16_f32_e32 v12, v74
	v_cvt_f16_f32_sdwa v13, v75 dst_sel:WORD_1 dst_unused:UNUSED_PAD src0_sel:DWORD
	v_cvt_f16_f32_e32 v14, v78
	v_cvt_f16_f32_sdwa v15, v79 dst_sel:WORD_1 dst_unused:UNUSED_PAD src0_sel:DWORD
	v_or_b32_e32 v10, v11, v10
	v_or_b32_e32 v11, v13, v12
	global_store_dwordx2 v56, v[10:11], s[4:5] offset:2560 sc1
	v_cvt_f16_f32_e32 v11, v38
	v_cvt_f16_f32_sdwa v12, v39 dst_sel:WORD_1 dst_unused:UNUSED_PAD src0_sel:DWORD
	v_or_b32_e32 v10, v15, v14
	v_cvt_f16_f32_e32 v13, v2
	v_cvt_f16_f32_sdwa v14, v3 dst_sel:WORD_1 dst_unused:UNUSED_PAD src0_sel:DWORD
	v_cvt_f16_f32_e32 v15, v4
	v_cvt_f16_f32_sdwa v24, v5 dst_sel:WORD_1 dst_unused:UNUSED_PAD src0_sel:DWORD
	v_or_b32_e32 v11, v12, v11
	global_store_dwordx2 v56, v[10:11], s[4:5] offset:3072 sc1
	v_or_b32_e32 v10, v14, v13
	v_or_b32_e32 v11, v24, v15
	v_mov_b32_e32 v12, v89
	v_mov_b32_e32 v13, v95
	global_store_dwordx2 v56, v[10:11], s[4:5] offset:3584 sc1
	v_mov_b32_e32 v10, v88
	v_mov_b32_e32 v11, v94
	v_pk_mul_f32 v[12:13], v[12:13], v[12:13]
	v_mov_b32_e32 v14, v91
	v_mov_b32_e32 v15, v93
	v_pk_fma_f32 v[10:11], v[10:11], v[10:11], v[12:13]
	v_mov_b32_e32 v12, v90
	v_mov_b32_e32 v13, v92
	v_pk_mul_f32 v[14:15], v[14:15], v[14:15]
	s_waitcnt vmcnt(14)
	v_pk_mul_f32 v[8:9], v[8:9], v[90:91]
	v_pk_fma_f32 v[12:13], v[12:13], v[12:13], v[14:15]
	v_pk_mul_f32 v[14:15], v[68:69], v[68:69]
	v_pk_add_f32 v[10:11], v[10:11], v[12:13]
	v_pk_mul_f32 v[12:13], v[66:67], v[66:67]
	v_pk_add_f32 v[10:11], v[10:11], v[10:11] op_sel_hi:[0,1]
	v_pk_mov_b32 v[24:25], v[14:15], v[12:13] op_sel:[1,0]
	v_mov_b32_e32 v15, v13
	v_mul_f32_e32 v10, v70, v70
	v_pk_add_f32 v[12:13], v[24:25], v[14:15]
	v_pk_fma_f32 v[14:15], v[70:71], v[70:71], v[10:11] op_sel_hi:[1,1,0]
	v_mul_f32_e32 v10, v18, v18
	v_pk_add_f32 v[12:13], v[12:13], v[12:13] op_sel_hi:[0,1]
	v_pk_fma_f32 v[24:25], v[18:19], v[18:19], v[10:11] op_sel_hi:[1,1,0]
	v_mul_f32_e32 v14, v72, v72
	v_mul_f32_e32 v24, v73, v73
	v_mul_f32_e32 v12, v16, v16
	v_mul_f32_e32 v10, v17, v17
	v_pk_add_f32 v[14:15], v[14:15], v[24:25]
	v_pk_add_f32 v[10:11], v[12:13], v[10:11]
	v_pk_mul_f32 v[12:13], v[74:75], v[74:75]
	v_pk_add_f32 v[10:11], v[14:15], v[10:11]
	v_pk_mul_f32 v[14:15], v[76:77], v[76:77]
	v_pk_add_f32 v[10:11], v[10:11], v[10:11] op_sel_hi:[0,1]
	v_pk_mov_b32 v[24:25], v[14:15], v[12:13] op_sel:[1,0]
	v_mov_b32_e32 v15, v13
	v_mul_f32_e32 v10, v78, v78
	v_pk_add_f32 v[12:13], v[24:25], v[14:15]
	v_pk_fma_f32 v[14:15], v[78:79], v[78:79], v[10:11] op_sel_hi:[1,1,0]
	v_mul_f32_e32 v10, v38, v38
	v_pk_add_f32 v[12:13], v[12:13], v[12:13] op_sel_hi:[0,1]
	v_pk_fma_f32 v[24:25], v[38:39], v[38:39], v[10:11] op_sel_hi:[1,1,0]
	v_mul_f32_e32 v14, v2, v2
	v_mul_f32_e32 v24, v3, v3
	v_mul_f32_e32 v12, v4, v4
	v_mul_f32_e32 v10, v5, v5
	v_pk_add_f32 v[14:15], v[14:15], v[24:25]
	v_pk_add_f32 v[10:11], v[12:13], v[10:11]
	s_waitcnt vmcnt(13)
	v_pk_mul_f32 v[12:13], v[54:55], v[92:93]
	v_pk_add_f32 v[10:11], v[14:15], v[10:11]
	v_pk_mul_f32 v[6:7], v[6:7], v[88:89]
	v_add_f32_e32 v10, v10, v11
	v_mov_b32_e32 v11, 0
	s_waitcnt vmcnt(8)
	v_pk_mul_f32 v[34:35], v[2:3], v[34:35]
	v_add_f32_dpp v10, v10, v10 quad_perm:[1,0,3,2] row_mask:0xf bank_mask:0xf bound_ctrl:1
	v_pk_mul_f32 v[2:3], v[4:5], v[36:37]
	s_nop 0
	v_add_f32_dpp v10, v10, v10 quad_perm:[2,3,0,1] row_mask:0xf bank_mask:0xf bound_ctrl:1
	s_nop 1
	v_add_f32_dpp v10, v10, v10 row_half_mirror row_mask:0xf bank_mask:0xf bound_ctrl:1
	s_nop 1
	v_add_f32_dpp v10, v10, v10 row_mirror row_mask:0xf bank_mask:0xf bound_ctrl:1
	s_nop 1
	v_mov_b32_dpp v11, v10 row_bcast:15 row_mask:0xa bank_mask:0xf
	v_add_f32_e32 v10, v10, v11
	v_mov_b32_e32 v11, 0
	s_nop 1
	v_mov_b32_dpp v11, v10 row_bcast:31 row_mask:0xc bank_mask:0xf
	v_add_f32_e32 v10, v10, v11
	s_nop 0
	v_readlane_b32 s4, v10, 63
	v_pk_mul_f32 v[10:11], v[52:53], v[94:95]
	s_nop 0
	v_fmac_f32_e32 v87, s4, v96
	v_rsq_f32_e32 v44, v87
	s_nop 0
	v_pk_mul_f32 v[24:25], v[12:13], v[44:45] op_sel_hi:[1,0]
	v_pk_mul_f32 v[30:31], v[8:9], v[44:45] op_sel_hi:[1,0]
	v_pk_mul_f32 v[28:29], v[10:11], v[44:45] op_sel_hi:[1,0]
	v_pk_mul_f32 v[32:33], v[6:7], v[44:45] op_sel_hi:[1,0]
	v_max_f32_e64 v6, |v30|, |v31|
	v_max_f32_e64 v7, |v24|, |v25|
	v_max3_f32 v6, |v32|, |v33|, v6
	v_max3_f32 v7, |v28|, |v29|, v7
	v_pk_mul_f32 v[8:9], v[22:23], v[66:67]
	v_max3_f32 v10, v6, 0, v7
	v_pk_mul_f32 v[6:7], v[20:21], v[68:69]
	v_pk_mul_f32 v[22:23], v[8:9], v[44:45] op_sel_hi:[1,0]
	v_pk_mul_f32 v[26:27], v[6:7], v[44:45] op_sel_hi:[1,0]
	v_max_f32_e64 v6, |v22|, |v23|
	v_pk_mul_f32 v[8:9], v[42:43], v[18:19]
	v_max3_f32 v11, |v26|, |v27|, v6
	v_pk_mul_f32 v[6:7], v[40:41], v[70:71]
	v_pk_mul_f32 v[18:19], v[8:9], v[44:45] op_sel_hi:[1,0]
	v_pk_mul_f32 v[20:21], v[6:7], v[44:45] op_sel_hi:[1,0]
	v_max_f32_e64 v6, |v18|, |v19|
	v_max3_f32 v6, |v20|, |v21|, v6
	v_pk_mul_f32 v[8:9], v[50:51], v[16:17]
	v_max3_f32 v40, v10, v11, v6
	v_pk_mul_f32 v[6:7], v[48:49], v[72:73]
	v_pk_mul_f32 v[14:15], v[8:9], v[44:45] op_sel_hi:[1,0]
	v_pk_mul_f32 v[16:17], v[6:7], v[44:45] op_sel_hi:[1,0]
	v_max_f32_e64 v6, |v14|, |v15|
	v_pk_mul_f32 v[8:9], v[60:61], v[74:75]
	v_max3_f32 v41, |v16|, |v17|, v6
	v_pk_mul_f32 v[6:7], v[58:59], v[76:77]
	v_pk_mul_f32 v[10:11], v[8:9], v[44:45] op_sel_hi:[1,0]
	v_pk_mul_f32 v[12:13], v[6:7], v[44:45] op_sel_hi:[1,0]
	v_max_f32_e64 v6, |v10|, |v11|
	v_max3_f32 v6, |v12|, |v13|, v6
	v_max3_f32 v40, v40, v41, v6
	v_pk_mul_f32 v[6:7], v[38:39], v[64:65]
	v_pk_mul_f32 v[8:9], v[78:79], v[62:63]
	v_pk_mul_f32 v[6:7], v[6:7], v[44:45] op_sel_hi:[1,0]
	v_pk_mul_f32 v[2:3], v[2:3], v[44:45] op_sel_hi:[1,0]
	v_pk_mul_f32 v[8:9], v[8:9], v[44:45] op_sel_hi:[1,0]
	v_max_f32_e64 v38, |v6|, |v7|
	v_pk_mul_f32 v[4:5], v[34:35], v[44:45] op_sel_hi:[1,0]
	v_max_f32_e64 v34, |v2|, |v3|
	v_max3_f32 v38, |v8|, |v9|, v38
	v_max3_f32 v34, |v4|, |v5|, v34
	v_max3_f32 v34, v40, v38, v34
	v_mov_b32_e32 v35, 0
	s_nop 1
	v_mov_b32_dpp v35, v34 quad_perm:[1,0,3,2] row_mask:0xf bank_mask:0xf
	v_max_f32_e32 v35, v35, v35
	v_max_f32_e32 v34, v34, v35
	v_mov_b32_e32 v35, 0
	s_nop 1
	v_mov_b32_dpp v35, v34 quad_perm:[2,3,0,1] row_mask:0xf bank_mask:0xf
	v_max_f32_e32 v35, v35, v35
	v_max_f32_e32 v34, v34, v35
	v_mov_b32_e32 v35, 0
	s_nop 1
	v_mov_b32_dpp v35, v34 row_half_mirror row_mask:0xf bank_mask:0xf
	v_max_f32_e32 v35, v35, v35
	v_max_f32_e32 v34, v34, v35
	v_mov_b32_e32 v35, 0
	s_nop 1
	v_mov_b32_dpp v35, v34 row_mirror row_mask:0xf bank_mask:0xf
	v_max_f32_e32 v35, v35, v35
	v_max_f32_e32 v34, v34, v35
	v_mov_b32_e32 v35, 0
	s_nop 1
	v_mov_b32_dpp v35, v34 row_bcast:15 row_mask:0xa bank_mask:0xf
	v_max_f32_e32 v35, v35, v35
	v_max_f32_e32 v34, v34, v35
	v_mov_b32_e32 v35, 0
	s_nop 1
	v_mov_b32_dpp v35, v34 row_bcast:31 row_mask:0xc bank_mask:0xf
	v_max_f32_e32 v35, v35, v35
	v_max_f32_e32 v34, v34, v35
	s_nop 0
	v_readlane_b32 s14, v34, 63
	s_nop 1
	v_cmp_gt_f32_e64 s[4:5], s14, 0
	s_and_saveexec_b64 s[12:13], vcc
	s_cbranch_execz .LBB0_649
	s_lshl_b64 s[16:17], s[6:7], 2
	v_mov_b32_e32 v34, 0x3c010204
	s_add_u32 s16, s86, s16
	v_mul_f32_e32 v34, s14, v34
	s_addc_u32 s17, s87, s17
	v_cndmask_b32_e64 v34, 1.0, v34, s[4:5]
	global_store_dword v1, v34, s[16:17]

.LBB0_651:
	s_cbranch_execz .LBB0_662
	s_ashr_i32 s5, s90, 5
	s_abs_i32 s4, s5
	v_cvt_f32_u32_e32 v1, s4
	s_sub_i32 s12, 0, s4
	s_abs_i32 s6, s62
	s_xor_b32 s7, s62, s5
	v_rcp_iflag_f32_e32 v1, v1
	s_ashr_i32 s7, s7, 31
	v_mul_f32_e32 v1, 0x4f7ffffe, v1
	v_cvt_u32_f32_e32 v1, v1
	s_nop 0
	v_readfirstlane_b32 s13, v1
	s_mul_i32 s12, s12, s13
	s_mul_hi_u32 s12, s13, s12
	s_add_i32 s13, s13, s12
	s_mul_hi_u32 s12, s6, s13
	s_mul_i32 s13, s12, s4
	s_sub_i32 s6, s6, s13
	s_add_i32 s14, s12, 1
	s_sub_i32 s13, s6, s4
	s_cmp_ge_u32 s6, s4
	s_cselect_b32 s12, s14, s12
	s_cselect_b32 s6, s13, s6
	s_add_i32 s13, s12, 1
	s_cmp_ge_u32 s6, s4
	s_cselect_b32 s4, s13, s12
	s_xor_b32 s4, s4, s7
	s_sub_i32 s4, s4, s7
	s_mul_i32 s5, s4, s5
	s_sub_i32 s5, s62, s5
	s_cmp_lg_u32 s5, 0
	s_cbranch_scc1 .LBB0_662
	s_ashr_i32 s5, s4, 31
	s_lshl_b64 s[6:7], s[4:5], 13
	v_readlane_b32 s12, v254, 58
	v_readlane_b32 s13, v254, 59
	s_add_u32 s6, s12, s6
	s_addc_u32 s7, s13, s7
	v_mov_b32_e32 v11, 0
	v_lshlrev_b32_e32 v10, 4, v0
	v_lshl_add_u64 v[2:3], s[6:7], 0, v[10:11]
	v_add_co_u32_e32 v4, vcc, 0x40000, v2
	s_waitcnt vmcnt(0)
	v_mov_b32_e32 v16, v184
	v_mov_b32_e32 v17, v185
	v_mov_b32_e32 v18, v186
	v_mov_b32_e32 v19, v187
	s_nop 0
	v_addc_co_u32_e32 v5, vcc, 0, v3, vcc
	v_add_co_u32_e32 v6, vcc, 0x80000, v2
	s_add_i32 s6, s4, 0x2000
	s_nop 0
	v_addc_co_u32_e32 v7, vcc, 0, v3, vcc
	v_add_co_u32_e32 v2, vcc, 0xc0000, v2
	v_mov_b32_e32 v20, v188
	v_mov_b32_e32 v21, v189
	v_mov_b32_e32 v22, v190
	v_mov_b32_e32 v23, v191
	v_mov_b32_e32 v24, v192
	v_mov_b32_e32 v25, v193
	v_mov_b32_e32 v26, v194
	v_mov_b32_e32 v27, v195
	v_addc_co_u32_e32 v3, vcc, 0, v3, vcc
	v_mov_b32_e32 v28, v196
	v_mov_b32_e32 v29, v197
	v_mov_b32_e32 v30, v198
	v_mov_b32_e32 v31, v199
	s_ashr_i32 s7, s6, 31
	s_lshl_b64 s[4:5], s[6:7], 12
	v_readlane_b32 s12, v254, 54
	v_readlane_b32 s13, v254, 55
	s_add_u32 s4, s12, s4
	s_addc_u32 s5, s13, s5
	v_lshlrev_b32_e32 v14, 3, v0
	v_mov_b32_e32 v6, v174
	v_mov_b32_e32 v7, v175
	v_mov_b32_e32 v8, v176
	v_mov_b32_e32 v9, v177
	v_mov_b32_e32 v2, v170
	v_mov_b32_e32 v3, v171
	v_mov_b32_e32 v4, v172
	v_mov_b32_e32 v5, v173
	v_mov_b32_e32 v12, v180
	v_mov_b32_e32 v13, v181
	v_mov_b32_e32 v1, v11
	v_mov_b32_e32 v10, v11
	v_mov_b32_e32 v15, v11
	v_lshl_add_u64 v[14:15], s[4:5], 0, v[14:15]
	v_cmp_eq_u32_e32 vcc, 0, v166
	s_waitcnt vmcnt(5)
	v_pk_add_f32 v[18:19], v[18:19], v[22:23]
	v_pk_add_f32 v[20:21], v[16:17], v[20:21]
	s_waitcnt vmcnt(3)
	v_pk_add_f32 v[16:17], v[26:27], v[30:31]
	v_pk_add_f32 v[22:23], v[24:25], v[28:29]
	v_pk_add_f32 v[16:17], v[18:19], v[16:17]
	v_pk_add_f32 v[18:19], v[20:21], v[22:23]
	v_mul_f32_e32 v21, v17, v17
	v_mul_f32_e32 v20, v19, v19
	v_fmac_f32_e32 v20, v18, v18
	v_fmac_f32_e32 v21, v16, v16
	v_add_f32_e32 v20, v20, v21
	s_nop 1
	v_add_f32_dpp v20, v20, v20 quad_perm:[1,0,3,2] row_mask:0xf bank_mask:0xf bound_ctrl:1
	s_nop 1
	v_add_f32_dpp v20, v20, v20 quad_perm:[2,3,0,1] row_mask:0xf bank_mask:0xf bound_ctrl:1
	s_nop 1
	v_add_f32_dpp v20, v20, v20 row_half_mirror row_mask:0xf bank_mask:0xf bound_ctrl:1
	s_nop 1
	v_add_f32_dpp v20, v20, v20 row_mirror row_mask:0xf bank_mask:0xf bound_ctrl:1
	s_nop 1
	v_mov_b32_dpp v1, v20 row_bcast:15 row_mask:0xa bank_mask:0xf
	v_add_f32_e32 v1, v20, v1
	s_nop 1
	v_mov_b32_dpp v10, v1 row_bcast:31 row_mask:0xc bank_mask:0xf
	v_add_f32_e32 v1, v1, v10
	s_nop 0
	v_readlane_b32 s8, v1, 63
	s_and_saveexec_b64 s[4:5], vcc
	s_lshl_b32 s9, s96, 2
	s_add_i32 s9, s9, 0
	v_mov_b32_e32 v1, s9
	v_mov_b32_e32 v10, s8
	ds_write_b32 v1, v10
	s_or_b64 exec, exec, s[4:5]
	s_waitcnt lgkmcnt(0)
	s_barrier
	ds_read_b128 v[20:23], v11
	ds_read_b128 v[24:27], v11 offset:16
	s_waitcnt vmcnt(2)
	v_pk_mul_f32 v[8:9], v[8:9], v[16:17]
	v_pk_mul_f32 v[6:7], v[6:7], v[18:19]
	s_waitcnt lgkmcnt(1)
	v_add_f32_e32 v1, 0, v20
	v_add_f32_e32 v1, v1, v21
	v_add_f32_e32 v1, v1, v22
	v_add_f32_e32 v1, v1, v23
	s_waitcnt lgkmcnt(0)
	v_add_f32_e32 v1, v1, v24
	v_add_f32_e32 v1, v1, v25
	v_add_f32_e32 v1, v1, v26
	v_add_f32_e32 v10, v1, v27
	v_mov_b32_e32 v1, 0x358637bd
	v_fmamk_f32 v10, v10, 0x3a000000, v1
	v_rsq_f32_e32 v10, v10
	s_waitcnt vmcnt(0)
	v_cvt_f32_f16_sdwa v21, v12 dst_sel:DWORD dst_unused:UNUSED_PAD src0_sel:WORD_1
	v_cvt_f32_f16_e32 v20, v12
	v_cvt_f32_f16_sdwa v23, v13 dst_sel:DWORD dst_unused:UNUSED_PAD src0_sel:WORD_1
	v_cvt_f32_f16_e32 v22, v13
	v_pk_fma_f32 v[6:7], v[6:7], v[10:11], v[20:21] op_sel_hi:[1,0,1]
	s_nop 0
	v_cvt_f16_f32_sdwa v12, v7 dst_sel:WORD_1 dst_unused:UNUSED_PAD src0_sel:DWORD
	v_pk_fma_f32 v[8:9], v[8:9], v[10:11], v[22:23] op_sel_hi:[1,0,1]
	v_cvt_f16_f32_e32 v10, v6
	v_cvt_f16_f32_e32 v13, v8
	v_cvt_f16_f32_sdwa v16, v9 dst_sel:WORD_1 dst_unused:UNUSED_PAD src0_sel:DWORD
	v_or_b32_e32 v12, v12, v10
	v_mul_f32_e32 v10, v7, v7
	v_or_b32_e32 v13, v16, v13
	global_store_dwordx2 v[14:15], v[12:13], off sc1
	v_mul_f32_e32 v12, v9, v9
	v_fmac_f32_e32 v10, v6, v6
	v_fmac_f32_e32 v12, v8, v8
	v_add_f32_e32 v10, v10, v12
	v_mov_b32_e32 v12, 0
	s_nop 0
	v_add_f32_dpp v10, v10, v10 quad_perm:[1,0,3,2] row_mask:0xf bank_mask:0xf bound_ctrl:1
	s_nop 1
	v_add_f32_dpp v10, v10, v10 quad_perm:[2,3,0,1] row_mask:0xf bank_mask:0xf bound_ctrl:1
	s_nop 1
	v_add_f32_dpp v10, v10, v10 row_half_mirror row_mask:0xf bank_mask:0xf bound_ctrl:1
	s_nop 1
	v_add_f32_dpp v10, v10, v10 row_mirror row_mask:0xf bank_mask:0xf bound_ctrl:1
	s_nop 1
	v_mov_b32_dpp v12, v10 row_bcast:15 row_mask:0xa bank_mask:0xf
	v_add_f32_e32 v10, v10, v12
	s_nop 1
	v_mov_b32_dpp v11, v10 row_bcast:31 row_mask:0xc bank_mask:0xf
	v_add_f32_e32 v10, v10, v11
	s_nop 0
	v_readlane_b32 s8, v10, 63
	s_and_saveexec_b64 s[4:5], vcc
	s_lshl_b32 s9, s96, 2
	s_add_i32 s9, s9, 0
	v_mov_b32_e32 v10, s9
	v_mov_b32_e32 v11, s8
	ds_write_b32 v10, v11 offset:32
	s_or_b64 exec, exec, s[4:5]
	v_mov_b32_e32 v10, 0
	s_waitcnt lgkmcnt(0)
	s_barrier
	ds_read_b128 v[12:15], v10 offset:32
	ds_read_b128 v[16:19], v10 offset:48
	v_pk_mul_f32 v[4:5], v[4:5], v[8:9]
	v_pk_mul_f32 v[6:7], v[2:3], v[6:7]
	s_waitcnt lgkmcnt(1)
	v_add_f32_e32 v11, 0, v12
	v_add_f32_e32 v11, v11, v13
	v_add_f32_e32 v11, v11, v14
	v_add_f32_e32 v11, v11, v15
	s_waitcnt lgkmcnt(0)
	v_add_f32_e32 v11, v11, v16
	v_add_f32_e32 v11, v11, v17
	v_add_f32_e32 v11, v11, v18
	v_add_f32_e32 v11, v11, v19
	v_fmac_f32_e32 v1, 0x3a000000, v11
	v_rsq_f32_e32 v12, v1
	s_nop 0
	v_pk_mul_f32 v[2:3], v[4:5], v[12:13] op_sel_hi:[1,0]
	v_pk_mul_f32 v[4:5], v[6:7], v[12:13] op_sel_hi:[1,0]
	v_max_f32_e64 v1, |v2|, |v3|
	v_max3_f32 v1, |v4|, |v5|, v1
	v_mov_b32_e32 v6, 0
	s_nop 1
	v_mov_b32_dpp v6, v1 quad_perm:[1,0,3,2] row_mask:0xf bank_mask:0xf
	v_max_f32_e32 v6, v6, v6
	v_max_f32_e32 v1, v1, v6
	v_mov_b32_e32 v6, 0
	s_nop 1
	v_mov_b32_dpp v6, v1 quad_perm:[2,3,0,1] row_mask:0xf bank_mask:0xf
	v_max_f32_e32 v6, v6, v6
	v_max_f32_e32 v1, v1, v6
	v_mov_b32_e32 v6, 0
	s_nop 1
	v_mov_b32_dpp v6, v1 row_half_mirror row_mask:0xf bank_mask:0xf
	v_max_f32_e32 v6, v6, v6
	v_max_f32_e32 v1, v1, v6
	v_mov_b32_e32 v6, 0
	s_nop 1
	v_mov_b32_dpp v6, v1 row_mirror row_mask:0xf bank_mask:0xf
	v_max_f32_e32 v6, v6, v6
	v_max_f32_e32 v1, v1, v6
	v_mov_b32_e32 v6, 0
	s_nop 1
	v_mov_b32_dpp v6, v1 row_bcast:15 row_mask:0xa bank_mask:0xf
	v_max_f32_e32 v6, v6, v6
	v_max_f32_e32 v1, v1, v6
	v_mov_b32_e32 v6, 0
	s_nop 1
	v_mov_b32_dpp v6, v1 row_bcast:31 row_mask:0xc bank_mask:0xf
	v_max_f32_e32 v6, v6, v6
	v_max_f32_e32 v1, v1, v6
	s_nop 0
	v_readlane_b32 s8, v1, 63
	s_and_saveexec_b64 s[4:5], vcc
	s_lshl_b32 s9, s96, 2
	s_add_i32 s9, s9, 0
	v_mov_b32_e32 v1, s9
	v_mov_b32_e32 v6, s8
	ds_write_b32 v1, v6 offset:64
	s_or_b64 exec, exec, s[4:5]
	s_waitcnt lgkmcnt(0)
	s_barrier
	ds_read_b128 v[6:9], v10 offset:64
	ds_read_b128 v[10:13], v10 offset:80
	s_lshl_b64 s[8:9], s[6:7], 11
	s_waitcnt lgkmcnt(1)
	v_max3_f32 v1, v6, 0, v7
	v_max3_f32 v1, v1, v8, v9
	s_waitcnt lgkmcnt(0)
	v_max3_f32 v1, v1, v10, v11
	v_max3_f32 v1, v1, v12, v13
	v_cmp_lt_f32_e64 s[4:5], 0, v1
	s_mov_b64 s[10:11], exec
	v_readlane_b32 s12, v254, 36
	v_readlane_b32 s13, v254, 37
	s_and_b64 s[12:13], s[10:11], s[12:13]
	s_mov_b64 exec, s[12:13]
	s_cbranch_execz .LBB0_661
	s_lshl_b64 s[6:7], s[6:7], 2
	v_mul_f32_e32 v6, 0x3c010204, v1
	s_add_u32 s6, s86, s6
	v_cndmask_b32_e64 v6, 1.0, v6, s[4:5]
	s_addc_u32 s7, s87, s7
	v_mov_b32_e32 v7, 0
	global_store_dword v7, v6, s[6:7]

.LBB0_917:
	s_cmp_gt_i32 s12, 31
	s_cbranch_scc1 .LBB0_921
	s_ashr_i32 s13, s12, 31
	s_lshl_b64 s[4:5], s[12:13], 13
	v_readlane_b32 s6, v254, 58
	v_readlane_b32 s7, v254, 59
	s_add_u32 s4, s6, s4
	s_addc_u32 s5, s7, s5
	s_add_u32 s6, s4, 0x40000
	s_addc_u32 s7, s5, 0
	v_lshlrev_b32_e32 v148, 4, v166
	s_add_u32 s14, s4, 0x80000
	v_or_b32_e32 v150, 0x400, v148
	v_or_b32_e32 v151, 0x800, v148
	v_or_b32_e32 v152, 0xc00, v148
	s_addc_u32 s15, s5, 0
	global_load_dwordx4 v[20:23], v148, s[4:5]
	global_load_dwordx4 v[24:27], v148, s[4:5] offset:1024
	global_load_dwordx4 v[28:31], v148, s[4:5] offset:2048
	global_load_dwordx4 v[32:35], v148, s[4:5] offset:3072
	v_or_b32_e32 v149, 0x1000, v148
	global_load_dwordx4 v[36:39], v148, s[6:7]
	global_load_dwordx4 v[40:43], v150, s[6:7]
	global_load_dwordx4 v[44:47], v151, s[6:7]
	global_load_dwordx4 v[48:51], v152, s[6:7]
	global_load_dwordx4 v[52:55], v149, s[4:5]
	global_load_dwordx4 v[56:59], v149, s[6:7]
	global_load_dwordx4 v[60:63], v148, s[14:15]
	s_add_u32 s16, s4, 0xc0000
	s_addc_u32 s17, s5, 0
	global_load_dwordx4 v[64:67], v148, s[16:17]
	global_load_dwordx4 v[68:71], v150, s[14:15]
	global_load_dwordx4 v[72:75], v150, s[16:17]
	global_load_dwordx4 v[76:79], v151, s[14:15]
	global_load_dwordx4 v[80:83], v151, s[16:17]
	global_load_dwordx4 v[84:87], v152, s[14:15]
	global_load_dwordx4 v[88:91], v152, s[16:17]
	global_load_dwordx4 v[92:95], v149, s[14:15]
	global_load_dwordx4 v[96:99], v149, s[16:17]
	v_or_b32_e32 v153, 0x1400, v148
	v_or_b32_e32 v154, 0x1800, v148
	v_or_b32_e32 v155, 0x1c00, v148
	global_load_dwordx4 v[100:103], v153, s[4:5]
	global_load_dwordx4 v[104:107], v153, s[6:7]
	global_load_dwordx4 v[108:111], v153, s[14:15]
	global_load_dwordx4 v[112:115], v153, s[16:17]
	global_load_dwordx4 v[116:119], v154, s[4:5]
	global_load_dwordx4 v[120:123], v154, s[6:7]
	global_load_dwordx4 v[124:127], v154, s[14:15]
	global_load_dwordx4 v[128:131], v154, s[16:17]
	global_load_dwordx4 v[132:135], v155, s[4:5]
	global_load_dwordx4 v[136:139], v155, s[6:7]
	global_load_dwordx4 v[140:143], v155, s[14:15]
	global_load_dwordx4 v[144:147], v155, s[16:17]
	s_add_i32 s6, s12, 0x2000
	s_ashr_i32 s7, s6, 31
	s_lshl_b64 s[4:5], s[6:7], 12
	v_readlane_b32 s12, v254, 54
	v_readlane_b32 s13, v254, 55
	s_add_u32 s4, s12, s4
	v_lshlrev_b32_e32 v1, 3, v166
	s_addc_u32 s5, s13, s5
	global_load_dwordx2 v[2:3], v1, s[4:5]
	global_load_dwordx2 v[18:19], v1, s[4:5] offset:512
	global_load_dwordx2 v[16:17], v1, s[4:5] offset:1024
	global_load_dwordx2 v[14:15], v1, s[4:5] offset:1536
	global_load_dwordx2 v[12:13], v1, s[4:5] offset:2048
	global_load_dwordx2 v[10:11], v1, s[4:5] offset:2560
	global_load_dwordx2 v[8:9], v1, s[4:5] offset:3072
	global_load_dwordx2 v[6:7], v1, s[4:5] offset:3584
	v_cmp_eq_u32_e32 vcc, 0, v166
	s_waitcnt vmcnt(35)
	v_pk_add_f32 v[4:5], v[22:23], v[38:39]
	v_pk_add_f32 v[20:21], v[20:21], v[36:37]
	s_waitcnt vmcnt(34)
	v_pk_add_f32 v[22:23], v[26:27], v[42:43]
	v_pk_add_f32 v[24:25], v[24:25], v[40:41]
	s_waitcnt vmcnt(33)
	v_pk_add_f32 v[26:27], v[30:31], v[46:47]
	v_pk_add_f32 v[28:29], v[28:29], v[44:45]
	s_waitcnt vmcnt(32)
	v_pk_add_f32 v[30:31], v[34:35], v[50:51]
	v_pk_add_f32 v[32:33], v[32:33], v[48:49]
	s_waitcnt vmcnt(30)
	v_pk_add_f32 v[34:35], v[54:55], v[58:59]
	v_pk_add_f32 v[40:41], v[52:53], v[56:57]
	s_waitcnt vmcnt(28)
	v_pk_add_f32 v[38:39], v[60:61], v[64:65]
	s_waitcnt vmcnt(24)
	v_pk_add_f32 v[52:53], v[76:77], v[80:81]
	s_waitcnt vmcnt(22)
	v_pk_add_f32 v[54:55], v[86:87], v[90:91]
	v_pk_add_f32 v[56:57], v[84:85], v[88:89]
	v_pk_add_f32 v[48:49], v[20:21], v[38:39]
	v_pk_add_f32 v[38:39], v[28:29], v[52:53]
	v_pk_add_f32 v[28:29], v[30:31], v[54:55]
	v_pk_add_f32 v[30:31], v[32:33], v[56:57]
	global_load_dwordx4 v[54:57], v148, s[8:9]
	v_pk_add_f32 v[36:37], v[62:63], v[66:67]
	v_pk_add_f32 v[42:43], v[70:71], v[74:75]
	v_pk_add_f32 v[44:45], v[68:69], v[72:73]
	v_pk_add_f32 v[50:51], v[78:79], v[82:83]
	s_waitcnt vmcnt(21)
	v_pk_add_f32 v[58:59], v[94:95], v[98:99]
	v_pk_add_f32 v[60:61], v[92:93], v[96:97]
	v_pk_add_f32 v[46:47], v[4:5], v[36:37]
	v_pk_add_f32 v[42:43], v[22:23], v[42:43]
	v_pk_add_f32 v[44:45], v[24:25], v[44:45]
	v_pk_add_f32 v[36:37], v[26:27], v[50:51]
	s_waitcnt vmcnt(11)
	v_pk_add_f32 v[50:51], v[132:133], v[136:137]
	s_waitcnt vmcnt(9)
	v_pk_add_f32 v[52:53], v[140:141], v[144:145]
	v_pk_add_f32 v[20:21], v[34:35], v[58:59]
	v_pk_add_f32 v[22:23], v[40:41], v[60:61]
	v_pk_add_f32 v[50:51], v[50:51], v[52:53]
	v_mul_f32_e32 v52, v45, v45
	v_mul_f32_e32 v53, v43, v43
	global_load_dwordx4 v[58:61], v150, s[8:9]
	v_fmac_f32_e32 v52, v44, v44
	v_fmac_f32_e32 v53, v42, v42
	v_add_f32_e32 v52, v52, v53
	v_mul_f32_e32 v53, v39, v39
	v_mul_f32_e32 v62, v37, v37
	v_fmac_f32_e32 v53, v38, v38
	v_fmac_f32_e32 v62, v36, v36
	v_add_f32_e32 v53, v53, v62
	v_mul_f32_e32 v66, v31, v31
	v_mul_f32_e32 v67, v29, v29
	global_load_dwordx4 v[62:65], v151, s[8:9]
	v_fmac_f32_e32 v66, v30, v30
	v_fmac_f32_e32 v67, v28, v28
	v_add_f32_e32 v86, v66, v67
	v_mul_f32_e32 v66, v23, v23
	v_mul_f32_e32 v67, v21, v21
	v_fmac_f32_e32 v66, v22, v22
	v_fmac_f32_e32 v67, v20, v20
	v_pk_add_f32 v[4:5], v[102:103], v[106:107]
	v_pk_add_f32 v[26:27], v[100:101], v[104:105]
	v_pk_add_f32 v[24:25], v[110:111], v[114:115]
	v_pk_add_f32 v[32:33], v[108:109], v[112:113]
	v_add_f32_e32 v87, v66, v67
	global_load_dwordx4 v[66:69], v152, s[8:9]
	v_pk_add_f32 v[24:25], v[4:5], v[24:25]
	v_pk_add_f32 v[26:27], v[26:27], v[32:33]
	v_mul_f32_e32 v71, v25, v25
	v_mul_f32_e32 v70, v27, v27
	v_fmac_f32_e32 v70, v26, v26
	v_fmac_f32_e32 v71, v24, v24
	v_pk_add_f32 v[4:5], v[118:119], v[122:123]
	v_pk_add_f32 v[34:35], v[116:117], v[120:121]
	v_pk_add_f32 v[32:33], v[126:127], v[130:131]
	v_pk_add_f32 v[40:41], v[124:125], v[128:129]
	v_add_f32_e32 v88, v70, v71
	global_load_dwordx4 v[70:73], v149, s[8:9]
	v_pk_add_f32 v[32:33], v[4:5], v[32:33]
	v_pk_add_f32 v[34:35], v[34:35], v[40:41]
	v_pk_add_f32 v[4:5], v[134:135], v[138:139]
	v_pk_add_f32 v[40:41], v[142:143], v[146:147]
	v_mul_f32_e32 v74, v35, v35
	v_mul_f32_e32 v75, v33, v33
	v_pk_add_f32 v[40:41], v[4:5], v[40:41]
	v_fmac_f32_e32 v74, v34, v34
	v_fmac_f32_e32 v75, v32, v32
	v_add_f32_e32 v89, v74, v75
	v_mul_f32_e32 v74, v51, v51
	v_mul_f32_e32 v75, v41, v41
	v_fmac_f32_e32 v74, v50, v50
	v_fmac_f32_e32 v75, v40, v40
	v_add_f32_e32 v90, v74, v75
	global_load_dwordx4 v[74:77], v153, s[8:9]
	global_load_dwordx4 v[78:81], v154, s[8:9]
	global_load_dwordx4 v[82:85], v155, s[8:9]
	v_mul_f32_e32 v4, v49, v49
	v_mul_f32_e32 v5, v47, v47
	v_fmac_f32_e32 v5, v46, v46
	v_fmac_f32_e32 v4, v48, v48
	v_add_f32_e32 v4, v4, v5
	v_add_f32_e32 v4, v4, v52
	v_add_f32_e32 v4, v4, v53
	v_add_f32_e32 v4, v4, v86
	v_add_f32_e32 v4, v4, v87
	v_add_f32_e32 v4, v4, v88
	v_add_f32_e32 v4, v4, v89
	v_add_f32_e32 v4, v4, v90
	v_mov_b32_e32 v5, 0
	v_mov_b32_e32 v53, 0x358637bd
	v_add_f32_dpp v4, v4, v4 quad_perm:[1,0,3,2] row_mask:0xf bank_mask:0xf bound_ctrl:1
	v_mov_b32_e32 v87, 0x3a000000
	s_waitcnt vmcnt(7)
	v_pk_mul_f32 v[48:49], v[48:49], v[54:55]
	v_add_f32_dpp v4, v4, v4 quad_perm:[2,3,0,1] row_mask:0xf bank_mask:0xf bound_ctrl:1
	v_cvt_f32_f16_e32 v54, v18
	v_cvt_f32_f16_sdwa v55, v18 dst_sel:DWORD dst_unused:UNUSED_PAD src0_sel:WORD_1
	v_add_f32_dpp v4, v4, v4 row_half_mirror row_mask:0xf bank_mask:0xf bound_ctrl:1
	v_cvt_f32_f16_e32 v18, v19
	v_cvt_f32_f16_sdwa v19, v19 dst_sel:DWORD dst_unused:UNUSED_PAD src0_sel:WORD_1
	v_add_f32_dpp v4, v4, v4 row_mirror row_mask:0xf bank_mask:0xf bound_ctrl:1
	v_cvt_f32_f16_e32 v88, v2
	v_cvt_f32_f16_sdwa v89, v2 dst_sel:DWORD dst_unused:UNUSED_PAD src0_sel:WORD_1
	v_mov_b32_dpp v5, v4 row_bcast:15 row_mask:0xa bank_mask:0xf
	v_add_f32_e32 v4, v4, v5
	v_mov_b32_e32 v5, 0
	s_waitcnt vmcnt(6)
	v_pk_mul_f32 v[42:43], v[42:43], v[60:61]
	v_cvt_f32_f16_e32 v90, v3
	v_mov_b32_dpp v5, v4 row_bcast:31 row_mask:0xc bank_mask:0xf
	v_add_f32_e32 v4, v4, v5
	v_cvt_f32_f16_sdwa v91, v3 dst_sel:DWORD dst_unused:UNUSED_PAD src0_sel:WORD_1
	v_readlane_b32 s12, v4, 63
	v_pk_mul_f32 v[46:47], v[46:47], v[56:57]
	v_pk_mul_f32 v[44:45], v[44:45], v[58:59]
	v_fma_f32 v4, s12, v87, v53
	v_rsq_f32_e32 v4, v4
	s_waitcnt vmcnt(5)
	v_pk_mul_f32 v[38:39], v[38:39], v[62:63]
	v_pk_mul_f32 v[36:37], v[36:37], v[64:65]
	global_load_dwordx4 v[58:61], v155, s[10:11]
	v_mul_f32_e32 v86, 0.5, v4
	v_pk_fma_f32 v[92:93], v[42:43], v[86:87], v[18:19] op_sel_hi:[1,0,1]
	v_cvt_f32_f16_e32 v42, v16
	v_cvt_f32_f16_sdwa v43, v16 dst_sel:DWORD dst_unused:UNUSED_PAD src0_sel:WORD_1
	global_load_dwordx4 v[2:5], v148, s[10:11]
	v_pk_fma_f32 v[90:91], v[46:47], v[86:87], v[90:91] op_sel_hi:[1,0,1]
	v_pk_fma_f32 v[88:89], v[48:49], v[86:87], v[88:89] op_sel_hi:[1,0,1]
	global_load_dwordx4 v[46:49], v150, s[10:11]
	v_pk_fma_f32 v[64:65], v[38:39], v[86:87], v[42:43] op_sel_hi:[1,0,1]
	v_cvt_f32_f16_e32 v42, v14
	v_cvt_f32_f16_sdwa v43, v14 dst_sel:DWORD dst_unused:UNUSED_PAD src0_sel:WORD_1
	v_pk_fma_f32 v[94:95], v[44:45], v[86:87], v[54:55] op_sel_hi:[1,0,1]
	v_cvt_f32_f16_e32 v44, v17
	v_cvt_f32_f16_sdwa v45, v17 dst_sel:DWORD dst_unused:UNUSED_PAD src0_sel:WORD_1
	global_load_dwordx4 v[16:19], v151, s[10:11]
	v_cvt_f32_f16_e32 v14, v15
	v_cvt_f32_f16_sdwa v15, v15 dst_sel:DWORD dst_unused:UNUSED_PAD src0_sel:WORD_1
	s_waitcnt vmcnt(8)
	v_pk_mul_f32 v[30:31], v[30:31], v[66:67]
	v_pk_mul_f32 v[28:29], v[28:29], v[68:69]
	v_pk_fma_f32 v[68:69], v[30:31], v[86:87], v[42:43] op_sel_hi:[1,0,1]
	v_cvt_f32_f16_e32 v30, v13
	v_cvt_f32_f16_sdwa v31, v13 dst_sel:DWORD dst_unused:UNUSED_PAD src0_sel:WORD_1
	v_pk_fma_f32 v[62:63], v[36:37], v[86:87], v[44:45] op_sel_hi:[1,0,1]
	global_load_dwordx4 v[36:39], v152, s[10:11]
	global_load_dwordx4 v[42:45], v153, s[10:11]
	v_pk_fma_f32 v[66:67], v[28:29], v[86:87], v[14:15] op_sel_hi:[1,0,1]
	v_cvt_f32_f16_e32 v28, v12
	v_cvt_f32_f16_sdwa v29, v12 dst_sel:DWORD dst_unused:UNUSED_PAD src0_sel:WORD_1
	s_waitcnt vmcnt(9)
	v_pk_mul_f32 v[20:21], v[20:21], v[72:73]
	global_load_dwordx4 v[12:15], v149, s[10:11]
	v_pk_mul_f32 v[22:23], v[22:23], v[70:71]
	v_pk_fma_f32 v[70:71], v[20:21], v[86:87], v[30:31] op_sel_hi:[1,0,1]
	v_cvt_f32_f16_e32 v20, v10
	v_cvt_f32_f16_sdwa v21, v10 dst_sel:DWORD dst_unused:UNUSED_PAD src0_sel:WORD_1
	v_pk_fma_f32 v[72:73], v[22:23], v[86:87], v[28:29] op_sel_hi:[1,0,1]
	s_waitcnt vmcnt(9)
	v_pk_mul_f32 v[22:23], v[24:25], v[76:77]
	v_pk_mul_f32 v[24:25], v[26:27], v[74:75]
	global_load_dwordx4 v[54:57], v154, s[10:11]
	v_pk_fma_f32 v[74:75], v[24:25], v[86:87], v[20:21] op_sel_hi:[1,0,1]
	v_cvt_f32_f16_e32 v20, v8
	v_cvt_f32_f16_sdwa v21, v8 dst_sel:DWORD dst_unused:UNUSED_PAD src0_sel:WORD_1
	v_cvt_f32_f16_e32 v10, v11
	v_cvt_f32_f16_sdwa v11, v11 dst_sel:DWORD dst_unused:UNUSED_PAD src0_sel:WORD_1
	v_cvt_f32_f16_e32 v8, v9
	v_cvt_f32_f16_sdwa v9, v9 dst_sel:DWORD dst_unused:UNUSED_PAD src0_sel:WORD_1
	s_waitcnt vmcnt(9)
	v_pk_mul_f32 v[24:25], v[34:35], v[78:79]
	v_pk_fma_f32 v[10:11], v[22:23], v[86:87], v[10:11] op_sel_hi:[1,0,1]
	v_pk_fma_f32 v[34:35], v[24:25], v[86:87], v[20:21] op_sel_hi:[1,0,1]
	v_cvt_f32_f16_e32 v20, v6
	v_cvt_f32_f16_sdwa v21, v6 dst_sel:DWORD dst_unused:UNUSED_PAD src0_sel:WORD_1
	v_cvt_f32_f16_e32 v6, v7
	v_cvt_f32_f16_sdwa v7, v7 dst_sel:DWORD dst_unused:UNUSED_PAD src0_sel:WORD_1
	v_pk_mul_f32 v[22:23], v[32:33], v[80:81]
	s_waitcnt vmcnt(8)
	v_pk_mul_f32 v[24:25], v[50:51], v[82:83]
	v_pk_fma_f32 v[8:9], v[22:23], v[86:87], v[8:9] op_sel_hi:[1,0,1]
	v_pk_mul_f32 v[22:23], v[40:41], v[84:85]
	v_cvt_f16_f32_e32 v26, v88
	v_cvt_f16_f32_sdwa v27, v89 dst_sel:WORD_1 dst_unused:UNUSED_PAD src0_sel:DWORD
	v_pk_fma_f32 v[40:41], v[22:23], v[86:87], v[6:7] op_sel_hi:[1,0,1]
	v_pk_fma_f32 v[50:51], v[24:25], v[86:87], v[20:21] op_sel_hi:[1,0,1]
	v_cvt_f16_f32_e32 v7, v90
	v_cvt_f16_f32_sdwa v20, v91 dst_sel:WORD_1 dst_unused:UNUSED_PAD src0_sel:DWORD
	v_cvt_f16_f32_e32 v21, v94
	v_cvt_f16_f32_sdwa v22, v95 dst_sel:WORD_1 dst_unused:UNUSED_PAD src0_sel:DWORD
	v_cvt_f16_f32_e32 v23, v92
	v_cvt_f16_f32_sdwa v24, v93 dst_sel:WORD_1 dst_unused:UNUSED_PAD src0_sel:DWORD
	v_or_b32_e32 v6, v27, v26
	v_or_b32_e32 v7, v20, v7
	global_store_dwordx2 v1, v[6:7], s[4:5] sc1
	v_or_b32_e32 v6, v22, v21
	v_or_b32_e32 v7, v24, v23
	global_store_dwordx2 v1, v[6:7], s[4:5] offset:512 sc1
	v_cvt_f16_f32_e32 v6, v64
	v_cvt_f16_f32_sdwa v7, v65 dst_sel:WORD_1 dst_unused:UNUSED_PAD src0_sel:DWORD
	v_cvt_f16_f32_e32 v20, v62
	v_cvt_f16_f32_sdwa v21, v63 dst_sel:WORD_1 dst_unused:UNUSED_PAD src0_sel:DWORD
	v_cvt_f16_f32_e32 v22, v68
	v_cvt_f16_f32_sdwa v23, v69 dst_sel:WORD_1 dst_unused:UNUSED_PAD src0_sel:DWORD
	v_or_b32_e32 v6, v7, v6
	v_or_b32_e32 v7, v21, v20
	global_store_dwordx2 v1, v[6:7], s[4:5] offset:1024 sc1
	v_cvt_f16_f32_e32 v7, v66
	v_cvt_f16_f32_sdwa v20, v67 dst_sel:WORD_1 dst_unused:UNUSED_PAD src0_sel:DWORD
	v_or_b32_e32 v6, v23, v22
	v_cvt_f16_f32_e32 v21, v72
	v_cvt_f16_f32_sdwa v22, v73 dst_sel:WORD_1 dst_unused:UNUSED_PAD src0_sel:DWORD
	v_cvt_f16_f32_e32 v23, v70
	v_cvt_f16_f32_sdwa v24, v71 dst_sel:WORD_1 dst_unused:UNUSED_PAD src0_sel:DWORD
	v_or_b32_e32 v7, v20, v7
	global_store_dwordx2 v1, v[6:7], s[4:5] offset:1536 sc1
	v_or_b32_e32 v6, v22, v21
	v_or_b32_e32 v7, v24, v23
	global_store_dwordx2 v1, v[6:7], s[4:5] offset:2048 sc1
	v_cvt_f16_f32_e32 v6, v74
	v_cvt_f16_f32_sdwa v7, v75 dst_sel:WORD_1 dst_unused:UNUSED_PAD src0_sel:DWORD
	v_cvt_f16_f32_e32 v20, v10
	v_cvt_f16_f32_sdwa v21, v11 dst_sel:WORD_1 dst_unused:UNUSED_PAD src0_sel:DWORD
	v_cvt_f16_f32_e32 v22, v34
	v_cvt_f16_f32_sdwa v23, v35 dst_sel:WORD_1 dst_unused:UNUSED_PAD src0_sel:DWORD
	v_or_b32_e32 v6, v7, v6
	v_or_b32_e32 v7, v21, v20
	global_store_dwordx2 v1, v[6:7], s[4:5] offset:2560 sc1
	v_cvt_f16_f32_e32 v7, v8
	v_cvt_f16_f32_sdwa v20, v9 dst_sel:WORD_1 dst_unused:UNUSED_PAD src0_sel:DWORD
	v_or_b32_e32 v6, v23, v22
	v_cvt_f16_f32_e32 v21, v50
	v_cvt_f16_f32_sdwa v22, v51 dst_sel:WORD_1 dst_unused:UNUSED_PAD src0_sel:DWORD
	v_cvt_f16_f32_e32 v23, v40
	v_cvt_f16_f32_sdwa v24, v41 dst_sel:WORD_1 dst_unused:UNUSED_PAD src0_sel:DWORD
	v_or_b32_e32 v7, v20, v7
	global_store_dwordx2 v1, v[6:7], s[4:5] offset:3072 sc1
	v_or_b32_e32 v6, v22, v21
	v_or_b32_e32 v7, v24, v23
	v_mov_b32_e32 v20, v89
	v_mov_b32_e32 v21, v95
	global_store_dwordx2 v1, v[6:7], s[4:5] offset:3584 sc1
	v_mov_b32_e32 v6, v88
	v_mov_b32_e32 v7, v94
	v_pk_mul_f32 v[20:21], v[20:21], v[20:21]
	v_mov_b32_e32 v22, v91
	v_mov_b32_e32 v23, v93
	v_pk_fma_f32 v[6:7], v[6:7], v[6:7], v[20:21]
	v_mov_b32_e32 v20, v90
	v_mov_b32_e32 v21, v92
	v_pk_mul_f32 v[22:23], v[22:23], v[22:23]
	s_waitcnt vmcnt(14)
	v_pk_mul_f32 v[4:5], v[4:5], v[90:91]
	v_pk_fma_f32 v[20:21], v[20:21], v[20:21], v[22:23]
	v_pk_mul_f32 v[22:23], v[64:65], v[64:65]
	v_pk_add_f32 v[6:7], v[6:7], v[20:21]
	v_pk_mul_f32 v[20:21], v[62:63], v[62:63]
	v_pk_add_f32 v[6:7], v[6:7], v[6:7] op_sel_hi:[0,1]
	v_pk_mov_b32 v[24:25], v[22:23], v[20:21] op_sel:[1,0]
	v_mov_b32_e32 v23, v21
	v_mul_f32_e32 v6, v68, v68
	v_pk_add_f32 v[20:21], v[24:25], v[22:23]
	v_pk_fma_f32 v[22:23], v[68:69], v[68:69], v[6:7] op_sel_hi:[1,1,0]
	v_mul_f32_e32 v6, v66, v66
	v_pk_add_f32 v[20:21], v[20:21], v[20:21] op_sel_hi:[0,1]
	v_pk_fma_f32 v[24:25], v[66:67], v[66:67], v[6:7] op_sel_hi:[1,1,0]
	v_mul_f32_e32 v22, v72, v72
	v_mul_f32_e32 v24, v73, v73
	v_mul_f32_e32 v20, v70, v70
	v_mul_f32_e32 v6, v71, v71
	v_pk_add_f32 v[22:23], v[22:23], v[24:25]
	v_pk_add_f32 v[6:7], v[20:21], v[6:7]
	v_pk_mul_f32 v[20:21], v[10:11], v[10:11]
	v_pk_add_f32 v[6:7], v[22:23], v[6:7]
	v_pk_mul_f32 v[22:23], v[74:75], v[74:75]
	v_pk_add_f32 v[6:7], v[6:7], v[6:7] op_sel_hi:[0,1]
	v_pk_mov_b32 v[24:25], v[22:23], v[20:21] op_sel:[1,0]
	v_mov_b32_e32 v23, v21
	v_mul_f32_e32 v6, v34, v34
	v_pk_add_f32 v[20:21], v[24:25], v[22:23]
	v_pk_fma_f32 v[22:23], v[34:35], v[34:35], v[6:7] op_sel_hi:[1,1,0]
	v_mul_f32_e32 v6, v8, v8
	v_pk_add_f32 v[20:21], v[20:21], v[20:21] op_sel_hi:[0,1]
	v_pk_fma_f32 v[24:25], v[8:9], v[8:9], v[6:7] op_sel_hi:[1,1,0]
	v_mul_f32_e32 v22, v50, v50
	v_mul_f32_e32 v24, v51, v51
	v_mul_f32_e32 v20, v40, v40
	v_mul_f32_e32 v6, v41, v41
	v_pk_add_f32 v[22:23], v[22:23], v[24:25]
	v_pk_add_f32 v[6:7], v[20:21], v[6:7]
	s_waitcnt vmcnt(13)
	v_pk_mul_f32 v[20:21], v[48:49], v[92:93]
	v_pk_add_f32 v[6:7], v[22:23], v[6:7]
	v_pk_mul_f32 v[2:3], v[2:3], v[88:89]
	v_add_f32_e32 v1, v6, v7
	v_mov_b32_e32 v6, 0
	v_mov_b32_e32 v52, 0
	v_add_f32_dpp v1, v1, v1 quad_perm:[1,0,3,2] row_mask:0xf bank_mask:0xf bound_ctrl:1
	s_nop 1
	v_add_f32_dpp v1, v1, v1 quad_perm:[2,3,0,1] row_mask:0xf bank_mask:0xf bound_ctrl:1
	s_nop 1
	v_add_f32_dpp v1, v1, v1 row_half_mirror row_mask:0xf bank_mask:0xf bound_ctrl:1
	s_nop 1
	v_add_f32_dpp v1, v1, v1 row_mirror row_mask:0xf bank_mask:0xf bound_ctrl:1
	s_nop 1
	v_mov_b32_dpp v6, v1 row_bcast:15 row_mask:0xa bank_mask:0xf
	v_add_f32_e32 v1, v1, v6
	v_mov_b32_e32 v6, 0
	s_nop 1
	v_mov_b32_dpp v6, v1 row_bcast:31 row_mask:0xc bank_mask:0xf
	v_add_f32_e32 v1, v1, v6
	v_pk_mul_f32 v[6:7], v[46:47], v[94:95]
	v_readlane_b32 s4, v1, 63
	s_nop 1
	v_fmac_f32_e32 v53, s4, v87
	v_rsq_f32_e32 v76, v53
	s_nop 0
	v_pk_mul_f32 v[24:25], v[20:21], v[76:77] op_sel_hi:[1,0]
	v_pk_mul_f32 v[30:31], v[4:5], v[76:77] op_sel_hi:[1,0]
	v_pk_mul_f32 v[28:29], v[6:7], v[76:77] op_sel_hi:[1,0]
	v_pk_mul_f32 v[32:33], v[2:3], v[76:77] op_sel_hi:[1,0]
	v_max_f32_e64 v1, |v30|, |v31|
	v_max_f32_e64 v2, |v24|, |v25|
	v_max3_f32 v1, |v32|, |v33|, v1
	v_max3_f32 v2, |v28|, |v29|, v2
	s_waitcnt vmcnt(12)
	v_pk_mul_f32 v[4:5], v[18:19], v[62:63]
	v_max3_f32 v1, v1, 0, v2
	v_pk_mul_f32 v[2:3], v[16:17], v[64:65]
	v_pk_mul_f32 v[22:23], v[4:5], v[76:77] op_sel_hi:[1,0]
	v_pk_mul_f32 v[26:27], v[2:3], v[76:77] op_sel_hi:[1,0]
	v_max_f32_e64 v2, |v22|, |v23|
	s_waitcnt vmcnt(11)
	v_pk_mul_f32 v[4:5], v[38:39], v[66:67]
	v_max3_f32 v6, |v26|, |v27|, v2
	v_pk_mul_f32 v[2:3], v[36:37], v[68:69]
	v_pk_mul_f32 v[18:19], v[4:5], v[76:77] op_sel_hi:[1,0]
	v_pk_mul_f32 v[20:21], v[2:3], v[76:77] op_sel_hi:[1,0]
	v_max_f32_e64 v2, |v18|, |v19|
	v_max3_f32 v2, |v20|, |v21|, v2
	s_waitcnt vmcnt(9)
	v_pk_mul_f32 v[4:5], v[14:15], v[70:71]
	v_max3_f32 v1, v1, v6, v2
	v_pk_mul_f32 v[2:3], v[12:13], v[72:73]
	v_pk_mul_f32 v[14:15], v[4:5], v[76:77] op_sel_hi:[1,0]
	v_pk_mul_f32 v[16:17], v[2:3], v[76:77] op_sel_hi:[1,0]
	v_max_f32_e64 v2, |v14|, |v15|
	v_pk_mul_f32 v[4:5], v[44:45], v[10:11]
	v_max3_f32 v6, |v16|, |v17|, v2
	v_pk_mul_f32 v[2:3], v[42:43], v[74:75]
	v_pk_mul_f32 v[10:11], v[4:5], v[76:77] op_sel_hi:[1,0]
	v_pk_mul_f32 v[12:13], v[2:3], v[76:77] op_sel_hi:[1,0]
	v_max_f32_e64 v2, |v10|, |v11|
	v_max3_f32 v2, |v12|, |v13|, v2
	s_waitcnt vmcnt(8)
	v_pk_mul_f32 v[4:5], v[56:57], v[8:9]
	v_max3_f32 v1, v1, v6, v2
	v_pk_mul_f32 v[2:3], v[54:55], v[34:35]
	v_pk_mul_f32 v[6:7], v[4:5], v[76:77] op_sel_hi:[1,0]
	v_pk_mul_f32 v[8:9], v[2:3], v[76:77] op_sel_hi:[1,0]
	v_max_f32_e64 v2, |v6|, |v7|
	v_max3_f32 v34, |v8|, |v9|, v2
	v_pk_mul_f32 v[2:3], v[40:41], v[60:61]
	v_pk_mul_f32 v[4:5], v[50:51], v[58:59]
	v_pk_mul_f32 v[2:3], v[2:3], v[76:77] op_sel_hi:[1,0]
	v_pk_mul_f32 v[4:5], v[4:5], v[76:77] op_sel_hi:[1,0]
	v_max_f32_e64 v35, |v2|, |v3|
	v_max3_f32 v35, |v4|, |v5|, v35
	v_max3_f32 v1, v1, v34, v35
	v_mov_b32_e32 v34, 0
	s_nop 1
	v_mov_b32_dpp v34, v1 quad_perm:[1,0,3,2] row_mask:0xf bank_mask:0xf
	v_max_f32_e32 v34, v34, v34
	v_max_f32_e32 v1, v1, v34
	v_mov_b32_e32 v34, 0
	s_nop 1
	v_mov_b32_dpp v34, v1 quad_perm:[2,3,0,1] row_mask:0xf bank_mask:0xf
	v_max_f32_e32 v34, v34, v34
	v_max_f32_e32 v1, v1, v34
	v_mov_b32_e32 v34, 0
	s_nop 1
	v_mov_b32_dpp v34, v1 row_half_mirror row_mask:0xf bank_mask:0xf
	v_max_f32_e32 v34, v34, v34
	v_max_f32_e32 v1, v1, v34
	v_mov_b32_e32 v34, 0
	s_nop 1
	v_mov_b32_dpp v34, v1 row_mirror row_mask:0xf bank_mask:0xf
	v_max_f32_e32 v34, v34, v34
	v_max_f32_e32 v1, v1, v34
	v_mov_b32_e32 v34, 0
	s_nop 1
	v_mov_b32_dpp v34, v1 row_bcast:15 row_mask:0xa bank_mask:0xf
	v_max_f32_e32 v34, v34, v34
	v_max_f32_e32 v1, v1, v34
	v_mov_b32_e32 v34, 0
	s_nop 1
	v_mov_b32_dpp v34, v1 row_bcast:31 row_mask:0xc bank_mask:0xf
	v_max_f32_e32 v34, v34, v34
	v_max_f32_e32 v1, v1, v34
	s_nop 0
	v_readlane_b32 s14, v1, 63
	s_nop 1
	v_cmp_gt_f32_e64 s[4:5], s14, 0
	s_and_saveexec_b64 s[12:13], vcc
	s_cbranch_execz .LBB0_920
	s_lshl_b64 s[16:17], s[6:7], 2
	v_mov_b32_e32 v1, 0x3c010204
	s_add_u32 s16, s86, s16
	v_mul_f32_e32 v1, s14, v1
	s_addc_u32 s17, s87, s17
	v_cndmask_b32_e64 v1, 1.0, v1, s[4:5]
	global_store_dword v52, v1, s[16:17]

.LBB0_922:
	s_cbranch_execz .LBB0_933
	s_ashr_i32 s5, s90, 5
	s_abs_i32 s4, s5
	v_cvt_f32_u32_e32 v1, s4
	s_sub_i32 s12, 0, s4
	s_abs_i32 s6, s62
	s_xor_b32 s7, s62, s5
	v_rcp_iflag_f32_e32 v1, v1
	s_ashr_i32 s7, s7, 31
	v_mul_f32_e32 v1, 0x4f7ffffe, v1
	v_cvt_u32_f32_e32 v1, v1
	s_nop 0
	v_readfirstlane_b32 s13, v1
	s_mul_i32 s12, s12, s13
	s_mul_hi_u32 s12, s13, s12
	s_add_i32 s13, s13, s12
	s_mul_hi_u32 s12, s6, s13
	s_mul_i32 s13, s12, s4
	s_sub_i32 s6, s6, s13
	s_add_i32 s14, s12, 1
	s_sub_i32 s13, s6, s4
	s_cmp_ge_u32 s6, s4
	s_cselect_b32 s12, s14, s12
	s_cselect_b32 s6, s13, s6
	s_add_i32 s13, s12, 1
	s_cmp_ge_u32 s6, s4
	s_cselect_b32 s4, s13, s12
	s_xor_b32 s4, s4, s7
	s_sub_i32 s4, s4, s7
	s_mul_i32 s5, s4, s5
	s_sub_i32 s5, s62, s5
	s_cmp_lg_u32 s5, 0
	s_cbranch_scc1 .LBB0_933
	s_ashr_i32 s5, s4, 31
	s_lshl_b64 s[6:7], s[4:5], 13
	v_readlane_b32 s12, v254, 58
	v_readlane_b32 s13, v254, 59
	s_add_u32 s6, s12, s6
	s_addc_u32 s7, s13, s7
	v_mov_b32_e32 v11, 0
	v_lshlrev_b32_e32 v10, 4, v0
	v_lshl_add_u64 v[2:3], s[6:7], 0, v[10:11]
	v_add_co_u32_e32 v4, vcc, 0x40000, v2
	s_waitcnt vmcnt(0)
	v_mov_b32_e32 v16, v184
	v_mov_b32_e32 v17, v185
	v_mov_b32_e32 v18, v186
	v_mov_b32_e32 v19, v187
	s_nop 0
	v_addc_co_u32_e32 v5, vcc, 0, v3, vcc
	v_add_co_u32_e32 v6, vcc, 0x80000, v2
	s_add_i32 s6, s4, 0x2000
	s_nop 0
	v_addc_co_u32_e32 v7, vcc, 0, v3, vcc
	v_add_co_u32_e32 v2, vcc, 0xc0000, v2
	v_mov_b32_e32 v20, v188
	v_mov_b32_e32 v21, v189
	v_mov_b32_e32 v22, v190
	v_mov_b32_e32 v23, v191
	v_mov_b32_e32 v24, v192
	v_mov_b32_e32 v25, v193
	v_mov_b32_e32 v26, v194
	v_mov_b32_e32 v27, v195
	v_addc_co_u32_e32 v3, vcc, 0, v3, vcc
	v_mov_b32_e32 v28, v196
	v_mov_b32_e32 v29, v197
	v_mov_b32_e32 v30, v198
	v_mov_b32_e32 v31, v199
	s_ashr_i32 s7, s6, 31
	s_lshl_b64 s[4:5], s[6:7], 12
	v_readlane_b32 s12, v254, 54
	v_readlane_b32 s13, v254, 55
	s_add_u32 s4, s12, s4
	s_addc_u32 s5, s13, s5
	v_lshlrev_b32_e32 v14, 3, v0
	v_mov_b32_e32 v6, v174
	v_mov_b32_e32 v7, v175
	v_mov_b32_e32 v8, v176
	v_mov_b32_e32 v9, v177
	v_mov_b32_e32 v2, v170
	v_mov_b32_e32 v3, v171
	v_mov_b32_e32 v4, v172
	v_mov_b32_e32 v5, v173
	v_mov_b32_e32 v12, v180
	v_mov_b32_e32 v13, v181
	v_mov_b32_e32 v1, v11
	v_mov_b32_e32 v10, v11
	v_mov_b32_e32 v15, v11
	v_lshl_add_u64 v[14:15], s[4:5], 0, v[14:15]
	v_cmp_eq_u32_e32 vcc, 0, v166
	s_waitcnt vmcnt(5)
	v_pk_add_f32 v[18:19], v[18:19], v[22:23]
	v_pk_add_f32 v[20:21], v[16:17], v[20:21]
	s_waitcnt vmcnt(3)
	v_pk_add_f32 v[16:17], v[26:27], v[30:31]
	v_pk_add_f32 v[22:23], v[24:25], v[28:29]
	v_pk_add_f32 v[16:17], v[18:19], v[16:17]
	v_pk_add_f32 v[18:19], v[20:21], v[22:23]
	v_mul_f32_e32 v21, v17, v17
	v_mul_f32_e32 v20, v19, v19
	v_fmac_f32_e32 v20, v18, v18
	v_fmac_f32_e32 v21, v16, v16
	v_add_f32_e32 v20, v20, v21
	s_nop 1
	v_add_f32_dpp v20, v20, v20 quad_perm:[1,0,3,2] row_mask:0xf bank_mask:0xf bound_ctrl:1
	s_nop 1
	v_add_f32_dpp v20, v20, v20 quad_perm:[2,3,0,1] row_mask:0xf bank_mask:0xf bound_ctrl:1
	s_nop 1
	v_add_f32_dpp v20, v20, v20 row_half_mirror row_mask:0xf bank_mask:0xf bound_ctrl:1
	s_nop 1
	v_add_f32_dpp v20, v20, v20 row_mirror row_mask:0xf bank_mask:0xf bound_ctrl:1
	s_nop 1
	v_mov_b32_dpp v1, v20 row_bcast:15 row_mask:0xa bank_mask:0xf
	v_add_f32_e32 v1, v20, v1
	s_nop 1
	v_mov_b32_dpp v10, v1 row_bcast:31 row_mask:0xc bank_mask:0xf
	v_add_f32_e32 v1, v1, v10
	s_nop 0
	v_readlane_b32 s8, v1, 63
	s_and_saveexec_b64 s[4:5], vcc
	s_lshl_b32 s9, s96, 2
	s_add_i32 s9, s9, 0
	v_mov_b32_e32 v1, s9
	v_mov_b32_e32 v10, s8
	ds_write_b32 v1, v10
	s_or_b64 exec, exec, s[4:5]
	s_waitcnt lgkmcnt(0)
	s_barrier
	ds_read_b128 v[20:23], v11
	ds_read_b128 v[24:27], v11 offset:16
	s_waitcnt vmcnt(2)
	v_pk_mul_f32 v[8:9], v[8:9], v[16:17]
	v_pk_mul_f32 v[6:7], v[6:7], v[18:19]
	s_waitcnt lgkmcnt(1)
	v_add_f32_e32 v1, 0, v20
	v_add_f32_e32 v1, v1, v21
	v_add_f32_e32 v1, v1, v22
	v_add_f32_e32 v1, v1, v23
	s_waitcnt lgkmcnt(0)
	v_add_f32_e32 v1, v1, v24
	v_add_f32_e32 v1, v1, v25
	v_add_f32_e32 v1, v1, v26
	v_add_f32_e32 v10, v1, v27
	v_mov_b32_e32 v1, 0x358637bd
	v_fmamk_f32 v10, v10, 0x3a000000, v1
	v_rsq_f32_e32 v10, v10
	s_waitcnt vmcnt(0)
	v_cvt_f32_f16_sdwa v21, v12 dst_sel:DWORD dst_unused:UNUSED_PAD src0_sel:WORD_1
	v_cvt_f32_f16_e32 v20, v12
	v_cvt_f32_f16_sdwa v23, v13 dst_sel:DWORD dst_unused:UNUSED_PAD src0_sel:WORD_1
	v_cvt_f32_f16_e32 v22, v13
	v_mul_f32_e32 v10, 0.5, v10
	v_pk_fma_f32 v[6:7], v[6:7], v[10:11], v[20:21] op_sel_hi:[1,0,1]
	v_pk_fma_f32 v[8:9], v[8:9], v[10:11], v[22:23] op_sel_hi:[1,0,1]
	v_cvt_f16_f32_e32 v10, v6
	v_cvt_f16_f32_sdwa v12, v7 dst_sel:WORD_1 dst_unused:UNUSED_PAD src0_sel:DWORD
	v_cvt_f16_f32_e32 v13, v8
	v_cvt_f16_f32_sdwa v16, v9 dst_sel:WORD_1 dst_unused:UNUSED_PAD src0_sel:DWORD
	v_or_b32_e32 v12, v12, v10
	v_mul_f32_e32 v10, v7, v7
	v_or_b32_e32 v13, v16, v13
	global_store_dwordx2 v[14:15], v[12:13], off sc1
	v_mul_f32_e32 v12, v9, v9
	v_fmac_f32_e32 v10, v6, v6
	v_fmac_f32_e32 v12, v8, v8
	v_add_f32_e32 v10, v10, v12
	v_mov_b32_e32 v12, 0
	s_nop 0
	v_add_f32_dpp v10, v10, v10 quad_perm:[1,0,3,2] row_mask:0xf bank_mask:0xf bound_ctrl:1
	s_nop 1
	v_add_f32_dpp v10, v10, v10 quad_perm:[2,3,0,1] row_mask:0xf bank_mask:0xf bound_ctrl:1
	s_nop 1
	v_add_f32_dpp v10, v10, v10 row_half_mirror row_mask:0xf bank_mask:0xf bound_ctrl:1
	s_nop 1
	v_add_f32_dpp v10, v10, v10 row_mirror row_mask:0xf bank_mask:0xf bound_ctrl:1
	s_nop 1
	v_mov_b32_dpp v12, v10 row_bcast:15 row_mask:0xa bank_mask:0xf
	v_add_f32_e32 v10, v10, v12
	s_nop 1
	v_mov_b32_dpp v11, v10 row_bcast:31 row_mask:0xc bank_mask:0xf
	v_add_f32_e32 v10, v10, v11
	s_nop 0
	v_readlane_b32 s8, v10, 63
	s_and_saveexec_b64 s[4:5], vcc
	s_lshl_b32 s9, s96, 2
	s_add_i32 s9, s9, 0
	v_mov_b32_e32 v10, s9
	v_mov_b32_e32 v11, s8
	ds_write_b32 v10, v11 offset:32
	s_or_b64 exec, exec, s[4:5]
	v_mov_b32_e32 v10, 0
	s_waitcnt lgkmcnt(0)
	s_barrier
	ds_read_b128 v[12:15], v10 offset:32
	ds_read_b128 v[16:19], v10 offset:48
	v_pk_mul_f32 v[4:5], v[4:5], v[8:9]
	v_pk_mul_f32 v[6:7], v[2:3], v[6:7]
	s_waitcnt lgkmcnt(1)
	v_add_f32_e32 v11, 0, v12
	v_add_f32_e32 v11, v11, v13
	v_add_f32_e32 v11, v11, v14
	v_add_f32_e32 v11, v11, v15
	s_waitcnt lgkmcnt(0)
	v_add_f32_e32 v11, v11, v16
	v_add_f32_e32 v11, v11, v17
	v_add_f32_e32 v11, v11, v18
	v_add_f32_e32 v11, v11, v19
	v_fmac_f32_e32 v1, 0x3a000000, v11
	v_rsq_f32_e32 v12, v1
	s_nop 0
	v_pk_mul_f32 v[2:3], v[4:5], v[12:13] op_sel_hi:[1,0]
	v_pk_mul_f32 v[4:5], v[6:7], v[12:13] op_sel_hi:[1,0]
	v_max_f32_e64 v1, |v2|, |v3|
	v_max3_f32 v1, |v4|, |v5|, v1
	v_mov_b32_e32 v6, 0
	s_nop 1
	v_mov_b32_dpp v6, v1 quad_perm:[1,0,3,2] row_mask:0xf bank_mask:0xf
	v_max_f32_e32 v6, v6, v6
	v_max_f32_e32 v1, v1, v6
	v_mov_b32_e32 v6, 0
	s_nop 1
	v_mov_b32_dpp v6, v1 quad_perm:[2,3,0,1] row_mask:0xf bank_mask:0xf
	v_max_f32_e32 v6, v6, v6
	v_max_f32_e32 v1, v1, v6
	v_mov_b32_e32 v6, 0
	s_nop 1
	v_mov_b32_dpp v6, v1 row_half_mirror row_mask:0xf bank_mask:0xf
	v_max_f32_e32 v6, v6, v6
	v_max_f32_e32 v1, v1, v6
	v_mov_b32_e32 v6, 0
	s_nop 1
	v_mov_b32_dpp v6, v1 row_mirror row_mask:0xf bank_mask:0xf
	v_max_f32_e32 v6, v6, v6
	v_max_f32_e32 v1, v1, v6
	v_mov_b32_e32 v6, 0
	s_nop 1
	v_mov_b32_dpp v6, v1 row_bcast:15 row_mask:0xa bank_mask:0xf
	v_max_f32_e32 v6, v6, v6
	v_max_f32_e32 v1, v1, v6
	v_mov_b32_e32 v6, 0
	s_nop 1
	v_mov_b32_dpp v6, v1 row_bcast:31 row_mask:0xc bank_mask:0xf
	v_max_f32_e32 v6, v6, v6
	v_max_f32_e32 v1, v1, v6
	s_nop 0
	v_readlane_b32 s8, v1, 63
	s_and_saveexec_b64 s[4:5], vcc
	s_lshl_b32 s9, s96, 2
	s_add_i32 s9, s9, 0
	v_mov_b32_e32 v1, s9
	v_mov_b32_e32 v6, s8
	ds_write_b32 v1, v6 offset:64
	s_or_b64 exec, exec, s[4:5]
	s_waitcnt lgkmcnt(0)
	s_barrier
	ds_read_b128 v[6:9], v10 offset:64
	ds_read_b128 v[10:13], v10 offset:80
	s_lshl_b64 s[8:9], s[6:7], 11
	s_waitcnt lgkmcnt(1)
	v_max3_f32 v1, v6, 0, v7
	v_max3_f32 v1, v1, v8, v9
	s_waitcnt lgkmcnt(0)
	v_max3_f32 v1, v1, v10, v11
	v_max3_f32 v1, v1, v12, v13
	v_cmp_lt_f32_e64 s[4:5], 0, v1
	s_mov_b64 s[10:11], exec
	v_readlane_b32 s12, v254, 36
	v_readlane_b32 s13, v254, 37
	s_and_b64 s[12:13], s[10:11], s[12:13]
	s_mov_b64 exec, s[12:13]
	s_cbranch_execz .LBB0_932
	s_lshl_b64 s[6:7], s[6:7], 2
	v_mul_f32_e32 v6, 0x3c010204, v1
	s_add_u32 s6, s86, s6
	v_cndmask_b32_e64 v6, 1.0, v6, s[4:5]
	s_addc_u32 s7, s87, s7
	v_mov_b32_e32 v7, 0
	global_store_dword v7, v6, s[6:7]

.LBB0_1496:
	s_or_b64 exec, exec, s[28:29]
	v_div_scale_f32 v140, s[28:29], s17, s17, v139
	v_rcp_f32_e32 v141, v140
	v_mov_b32_e32 v142, s17
	v_div_scale_f32 v142, vcc, s34, v142, s34
	v_fma_f32 v143, -v140, v141, 1.0
	v_fmac_f32_e32 v141, v143, v141
	v_mul_f32_e32 v143, v142, v141
	v_fma_f32 v144, -v140, v143, v142
	v_fmac_f32_e32 v143, v144, v141
	v_fma_f32 v140, -v140, v143, v142
	v_div_fmas_f32 v140, v140, v141, v143
	v_div_fixup_f32 v140, v140, s17, v139
	v_cndmask_b32_e64 v140, 0, v140, s[6:7]
	v_fmaak_f32 v128, v128, v140, 0x4b400000
	v_fmaak_f32 v129, v129, v140, 0x4b400000
	v_fmaak_f32 v122, v122, v140, 0x4b400000
	v_perm_b32 v128, v129, v128, s35
	v_fmaak_f32 v123, v123, v140, 0x4b400000
	v_perm_b32 v122, v122, v128, s36
	v_perm_b32 v122, v123, v122, s37
	v_fmaak_f32 v123, v124, v140, 0x4b400000
	v_fmaak_f32 v124, v125, v140, 0x4b400000
	v_fmaak_f32 v114, v114, v140, 0x4b400000
	v_fmaak_f32 v115, v115, v140, 0x4b400000
	v_fmaak_f32 v106, v106, v140, 0x4b400000
	v_fmaak_f32 v107, v107, v140, 0x4b400000
	v_fmaak_f32 v98, v98, v140, 0x4b400000
	v_fmaak_f32 v99, v99, v140, 0x4b400000
	v_fmaak_f32 v125, v126, v140, 0x4b400000
	v_perm_b32 v123, v124, v123, s35
	v_perm_b32 v114, v115, v114, s35
	v_fmaak_f32 v115, v116, v140, 0x4b400000
	v_fmaak_f32 v116, v117, v140, 0x4b400000
	v_perm_b32 v106, v107, v106, s35
	v_fmaak_f32 v107, v108, v140, 0x4b400000
	v_fmaak_f32 v108, v109, v140, 0x4b400000
	v_perm_b32 v98, v99, v98, s35
	v_fmaak_f32 v99, v100, v140, 0x4b400000
	v_fmaak_f32 v100, v101, v140, 0x4b400000
	v_perm_b32 v123, v125, v123, s36
	v_lshl_add_u64 v[124:125], s[94:95], 0, v[130:131]
	v_fmaak_f32 v118, v118, v140, 0x4b400000
	v_fmaak_f32 v117, v120, v140, 0x4b400000
	v_perm_b32 v115, v116, v115, s35
	v_fmaak_f32 v110, v110, v140, 0x4b400000
	v_fmaak_f32 v109, v112, v140, 0x4b400000
	v_perm_b32 v107, v108, v107, s35
	v_fmaak_f32 v102, v102, v140, 0x4b400000
	v_fmaak_f32 v101, v104, v140, 0x4b400000
	v_perm_b32 v99, v100, v99, s35
	v_fmaak_f32 v126, v127, v140, 0x4b400000
	v_add_co_u32_e32 v124, vcc, s38, v124
	v_fmaak_f32 v119, v119, v140, 0x4b400000
	v_perm_b32 v114, v118, v114, s36
	v_fmaak_f32 v118, v121, v140, 0x4b400000
	v_perm_b32 v115, v117, v115, s36
	v_fmaak_f32 v111, v111, v140, 0x4b400000
	v_perm_b32 v106, v110, v106, s36
	v_fmaak_f32 v110, v113, v140, 0x4b400000
	v_perm_b32 v107, v109, v107, s36
	v_fmaak_f32 v103, v103, v140, 0x4b400000
	v_perm_b32 v98, v102, v98, s36
	v_fmaak_f32 v102, v105, v140, 0x4b400000
	v_perm_b32 v99, v101, v99, s36
	v_perm_b32 v123, v126, v123, s37
	v_addc_co_u32_e32 v125, vcc, 0, v125, vcc
	v_perm_b32 v114, v119, v114, s37
	v_perm_b32 v115, v118, v115, s37
	v_perm_b32 v106, v111, v106, s37
	v_perm_b32 v107, v110, v107, s37
	v_perm_b32 v98, v103, v98, s37
	v_perm_b32 v99, v102, v99, s37
	global_store_dwordx2 v[124:125], v[122:123], off sc1
	global_store_dwordx2 v[124:125], v[114:115], off offset:512 sc1
	global_store_dwordx2 v[124:125], v[106:107], off offset:1024 sc1
	global_store_dwordx2 v[124:125], v[98:99], off offset:1536 sc1
	s_add_u32 s15, s15, s20
	v_mov_b64_e32 v[128:129], v[76:77]
	v_mov_b64_e32 v[124:125], v[84:85]
	v_mov_b64_e32 v[120:121], v[88:89]
	v_mov_b64_e32 v[116:117], v[92:93]
	v_mov_b64_e32 v[112:113], v[68:69]
	v_mov_b64_e32 v[108:109], v[72:73]
	v_mov_b64_e32 v[104:105], v[80:81]
	v_mov_b64_e32 v[100:101], v[96:97]
	s_addc_u32 s39, s39, s21
	v_lshl_add_u64 v[130:131], v[130:131], 0, s[22:23]
	v_lshl_add_u64 v[132:133], v[132:133], 0, s[24:25]
	v_lshl_add_u64 v[134:135], v[134:135], 0, s[24:25]
	s_andn2_b64 vcc, exec, s[26:27]
	v_mov_b64_e32 v[126:127], v[74:75]
	v_mov_b64_e32 v[122:123], v[82:83]
	v_mov_b64_e32 v[118:119], v[86:87]
	v_mov_b64_e32 v[114:115], v[90:91]
	v_mov_b64_e32 v[110:111], v[66:67]
	v_mov_b64_e32 v[106:107], v[70:71]
	v_mov_b64_e32 v[102:103], v[78:79]
	v_mov_b64_e32 v[98:99], v[94:95]
	s_cbranch_vccz .LBB0_1501

.LBB0_2038:
	v_lshlrev_b32_e32 v134, 16, v126
	v_and_b32_e32 v135, 0xffff0000, v126
	v_lshlrev_b32_e32 v126, 16, v127
	v_and_b32_e32 v127, 0xffff0000, v127
	v_pk_mul_f32 v[136:137], v[126:127], v[126:127]
	v_lshlrev_b32_e32 v138, 16, v128
	v_pk_fma_f32 v[136:137], v[134:135], v[134:135], v[136:137]
	v_and_b32_e32 v139, 0xffff0000, v128
	v_pk_fma_f32 v[136:137], v[138:139], v[138:139], v[136:137]
	v_lshlrev_b32_e32 v128, 16, v129
	v_and_b32_e32 v129, 0xffff0000, v129
	v_pk_fma_f32 v[136:137], v[128:129], v[128:129], v[136:137]
	v_lshlrev_b32_e32 v140, 16, v122
	v_and_b32_e32 v141, 0xffff0000, v122
	v_pk_fma_f32 v[136:137], v[140:141], v[140:141], v[136:137]
	v_lshlrev_b32_e32 v122, 16, v123
	v_and_b32_e32 v123, 0xffff0000, v123
	v_pk_fma_f32 v[136:137], v[122:123], v[122:123], v[136:137]
	v_lshlrev_b32_e32 v142, 16, v124
	v_and_b32_e32 v143, 0xffff0000, v124
	v_pk_fma_f32 v[136:137], v[142:143], v[142:143], v[136:137]
	v_lshlrev_b32_e32 v124, 16, v125
	v_and_b32_e32 v125, 0xffff0000, v125
	v_pk_fma_f32 v[136:137], v[124:125], v[124:125], v[136:137]
	v_lshlrev_b32_e32 v144, 16, v118
	v_and_b32_e32 v145, 0xffff0000, v118
	v_pk_fma_f32 v[136:137], v[144:145], v[144:145], v[136:137]
	v_lshlrev_b32_e32 v118, 16, v119
	v_and_b32_e32 v119, 0xffff0000, v119
	v_pk_fma_f32 v[136:137], v[118:119], v[118:119], v[136:137]
	v_lshlrev_b32_e32 v146, 16, v120
	v_and_b32_e32 v147, 0xffff0000, v120
	v_pk_fma_f32 v[136:137], v[146:147], v[146:147], v[136:137]
	v_lshlrev_b32_e32 v120, 16, v121
	v_and_b32_e32 v121, 0xffff0000, v121
	v_pk_fma_f32 v[136:137], v[120:121], v[120:121], v[136:137]
	v_lshlrev_b32_e32 v148, 16, v114
	v_and_b32_e32 v149, 0xffff0000, v114
	v_pk_fma_f32 v[136:137], v[148:149], v[148:149], v[136:137]
	v_lshlrev_b32_e32 v114, 16, v115
	v_and_b32_e32 v115, 0xffff0000, v115
	v_pk_fma_f32 v[136:137], v[114:115], v[114:115], v[136:137]
	v_lshlrev_b32_e32 v150, 16, v116
	v_and_b32_e32 v151, 0xffff0000, v116
	v_pk_fma_f32 v[136:137], v[150:151], v[150:151], v[136:137]
	v_lshlrev_b32_e32 v116, 16, v117
	v_and_b32_e32 v117, 0xffff0000, v117
	v_pk_fma_f32 v[136:137], v[116:117], v[116:117], v[136:137]
	v_cvt_f32_f16_sdwa v153, v110 dst_sel:DWORD dst_unused:UNUSED_PAD src0_sel:WORD_1
	v_add_f32_e32 v133, v136, v137
	v_mov_b32_e32 v136, 0
	v_cvt_f32_f16_e32 v152, v110
	v_add_f32_dpp v133, v133, v133 quad_perm:[1,0,3,2] row_mask:0xf bank_mask:0xf bound_ctrl:1
	v_cvt_f32_f16_sdwa v155, v111 dst_sel:DWORD dst_unused:UNUSED_PAD src0_sel:WORD_1
	v_cvt_f32_f16_e32 v154, v111
	v_add_f32_dpp v133, v133, v133 quad_perm:[2,3,0,1] row_mask:0xf bank_mask:0xf bound_ctrl:1
	v_pk_mul_f32 v[110:111], v[6:7], v[134:135]
	v_cvt_f32_f16_sdwa v135, v112 dst_sel:DWORD dst_unused:UNUSED_PAD src0_sel:WORD_1
	v_add_f32_dpp v133, v133, v133 row_half_mirror row_mask:0xf bank_mask:0xf bound_ctrl:1
	v_cvt_f32_f16_e32 v134, v112
	v_pk_mul_f32 v[122:123], v[16:17], v[122:123]
	v_add_f32_dpp v133, v133, v133 row_mirror row_mask:0xf bank_mask:0xf bound_ctrl:1
	v_pk_mul_f32 v[124:125], v[12:13], v[124:125]
	v_pk_mul_f32 v[126:127], v[8:9], v[126:127]
	v_mov_b32_dpp v136, v133 row_bcast:15 row_mask:0xa bank_mask:0xf
	v_add_f32_e32 v133, v133, v136
	v_mov_b32_e32 v136, 0
	v_pk_mul_f32 v[118:119], v[24:25], v[118:119]
	v_pk_mul_f32 v[128:129], v[4:5], v[128:129]
	v_mov_b32_dpp v136, v133 row_bcast:31 row_mask:0xc bank_mask:0xf
	v_add_f32_e32 v133, v133, v136
	v_pk_mul_f32 v[120:121], v[20:21], v[120:121]
	v_readlane_b32 s13, v133, 63
	s_nop 1
	v_fma_f32 v133, s13, v132, v1
	v_rsq_f32_e32 v133, v133
	s_nop 0
	v_mul_f32_e32 v136, 0.5, v133
	v_pk_fma_f32 v[110:111], v[110:111], v[136:137], v[152:153] op_sel_hi:[1,0,1]
	v_cvt_f32_f16_sdwa v153, v113 dst_sel:DWORD dst_unused:UNUSED_PAD src0_sel:WORD_1
	v_cvt_f32_f16_e32 v152, v113
	v_pk_mul_f32 v[112:113], v[2:3], v[138:139]
	v_cvt_f32_f16_sdwa v139, v107 dst_sel:DWORD dst_unused:UNUSED_PAD src0_sel:WORD_1
	v_pk_fma_f32 v[112:113], v[112:113], v[136:137], v[134:135] op_sel_hi:[1,0,1]
	v_cvt_f32_f16_sdwa v135, v106 dst_sel:DWORD dst_unused:UNUSED_PAD src0_sel:WORD_1
	v_cvt_f32_f16_e32 v134, v106
	v_cvt_f32_f16_e32 v138, v107
	v_pk_mul_f32 v[106:107], v[14:15], v[140:141]
	v_pk_fma_f32 v[126:127], v[126:127], v[136:137], v[154:155] op_sel_hi:[1,0,1]
	v_pk_fma_f32 v[106:107], v[106:107], v[136:137], v[134:135] op_sel_hi:[1,0,1]
	v_cvt_f32_f16_sdwa v135, v108 dst_sel:DWORD dst_unused:UNUSED_PAD src0_sel:WORD_1
	v_cvt_f32_f16_e32 v134, v108
	v_pk_fma_f32 v[122:123], v[122:123], v[136:137], v[138:139] op_sel_hi:[1,0,1]
	v_cvt_f32_f16_sdwa v139, v109 dst_sel:DWORD dst_unused:UNUSED_PAD src0_sel:WORD_1
	v_cvt_f32_f16_e32 v138, v109
	v_pk_mul_f32 v[108:109], v[10:11], v[142:143]
	v_pk_mul_f32 v[142:143], v[126:127], v[126:127]
	v_pk_fma_f32 v[108:109], v[108:109], v[136:137], v[134:135] op_sel_hi:[1,0,1]
	v_cvt_f32_f16_sdwa v135, v102 dst_sel:DWORD dst_unused:UNUSED_PAD src0_sel:WORD_1
	v_cvt_f32_f16_e32 v134, v102
	v_pk_fma_f32 v[124:125], v[124:125], v[136:137], v[138:139] op_sel_hi:[1,0,1]
	v_cvt_f32_f16_sdwa v139, v103 dst_sel:DWORD dst_unused:UNUSED_PAD src0_sel:WORD_1
	v_cvt_f32_f16_e32 v138, v103
	v_pk_mul_f32 v[102:103], v[22:23], v[144:145]
	v_pk_fma_f32 v[142:143], v[110:111], v[110:111], v[142:143]
	v_pk_fma_f32 v[102:103], v[102:103], v[136:137], v[134:135] op_sel_hi:[1,0,1]
	v_cvt_f32_f16_sdwa v135, v104 dst_sel:DWORD dst_unused:UNUSED_PAD src0_sel:WORD_1
	v_cvt_f32_f16_e32 v134, v104
	v_pk_fma_f32 v[118:119], v[118:119], v[136:137], v[138:139] op_sel_hi:[1,0,1]
	v_cvt_f32_f16_sdwa v139, v105 dst_sel:DWORD dst_unused:UNUSED_PAD src0_sel:WORD_1
	v_cvt_f32_f16_e32 v138, v105
	v_pk_fma_f32 v[128:129], v[128:129], v[136:137], v[152:153] op_sel_hi:[1,0,1]
	v_pk_fma_f32 v[142:143], v[112:113], v[112:113], v[142:143]
	v_pk_mul_f32 v[104:105], v[18:19], v[146:147]
	v_pk_fma_f32 v[142:143], v[128:129], v[128:129], v[142:143]
	v_pk_fma_f32 v[104:105], v[104:105], v[136:137], v[134:135] op_sel_hi:[1,0,1]
	v_cvt_f32_f16_sdwa v135, v98 dst_sel:DWORD dst_unused:UNUSED_PAD src0_sel:WORD_1
	v_cvt_f32_f16_e32 v134, v98
	v_pk_fma_f32 v[142:143], v[106:107], v[106:107], v[142:143]
	v_pk_fma_f32 v[120:121], v[120:121], v[136:137], v[138:139] op_sel_hi:[1,0,1]
	v_cvt_f32_f16_sdwa v139, v99 dst_sel:DWORD dst_unused:UNUSED_PAD src0_sel:WORD_1
	v_cvt_f32_f16_e32 v138, v99
	v_pk_fma_f32 v[142:143], v[122:123], v[122:123], v[142:143]
	v_pk_mul_f32 v[98:99], v[30:31], v[148:149]
	v_pk_fma_f32 v[142:143], v[108:109], v[108:109], v[142:143]
	v_pk_fma_f32 v[134:135], v[98:99], v[136:137], v[134:135] op_sel_hi:[1,0,1]
	v_pk_fma_f32 v[142:143], v[124:125], v[124:125], v[142:143]
	v_pk_mul_f32 v[98:99], v[32:33], v[114:115]
	v_pk_fma_f32 v[142:143], v[102:103], v[102:103], v[142:143]
	v_pk_fma_f32 v[114:115], v[98:99], v[136:137], v[138:139] op_sel_hi:[1,0,1]
	v_cvt_f32_f16_sdwa v99, v100 dst_sel:DWORD dst_unused:UNUSED_PAD src0_sel:WORD_1
	v_cvt_f32_f16_e32 v98, v100
	v_pk_fma_f32 v[142:143], v[118:119], v[118:119], v[142:143]
	v_cvt_f32_f16_sdwa v139, v101 dst_sel:DWORD dst_unused:UNUSED_PAD src0_sel:WORD_1
	v_cvt_f32_f16_e32 v138, v101
	v_pk_fma_f32 v[142:143], v[104:105], v[104:105], v[142:143]
	v_pk_mul_f32 v[100:101], v[26:27], v[150:151]
	v_pk_fma_f32 v[142:143], v[120:121], v[120:121], v[142:143]
	v_pk_fma_f32 v[140:141], v[100:101], v[136:137], v[98:99] op_sel_hi:[1,0,1]
	v_pk_fma_f32 v[142:143], v[134:135], v[134:135], v[142:143]
	v_pk_mul_f32 v[98:99], v[28:29], v[116:117]
	v_pk_fma_f32 v[142:143], v[114:115], v[114:115], v[142:143]
	v_pk_fma_f32 v[116:117], v[98:99], v[136:137], v[138:139] op_sel_hi:[1,0,1]
	v_pk_fma_f32 v[142:143], v[140:141], v[140:141], v[142:143]
	v_lshl_add_u64 v[136:137], s[14:15], 0, v[130:131]
	v_pk_fma_f32 v[142:143], v[116:117], v[116:117], v[142:143]
	v_add_co_u32_e32 v138, vcc, s11, v136
	v_add_f32_e32 v133, v142, v143
	v_mov_b32_e32 v142, 0
	v_cvt_pk_f16_f32 v98, v110, v111
	v_add_f32_dpp v133, v133, v133 quad_perm:[1,0,3,2] row_mask:0xf bank_mask:0xf bound_ctrl:1
	v_cvt_pk_f16_f32 v99, v126, v127
	v_cvt_pk_f16_f32 v100, v112, v113
	v_add_f32_dpp v133, v133, v133 quad_perm:[2,3,0,1] row_mask:0xf bank_mask:0xf bound_ctrl:1
	v_cvt_pk_f16_f32 v101, v128, v129
	v_addc_co_u32_e32 v139, vcc, 0, v137, vcc
	v_add_f32_dpp v133, v133, v133 row_half_mirror row_mask:0xf bank_mask:0xf bound_ctrl:1
	global_store_dwordx4 v[138:139], v[98:101], off offset:1024 sc1
	s_add_u32 s14, s14, s16
	v_add_f32_dpp v133, v133, v133 row_mirror row_mask:0xf bank_mask:0xf bound_ctrl:1
	v_cvt_pk_f16_f32 v98, v106, v107
	v_cvt_pk_f16_f32 v99, v122, v123
	v_mov_b32_dpp v142, v133 row_bcast:15 row_mask:0xa bank_mask:0xf
	v_add_f32_e32 v133, v133, v142
	v_mov_b32_e32 v142, 0
	v_cvt_pk_f16_f32 v100, v108, v109
	v_cvt_pk_f16_f32 v101, v124, v125
	v_mov_b32_dpp v142, v133 row_bcast:31 row_mask:0xc bank_mask:0xf
	v_add_f32_e32 v133, v133, v142
	global_store_dwordx4 v[138:139], v[98:101], off offset:2048 sc1
	v_readlane_b32 s13, v133, 63
	s_addc_u32 s15, s15, s17
	v_cvt_pk_f16_f32 v98, v102, v103
	v_fma_f32 v133, s13, v132, v1
	v_cvt_pk_f16_f32 v99, v118, v119
	v_cvt_pk_f16_f32 v100, v104, v105
	v_cvt_pk_f16_f32 v101, v120, v121
	v_rsq_f32_e32 v142, v133
	global_store_dwordx4 v[138:139], v[98:101], off offset:3072 sc1
	v_add_co_u32_e32 v138, vcc, s24, v136
	s_nop 0
	v_cvt_pk_f16_f32 v98, v134, v135
	v_cvt_pk_f16_f32 v99, v114, v115
	v_cvt_pk_f16_f32 v100, v140, v141
	v_cvt_pk_f16_f32 v101, v116, v117
	v_addc_co_u32_e32 v139, vcc, 0, v137, vcc
	global_store_dwordx4 v[138:139], v[98:101], off sc1
	s_add_u32 s20, s20, s16
	s_addc_u32 s21, s21, s17
	v_pk_mul_f32 v[98:99], v[40:41], v[126:127]
	s_nop 0
	v_pk_mul_f32 v[100:101], v[98:99], v[142:143] op_sel_hi:[1,0]
	v_pk_mul_f32 v[98:99], v[38:39], v[110:111]
	v_pk_mul_f32 v[110:111], v[36:37], v[128:129]
	v_pk_mul_f32 v[98:99], v[98:99], v[142:143] op_sel_hi:[1,0]
	v_pk_mul_f32 v[110:111], v[110:111], v[142:143] op_sel_hi:[1,0]
	v_cvt_pk_bf16_f32 v98, v98, v99
	v_cvt_pk_bf16_f32 v99, v100, v101
	v_pk_mul_f32 v[100:101], v[34:35], v[112:113]
	s_waitcnt vmcnt(9)
	v_mov_b64_e32 v[128:129], v[76:77]
	v_pk_mul_f32 v[100:101], v[100:101], v[142:143] op_sel_hi:[1,0]
	v_mov_b64_e32 v[126:127], v[74:75]
	v_cvt_pk_bf16_f32 v100, v100, v101
	v_cvt_pk_bf16_f32 v101, v110, v111
	v_add_co_u32_e32 v110, vcc, s25, v136
	s_nop 1
	v_addc_co_u32_e32 v111, vcc, 0, v137, vcc
	global_store_dwordx4 v[110:111], v[98:101], off sc1
	s_andn2_b64 vcc, exec, s[22:23]
	s_nop 0
	v_pk_mul_f32 v[98:99], v[46:47], v[106:107]
	v_pk_mul_f32 v[100:101], v[48:49], v[122:123]
	v_pk_mul_f32 v[98:99], v[98:99], v[142:143] op_sel_hi:[1,0]
	v_pk_mul_f32 v[100:101], v[100:101], v[142:143] op_sel_hi:[1,0]
	v_cvt_pk_bf16_f32 v98, v98, v99
	v_pk_mul_f32 v[106:107], v[44:45], v[124:125]
	v_cvt_pk_bf16_f32 v99, v100, v101
	v_pk_mul_f32 v[100:101], v[42:43], v[108:109]
	v_pk_mul_f32 v[106:107], v[106:107], v[142:143] op_sel_hi:[1,0]
	v_pk_mul_f32 v[100:101], v[100:101], v[142:143] op_sel_hi:[1,0]
	s_waitcnt vmcnt(8)
	v_mov_b64_e32 v[124:125], v[84:85]
	v_cvt_pk_bf16_f32 v100, v100, v101
	v_cvt_pk_bf16_f32 v101, v106, v107
	global_store_dwordx4 v[110:111], v[98:101], off offset:1024 sc1
	v_mov_b64_e32 v[108:109], v[72:73]
	v_mov_b64_e32 v[122:123], v[82:83]
	v_pk_mul_f32 v[98:99], v[54:55], v[102:103]
	v_pk_mul_f32 v[100:101], v[56:57], v[118:119]
	v_pk_mul_f32 v[98:99], v[98:99], v[142:143] op_sel_hi:[1,0]
	v_pk_mul_f32 v[100:101], v[100:101], v[142:143] op_sel_hi:[1,0]
	v_cvt_pk_bf16_f32 v98, v98, v99
	v_pk_mul_f32 v[102:103], v[52:53], v[120:121]
	v_cvt_pk_bf16_f32 v99, v100, v101
	v_pk_mul_f32 v[100:101], v[50:51], v[104:105]
	v_pk_mul_f32 v[102:103], v[102:103], v[142:143] op_sel_hi:[1,0]
	v_pk_mul_f32 v[100:101], v[100:101], v[142:143] op_sel_hi:[1,0]
	s_waitcnt vmcnt(8)
	v_mov_b64_e32 v[120:121], v[88:89]
	v_cvt_pk_bf16_f32 v100, v100, v101
	v_cvt_pk_bf16_f32 v101, v102, v103
	global_store_dwordx4 v[110:111], v[98:101], off offset:2048 sc1
	s_waitcnt vmcnt(8)
	v_pk_mul_f32 v[102:103], v[60:61], v[116:117]
	v_mov_b64_e32 v[118:119], v[86:87]
	s_waitcnt vmcnt(7)
	v_pk_mul_f32 v[98:99], v[62:63], v[134:135]
	v_pk_mul_f32 v[100:101], v[64:65], v[114:115]
	v_pk_mul_f32 v[98:99], v[98:99], v[142:143] op_sel_hi:[1,0]
	v_pk_mul_f32 v[100:101], v[100:101], v[142:143] op_sel_hi:[1,0]
	v_cvt_pk_bf16_f32 v98, v98, v99
	v_pk_mul_f32 v[102:103], v[102:103], v[142:143] op_sel_hi:[1,0]
	v_cvt_pk_bf16_f32 v99, v100, v101
	v_pk_mul_f32 v[100:101], v[58:59], v[140:141]
	v_mov_b64_e32 v[116:117], v[92:93]
	v_pk_mul_f32 v[100:101], v[100:101], v[142:143] op_sel_hi:[1,0]
	v_mov_b64_e32 v[114:115], v[90:91]
	v_cvt_pk_bf16_f32 v100, v100, v101
	v_cvt_pk_bf16_f32 v101, v102, v103
	global_store_dwordx4 v[110:111], v[98:101], off offset:3072 sc1
	v_mov_b64_e32 v[112:113], v[68:69]
	v_mov_b64_e32 v[104:105], v[80:81]
	v_mov_b64_e32 v[100:101], v[96:97]
	v_mov_b64_e32 v[110:111], v[66:67]
	v_mov_b64_e32 v[106:107], v[70:71]
	v_mov_b64_e32 v[102:103], v[78:79]
	v_mov_b64_e32 v[98:99], v[94:95]
	s_cbranch_vccz .LBB0_2041

.LBB0_2371:
	s_or_b64 exec, exec, s[26:27]
	v_div_scale_f32 v140, s[26:27], s15, s15, v139
	v_rcp_f32_e32 v141, v140
	v_mov_b32_e32 v142, s15
	v_div_scale_f32 v142, vcc, s30, v142, s30
	v_fma_f32 v143, -v140, v141, 1.0
	v_fmac_f32_e32 v141, v143, v141
	v_mul_f32_e32 v143, v142, v141
	v_fma_f32 v144, -v140, v143, v142
	v_fmac_f32_e32 v143, v144, v141
	v_fma_f32 v140, -v140, v143, v142
	v_div_fmas_f32 v140, v140, v141, v143
	v_div_fixup_f32 v140, v140, s15, v139
	v_cndmask_b32_e64 v140, 0, v140, s[4:5]
	v_fmaak_f32 v128, v128, v140, 0x4b400000
	v_fmaak_f32 v129, v129, v140, 0x4b400000
	v_fmaak_f32 v122, v122, v140, 0x4b400000
	v_perm_b32 v128, v129, v128, s31
	v_fmaak_f32 v123, v123, v140, 0x4b400000
	v_perm_b32 v122, v122, v128, s34
	v_perm_b32 v122, v123, v122, s35
	v_fmaak_f32 v123, v124, v140, 0x4b400000
	v_fmaak_f32 v124, v125, v140, 0x4b400000
	v_fmaak_f32 v114, v114, v140, 0x4b400000
	v_fmaak_f32 v115, v115, v140, 0x4b400000
	v_fmaak_f32 v106, v106, v140, 0x4b400000
	v_fmaak_f32 v107, v107, v140, 0x4b400000
	v_fmaak_f32 v98, v98, v140, 0x4b400000
	v_fmaak_f32 v99, v99, v140, 0x4b400000
	v_fmaak_f32 v125, v126, v140, 0x4b400000
	v_perm_b32 v123, v124, v123, s31
	v_perm_b32 v114, v115, v114, s31
	v_fmaak_f32 v115, v116, v140, 0x4b400000
	v_fmaak_f32 v116, v117, v140, 0x4b400000
	v_perm_b32 v106, v107, v106, s31
	v_fmaak_f32 v107, v108, v140, 0x4b400000
	v_fmaak_f32 v108, v109, v140, 0x4b400000
	v_perm_b32 v98, v99, v98, s31
	v_fmaak_f32 v99, v100, v140, 0x4b400000
	v_fmaak_f32 v100, v101, v140, 0x4b400000
	v_perm_b32 v123, v125, v123, s34
	v_lshl_add_u64 v[124:125], s[94:95], 0, v[130:131]
	v_fmaak_f32 v118, v118, v140, 0x4b400000
	v_fmaak_f32 v117, v120, v140, 0x4b400000
	v_perm_b32 v115, v116, v115, s31
	v_fmaak_f32 v110, v110, v140, 0x4b400000
	v_fmaak_f32 v109, v112, v140, 0x4b400000
	v_perm_b32 v107, v108, v107, s31
	v_fmaak_f32 v102, v102, v140, 0x4b400000
	v_fmaak_f32 v101, v104, v140, 0x4b400000
	v_perm_b32 v99, v100, v99, s31
	v_fmaak_f32 v126, v127, v140, 0x4b400000
	v_add_co_u32_e32 v124, vcc, s36, v124
	v_fmaak_f32 v119, v119, v140, 0x4b400000
	v_perm_b32 v114, v118, v114, s34
	v_fmaak_f32 v118, v121, v140, 0x4b400000
	v_perm_b32 v115, v117, v115, s34
	v_fmaak_f32 v111, v111, v140, 0x4b400000
	v_perm_b32 v106, v110, v106, s34
	v_fmaak_f32 v110, v113, v140, 0x4b400000
	v_perm_b32 v107, v109, v107, s34
	v_fmaak_f32 v103, v103, v140, 0x4b400000
	v_perm_b32 v98, v102, v98, s34
	v_fmaak_f32 v102, v105, v140, 0x4b400000
	v_perm_b32 v99, v101, v99, s34
	v_perm_b32 v123, v126, v123, s35
	v_addc_co_u32_e32 v125, vcc, 0, v125, vcc
	v_perm_b32 v114, v119, v114, s35
	v_perm_b32 v115, v118, v115, s35
	v_perm_b32 v106, v111, v106, s35
	v_perm_b32 v107, v110, v107, s35
	v_perm_b32 v98, v103, v98, s35
	v_perm_b32 v99, v102, v99, s35
	global_store_dwordx2 v[124:125], v[122:123], off sc1
	global_store_dwordx2 v[124:125], v[114:115], off offset:512 sc1
	global_store_dwordx2 v[124:125], v[106:107], off offset:1024 sc1
	global_store_dwordx2 v[124:125], v[98:99], off offset:1536 sc1
	s_add_u32 s13, s13, s16
	v_mov_b64_e32 v[128:129], v[76:77]
	v_mov_b64_e32 v[124:125], v[84:85]
	v_mov_b64_e32 v[120:121], v[88:89]
	v_mov_b64_e32 v[116:117], v[92:93]
	v_mov_b64_e32 v[112:113], v[68:69]
	v_mov_b64_e32 v[108:109], v[72:73]
	v_mov_b64_e32 v[104:105], v[80:81]
	v_mov_b64_e32 v[100:101], v[96:97]
	s_addc_u32 s37, s37, s17
	v_lshl_add_u64 v[130:131], v[130:131], 0, s[20:21]
	v_lshl_add_u64 v[132:133], v[132:133], 0, s[22:23]
	v_lshl_add_u64 v[134:135], v[134:135], 0, s[22:23]
	s_andn2_b64 vcc, exec, s[24:25]
	v_mov_b64_e32 v[126:127], v[74:75]
	v_mov_b64_e32 v[122:123], v[82:83]
	v_mov_b64_e32 v[118:119], v[86:87]
	v_mov_b64_e32 v[114:115], v[90:91]
	v_mov_b64_e32 v[110:111], v[66:67]
	v_mov_b64_e32 v[106:107], v[70:71]
	v_mov_b64_e32 v[102:103], v[78:79]
	v_mov_b64_e32 v[98:99], v[94:95]
	s_cbranch_vccz .LBB0_2376

.LBB0_2379:
	s_cmp_gt_i32 s10, 31
	s_cbranch_scc1 .LBB0_2383
	s_ashr_i32 s11, s10, 31
	s_lshl_b64 s[0:1], s[10:11], 13
	v_readlane_b32 s4, v254, 58
	v_readlane_b32 s5, v254, 59
	s_add_u32 s0, s4, s0
	s_addc_u32 s1, s5, s1
	s_add_u32 s4, s0, 0x40000
	s_addc_u32 s5, s1, 0
	s_add_u32 s12, s0, 0x80000
	s_addc_u32 s13, s1, 0
	v_lshlrev_b32_e32 v116, 4, v166
	s_add_u32 s14, s0, 0xc0000
	v_or_b32_e32 v118, 0x400, v116
	v_or_b32_e32 v117, 0x800, v116
	v_or_b32_e32 v115, 0xc00, v116
	s_addc_u32 s15, s1, 0
	v_or_b32_e32 v122, 0x1000, v116
	v_or_b32_e32 v121, 0x1400, v116
	global_load_dwordx4 v[74:77], v116, s[0:1]
	global_load_dwordx4 v[94:97], v116, s[0:1] offset:1024
	global_load_dwordx4 v[100:103], v116, s[0:1] offset:2048
	global_load_dwordx4 v[106:109], v116, s[0:1] offset:3072
	global_load_dwordx4 v[110:113], v116, s[4:5]
	global_load_dwordx4 v[132:135], v115, s[4:5]
	global_load_dwordx4 v[124:127], v118, s[4:5]
	global_load_dwordx4 v[128:131], v117, s[4:5]
	global_load_dwordx4 v[136:139], v116, s[12:13]
	global_load_dwordx4 v[140:143], v116, s[14:15]
	global_load_dwordx4 v[144:147], v118, s[12:13]
	global_load_dwordx4 v[148:151], v118, s[14:15]
	global_load_dwordx4 v[152:155], v117, s[12:13]
	global_load_dwordx4 v[156:159], v117, s[14:15]
	global_load_dwordx4 v[160:163], v115, s[12:13]
	global_load_dwordx4 v[170:173], v115, s[14:15]
	global_load_dwordx4 v[50:53], v122, s[0:1]
	global_load_dwordx4 v[58:61], v122, s[4:5]
	global_load_dwordx4 v[54:57], v122, s[12:13]
	global_load_dwordx4 v[62:65], v122, s[14:15]
	global_load_dwordx4 v[38:41], v121, s[0:1]
	global_load_dwordx4 v[46:49], v121, s[4:5]
	global_load_dwordx4 v[34:37], v121, s[12:13]
	global_load_dwordx4 v[42:45], v121, s[14:15]
	v_or_b32_e32 v120, 0x1800, v116
	global_load_dwordx4 v[18:21], v120, s[0:1]
	global_load_dwordx4 v[26:29], v120, s[4:5]
	global_load_dwordx4 v[22:25], v120, s[12:13]
	global_load_dwordx4 v[30:33], v120, s[14:15]
	v_or_b32_e32 v119, 0x1c00, v116
	global_load_dwordx4 v[2:5], v119, s[0:1]
	global_load_dwordx4 v[10:13], v119, s[4:5]
	global_load_dwordx4 v[6:9], v119, s[12:13]
	global_load_dwordx4 v[14:17], v119, s[14:15]
	v_readlane_b32 s64, v254, 18
	v_readlane_b32 s66, v254, 20
	v_readlane_b32 s67, v254, 21
	s_nop 4
	global_load_dwordx4 v[70:73], v116, s[66:67]
	global_load_dwordx4 v[66:69], v116, s[66:67] offset:1024
	s_add_i32 s4, s10, 0x2000
	s_ashr_i32 s5, s4, 31
	s_lshl_b64 s[10:11], s[4:5], 12
	v_readlane_b32 s0, v254, 54
	v_readlane_b32 s1, v254, 55
	s_add_u32 s0, s0, s10
	s_addc_u32 s1, s1, s11
	v_lshlrev_b32_e32 v114, 3, v166
	s_add_u32 s10, s84, s10
	s_addc_u32 s11, s85, s11
	global_load_dwordx2 v[92:93], v114, s[0:1]
	global_load_dwordx2 v[82:83], v114, s[0:1] offset:2560
	global_load_dwordx2 v[80:81], v114, s[0:1] offset:3072
	global_load_dwordx2 v[78:79], v114, s[0:1] offset:3584
	global_load_dwordx2 v[104:105], v114, s[10:11]
	global_load_dwordx2 v[90:91], v114, s[0:1] offset:512
	global_load_dwordx2 v[88:89], v114, s[0:1] offset:1024
	global_load_dwordx2 v[86:87], v114, s[0:1] offset:1536
	global_load_dwordx2 v[84:85], v114, s[0:1] offset:2048
	global_load_dwordx2 v[98:99], v114, s[10:11] offset:512
	v_mov_b32_e32 v1, 0
	v_cmp_eq_u32_e32 vcc, 0, v166
	v_readlane_b32 s65, v254, 19
	v_readlane_b32 s68, v254, 22
	v_readlane_b32 s69, v254, 23
	v_readlane_b32 s70, v254, 24
	v_readlane_b32 s71, v254, 25
	v_readlane_b32 s72, v254, 26
	v_readlane_b32 s73, v254, 27
	v_readlane_b32 s74, v254, 28
	v_readlane_b32 s75, v254, 29
	v_readlane_b32 s76, v254, 30
	v_readlane_b32 s77, v254, 31
	v_readlane_b32 s78, v254, 32
	v_readlane_b32 s79, v254, 33
	s_waitcnt vmcnt(39)
	v_pk_add_f32 v[74:75], v[74:75], v[110:111]
	v_pk_add_f32 v[76:77], v[76:77], v[112:113]
	s_waitcnt vmcnt(37)
	v_pk_add_f32 v[94:95], v[94:95], v[124:125]
	s_waitcnt vmcnt(36)
	v_pk_add_f32 v[124:125], v[100:101], v[128:129]
	v_pk_add_f32 v[128:129], v[106:107], v[132:133]
	s_waitcnt vmcnt(22)
	v_pk_add_f32 v[48:49], v[40:41], v[48:49]
	v_pk_add_f32 v[46:47], v[38:39], v[46:47]
	global_load_dwordx4 v[38:41], v116, s[66:67] offset:2048
	v_pk_add_f32 v[106:107], v[136:137], v[140:141]
	v_pk_add_f32 v[96:97], v[96:97], v[126:127]
	v_pk_add_f32 v[126:127], v[108:109], v[134:135]
	v_pk_add_f32 v[100:101], v[138:139], v[142:143]
	v_pk_add_f32 v[108:109], v[146:147], v[150:151]
	v_pk_add_f32 v[112:113], v[74:75], v[106:107]
	v_pk_add_f32 v[74:75], v[160:161], v[170:171]
	v_pk_add_f32 v[52:53], v[52:53], v[60:61]
	v_pk_add_f32 v[50:51], v[50:51], v[58:59]
	v_pk_add_f32 v[56:57], v[56:57], v[64:65]
	v_pk_add_f32 v[54:55], v[54:55], v[62:63]
	s_waitcnt vmcnt(21)
	v_pk_add_f32 v[36:37], v[36:37], v[44:45]
	v_pk_add_f32 v[34:35], v[34:35], v[42:43]
	s_waitcnt vmcnt(19)
	v_pk_add_f32 v[20:21], v[20:21], v[28:29]
	v_pk_add_f32 v[18:19], v[18:19], v[26:27]
	s_waitcnt vmcnt(17)
	v_pk_add_f32 v[24:25], v[24:25], v[32:33]
	v_pk_add_f32 v[22:23], v[22:23], v[30:31]
	v_pk_add_f32 v[110:111], v[76:77], v[100:101]
	v_pk_add_f32 v[106:107], v[96:97], v[108:109]
	v_pk_add_f32 v[96:97], v[128:129], v[74:75]
	global_load_dwordx4 v[74:77], v122, s[8:9]
	v_pk_add_f32 v[56:57], v[52:53], v[56:57]
	v_pk_add_f32 v[54:55], v[50:51], v[54:55]
	global_load_dwordx4 v[50:53], v121, s[8:9]
	v_pk_add_f32 v[42:43], v[48:49], v[36:37]
	v_pk_add_f32 v[44:45], v[46:47], v[34:35]
	global_load_dwordx4 v[34:37], v120, s[8:9]
	v_pk_add_f32 v[46:47], v[20:21], v[24:25]
	v_pk_add_f32 v[48:49], v[18:19], v[22:23]
	global_load_dwordx2 v[58:59], v114, s[10:11] offset:1024
	global_load_dwordx4 v[18:21], v119, s[8:9]
	s_waitcnt vmcnt(20)
	v_pk_add_f32 v[4:5], v[4:5], v[12:13]
	s_waitcnt vmcnt(18)
	v_pk_add_f32 v[8:9], v[8:9], v[16:17]
	v_pk_add_f32 v[2:3], v[2:3], v[10:11]
	v_pk_add_f32 v[6:7], v[6:7], v[14:15]
	v_pk_add_f32 v[16:17], v[4:5], v[8:9]
	global_load_dwordx4 v[8:11], v116, s[66:67] offset:3072
	global_load_dwordx4 v[12:15], v122, s[66:67]
	global_load_dwordx2 v[62:63], v114, s[10:11] offset:1536
	global_load_dwordx2 v[64:65], v114, s[10:11] offset:2048
	global_load_dwordx4 v[22:25], v121, s[66:67]
	global_load_dwordx4 v[26:29], v120, s[66:67]
	global_load_dwordx4 v[30:33], v119, s[66:67]
	v_pk_add_f32 v[102:103], v[102:103], v[130:131]
	v_pk_add_f32 v[132:133], v[154:155], v[158:159]
	v_pk_add_f32 v[134:135], v[152:153], v[156:157]
	v_pk_add_f32 v[100:101], v[102:103], v[132:133]
	v_pk_add_f32 v[102:103], v[124:125], v[134:135]
	v_pk_add_f32 v[60:61], v[2:3], v[6:7]
	s_waitcnt vmcnt(24)
	v_add_f32_e32 v2, v112, v70
	v_add_f32_e32 v3, v113, v71
	global_load_dwordx2 v[70:71], v114, s[10:11] offset:2560
	global_load_dwordx2 v[112:113], v114, s[10:11] offset:3072
	global_load_dwordx2 v[124:125], v114, s[10:11] offset:3584
	v_mul_f32_e32 v2, 0xbfb8aa3b, v2
	v_mul_f32_e32 v3, 0xbfb8aa3b, v3
	v_exp_f32_e32 v2, v2
	v_exp_f32_e32 v3, v3
	v_add_f32_e32 v6, v110, v72
	v_add_f32_e32 v7, v111, v73
	v_add_f32_e32 v2, 1.0, v2
	v_add_f32_e32 v3, 1.0, v3
	v_mul_f32_e32 v6, 0xbfb8aa3b, v6
	v_mul_f32_e32 v7, 0xbfb8aa3b, v7
	v_rcp_f32_e32 v2, v2
	v_rcp_f32_e32 v3, v3
	v_exp_f32_e32 v6, v6
	v_exp_f32_e32 v7, v7
	v_pk_add_f32 v[130:131], v[144:145], v[148:149]
	s_waitcnt vmcnt(21)
	v_and_b32_e32 v5, 0xffff0000, v104
	v_pk_add_f32 v[108:109], v[94:95], v[130:131]
	v_lshlrev_b32_e32 v4, 16, v104
	v_add_f32_e32 v66, v108, v66
	v_add_f32_e32 v67, v109, v67
	v_pk_mul_f32 v[2:3], v[2:3], v[4:5]
	v_add_f32_e32 v4, 1.0, v6
	v_add_f32_e32 v5, 1.0, v7
	v_mul_f32_e32 v66, 0xbfb8aa3b, v66
	v_mul_f32_e32 v67, 0xbfb8aa3b, v67
	v_rcp_f32_e32 v4, v4
	v_rcp_f32_e32 v5, v5
	v_exp_f32_e32 v66, v66
	v_exp_f32_e32 v67, v67
	v_and_b32_e32 v7, 0xffff0000, v105
	v_lshlrev_b32_e32 v6, 16, v105
	v_add_f32_e32 v68, v106, v68
	v_add_f32_e32 v69, v107, v69
	v_pk_mul_f32 v[4:5], v[4:5], v[6:7]
	v_add_f32_e32 v6, 1.0, v66
	v_add_f32_e32 v7, 1.0, v67
	v_mul_f32_e32 v68, 0xbfb8aa3b, v68
	v_mul_f32_e32 v69, 0xbfb8aa3b, v69
	s_waitcnt vmcnt(15)
	v_add_f32_e32 v38, v102, v38
	v_add_f32_e32 v39, v103, v39
	v_rcp_f32_e32 v6, v6
	v_rcp_f32_e32 v7, v7
	v_exp_f32_e32 v68, v68
	v_exp_f32_e32 v69, v69
	v_mul_f32_e32 v38, 0xbfb8aa3b, v38
	v_mul_f32_e32 v39, 0xbfb8aa3b, v39
	v_exp_f32_e32 v38, v38
	v_exp_f32_e32 v39, v39
	v_and_b32_e32 v67, 0xffff0000, v98
	v_lshlrev_b32_e32 v66, 16, v98
	v_pk_mul_f32 v[6:7], v[6:7], v[66:67]
	v_add_f32_e32 v66, 1.0, v68
	v_add_f32_e32 v67, 1.0, v69
	v_add_f32_e32 v40, v100, v40
	v_add_f32_e32 v41, v101, v41
	v_rcp_f32_e32 v66, v66
	v_rcp_f32_e32 v67, v67
	v_add_f32_e32 v38, 1.0, v38
	v_add_f32_e32 v39, 1.0, v39
	v_mul_f32_e32 v40, 0xbfb8aa3b, v40
	v_mul_f32_e32 v41, 0xbfb8aa3b, v41
	v_rcp_f32_e32 v38, v38
	v_rcp_f32_e32 v39, v39
	v_exp_f32_e32 v40, v40
	s_waitcnt vmcnt(9)
	v_add_f32_e32 v8, v96, v8
	v_add_f32_e32 v9, v97, v9
	v_exp_f32_e32 v41, v41
	v_mul_f32_e32 v8, 0xbfb8aa3b, v8
	v_mul_f32_e32 v9, 0xbfb8aa3b, v9
	v_exp_f32_e32 v8, v8
	v_exp_f32_e32 v9, v9
	v_pk_add_f32 v[136:137], v[162:163], v[172:173]
	v_and_b32_e32 v69, 0xffff0000, v99
	v_lshlrev_b32_e32 v68, 16, v99
	v_pk_add_f32 v[94:95], v[126:127], v[136:137]
	v_pk_mul_f32 v[66:67], v[66:67], v[68:69]
	v_and_b32_e32 v69, 0xffff0000, v58
	v_lshlrev_b32_e32 v68, 16, v58
	v_pk_mul_f32 v[68:69], v[38:39], v[68:69]
	v_add_f32_e32 v38, 1.0, v40
	v_add_f32_e32 v39, 1.0, v41
	v_add_f32_e32 v10, v94, v10
	v_rcp_f32_e32 v38, v38
	v_rcp_f32_e32 v39, v39
	v_add_f32_e32 v8, 1.0, v8
	v_add_f32_e32 v9, 1.0, v9
	v_mul_f32_e32 v10, 0xbfb8aa3b, v10
	v_add_f32_e32 v11, v95, v11
	v_rcp_f32_e32 v8, v8
	v_rcp_f32_e32 v9, v9
	v_exp_f32_e32 v10, v10
	v_mul_f32_e32 v11, 0xbfb8aa3b, v11
	s_waitcnt vmcnt(8)
	v_add_f32_e32 v12, v54, v12
	v_add_f32_e32 v13, v55, v13
	v_exp_f32_e32 v11, v11
	v_mul_f32_e32 v12, 0xbfb8aa3b, v12
	v_mul_f32_e32 v13, 0xbfb8aa3b, v13
	v_and_b32_e32 v41, 0xffff0000, v59
	v_lshlrev_b32_e32 v40, 16, v59
	v_exp_f32_e32 v12, v12
	v_exp_f32_e32 v13, v13
	v_pk_mul_f32 v[72:73], v[38:39], v[40:41]
	s_waitcnt vmcnt(7)
	v_and_b32_e32 v39, 0xffff0000, v62
	v_lshlrev_b32_e32 v38, 16, v62
	v_pk_mul_f32 v[94:95], v[8:9], v[38:39]
	v_add_f32_e32 v8, 1.0, v10
	v_rcp_f32_e32 v38, v8
	v_add_f32_e32 v8, 1.0, v11
	v_add_f32_e32 v14, v56, v14
	v_rcp_f32_e32 v39, v8
	v_add_f32_e32 v12, 1.0, v12
	v_add_f32_e32 v13, 1.0, v13
	v_mul_f32_e32 v14, 0xbfb8aa3b, v14
	v_add_f32_e32 v15, v57, v15
	v_rcp_f32_e32 v12, v12
	v_rcp_f32_e32 v13, v13
	v_exp_f32_e32 v14, v14
	v_mul_f32_e32 v15, 0xbfb8aa3b, v15
	s_waitcnt vmcnt(5)
	v_add_f32_e32 v22, v44, v22
	v_add_f32_e32 v23, v45, v23
	v_exp_f32_e32 v15, v15
	v_mul_f32_e32 v22, 0xbfb8aa3b, v22
	v_mul_f32_e32 v23, 0xbfb8aa3b, v23
	v_and_b32_e32 v41, 0xffff0000, v63
	v_lshlrev_b32_e32 v40, 16, v63
	v_exp_f32_e32 v22, v22
	v_exp_f32_e32 v23, v23
	v_pk_mul_f32 v[62:63], v[38:39], v[40:41]
	v_and_b32_e32 v39, 0xffff0000, v64
	v_lshlrev_b32_e32 v38, 16, v64
	v_pk_mul_f32 v[96:97], v[12:13], v[38:39]
	v_add_f32_e32 v12, 1.0, v14
	v_rcp_f32_e32 v38, v12
	v_add_f32_e32 v12, 1.0, v15
	v_add_f32_e32 v24, v42, v24
	v_rcp_f32_e32 v39, v12
	v_add_f32_e32 v22, 1.0, v22
	v_add_f32_e32 v23, 1.0, v23
	v_mul_f32_e32 v24, 0xbfb8aa3b, v24
	v_add_f32_e32 v25, v43, v25
	v_rcp_f32_e32 v22, v22
	v_rcp_f32_e32 v23, v23
	v_exp_f32_e32 v24, v24
	v_mul_f32_e32 v25, 0xbfb8aa3b, v25
	s_waitcnt vmcnt(4)
	v_add_f32_e32 v26, v48, v26
	v_add_f32_e32 v27, v49, v27
	v_exp_f32_e32 v25, v25
	v_mul_f32_e32 v26, 0xbfb8aa3b, v26
	v_mul_f32_e32 v27, 0xbfb8aa3b, v27
	v_and_b32_e32 v41, 0xffff0000, v65
	v_lshlrev_b32_e32 v40, 16, v65
	v_exp_f32_e32 v26, v26
	v_exp_f32_e32 v27, v27
	v_pk_mul_f32 v[64:65], v[38:39], v[40:41]
	s_waitcnt vmcnt(2)
	v_and_b32_e32 v39, 0xffff0000, v70
	v_lshlrev_b32_e32 v38, 16, v70
	v_pk_mul_f32 v[98:99], v[22:23], v[38:39]
	v_add_f32_e32 v22, 1.0, v24
	v_rcp_f32_e32 v38, v22
	v_add_f32_e32 v22, 1.0, v25
	v_add_f32_e32 v28, v46, v28
	v_rcp_f32_e32 v39, v22
	v_add_f32_e32 v26, 1.0, v26
	v_add_f32_e32 v27, 1.0, v27
	v_mul_f32_e32 v28, 0xbfb8aa3b, v28
	v_add_f32_e32 v29, v47, v29
	v_rcp_f32_e32 v26, v26
	v_rcp_f32_e32 v27, v27
	v_exp_f32_e32 v28, v28
	v_mul_f32_e32 v29, 0xbfb8aa3b, v29
	v_add_f32_e32 v30, v60, v30
	v_add_f32_e32 v31, v61, v31
	v_exp_f32_e32 v29, v29
	v_mul_f32_e32 v30, 0xbfb8aa3b, v30
	v_mul_f32_e32 v31, 0xbfb8aa3b, v31
	v_add_f32_e32 v16, v16, v32
	v_add_f32_e32 v17, v17, v33
	v_and_b32_e32 v41, 0xffff0000, v71
	v_lshlrev_b32_e32 v40, 16, v71
	v_exp_f32_e32 v30, v30
	v_exp_f32_e32 v31, v31
	v_mul_f32_e32 v16, 0xbfb8aa3b, v16
	v_mul_f32_e32 v17, 0xbfb8aa3b, v17
	v_pk_mul_f32 v[70:71], v[38:39], v[40:41]
	s_waitcnt vmcnt(1)
	v_and_b32_e32 v39, 0xffff0000, v112
	v_lshlrev_b32_e32 v38, 16, v112
	v_exp_f32_e32 v16, v16
	v_exp_f32_e32 v17, v17
	v_pk_mul_f32 v[100:101], v[26:27], v[38:39]
	v_add_f32_e32 v26, 1.0, v28
	v_rcp_f32_e32 v38, v26
	v_add_f32_e32 v26, 1.0, v29
	v_rcp_f32_e32 v39, v26
	v_add_f32_e32 v30, 1.0, v30
	v_add_f32_e32 v31, 1.0, v31
	v_rcp_f32_e32 v30, v30
	v_rcp_f32_e32 v31, v31
	v_add_f32_e32 v16, 1.0, v16
	v_add_f32_e32 v17, 1.0, v17
	v_rcp_f32_e32 v16, v16
	v_rcp_f32_e32 v17, v17
	v_and_b32_e32 v41, 0xffff0000, v113
	v_lshlrev_b32_e32 v40, 16, v113
	v_pk_mul_f32 v[102:103], v[38:39], v[40:41]
	s_waitcnt vmcnt(0)
	v_and_b32_e32 v39, 0xffff0000, v124
	v_lshlrev_b32_e32 v38, 16, v124
	v_pk_mul_f32 v[104:105], v[30:31], v[38:39]
	v_and_b32_e32 v31, 0xffff0000, v125
	v_lshlrev_b32_e32 v30, 16, v125
	v_pk_mul_f32 v[16:17], v[16:17], v[30:31]
	global_load_dwordx4 v[30:33], v116, s[6:7]
	v_mov_b32_e32 v40, v69
	v_mov_b32_e32 v41, v73
	v_mov_b32_e32 v38, v68
	v_mov_b32_e32 v39, v72
	v_pk_mul_f32 v[40:41], v[40:41], v[40:41]
	v_mul_f32_e32 v42, v63, v63
	v_pk_fma_f32 v[38:39], v[38:39], v[38:39], v[40:41]
	v_mov_b32_e32 v48, v99
	v_pk_add_f32 v[54:55], v[38:39], v[38:39] op_sel:[0,1] op_sel_hi:[1,0]
	v_mul_f32_e32 v38, v95, v95
	v_pk_fma_f32 v[56:57], v[94:95], v[94:95], v[38:39] op_sel_hi:[1,1,0]
	global_load_dwordx4 v[38:41], v118, s[6:7]
	v_mov_b32_e32 v49, v71
	v_pk_fma_f32 v[58:59], v[62:63], v[62:63], v[42:43] op_sel_hi:[1,1,0]
	v_mov_b32_e32 v46, v98
	v_mov_b32_e32 v47, v70
	global_load_dwordx4 v[42:45], v117, s[6:7]
	v_pk_mul_f32 v[48:49], v[48:49], v[48:49]
	global_load_dwordx4 v[8:11], v122, s[6:7]
	global_load_dwordx4 v[12:15], v121, s[6:7]
	v_pk_fma_f32 v[46:47], v[46:47], v[46:47], v[48:49]
	global_load_dwordx4 v[22:25], v120, s[6:7]
	global_load_dwordx4 v[26:29], v119, s[6:7]
	v_pk_add_f32 v[108:109], v[46:47], v[46:47] op_sel:[0,1] op_sel_hi:[1,0]
	v_mul_f32_e32 v46, v101, v101
	v_pk_fma_f32 v[110:111], v[100:101], v[100:101], v[46:47] op_sel_hi:[1,1,0]
	v_mul_f32_e32 v46, v103, v103
	v_pk_fma_f32 v[112:113], v[102:103], v[102:103], v[46:47] op_sel_hi:[1,1,0]
	global_load_dwordx4 v[46:49], v115, s[6:7]
	v_mov_b32_e32 v128, v5
	v_mov_b32_e32 v129, v67
	v_mov_b32_e32 v124, v3
	v_mov_b32_e32 v125, v7
	v_mov_b32_e32 v126, v4
	v_mov_b32_e32 v127, v66
	v_pk_mul_f32 v[128:129], v[128:129], v[128:129]
	v_pk_mul_f32 v[124:125], v[124:125], v[124:125]
	v_pk_fma_f32 v[126:127], v[126:127], v[126:127], v[128:129]
	v_mov_b32_e32 v128, v2
	v_mov_b32_e32 v129, v6
	v_pk_fma_f32 v[124:125], v[128:129], v[128:129], v[124:125]
	v_pk_mul_f32 v[60:61], v[96:97], v[96:97]
	v_pk_add_f32 v[124:125], v[124:125], v[126:127]
	v_pk_mul_f32 v[106:107], v[64:65], v[64:65]
	v_pk_add_f32 v[124:125], v[124:125], v[124:125] op_sel:[0,1] op_sel_hi:[1,0]
	v_mov_b32_e32 v57, v106
	v_mov_b32_e32 v59, v107
	v_mov_b32_e32 v125, v60
	v_mov_b32_e32 v55, v61
	v_pk_add_f32 v[56:57], v[56:57], v[58:59]
	v_pk_add_f32 v[54:55], v[124:125], v[54:55]
	v_pk_mul_f32 v[120:121], v[104:105], v[104:105]
	v_pk_add_f32 v[54:55], v[54:55], v[56:57]
	v_pk_mul_f32 v[122:123], v[16:17], v[16:17]
	v_pk_add_f32 v[54:55], v[54:55], v[54:55] op_sel:[0,1] op_sel_hi:[1,0]
	v_mov_b32_e32 v111, v122
	v_mov_b32_e32 v113, v123
	v_mov_b32_e32 v55, v120
	v_mov_b32_e32 v109, v121
	v_pk_add_f32 v[56:57], v[110:111], v[112:113]
	v_pk_add_f32 v[54:55], v[54:55], v[108:109]
	v_mov_b32_e32 v107, 0x358637bd
	v_pk_add_f32 v[54:55], v[54:55], v[56:57]
	v_mov_b32_e32 v108, 0x3a000000
	v_add_f32_e32 v54, v54, v55
	v_mov_b32_e32 v55, 0
	v_cvt_f32_f16_e32 v58, v92
	v_add_f32_dpp v54, v54, v54 quad_perm:[1,0,3,2] row_mask:0xf bank_mask:0xf bound_ctrl:1
	v_cvt_f32_f16_sdwa v59, v92 dst_sel:DWORD dst_unused:UNUSED_PAD src0_sel:WORD_1
	v_cvt_f32_f16_e32 v60, v93
	v_add_f32_dpp v54, v54, v54 quad_perm:[2,3,0,1] row_mask:0xf bank_mask:0xf bound_ctrl:1
	v_cvt_f32_f16_sdwa v61, v93 dst_sel:DWORD dst_unused:UNUSED_PAD src0_sel:WORD_1
	s_waitcnt vmcnt(4)
	v_pk_mul_f32 v[10:11], v[64:65], v[10:11]
	v_add_f32_dpp v54, v54, v54 row_half_mirror row_mask:0xf bank_mask:0xf bound_ctrl:1
	v_pk_mul_f32 v[8:9], v[96:97], v[8:9]
	s_waitcnt vmcnt(3)
	v_pk_mul_f32 v[14:15], v[70:71], v[14:15]
	v_add_f32_dpp v54, v54, v54 row_mirror row_mask:0xf bank_mask:0xf bound_ctrl:1
	v_pk_mul_f32 v[12:13], v[98:99], v[12:13]
	s_waitcnt vmcnt(2)
	v_pk_mul_f32 v[22:23], v[22:23], v[100:101]
	v_mov_b32_dpp v55, v54 row_bcast:15 row_mask:0xa bank_mask:0xf
	v_add_f32_e32 v54, v54, v55
	v_mov_b32_e32 v55, 0
	v_pk_mul_f32 v[24:25], v[24:25], v[102:103]
	s_waitcnt vmcnt(1)
	v_pk_mul_f32 v[16:17], v[28:29], v[16:17]
	v_mov_b32_dpp v55, v54 row_bcast:31 row_mask:0xc bank_mask:0xf
	v_add_f32_e32 v54, v54, v55
	s_nop 0
	v_readlane_b32 s10, v54, 63
	s_nop 1
	v_fma_f32 v54, s10, v108, v107
	v_rsq_f32_e32 v106, v54
	global_load_dwordx4 v[54:57], v116, s[8:9]
	v_pk_mul_f32 v[2:3], v[2:3], v[30:31]
	v_pk_mul_f32 v[4:5], v[4:5], v[32:33]
	v_pk_fma_f32 v[92:93], v[2:3], v[106:107], v[58:59] op_sel_hi:[1,0,1]
	v_cvt_f32_f16_e32 v58, v91
	v_cvt_f32_f16_sdwa v59, v91 dst_sel:DWORD dst_unused:UNUSED_PAD src0_sel:WORD_1
	v_pk_fma_f32 v[30:31], v[4:5], v[106:107], v[60:61] op_sel_hi:[1,0,1]
	v_cvt_f32_f16_e32 v32, v90
	v_cvt_f32_f16_sdwa v33, v90 dst_sel:DWORD dst_unused:UNUSED_PAD src0_sel:WORD_1
	global_load_dwordx4 v[2:5], v118, s[8:9]
	v_pk_mul_f32 v[40:41], v[66:67], v[40:41]
	v_pk_mul_f32 v[6:7], v[6:7], v[38:39]
	v_pk_fma_f32 v[38:39], v[40:41], v[106:107], v[58:59] op_sel_hi:[1,0,1]
	v_cvt_f32_f16_e32 v40, v89
	v_cvt_f32_f16_sdwa v41, v89 dst_sel:DWORD dst_unused:UNUSED_PAD src0_sel:WORD_1
	v_pk_fma_f32 v[6:7], v[6:7], v[106:107], v[32:33] op_sel_hi:[1,0,1]
	v_cvt_f32_f16_e32 v32, v88
	v_cvt_f32_f16_sdwa v33, v88 dst_sel:DWORD dst_unused:UNUSED_PAD src0_sel:WORD_1
	global_load_dwordx4 v[58:61], v117, s[8:9]
	v_pk_mul_f32 v[44:45], v[72:73], v[44:45]
	v_pk_mul_f32 v[42:43], v[68:69], v[42:43]
	v_pk_fma_f32 v[66:67], v[44:45], v[106:107], v[40:41] op_sel_hi:[1,0,1]
	v_cvt_f32_f16_e32 v40, v87
	v_cvt_f32_f16_sdwa v41, v87 dst_sel:DWORD dst_unused:UNUSED_PAD src0_sel:WORD_1
	v_pk_fma_f32 v[68:69], v[42:43], v[106:107], v[32:33] op_sel_hi:[1,0,1]
	v_cvt_f32_f16_e32 v32, v86
	v_cvt_f32_f16_sdwa v33, v86 dst_sel:DWORD dst_unused:UNUSED_PAD src0_sel:WORD_1
	global_load_dwordx4 v[42:45], v115, s[8:9]
	s_waitcnt vmcnt(4)
	v_pk_mul_f32 v[48:49], v[62:63], v[48:49]
	v_pk_mul_f32 v[46:47], v[94:95], v[46:47]
	v_pk_fma_f32 v[48:49], v[48:49], v[106:107], v[40:41] op_sel_hi:[1,0,1]
	v_cvt_f32_f16_e32 v40, v85
	v_cvt_f32_f16_sdwa v41, v85 dst_sel:DWORD dst_unused:UNUSED_PAD src0_sel:WORD_1
	v_pk_fma_f32 v[46:47], v[46:47], v[106:107], v[32:33] op_sel_hi:[1,0,1]
	v_cvt_f32_f16_e32 v32, v84
	v_cvt_f32_f16_sdwa v33, v84 dst_sel:DWORD dst_unused:UNUSED_PAD src0_sel:WORD_1
	v_pk_fma_f32 v[10:11], v[10:11], v[106:107], v[40:41] op_sel_hi:[1,0,1]
	v_cvt_f32_f16_e32 v40, v83
	v_cvt_f32_f16_sdwa v41, v83 dst_sel:DWORD dst_unused:UNUSED_PAD src0_sel:WORD_1
	v_pk_fma_f32 v[8:9], v[8:9], v[106:107], v[32:33] op_sel_hi:[1,0,1]
	v_cvt_f32_f16_e32 v32, v82
	v_cvt_f32_f16_sdwa v33, v82 dst_sel:DWORD dst_unused:UNUSED_PAD src0_sel:WORD_1
	v_pk_fma_f32 v[62:63], v[14:15], v[106:107], v[40:41] op_sel_hi:[1,0,1]
	v_cvt_f32_f16_e32 v14, v80
	v_cvt_f32_f16_sdwa v15, v80 dst_sel:DWORD dst_unused:UNUSED_PAD src0_sel:WORD_1
	v_pk_fma_f32 v[12:13], v[12:13], v[106:107], v[32:33] op_sel_hi:[1,0,1]
	v_cvt_f32_f16_e32 v32, v81
	v_cvt_f32_f16_sdwa v33, v81 dst_sel:DWORD dst_unused:UNUSED_PAD src0_sel:WORD_1
	v_pk_fma_f32 v[70:71], v[22:23], v[106:107], v[14:15] op_sel_hi:[1,0,1]
	v_cvt_f32_f16_e32 v14, v78
	v_cvt_f32_f16_sdwa v15, v78 dst_sel:DWORD dst_unused:UNUSED_PAD src0_sel:WORD_1
	v_cvt_f32_f16_e32 v22, v79
	v_cvt_f32_f16_sdwa v23, v79 dst_sel:DWORD dst_unused:UNUSED_PAD src0_sel:WORD_1
	v_pk_fma_f32 v[64:65], v[24:25], v[106:107], v[32:33] op_sel_hi:[1,0,1]
	v_pk_mul_f32 v[24:25], v[26:27], v[104:105]
	v_cvt_f16_f32_e32 v28, v92
	v_cvt_f16_f32_sdwa v29, v93 dst_sel:WORD_1 dst_unused:UNUSED_PAD src0_sel:DWORD
	v_pk_fma_f32 v[72:73], v[16:17], v[106:107], v[22:23] op_sel_hi:[1,0,1]
	v_pk_fma_f32 v[78:79], v[24:25], v[106:107], v[14:15] op_sel_hi:[1,0,1]
	v_cvt_f16_f32_e32 v15, v30
	v_cvt_f16_f32_sdwa v16, v31 dst_sel:WORD_1 dst_unused:UNUSED_PAD src0_sel:DWORD
	v_cvt_f16_f32_e32 v17, v6
	v_cvt_f16_f32_sdwa v22, v7 dst_sel:WORD_1 dst_unused:UNUSED_PAD src0_sel:DWORD
	v_cvt_f16_f32_e32 v23, v38
	v_cvt_f16_f32_sdwa v24, v39 dst_sel:WORD_1 dst_unused:UNUSED_PAD src0_sel:DWORD
	v_or_b32_e32 v14, v29, v28
	v_or_b32_e32 v15, v16, v15
	global_store_dwordx2 v114, v[14:15], s[0:1] sc1
	v_or_b32_e32 v14, v22, v17
	v_or_b32_e32 v15, v24, v23
	global_store_dwordx2 v114, v[14:15], s[0:1] offset:512 sc1
	v_cvt_f16_f32_e32 v14, v68
	v_cvt_f16_f32_sdwa v15, v69 dst_sel:WORD_1 dst_unused:UNUSED_PAD src0_sel:DWORD
	v_cvt_f16_f32_e32 v16, v66
	v_cvt_f16_f32_sdwa v17, v67 dst_sel:WORD_1 dst_unused:UNUSED_PAD src0_sel:DWORD
	v_cvt_f16_f32_e32 v22, v46
	v_cvt_f16_f32_sdwa v23, v47 dst_sel:WORD_1 dst_unused:UNUSED_PAD src0_sel:DWORD
	v_or_b32_e32 v14, v15, v14
	v_or_b32_e32 v15, v17, v16
	global_store_dwordx2 v114, v[14:15], s[0:1] offset:1024 sc1
	v_cvt_f16_f32_e32 v15, v48
	v_cvt_f16_f32_sdwa v16, v49 dst_sel:WORD_1 dst_unused:UNUSED_PAD src0_sel:DWORD
	v_or_b32_e32 v14, v23, v22
	v_cvt_f16_f32_e32 v17, v8
	v_cvt_f16_f32_sdwa v22, v9 dst_sel:WORD_1 dst_unused:UNUSED_PAD src0_sel:DWORD
	v_cvt_f16_f32_e32 v23, v10
	v_cvt_f16_f32_sdwa v24, v11 dst_sel:WORD_1 dst_unused:UNUSED_PAD src0_sel:DWORD
	v_or_b32_e32 v15, v16, v15
	global_store_dwordx2 v114, v[14:15], s[0:1] offset:1536 sc1
	v_or_b32_e32 v14, v22, v17
	v_or_b32_e32 v15, v24, v23
	global_store_dwordx2 v114, v[14:15], s[0:1] offset:2048 sc1
	v_cvt_f16_f32_e32 v14, v12
	v_cvt_f16_f32_sdwa v15, v13 dst_sel:WORD_1 dst_unused:UNUSED_PAD src0_sel:DWORD
	v_cvt_f16_f32_e32 v16, v62
	v_cvt_f16_f32_sdwa v17, v63 dst_sel:WORD_1 dst_unused:UNUSED_PAD src0_sel:DWORD
	v_cvt_f16_f32_e32 v22, v70
	v_cvt_f16_f32_sdwa v23, v71 dst_sel:WORD_1 dst_unused:UNUSED_PAD src0_sel:DWORD
	v_or_b32_e32 v14, v15, v14
	v_or_b32_e32 v15, v17, v16
	global_store_dwordx2 v114, v[14:15], s[0:1] offset:2560 sc1
	v_cvt_f16_f32_e32 v15, v64
	v_cvt_f16_f32_sdwa v16, v65 dst_sel:WORD_1 dst_unused:UNUSED_PAD src0_sel:DWORD
	v_or_b32_e32 v14, v23, v22
	v_cvt_f16_f32_e32 v17, v78
	v_cvt_f16_f32_sdwa v22, v79 dst_sel:WORD_1 dst_unused:UNUSED_PAD src0_sel:DWORD
	v_cvt_f16_f32_e32 v23, v72
	v_cvt_f16_f32_sdwa v24, v73 dst_sel:WORD_1 dst_unused:UNUSED_PAD src0_sel:DWORD
	v_or_b32_e32 v15, v16, v15
	global_store_dwordx2 v114, v[14:15], s[0:1] offset:3072 sc1
	v_or_b32_e32 v14, v22, v17
	v_or_b32_e32 v15, v24, v23
	v_mov_b32_e32 v16, v93
	v_mov_b32_e32 v17, v7
	global_store_dwordx2 v114, v[14:15], s[0:1] offset:3584 sc1
	v_mov_b32_e32 v14, v92
	v_mov_b32_e32 v15, v6
	v_pk_mul_f32 v[16:17], v[16:17], v[16:17]
	v_mov_b32_e32 v22, v31
	v_mov_b32_e32 v23, v39
	v_pk_fma_f32 v[14:15], v[14:15], v[14:15], v[16:17]
	v_mov_b32_e32 v16, v30
	v_mov_b32_e32 v17, v38
	v_pk_mul_f32 v[22:23], v[22:23], v[22:23]
	s_waitcnt vmcnt(10)
	v_pk_mul_f32 v[4:5], v[4:5], v[38:39]
	v_pk_fma_f32 v[16:17], v[16:17], v[16:17], v[22:23]
	v_pk_mul_f32 v[22:23], v[68:69], v[68:69]
	v_pk_add_f32 v[14:15], v[14:15], v[16:17]
	v_pk_mul_f32 v[16:17], v[66:67], v[66:67]
	v_pk_add_f32 v[14:15], v[14:15], v[14:15] op_sel_hi:[0,1]
	v_pk_mov_b32 v[24:25], v[22:23], v[16:17] op_sel:[1,0]
	v_mov_b32_e32 v23, v17
	v_mul_f32_e32 v14, v46, v46
	v_pk_add_f32 v[16:17], v[24:25], v[22:23]
	v_pk_fma_f32 v[22:23], v[46:47], v[46:47], v[14:15] op_sel_hi:[1,1,0]
	v_mul_f32_e32 v14, v48, v48
	v_pk_add_f32 v[16:17], v[16:17], v[16:17] op_sel_hi:[0,1]
	v_pk_fma_f32 v[24:25], v[48:49], v[48:49], v[14:15] op_sel_hi:[1,1,0]
	v_mul_f32_e32 v22, v8, v8
	v_mul_f32_e32 v24, v9, v9
	v_mul_f32_e32 v16, v10, v10
	v_mul_f32_e32 v14, v11, v11
	v_pk_add_f32 v[22:23], v[22:23], v[24:25]
	v_pk_add_f32 v[14:15], v[16:17], v[14:15]
	v_pk_mul_f32 v[16:17], v[62:63], v[62:63]
	v_pk_add_f32 v[14:15], v[22:23], v[14:15]
	v_pk_mul_f32 v[22:23], v[12:13], v[12:13]
	v_pk_add_f32 v[14:15], v[14:15], v[14:15] op_sel_hi:[0,1]
	v_pk_mov_b32 v[24:25], v[22:23], v[16:17] op_sel:[1,0]
	v_mov_b32_e32 v23, v17
	v_mul_f32_e32 v14, v70, v70
	v_pk_add_f32 v[16:17], v[24:25], v[22:23]
	v_pk_fma_f32 v[22:23], v[70:71], v[70:71], v[14:15] op_sel_hi:[1,1,0]
	v_mul_f32_e32 v14, v64, v64
	v_pk_add_f32 v[16:17], v[16:17], v[16:17] op_sel_hi:[0,1]
	v_pk_fma_f32 v[24:25], v[64:65], v[64:65], v[14:15] op_sel_hi:[1,1,0]
	v_mul_f32_e32 v22, v78, v78
	v_mul_f32_e32 v24, v79, v79
	v_mul_f32_e32 v16, v72, v72
	v_mul_f32_e32 v14, v73, v73
	v_pk_add_f32 v[22:23], v[22:23], v[24:25]
	v_pk_add_f32 v[14:15], v[16:17], v[14:15]
	v_pk_mul_f32 v[2:3], v[2:3], v[6:7]
	v_pk_add_f32 v[14:15], v[22:23], v[14:15]
	s_nop 0
	v_add_f32_e32 v14, v14, v15
	v_mov_b32_e32 v15, 0
	s_nop 0
	v_add_f32_dpp v14, v14, v14 quad_perm:[1,0,3,2] row_mask:0xf bank_mask:0xf bound_ctrl:1
	s_nop 1
	v_add_f32_dpp v14, v14, v14 quad_perm:[2,3,0,1] row_mask:0xf bank_mask:0xf bound_ctrl:1
	s_nop 1
	v_add_f32_dpp v14, v14, v14 row_half_mirror row_mask:0xf bank_mask:0xf bound_ctrl:1
	s_nop 1
	v_add_f32_dpp v14, v14, v14 row_mirror row_mask:0xf bank_mask:0xf bound_ctrl:1
	s_nop 1
	v_mov_b32_dpp v15, v14 row_bcast:15 row_mask:0xa bank_mask:0xf
	v_add_f32_e32 v14, v14, v15
	v_mov_b32_e32 v15, 0
	s_nop 1
	v_mov_b32_dpp v15, v14 row_bcast:31 row_mask:0xc bank_mask:0xf
	v_add_f32_e32 v14, v14, v15
	s_nop 0
	v_readlane_b32 s0, v14, 63
	s_nop 1
	v_fmac_f32_e32 v107, s0, v108
	v_rsq_f32_e32 v80, v107
	s_nop 0
	v_pk_mul_f32 v[28:29], v[4:5], v[80:81] op_sel_hi:[1,0]
	v_pk_mul_f32 v[4:5], v[56:57], v[30:31]
	v_pk_mul_f32 v[32:33], v[2:3], v[80:81] op_sel_hi:[1,0]
	v_pk_mul_f32 v[2:3], v[54:55], v[92:93]
	v_pk_mul_f32 v[38:39], v[4:5], v[80:81] op_sel_hi:[1,0]
	v_pk_mul_f32 v[40:41], v[2:3], v[80:81] op_sel_hi:[1,0]
	v_max_f32_e64 v2, |v38|, |v39|
	v_max_f32_e64 v3, |v28|, |v29|
	v_max3_f32 v2, |v40|, |v41|, v2
	v_max3_f32 v3, |v32|, |v33|, v3
	s_waitcnt vmcnt(9)
	v_pk_mul_f32 v[4:5], v[60:61], v[66:67]
	v_max3_f32 v6, v2, 0, v3
	v_pk_mul_f32 v[2:3], v[58:59], v[68:69]
	v_pk_mul_f32 v[26:27], v[4:5], v[80:81] op_sel_hi:[1,0]
	v_pk_mul_f32 v[30:31], v[2:3], v[80:81] op_sel_hi:[1,0]
	v_max_f32_e64 v2, |v26|, |v27|
	s_waitcnt vmcnt(8)
	v_pk_mul_f32 v[4:5], v[44:45], v[48:49]
	v_max3_f32 v7, |v30|, |v31|, v2
	v_pk_mul_f32 v[2:3], v[42:43], v[46:47]
	v_pk_mul_f32 v[22:23], v[4:5], v[80:81] op_sel_hi:[1,0]
	v_pk_mul_f32 v[24:25], v[2:3], v[80:81] op_sel_hi:[1,0]
	v_max_f32_e64 v2, |v22|, |v23|
	v_max3_f32 v2, |v24|, |v25|, v2
	v_pk_mul_f32 v[4:5], v[76:77], v[10:11]
	v_max3_f32 v6, v6, v7, v2
	v_pk_mul_f32 v[2:3], v[74:75], v[8:9]
	v_pk_mul_f32 v[14:15], v[4:5], v[80:81] op_sel_hi:[1,0]
	v_pk_mul_f32 v[16:17], v[2:3], v[80:81] op_sel_hi:[1,0]
	v_max_f32_e64 v2, |v14|, |v15|
	v_pk_mul_f32 v[4:5], v[52:53], v[62:63]
	v_max3_f32 v7, |v16|, |v17|, v2
	v_pk_mul_f32 v[2:3], v[50:51], v[12:13]
	v_pk_mul_f32 v[10:11], v[4:5], v[80:81] op_sel_hi:[1,0]
	v_pk_mul_f32 v[12:13], v[2:3], v[80:81] op_sel_hi:[1,0]
	v_max_f32_e64 v2, |v10|, |v11|
	v_max3_f32 v2, |v12|, |v13|, v2
	v_pk_mul_f32 v[4:5], v[64:65], v[36:37]
	v_max3_f32 v42, v6, v7, v2
	v_pk_mul_f32 v[2:3], v[70:71], v[34:35]
	v_pk_mul_f32 v[6:7], v[4:5], v[80:81] op_sel_hi:[1,0]
	v_pk_mul_f32 v[8:9], v[2:3], v[80:81] op_sel_hi:[1,0]
	v_max_f32_e64 v2, |v6|, |v7|
	v_max3_f32 v34, |v8|, |v9|, v2
	v_pk_mul_f32 v[2:3], v[72:73], v[20:21]
	v_pk_mul_f32 v[4:5], v[78:79], v[18:19]
	v_pk_mul_f32 v[2:3], v[2:3], v[80:81] op_sel_hi:[1,0]
	v_pk_mul_f32 v[4:5], v[4:5], v[80:81] op_sel_hi:[1,0]
	v_max_f32_e64 v18, |v2|, |v3|
	v_max3_f32 v18, |v4|, |v5|, v18
	v_max3_f32 v18, v42, v34, v18
	v_mov_b32_e32 v19, 0
	s_nop 1
	v_mov_b32_dpp v19, v18 quad_perm:[1,0,3,2] row_mask:0xf bank_mask:0xf
	v_max_f32_e32 v19, v19, v19
	v_max_f32_e32 v18, v18, v19
	v_mov_b32_e32 v19, 0
	s_nop 1
	v_mov_b32_dpp v19, v18 quad_perm:[2,3,0,1] row_mask:0xf bank_mask:0xf
	v_max_f32_e32 v19, v19, v19
	v_max_f32_e32 v18, v18, v19
	v_mov_b32_e32 v19, 0
	s_nop 1
	v_mov_b32_dpp v19, v18 row_half_mirror row_mask:0xf bank_mask:0xf
	v_max_f32_e32 v19, v19, v19
	v_max_f32_e32 v18, v18, v19
	v_mov_b32_e32 v19, 0
	s_nop 1
	v_mov_b32_dpp v19, v18 row_mirror row_mask:0xf bank_mask:0xf
	v_max_f32_e32 v19, v19, v19
	v_max_f32_e32 v18, v18, v19
	v_mov_b32_e32 v19, 0
	s_nop 1
	v_mov_b32_dpp v19, v18 row_bcast:15 row_mask:0xa bank_mask:0xf
	v_max_f32_e32 v19, v19, v19
	v_max_f32_e32 v18, v18, v19
	v_mov_b32_e32 v19, 0
	s_nop 1
	v_mov_b32_dpp v19, v18 row_bcast:31 row_mask:0xc bank_mask:0xf
	v_max_f32_e32 v19, v19, v19
	v_max_f32_e32 v18, v18, v19
	s_nop 0
	v_readlane_b32 s12, v18, 63
	s_nop 1
	v_cmp_gt_f32_e64 s[0:1], s12, 0
	s_and_saveexec_b64 s[10:11], vcc
	s_cbranch_execz .LBB0_2382
	s_lshl_b64 s[14:15], s[4:5], 2
	v_mov_b32_e32 v18, 0x3c010204
	s_add_u32 s14, s86, s14
	v_mul_f32_e32 v18, s12, v18
	s_addc_u32 s15, s87, s15
	v_cndmask_b32_e64 v18, 1.0, v18, s[0:1]
	global_store_dword v1, v18, s[14:15]

.LBB0_2384:
	s_cbranch_execz .LBB0_2395
	s_ashr_i32 s1, s90, 5
	s_abs_i32 s0, s1
	v_cvt_f32_u32_e32 v1, s0
	s_sub_i32 s10, 0, s0
	s_abs_i32 s4, s62
	s_xor_b32 s5, s62, s1
	v_rcp_iflag_f32_e32 v1, v1
	s_ashr_i32 s5, s5, 31
	v_mul_f32_e32 v1, 0x4f7ffffe, v1
	v_cvt_u32_f32_e32 v1, v1
	s_nop 0
	v_readfirstlane_b32 s11, v1
	s_mul_i32 s10, s10, s11
	s_mul_hi_u32 s10, s11, s10
	s_add_i32 s11, s11, s10
	s_mul_hi_u32 s10, s4, s11
	s_mul_i32 s11, s10, s0
	s_sub_i32 s4, s4, s11
	s_add_i32 s12, s10, 1
	s_sub_i32 s11, s4, s0
	s_cmp_ge_u32 s4, s0
	s_cselect_b32 s10, s12, s10
	s_cselect_b32 s4, s11, s4
	s_add_i32 s11, s10, 1
	s_cmp_ge_u32 s4, s0
	s_cselect_b32 s0, s11, s10
	s_xor_b32 s0, s0, s5
	s_sub_i32 s0, s0, s5
	s_mul_i32 s1, s0, s1
	s_sub_i32 s1, s62, s1
	s_cmp_lg_u32 s1, 0
	s_cbranch_scc1 .LBB0_2395
	s_ashr_i32 s1, s0, 31
	s_lshl_b64 s[4:5], s[0:1], 13
	v_readlane_b32 s10, v254, 58
	v_readlane_b32 s11, v254, 59
	s_add_u32 s4, s10, s4
	s_addc_u32 s5, s11, s5
	v_mov_b32_e32 v11, 0
	v_lshlrev_b32_e32 v10, 4, v0
	v_lshl_add_u64 v[2:3], s[4:5], 0, v[10:11]
	v_add_co_u32_e32 v4, vcc, 0x40000, v2
	s_waitcnt vmcnt(0)
	v_mov_b32_e32 v16, v190
	v_mov_b32_e32 v17, v191
	v_mov_b32_e32 v18, v192
	v_mov_b32_e32 v19, v193
	s_nop 0
	v_addc_co_u32_e32 v5, vcc, 0, v3, vcc
	v_add_co_u32_e32 v6, vcc, 0x80000, v2
	s_add_i32 s4, s0, 0x2000
	s_nop 0
	v_addc_co_u32_e32 v7, vcc, 0, v3, vcc
	v_add_co_u32_e32 v2, vcc, 0xc0000, v2
	s_ashr_i32 s5, s4, 31
	s_nop 0
	v_addc_co_u32_e32 v3, vcc, 0, v3, vcc
	v_mov_b32_e32 v20, v194
	v_mov_b32_e32 v21, v195
	v_mov_b32_e32 v22, v196
	v_mov_b32_e32 v23, v197
	v_mov_b32_e32 v24, v198
	v_mov_b32_e32 v25, v199
	v_mov_b32_e32 v26, v200
	v_mov_b32_e32 v27, v201
	v_mov_b32_e32 v28, v202
	v_mov_b32_e32 v29, v203
	v_mov_b32_e32 v30, v204
	v_mov_b32_e32 v31, v205
	s_lshl_b64 s[0:1], s[4:5], 12
	v_readlane_b32 s10, v254, 54
	v_readlane_b32 s11, v254, 55
	s_add_u32 s10, s10, s0
	s_addc_u32 s11, s11, s1
	s_add_u32 s0, s84, s0
	v_readlane_b32 s64, v254, 18
	v_lshlrev_b32_e32 v14, 3, v0
	s_addc_u32 s1, s85, s1
	v_readlane_b32 s66, v254, 20
	v_readlane_b32 s67, v254, 21
	v_mov_b32_e32 v36, v210
	v_mov_b32_e32 v37, v211
	s_nop 3
	v_mov_b32_e32 v32, v206
	v_mov_b32_e32 v33, v207
	v_mov_b32_e32 v34, v208
	v_mov_b32_e32 v35, v209
	v_mov_b32_e32 v6, v180
	v_mov_b32_e32 v7, v181
	v_mov_b32_e32 v8, v182
	v_mov_b32_e32 v9, v183
	v_mov_b32_e32 v2, v176
	v_mov_b32_e32 v3, v177
	v_mov_b32_e32 v4, v178
	v_mov_b32_e32 v5, v179
	v_mov_b32_e32 v12, v186
	v_mov_b32_e32 v13, v187
	v_mov_b32_e32 v1, v11
	v_mov_b32_e32 v10, v11
	v_mov_b32_e32 v15, v11
	v_lshl_add_u64 v[14:15], s[10:11], 0, v[14:15]
	v_cmp_eq_u32_e32 vcc, 0, v166
	v_readlane_b32 s65, v254, 19
	v_readlane_b32 s68, v254, 22
	v_readlane_b32 s69, v254, 23
	v_readlane_b32 s70, v254, 24
	v_readlane_b32 s71, v254, 25
	v_readlane_b32 s72, v254, 26
	v_readlane_b32 s73, v254, 27
	v_readlane_b32 s74, v254, 28
	v_readlane_b32 s75, v254, 29
	v_readlane_b32 s76, v254, 30
	v_readlane_b32 s77, v254, 31
	v_readlane_b32 s78, v254, 32
	v_readlane_b32 s79, v254, 33
	s_waitcnt vmcnt(7)
	v_pk_add_f32 v[18:19], v[18:19], v[22:23]
	v_pk_add_f32 v[16:17], v[16:17], v[20:21]
	s_waitcnt vmcnt(5)
	v_pk_add_f32 v[20:21], v[26:27], v[30:31]
	v_pk_add_f32 v[22:23], v[24:25], v[28:29]
	v_pk_add_f32 v[18:19], v[18:19], v[20:21]
	v_pk_add_f32 v[16:17], v[16:17], v[22:23]
	s_waitcnt vmcnt(3)
	v_add_f32_e32 v18, v18, v34
	v_add_f32_e32 v16, v16, v32
	v_add_f32_e32 v17, v17, v33
	v_add_f32_e32 v19, v19, v35
	v_mul_f32_e32 v16, 0xbfb8aa3b, v16
	v_mul_f32_e32 v17, 0xbfb8aa3b, v17
	v_mul_f32_e32 v18, 0xbfb8aa3b, v18
	v_mul_f32_e32 v19, 0xbfb8aa3b, v19
	v_exp_f32_e32 v16, v16
	v_exp_f32_e32 v17, v17
	v_exp_f32_e32 v18, v18
	v_exp_f32_e32 v19, v19
	v_add_f32_e32 v16, 1.0, v16
	v_add_f32_e32 v17, 1.0, v17
	v_add_f32_e32 v18, 1.0, v18
	v_add_f32_e32 v19, 1.0, v19
	v_rcp_f32_e32 v16, v16
	v_rcp_f32_e32 v17, v17
	v_rcp_f32_e32 v22, v18
	v_rcp_f32_e32 v23, v19
	v_and_b32_e32 v21, 0xffff0000, v36
	v_lshlrev_b32_e32 v20, 16, v36
	v_and_b32_e32 v25, 0xffff0000, v37
	v_lshlrev_b32_e32 v24, 16, v37
	v_pk_mul_f32 v[18:19], v[16:17], v[20:21]
	v_pk_mul_f32 v[16:17], v[22:23], v[24:25]
	v_pk_mul_f32 v[20:21], v[18:19], v[18:19]
	v_pk_mul_f32 v[22:23], v[16:17], v[16:17]
	v_add_f32_e32 v20, v20, v21
	v_add_f32_e32 v22, v22, v23
	v_add_f32_e32 v20, v20, v22
	s_nop 1
	v_add_f32_dpp v20, v20, v20 quad_perm:[1,0,3,2] row_mask:0xf bank_mask:0xf bound_ctrl:1
	s_nop 1
	v_add_f32_dpp v20, v20, v20 quad_perm:[2,3,0,1] row_mask:0xf bank_mask:0xf bound_ctrl:1
	s_nop 1
	v_add_f32_dpp v20, v20, v20 row_half_mirror row_mask:0xf bank_mask:0xf bound_ctrl:1
	s_nop 1
	v_add_f32_dpp v20, v20, v20 row_mirror row_mask:0xf bank_mask:0xf bound_ctrl:1
	s_nop 1
	v_mov_b32_dpp v1, v20 row_bcast:15 row_mask:0xa bank_mask:0xf
	v_add_f32_e32 v1, v20, v1
	s_nop 1
	v_mov_b32_dpp v10, v1 row_bcast:31 row_mask:0xc bank_mask:0xf
	v_add_f32_e32 v1, v1, v10
	s_nop 0
	v_readlane_b32 s6, v1, 63
	s_and_saveexec_b64 s[0:1], vcc
	s_lshl_b32 s7, s96, 2
	s_add_i32 s7, s7, 0
	v_mov_b32_e32 v1, s7
	v_mov_b32_e32 v10, s6
	ds_write_b32 v1, v10
	s_or_b64 exec, exec, s[0:1]
	s_waitcnt lgkmcnt(0)
	s_barrier
	ds_read_b128 v[20:23], v11
	ds_read_b128 v[24:27], v11 offset:16
	s_waitcnt lgkmcnt(1)
	v_add_f32_e32 v1, 0, v20
	v_add_f32_e32 v1, v1, v21
	v_add_f32_e32 v1, v1, v22
	v_add_f32_e32 v1, v1, v23
	s_waitcnt lgkmcnt(0)
	v_add_f32_e32 v1, v1, v24
	v_add_f32_e32 v1, v1, v25
	v_add_f32_e32 v1, v1, v26
	v_add_f32_e32 v10, v1, v27
	v_mov_b32_e32 v1, 0x358637bd
	v_fmamk_f32 v10, v10, 0x3a000000, v1
	v_rsq_f32_e32 v10, v10
	s_waitcnt vmcnt(0)
	v_cvt_f32_f16_sdwa v21, v12 dst_sel:DWORD dst_unused:UNUSED_PAD src0_sel:WORD_1
	v_cvt_f32_f16_sdwa v23, v13 dst_sel:DWORD dst_unused:UNUSED_PAD src0_sel:WORD_1
	v_cvt_f32_f16_e32 v22, v13
	v_cvt_f32_f16_e32 v20, v12
	v_pk_mul_f32 v[12:13], v[6:7], v[18:19]
	v_pk_mul_f32 v[6:7], v[8:9], v[16:17]
	v_pk_fma_f32 v[8:9], v[12:13], v[10:11], v[20:21] op_sel_hi:[1,0,1]
	v_pk_fma_f32 v[6:7], v[6:7], v[10:11], v[22:23] op_sel_hi:[1,0,1]
	v_cvt_f16_f32_e32 v10, v8
	v_cvt_f16_f32_sdwa v12, v9 dst_sel:WORD_1 dst_unused:UNUSED_PAD src0_sel:DWORD
	v_cvt_f16_f32_e32 v13, v6
	v_cvt_f16_f32_sdwa v16, v7 dst_sel:WORD_1 dst_unused:UNUSED_PAD src0_sel:DWORD
	v_or_b32_e32 v12, v12, v10
	v_mul_f32_e32 v10, v9, v9
	v_or_b32_e32 v13, v16, v13
	global_store_dwordx2 v[14:15], v[12:13], off sc1
	v_mul_f32_e32 v12, v7, v7
	v_fmac_f32_e32 v10, v8, v8
	v_fmac_f32_e32 v12, v6, v6
	v_add_f32_e32 v10, v10, v12
	v_mov_b32_e32 v12, 0
	s_nop 0
	v_add_f32_dpp v10, v10, v10 quad_perm:[1,0,3,2] row_mask:0xf bank_mask:0xf bound_ctrl:1
	s_nop 1
	v_add_f32_dpp v10, v10, v10 quad_perm:[2,3,0,1] row_mask:0xf bank_mask:0xf bound_ctrl:1
	s_nop 1
	v_add_f32_dpp v10, v10, v10 row_half_mirror row_mask:0xf bank_mask:0xf bound_ctrl:1
	s_nop 1
	v_add_f32_dpp v10, v10, v10 row_mirror row_mask:0xf bank_mask:0xf bound_ctrl:1
	s_nop 1
	v_mov_b32_dpp v12, v10 row_bcast:15 row_mask:0xa bank_mask:0xf
	v_add_f32_e32 v10, v10, v12
	s_nop 1
	v_mov_b32_dpp v11, v10 row_bcast:31 row_mask:0xc bank_mask:0xf
	v_add_f32_e32 v10, v10, v11
	s_nop 0
	v_readlane_b32 s6, v10, 63
	s_and_saveexec_b64 s[0:1], vcc
	s_lshl_b32 s7, s96, 2
	s_add_i32 s7, s7, 0
	v_mov_b32_e32 v10, s7
	v_mov_b32_e32 v11, s6
	ds_write_b32 v10, v11 offset:32
	s_or_b64 exec, exec, s[0:1]
	v_mov_b32_e32 v10, 0
	s_waitcnt lgkmcnt(0)
	s_barrier
	ds_read_b128 v[12:15], v10 offset:32
	ds_read_b128 v[16:19], v10 offset:48
	v_pk_mul_f32 v[4:5], v[4:5], v[6:7]
	v_pk_mul_f32 v[6:7], v[2:3], v[8:9]
	s_waitcnt lgkmcnt(1)
	v_add_f32_e32 v11, 0, v12
	v_add_f32_e32 v11, v11, v13
	v_add_f32_e32 v11, v11, v14
	v_add_f32_e32 v11, v11, v15
	s_waitcnt lgkmcnt(0)
	v_add_f32_e32 v11, v11, v16
	v_add_f32_e32 v11, v11, v17
	v_add_f32_e32 v11, v11, v18
	v_add_f32_e32 v11, v11, v19
	v_fmac_f32_e32 v1, 0x3a000000, v11
	v_rsq_f32_e32 v12, v1
	s_nop 0
	v_pk_mul_f32 v[2:3], v[4:5], v[12:13] op_sel_hi:[1,0]
	v_pk_mul_f32 v[4:5], v[6:7], v[12:13] op_sel_hi:[1,0]
	v_max_f32_e64 v1, |v2|, |v3|
	v_max3_f32 v1, |v4|, |v5|, v1
	v_mov_b32_e32 v6, 0
	s_nop 1
	v_mov_b32_dpp v6, v1 quad_perm:[1,0,3,2] row_mask:0xf bank_mask:0xf
	v_max_f32_e32 v6, v6, v6
	v_max_f32_e32 v1, v1, v6
	v_mov_b32_e32 v6, 0
	s_nop 1
	v_mov_b32_dpp v6, v1 quad_perm:[2,3,0,1] row_mask:0xf bank_mask:0xf
	v_max_f32_e32 v6, v6, v6
	v_max_f32_e32 v1, v1, v6
	v_mov_b32_e32 v6, 0
	s_nop 1
	v_mov_b32_dpp v6, v1 row_half_mirror row_mask:0xf bank_mask:0xf
	v_max_f32_e32 v6, v6, v6
	v_max_f32_e32 v1, v1, v6
	v_mov_b32_e32 v6, 0
	s_nop 1
	v_mov_b32_dpp v6, v1 row_mirror row_mask:0xf bank_mask:0xf
	v_max_f32_e32 v6, v6, v6
	v_max_f32_e32 v1, v1, v6
	v_mov_b32_e32 v6, 0
	s_nop 1
	v_mov_b32_dpp v6, v1 row_bcast:15 row_mask:0xa bank_mask:0xf
	v_max_f32_e32 v6, v6, v6
	v_max_f32_e32 v1, v1, v6
	v_mov_b32_e32 v6, 0
	s_nop 1
	v_mov_b32_dpp v6, v1 row_bcast:31 row_mask:0xc bank_mask:0xf
	v_max_f32_e32 v6, v6, v6
	v_max_f32_e32 v1, v1, v6
	s_nop 0
	v_readlane_b32 s6, v1, 63
	s_and_saveexec_b64 s[0:1], vcc
	s_lshl_b32 s7, s96, 2
	s_add_i32 s7, s7, 0
	v_mov_b32_e32 v1, s7
	v_mov_b32_e32 v6, s6
	ds_write_b32 v1, v6 offset:64
	s_or_b64 exec, exec, s[0:1]
	s_waitcnt lgkmcnt(0)
	s_barrier
	ds_read_b128 v[6:9], v10 offset:64
	ds_read_b128 v[10:13], v10 offset:80
	s_lshl_b64 s[6:7], s[4:5], 11
	s_waitcnt lgkmcnt(1)
	v_max3_f32 v1, v6, 0, v7
	v_max3_f32 v1, v1, v8, v9
	s_waitcnt lgkmcnt(0)
	v_max3_f32 v1, v1, v10, v11
	v_max3_f32 v1, v1, v12, v13
	v_cmp_lt_f32_e64 s[0:1], 0, v1
	s_mov_b64 s[8:9], exec
	v_readlane_b32 s10, v254, 36
	v_readlane_b32 s11, v254, 37
	s_and_b64 s[10:11], s[8:9], s[10:11]
	s_mov_b64 exec, s[10:11]
	s_cbranch_execz .LBB0_2394
	s_lshl_b64 s[4:5], s[4:5], 2
	v_mul_f32_e32 v6, 0x3c010204, v1
	s_add_u32 s4, s86, s4
	v_cndmask_b32_e64 v6, 1.0, v6, s[0:1]
	s_addc_u32 s5, s87, s5
	v_mov_b32_e32 v7, 0
	global_store_dword v7, v6, s[4:5]

.LBB0_2650:
	s_cmp_gt_i32 s10, 31
	s_cbranch_scc1 .LBB0_2654
	s_ashr_i32 s11, s10, 31
	s_lshl_b64 s[0:1], s[10:11], 13
	v_readlane_b32 s4, v254, 58
	v_readlane_b32 s5, v254, 59
	s_add_u32 s0, s4, s0
	s_addc_u32 s1, s5, s1
	s_add_u32 s4, s0, 0x40000
	s_addc_u32 s5, s1, 0
	v_lshlrev_b32_e32 v148, 4, v166
	s_add_u32 s12, s0, 0x80000
	v_or_b32_e32 v150, 0x400, v148
	v_or_b32_e32 v151, 0x800, v148
	v_or_b32_e32 v152, 0xc00, v148
	s_addc_u32 s13, s1, 0
	global_load_dwordx4 v[20:23], v148, s[0:1]
	global_load_dwordx4 v[24:27], v148, s[0:1] offset:1024
	global_load_dwordx4 v[28:31], v148, s[0:1] offset:2048
	global_load_dwordx4 v[32:35], v148, s[0:1] offset:3072
	v_or_b32_e32 v149, 0x1000, v148
	global_load_dwordx4 v[36:39], v148, s[4:5]
	global_load_dwordx4 v[40:43], v150, s[4:5]
	global_load_dwordx4 v[44:47], v151, s[4:5]
	global_load_dwordx4 v[48:51], v152, s[4:5]
	global_load_dwordx4 v[52:55], v149, s[0:1]
	global_load_dwordx4 v[56:59], v149, s[4:5]
	global_load_dwordx4 v[60:63], v148, s[12:13]
	s_add_u32 s14, s0, 0xc0000
	s_addc_u32 s15, s1, 0
	global_load_dwordx4 v[64:67], v148, s[14:15]
	global_load_dwordx4 v[68:71], v150, s[12:13]
	global_load_dwordx4 v[72:75], v150, s[14:15]
	global_load_dwordx4 v[76:79], v151, s[12:13]
	global_load_dwordx4 v[80:83], v151, s[14:15]
	global_load_dwordx4 v[84:87], v152, s[12:13]
	global_load_dwordx4 v[88:91], v152, s[14:15]
	global_load_dwordx4 v[92:95], v149, s[12:13]
	global_load_dwordx4 v[96:99], v149, s[14:15]
	v_or_b32_e32 v153, 0x1400, v148
	v_or_b32_e32 v154, 0x1800, v148
	v_or_b32_e32 v155, 0x1c00, v148
	global_load_dwordx4 v[100:103], v153, s[0:1]
	global_load_dwordx4 v[104:107], v153, s[4:5]
	global_load_dwordx4 v[108:111], v153, s[12:13]
	global_load_dwordx4 v[112:115], v153, s[14:15]
	global_load_dwordx4 v[116:119], v154, s[0:1]
	global_load_dwordx4 v[120:123], v154, s[4:5]
	global_load_dwordx4 v[124:127], v154, s[12:13]
	global_load_dwordx4 v[128:131], v154, s[14:15]
	global_load_dwordx4 v[132:135], v155, s[0:1]
	global_load_dwordx4 v[136:139], v155, s[4:5]
	global_load_dwordx4 v[140:143], v155, s[12:13]
	global_load_dwordx4 v[144:147], v155, s[14:15]
	s_add_i32 s4, s10, 0x2000
	s_ashr_i32 s5, s4, 31
	s_lshl_b64 s[0:1], s[4:5], 12
	v_readlane_b32 s10, v254, 54
	v_readlane_b32 s11, v254, 55
	s_add_u32 s0, s10, s0
	v_lshlrev_b32_e32 v1, 3, v166
	s_addc_u32 s1, s11, s1
	global_load_dwordx2 v[2:3], v1, s[0:1]
	global_load_dwordx2 v[18:19], v1, s[0:1] offset:512
	global_load_dwordx2 v[16:17], v1, s[0:1] offset:1024
	global_load_dwordx2 v[14:15], v1, s[0:1] offset:1536
	global_load_dwordx2 v[12:13], v1, s[0:1] offset:2048
	global_load_dwordx2 v[10:11], v1, s[0:1] offset:2560
	global_load_dwordx2 v[8:9], v1, s[0:1] offset:3072
	global_load_dwordx2 v[6:7], v1, s[0:1] offset:3584
	v_cmp_eq_u32_e32 vcc, 0, v166
	s_waitcnt vmcnt(35)
	v_pk_add_f32 v[4:5], v[22:23], v[38:39]
	v_pk_add_f32 v[20:21], v[20:21], v[36:37]
	s_waitcnt vmcnt(34)
	v_pk_add_f32 v[22:23], v[26:27], v[42:43]
	v_pk_add_f32 v[24:25], v[24:25], v[40:41]
	s_waitcnt vmcnt(33)
	v_pk_add_f32 v[26:27], v[30:31], v[46:47]
	v_pk_add_f32 v[28:29], v[28:29], v[44:45]
	s_waitcnt vmcnt(32)
	v_pk_add_f32 v[30:31], v[34:35], v[50:51]
	v_pk_add_f32 v[32:33], v[32:33], v[48:49]
	s_waitcnt vmcnt(30)
	v_pk_add_f32 v[34:35], v[54:55], v[58:59]
	v_pk_add_f32 v[40:41], v[52:53], v[56:57]
	s_waitcnt vmcnt(28)
	v_pk_add_f32 v[38:39], v[60:61], v[64:65]
	s_waitcnt vmcnt(24)
	v_pk_add_f32 v[52:53], v[76:77], v[80:81]
	s_waitcnt vmcnt(22)
	v_pk_add_f32 v[54:55], v[86:87], v[90:91]
	v_pk_add_f32 v[56:57], v[84:85], v[88:89]
	v_pk_add_f32 v[48:49], v[20:21], v[38:39]
	v_pk_add_f32 v[38:39], v[28:29], v[52:53]
	v_pk_add_f32 v[28:29], v[30:31], v[54:55]
	v_pk_add_f32 v[30:31], v[32:33], v[56:57]
	global_load_dwordx4 v[54:57], v148, s[6:7]
	v_pk_add_f32 v[36:37], v[62:63], v[66:67]
	v_pk_add_f32 v[42:43], v[70:71], v[74:75]
	v_pk_add_f32 v[44:45], v[68:69], v[72:73]
	v_pk_add_f32 v[50:51], v[78:79], v[82:83]
	s_waitcnt vmcnt(21)
	v_pk_add_f32 v[58:59], v[94:95], v[98:99]
	v_pk_add_f32 v[60:61], v[92:93], v[96:97]
	v_pk_add_f32 v[46:47], v[4:5], v[36:37]
	v_pk_add_f32 v[42:43], v[22:23], v[42:43]
	v_pk_add_f32 v[44:45], v[24:25], v[44:45]
	v_pk_add_f32 v[36:37], v[26:27], v[50:51]
	s_waitcnt vmcnt(11)
	v_pk_add_f32 v[50:51], v[132:133], v[136:137]
	s_waitcnt vmcnt(9)
	v_pk_add_f32 v[52:53], v[140:141], v[144:145]
	v_pk_add_f32 v[20:21], v[34:35], v[58:59]
	v_pk_add_f32 v[22:23], v[40:41], v[60:61]
	v_pk_add_f32 v[50:51], v[50:51], v[52:53]
	v_mul_f32_e32 v52, v45, v45
	v_mul_f32_e32 v53, v43, v43
	global_load_dwordx4 v[58:61], v150, s[6:7]
	v_fmac_f32_e32 v52, v44, v44
	v_fmac_f32_e32 v53, v42, v42
	v_add_f32_e32 v52, v52, v53
	v_mul_f32_e32 v53, v39, v39
	v_mul_f32_e32 v62, v37, v37
	v_fmac_f32_e32 v53, v38, v38
	v_fmac_f32_e32 v62, v36, v36
	v_add_f32_e32 v53, v53, v62
	v_mul_f32_e32 v66, v31, v31
	v_mul_f32_e32 v67, v29, v29
	global_load_dwordx4 v[62:65], v151, s[6:7]
	v_fmac_f32_e32 v66, v30, v30
	v_fmac_f32_e32 v67, v28, v28
	v_add_f32_e32 v86, v66, v67
	v_mul_f32_e32 v66, v23, v23
	v_mul_f32_e32 v67, v21, v21
	v_fmac_f32_e32 v66, v22, v22
	v_fmac_f32_e32 v67, v20, v20
	v_pk_add_f32 v[4:5], v[102:103], v[106:107]
	v_pk_add_f32 v[26:27], v[100:101], v[104:105]
	v_pk_add_f32 v[24:25], v[110:111], v[114:115]
	v_pk_add_f32 v[32:33], v[108:109], v[112:113]
	v_add_f32_e32 v87, v66, v67
	global_load_dwordx4 v[66:69], v152, s[6:7]
	v_pk_add_f32 v[24:25], v[4:5], v[24:25]
	v_pk_add_f32 v[26:27], v[26:27], v[32:33]
	v_mul_f32_e32 v71, v25, v25
	v_mul_f32_e32 v70, v27, v27
	v_fmac_f32_e32 v70, v26, v26
	v_fmac_f32_e32 v71, v24, v24
	v_pk_add_f32 v[4:5], v[118:119], v[122:123]
	v_pk_add_f32 v[34:35], v[116:117], v[120:121]
	v_pk_add_f32 v[32:33], v[126:127], v[130:131]
	v_pk_add_f32 v[40:41], v[124:125], v[128:129]
	v_add_f32_e32 v88, v70, v71
	global_load_dwordx4 v[70:73], v149, s[6:7]
	v_pk_add_f32 v[32:33], v[4:5], v[32:33]
	v_pk_add_f32 v[34:35], v[34:35], v[40:41]
	v_pk_add_f32 v[4:5], v[134:135], v[138:139]
	v_pk_add_f32 v[40:41], v[142:143], v[146:147]
	v_mul_f32_e32 v74, v35, v35
	v_mul_f32_e32 v75, v33, v33
	v_pk_add_f32 v[40:41], v[4:5], v[40:41]
	v_fmac_f32_e32 v74, v34, v34
	v_fmac_f32_e32 v75, v32, v32
	v_add_f32_e32 v89, v74, v75
	v_mul_f32_e32 v74, v51, v51
	v_mul_f32_e32 v75, v41, v41
	v_fmac_f32_e32 v74, v50, v50
	v_fmac_f32_e32 v75, v40, v40
	v_add_f32_e32 v90, v74, v75
	global_load_dwordx4 v[74:77], v153, s[6:7]
	global_load_dwordx4 v[78:81], v154, s[6:7]
	global_load_dwordx4 v[82:85], v155, s[6:7]
	v_mul_f32_e32 v4, v49, v49
	v_mul_f32_e32 v5, v47, v47
	v_fmac_f32_e32 v5, v46, v46
	v_fmac_f32_e32 v4, v48, v48
	v_add_f32_e32 v4, v4, v5
	v_add_f32_e32 v4, v4, v52
	v_add_f32_e32 v4, v4, v53
	v_add_f32_e32 v4, v4, v86
	v_add_f32_e32 v4, v4, v87
	v_add_f32_e32 v4, v4, v88
	v_add_f32_e32 v4, v4, v89
	v_add_f32_e32 v4, v4, v90
	v_mov_b32_e32 v5, 0
	v_mov_b32_e32 v53, 0x358637bd
	v_add_f32_dpp v4, v4, v4 quad_perm:[1,0,3,2] row_mask:0xf bank_mask:0xf bound_ctrl:1
	v_mov_b32_e32 v87, 0x3a000000
	s_waitcnt vmcnt(7)
	v_pk_mul_f32 v[48:49], v[48:49], v[54:55]
	v_add_f32_dpp v4, v4, v4 quad_perm:[2,3,0,1] row_mask:0xf bank_mask:0xf bound_ctrl:1
	v_cvt_f32_f16_e32 v54, v18
	v_cvt_f32_f16_sdwa v55, v18 dst_sel:DWORD dst_unused:UNUSED_PAD src0_sel:WORD_1
	v_add_f32_dpp v4, v4, v4 row_half_mirror row_mask:0xf bank_mask:0xf bound_ctrl:1
	v_cvt_f32_f16_e32 v18, v19
	v_cvt_f32_f16_sdwa v19, v19 dst_sel:DWORD dst_unused:UNUSED_PAD src0_sel:WORD_1
	v_add_f32_dpp v4, v4, v4 row_mirror row_mask:0xf bank_mask:0xf bound_ctrl:1
	v_cvt_f32_f16_e32 v88, v2
	v_cvt_f32_f16_sdwa v89, v2 dst_sel:DWORD dst_unused:UNUSED_PAD src0_sel:WORD_1
	v_mov_b32_dpp v5, v4 row_bcast:15 row_mask:0xa bank_mask:0xf
	v_add_f32_e32 v4, v4, v5
	v_mov_b32_e32 v5, 0
	s_waitcnt vmcnt(6)
	v_pk_mul_f32 v[42:43], v[42:43], v[60:61]
	v_cvt_f32_f16_e32 v90, v3
	v_mov_b32_dpp v5, v4 row_bcast:31 row_mask:0xc bank_mask:0xf
	v_add_f32_e32 v4, v4, v5
	v_cvt_f32_f16_sdwa v91, v3 dst_sel:DWORD dst_unused:UNUSED_PAD src0_sel:WORD_1
	v_readlane_b32 s10, v4, 63
	v_pk_mul_f32 v[46:47], v[46:47], v[56:57]
	v_pk_mul_f32 v[44:45], v[44:45], v[58:59]
	v_fma_f32 v4, s10, v87, v53
	v_rsq_f32_e32 v4, v4
	s_waitcnt vmcnt(5)
	v_pk_mul_f32 v[38:39], v[38:39], v[62:63]
	v_pk_mul_f32 v[36:37], v[36:37], v[64:65]
	global_load_dwordx4 v[58:61], v155, s[8:9]
	v_mul_f32_e32 v86, 0.5, v4
	v_pk_fma_f32 v[92:93], v[42:43], v[86:87], v[18:19] op_sel_hi:[1,0,1]
	v_cvt_f32_f16_e32 v42, v16
	v_cvt_f32_f16_sdwa v43, v16 dst_sel:DWORD dst_unused:UNUSED_PAD src0_sel:WORD_1
	global_load_dwordx4 v[2:5], v148, s[8:9]
	v_pk_fma_f32 v[90:91], v[46:47], v[86:87], v[90:91] op_sel_hi:[1,0,1]
	v_pk_fma_f32 v[88:89], v[48:49], v[86:87], v[88:89] op_sel_hi:[1,0,1]
	global_load_dwordx4 v[46:49], v150, s[8:9]
	v_pk_fma_f32 v[64:65], v[38:39], v[86:87], v[42:43] op_sel_hi:[1,0,1]
	v_cvt_f32_f16_e32 v42, v14
	v_cvt_f32_f16_sdwa v43, v14 dst_sel:DWORD dst_unused:UNUSED_PAD src0_sel:WORD_1
	v_pk_fma_f32 v[94:95], v[44:45], v[86:87], v[54:55] op_sel_hi:[1,0,1]
	v_cvt_f32_f16_e32 v44, v17
	v_cvt_f32_f16_sdwa v45, v17 dst_sel:DWORD dst_unused:UNUSED_PAD src0_sel:WORD_1
	global_load_dwordx4 v[16:19], v151, s[8:9]
	v_cvt_f32_f16_e32 v14, v15
	v_cvt_f32_f16_sdwa v15, v15 dst_sel:DWORD dst_unused:UNUSED_PAD src0_sel:WORD_1
	s_waitcnt vmcnt(8)
	v_pk_mul_f32 v[30:31], v[30:31], v[66:67]
	v_pk_mul_f32 v[28:29], v[28:29], v[68:69]
	v_pk_fma_f32 v[68:69], v[30:31], v[86:87], v[42:43] op_sel_hi:[1,0,1]
	v_cvt_f32_f16_e32 v30, v13
	v_cvt_f32_f16_sdwa v31, v13 dst_sel:DWORD dst_unused:UNUSED_PAD src0_sel:WORD_1
	v_pk_fma_f32 v[62:63], v[36:37], v[86:87], v[44:45] op_sel_hi:[1,0,1]
	global_load_dwordx4 v[36:39], v152, s[8:9]
	global_load_dwordx4 v[42:45], v153, s[8:9]
	v_pk_fma_f32 v[66:67], v[28:29], v[86:87], v[14:15] op_sel_hi:[1,0,1]
	v_cvt_f32_f16_e32 v28, v12
	v_cvt_f32_f16_sdwa v29, v12 dst_sel:DWORD dst_unused:UNUSED_PAD src0_sel:WORD_1
	s_waitcnt vmcnt(9)
	v_pk_mul_f32 v[20:21], v[20:21], v[72:73]
	global_load_dwordx4 v[12:15], v149, s[8:9]
	v_pk_mul_f32 v[22:23], v[22:23], v[70:71]
	v_pk_fma_f32 v[70:71], v[20:21], v[86:87], v[30:31] op_sel_hi:[1,0,1]
	v_cvt_f32_f16_e32 v20, v10
	v_cvt_f32_f16_sdwa v21, v10 dst_sel:DWORD dst_unused:UNUSED_PAD src0_sel:WORD_1
	v_pk_fma_f32 v[72:73], v[22:23], v[86:87], v[28:29] op_sel_hi:[1,0,1]
	s_waitcnt vmcnt(9)
	v_pk_mul_f32 v[22:23], v[24:25], v[76:77]
	v_pk_mul_f32 v[24:25], v[26:27], v[74:75]
	global_load_dwordx4 v[54:57], v154, s[8:9]
	v_pk_fma_f32 v[74:75], v[24:25], v[86:87], v[20:21] op_sel_hi:[1,0,1]
	v_cvt_f32_f16_e32 v20, v8
	v_cvt_f32_f16_sdwa v21, v8 dst_sel:DWORD dst_unused:UNUSED_PAD src0_sel:WORD_1
	v_cvt_f32_f16_e32 v10, v11
	v_cvt_f32_f16_sdwa v11, v11 dst_sel:DWORD dst_unused:UNUSED_PAD src0_sel:WORD_1
	v_cvt_f32_f16_e32 v8, v9
	v_cvt_f32_f16_sdwa v9, v9 dst_sel:DWORD dst_unused:UNUSED_PAD src0_sel:WORD_1
	s_waitcnt vmcnt(9)
	v_pk_mul_f32 v[24:25], v[34:35], v[78:79]
	v_pk_fma_f32 v[10:11], v[22:23], v[86:87], v[10:11] op_sel_hi:[1,0,1]
	v_pk_fma_f32 v[34:35], v[24:25], v[86:87], v[20:21] op_sel_hi:[1,0,1]
	v_cvt_f32_f16_e32 v20, v6
	v_cvt_f32_f16_sdwa v21, v6 dst_sel:DWORD dst_unused:UNUSED_PAD src0_sel:WORD_1
	v_cvt_f32_f16_e32 v6, v7
	v_cvt_f32_f16_sdwa v7, v7 dst_sel:DWORD dst_unused:UNUSED_PAD src0_sel:WORD_1
	v_pk_mul_f32 v[22:23], v[32:33], v[80:81]
	s_waitcnt vmcnt(8)
	v_pk_mul_f32 v[24:25], v[50:51], v[82:83]
	v_pk_fma_f32 v[8:9], v[22:23], v[86:87], v[8:9] op_sel_hi:[1,0,1]
	v_pk_mul_f32 v[22:23], v[40:41], v[84:85]
	v_cvt_f16_f32_e32 v26, v88
	v_cvt_f16_f32_sdwa v27, v89 dst_sel:WORD_1 dst_unused:UNUSED_PAD src0_sel:DWORD
	v_pk_fma_f32 v[40:41], v[22:23], v[86:87], v[6:7] op_sel_hi:[1,0,1]
	v_pk_fma_f32 v[50:51], v[24:25], v[86:87], v[20:21] op_sel_hi:[1,0,1]
	v_cvt_f16_f32_e32 v7, v90
	v_cvt_f16_f32_sdwa v20, v91 dst_sel:WORD_1 dst_unused:UNUSED_PAD src0_sel:DWORD
	v_cvt_f16_f32_e32 v21, v94
	v_cvt_f16_f32_sdwa v22, v95 dst_sel:WORD_1 dst_unused:UNUSED_PAD src0_sel:DWORD
	v_cvt_f16_f32_e32 v23, v92
	v_cvt_f16_f32_sdwa v24, v93 dst_sel:WORD_1 dst_unused:UNUSED_PAD src0_sel:DWORD
	v_or_b32_e32 v6, v27, v26
	v_or_b32_e32 v7, v20, v7
	global_store_dwordx2 v1, v[6:7], s[0:1] sc1
	v_or_b32_e32 v6, v22, v21
	v_or_b32_e32 v7, v24, v23
	global_store_dwordx2 v1, v[6:7], s[0:1] offset:512 sc1
	v_cvt_f16_f32_e32 v6, v64
	v_cvt_f16_f32_sdwa v7, v65 dst_sel:WORD_1 dst_unused:UNUSED_PAD src0_sel:DWORD
	v_cvt_f16_f32_e32 v20, v62
	v_cvt_f16_f32_sdwa v21, v63 dst_sel:WORD_1 dst_unused:UNUSED_PAD src0_sel:DWORD
	v_cvt_f16_f32_e32 v22, v68
	v_cvt_f16_f32_sdwa v23, v69 dst_sel:WORD_1 dst_unused:UNUSED_PAD src0_sel:DWORD
	v_or_b32_e32 v6, v7, v6
	v_or_b32_e32 v7, v21, v20
	global_store_dwordx2 v1, v[6:7], s[0:1] offset:1024 sc1
	v_cvt_f16_f32_e32 v7, v66
	v_cvt_f16_f32_sdwa v20, v67 dst_sel:WORD_1 dst_unused:UNUSED_PAD src0_sel:DWORD
	v_or_b32_e32 v6, v23, v22
	v_cvt_f16_f32_e32 v21, v72
	v_cvt_f16_f32_sdwa v22, v73 dst_sel:WORD_1 dst_unused:UNUSED_PAD src0_sel:DWORD
	v_cvt_f16_f32_e32 v23, v70
	v_cvt_f16_f32_sdwa v24, v71 dst_sel:WORD_1 dst_unused:UNUSED_PAD src0_sel:DWORD
	v_or_b32_e32 v7, v20, v7
	global_store_dwordx2 v1, v[6:7], s[0:1] offset:1536 sc1
	v_or_b32_e32 v6, v22, v21
	v_or_b32_e32 v7, v24, v23
	global_store_dwordx2 v1, v[6:7], s[0:1] offset:2048 sc1
	v_cvt_f16_f32_e32 v6, v74
	v_cvt_f16_f32_sdwa v7, v75 dst_sel:WORD_1 dst_unused:UNUSED_PAD src0_sel:DWORD
	v_cvt_f16_f32_e32 v20, v10
	v_cvt_f16_f32_sdwa v21, v11 dst_sel:WORD_1 dst_unused:UNUSED_PAD src0_sel:DWORD
	v_cvt_f16_f32_e32 v22, v34
	v_cvt_f16_f32_sdwa v23, v35 dst_sel:WORD_1 dst_unused:UNUSED_PAD src0_sel:DWORD
	v_or_b32_e32 v6, v7, v6
	v_or_b32_e32 v7, v21, v20
	global_store_dwordx2 v1, v[6:7], s[0:1] offset:2560 sc1
	v_cvt_f16_f32_e32 v7, v8
	v_cvt_f16_f32_sdwa v20, v9 dst_sel:WORD_1 dst_unused:UNUSED_PAD src0_sel:DWORD
	v_or_b32_e32 v6, v23, v22
	v_cvt_f16_f32_e32 v21, v50
	v_cvt_f16_f32_sdwa v22, v51 dst_sel:WORD_1 dst_unused:UNUSED_PAD src0_sel:DWORD
	v_cvt_f16_f32_e32 v23, v40
	v_cvt_f16_f32_sdwa v24, v41 dst_sel:WORD_1 dst_unused:UNUSED_PAD src0_sel:DWORD
	v_or_b32_e32 v7, v20, v7
	global_store_dwordx2 v1, v[6:7], s[0:1] offset:3072 sc1
	v_or_b32_e32 v6, v22, v21
	v_or_b32_e32 v7, v24, v23
	v_mov_b32_e32 v20, v89
	v_mov_b32_e32 v21, v95
	global_store_dwordx2 v1, v[6:7], s[0:1] offset:3584 sc1
	v_mov_b32_e32 v6, v88
	v_mov_b32_e32 v7, v94
	v_pk_mul_f32 v[20:21], v[20:21], v[20:21]
	v_mov_b32_e32 v22, v91
	v_mov_b32_e32 v23, v93
	v_pk_fma_f32 v[6:7], v[6:7], v[6:7], v[20:21]
	v_mov_b32_e32 v20, v90
	v_mov_b32_e32 v21, v92
	v_pk_mul_f32 v[22:23], v[22:23], v[22:23]
	s_waitcnt vmcnt(14)
	v_pk_mul_f32 v[4:5], v[4:5], v[90:91]
	v_pk_fma_f32 v[20:21], v[20:21], v[20:21], v[22:23]
	v_pk_mul_f32 v[22:23], v[64:65], v[64:65]
	v_pk_add_f32 v[6:7], v[6:7], v[20:21]
	v_pk_mul_f32 v[20:21], v[62:63], v[62:63]
	v_pk_add_f32 v[6:7], v[6:7], v[6:7] op_sel_hi:[0,1]
	v_pk_mov_b32 v[24:25], v[22:23], v[20:21] op_sel:[1,0]
	v_mov_b32_e32 v23, v21
	v_mul_f32_e32 v6, v68, v68
	v_pk_add_f32 v[20:21], v[24:25], v[22:23]
	v_pk_fma_f32 v[22:23], v[68:69], v[68:69], v[6:7] op_sel_hi:[1,1,0]
	v_mul_f32_e32 v6, v66, v66
	v_pk_add_f32 v[20:21], v[20:21], v[20:21] op_sel_hi:[0,1]
	v_pk_fma_f32 v[24:25], v[66:67], v[66:67], v[6:7] op_sel_hi:[1,1,0]
	v_mul_f32_e32 v22, v72, v72
	v_mul_f32_e32 v24, v73, v73
	v_mul_f32_e32 v20, v70, v70
	v_mul_f32_e32 v6, v71, v71
	v_pk_add_f32 v[22:23], v[22:23], v[24:25]
	v_pk_add_f32 v[6:7], v[20:21], v[6:7]
	v_pk_mul_f32 v[20:21], v[10:11], v[10:11]
	v_pk_add_f32 v[6:7], v[22:23], v[6:7]
	v_pk_mul_f32 v[22:23], v[74:75], v[74:75]
	v_pk_add_f32 v[6:7], v[6:7], v[6:7] op_sel_hi:[0,1]
	v_pk_mov_b32 v[24:25], v[22:23], v[20:21] op_sel:[1,0]
	v_mov_b32_e32 v23, v21
	v_mul_f32_e32 v6, v34, v34
	v_pk_add_f32 v[20:21], v[24:25], v[22:23]
	v_pk_fma_f32 v[22:23], v[34:35], v[34:35], v[6:7] op_sel_hi:[1,1,0]
	v_mul_f32_e32 v6, v8, v8
	v_pk_add_f32 v[20:21], v[20:21], v[20:21] op_sel_hi:[0,1]
	v_pk_fma_f32 v[24:25], v[8:9], v[8:9], v[6:7] op_sel_hi:[1,1,0]
	v_mul_f32_e32 v22, v50, v50
	v_mul_f32_e32 v24, v51, v51
	v_mul_f32_e32 v20, v40, v40
	v_mul_f32_e32 v6, v41, v41
	v_pk_add_f32 v[22:23], v[22:23], v[24:25]
	v_pk_add_f32 v[6:7], v[20:21], v[6:7]
	s_waitcnt vmcnt(13)
	v_pk_mul_f32 v[20:21], v[48:49], v[92:93]
	v_pk_add_f32 v[6:7], v[22:23], v[6:7]
	v_pk_mul_f32 v[2:3], v[2:3], v[88:89]
	v_add_f32_e32 v1, v6, v7
	v_mov_b32_e32 v6, 0
	v_mov_b32_e32 v52, 0
	v_add_f32_dpp v1, v1, v1 quad_perm:[1,0,3,2] row_mask:0xf bank_mask:0xf bound_ctrl:1
	s_nop 1
	v_add_f32_dpp v1, v1, v1 quad_perm:[2,3,0,1] row_mask:0xf bank_mask:0xf bound_ctrl:1
	s_nop 1
	v_add_f32_dpp v1, v1, v1 row_half_mirror row_mask:0xf bank_mask:0xf bound_ctrl:1
	s_nop 1
	v_add_f32_dpp v1, v1, v1 row_mirror row_mask:0xf bank_mask:0xf bound_ctrl:1
	s_nop 1
	v_mov_b32_dpp v6, v1 row_bcast:15 row_mask:0xa bank_mask:0xf
	v_add_f32_e32 v1, v1, v6
	v_mov_b32_e32 v6, 0
	s_nop 1
	v_mov_b32_dpp v6, v1 row_bcast:31 row_mask:0xc bank_mask:0xf
	v_add_f32_e32 v1, v1, v6
	v_pk_mul_f32 v[6:7], v[46:47], v[94:95]
	v_readlane_b32 s0, v1, 63
	s_nop 1
	v_fmac_f32_e32 v53, s0, v87
	v_rsq_f32_e32 v76, v53
	s_nop 0
	v_pk_mul_f32 v[24:25], v[20:21], v[76:77] op_sel_hi:[1,0]
	v_pk_mul_f32 v[30:31], v[4:5], v[76:77] op_sel_hi:[1,0]
	v_pk_mul_f32 v[28:29], v[6:7], v[76:77] op_sel_hi:[1,0]
	v_pk_mul_f32 v[32:33], v[2:3], v[76:77] op_sel_hi:[1,0]
	v_max_f32_e64 v1, |v30|, |v31|
	v_max_f32_e64 v2, |v24|, |v25|
	v_max3_f32 v1, |v32|, |v33|, v1
	v_max3_f32 v2, |v28|, |v29|, v2
	s_waitcnt vmcnt(12)
	v_pk_mul_f32 v[4:5], v[18:19], v[62:63]
	v_max3_f32 v1, v1, 0, v2
	v_pk_mul_f32 v[2:3], v[16:17], v[64:65]
	v_pk_mul_f32 v[22:23], v[4:5], v[76:77] op_sel_hi:[1,0]
	v_pk_mul_f32 v[26:27], v[2:3], v[76:77] op_sel_hi:[1,0]
	v_max_f32_e64 v2, |v22|, |v23|
	s_waitcnt vmcnt(11)
	v_pk_mul_f32 v[4:5], v[38:39], v[66:67]
	v_max3_f32 v6, |v26|, |v27|, v2
	v_pk_mul_f32 v[2:3], v[36:37], v[68:69]
	v_pk_mul_f32 v[18:19], v[4:5], v[76:77] op_sel_hi:[1,0]
	v_pk_mul_f32 v[20:21], v[2:3], v[76:77] op_sel_hi:[1,0]
	v_max_f32_e64 v2, |v18|, |v19|
	v_max3_f32 v2, |v20|, |v21|, v2
	s_waitcnt vmcnt(9)
	v_pk_mul_f32 v[4:5], v[14:15], v[70:71]
	v_max3_f32 v1, v1, v6, v2
	v_pk_mul_f32 v[2:3], v[12:13], v[72:73]
	v_pk_mul_f32 v[14:15], v[4:5], v[76:77] op_sel_hi:[1,0]
	v_pk_mul_f32 v[16:17], v[2:3], v[76:77] op_sel_hi:[1,0]
	v_max_f32_e64 v2, |v14|, |v15|
	v_pk_mul_f32 v[4:5], v[44:45], v[10:11]
	v_max3_f32 v6, |v16|, |v17|, v2
	v_pk_mul_f32 v[2:3], v[42:43], v[74:75]
	v_pk_mul_f32 v[10:11], v[4:5], v[76:77] op_sel_hi:[1,0]
	v_pk_mul_f32 v[12:13], v[2:3], v[76:77] op_sel_hi:[1,0]
	v_max_f32_e64 v2, |v10|, |v11|
	v_max3_f32 v2, |v12|, |v13|, v2
	s_waitcnt vmcnt(8)
	v_pk_mul_f32 v[4:5], v[56:57], v[8:9]
	v_max3_f32 v1, v1, v6, v2
	v_pk_mul_f32 v[2:3], v[54:55], v[34:35]
	v_pk_mul_f32 v[6:7], v[4:5], v[76:77] op_sel_hi:[1,0]
	v_pk_mul_f32 v[8:9], v[2:3], v[76:77] op_sel_hi:[1,0]
	v_max_f32_e64 v2, |v6|, |v7|
	v_max3_f32 v34, |v8|, |v9|, v2
	v_pk_mul_f32 v[2:3], v[40:41], v[60:61]
	v_pk_mul_f32 v[4:5], v[50:51], v[58:59]
	v_pk_mul_f32 v[2:3], v[2:3], v[76:77] op_sel_hi:[1,0]
	v_pk_mul_f32 v[4:5], v[4:5], v[76:77] op_sel_hi:[1,0]
	v_max_f32_e64 v35, |v2|, |v3|
	v_max3_f32 v35, |v4|, |v5|, v35
	v_max3_f32 v1, v1, v34, v35
	v_mov_b32_e32 v34, 0
	s_nop 1
	v_mov_b32_dpp v34, v1 quad_perm:[1,0,3,2] row_mask:0xf bank_mask:0xf
	v_max_f32_e32 v34, v34, v34
	v_max_f32_e32 v1, v1, v34
	v_mov_b32_e32 v34, 0
	s_nop 1
	v_mov_b32_dpp v34, v1 quad_perm:[2,3,0,1] row_mask:0xf bank_mask:0xf
	v_max_f32_e32 v34, v34, v34
	v_max_f32_e32 v1, v1, v34
	v_mov_b32_e32 v34, 0
	s_nop 1
	v_mov_b32_dpp v34, v1 row_half_mirror row_mask:0xf bank_mask:0xf
	v_max_f32_e32 v34, v34, v34
	v_max_f32_e32 v1, v1, v34
	v_mov_b32_e32 v34, 0
	s_nop 1
	v_mov_b32_dpp v34, v1 row_mirror row_mask:0xf bank_mask:0xf
	v_max_f32_e32 v34, v34, v34
	v_max_f32_e32 v1, v1, v34
	v_mov_b32_e32 v34, 0
	s_nop 1
	v_mov_b32_dpp v34, v1 row_bcast:15 row_mask:0xa bank_mask:0xf
	v_max_f32_e32 v34, v34, v34
	v_max_f32_e32 v1, v1, v34
	v_mov_b32_e32 v34, 0
	s_nop 1
	v_mov_b32_dpp v34, v1 row_bcast:31 row_mask:0xc bank_mask:0xf
	v_max_f32_e32 v34, v34, v34
	v_max_f32_e32 v1, v1, v34
	s_nop 0
	v_readlane_b32 s12, v1, 63
	s_nop 1
	v_cmp_gt_f32_e64 s[0:1], s12, 0
	s_and_saveexec_b64 s[10:11], vcc
	s_cbranch_execz .LBB0_2653
	s_lshl_b64 s[14:15], s[4:5], 2
	v_mov_b32_e32 v1, 0x3c010204
	s_add_u32 s14, s86, s14
	v_mul_f32_e32 v1, s12, v1
	s_addc_u32 s15, s87, s15
	v_cndmask_b32_e64 v1, 1.0, v1, s[0:1]
	global_store_dword v52, v1, s[14:15]

.LBB0_2655:
	s_cbranch_execz .LBB0_2666
	s_ashr_i32 s1, s90, 5
	s_abs_i32 s0, s1
	v_cvt_f32_u32_e32 v1, s0
	s_sub_i32 s10, 0, s0
	s_abs_i32 s4, s62
	s_xor_b32 s5, s62, s1
	v_rcp_iflag_f32_e32 v1, v1
	s_ashr_i32 s5, s5, 31
	v_mul_f32_e32 v1, 0x4f7ffffe, v1
	v_cvt_u32_f32_e32 v1, v1
	s_nop 0
	v_readfirstlane_b32 s11, v1
	s_mul_i32 s10, s10, s11
	s_mul_hi_u32 s10, s11, s10
	s_add_i32 s11, s11, s10
	s_mul_hi_u32 s10, s4, s11
	s_mul_i32 s11, s10, s0
	s_sub_i32 s4, s4, s11
	s_add_i32 s12, s10, 1
	s_sub_i32 s11, s4, s0
	s_cmp_ge_u32 s4, s0
	s_cselect_b32 s10, s12, s10
	s_cselect_b32 s4, s11, s4
	s_add_i32 s11, s10, 1
	s_cmp_ge_u32 s4, s0
	s_cselect_b32 s0, s11, s10
	s_xor_b32 s0, s0, s5
	s_sub_i32 s0, s0, s5
	s_mul_i32 s1, s0, s1
	s_sub_i32 s1, s62, s1
	s_cmp_lg_u32 s1, 0
	s_cbranch_scc1 .LBB0_2666
	s_ashr_i32 s1, s0, 31
	s_lshl_b64 s[4:5], s[0:1], 13
	v_readlane_b32 s10, v254, 58
	v_readlane_b32 s11, v254, 59
	s_add_u32 s4, s10, s4
	s_addc_u32 s5, s11, s5
	v_mov_b32_e32 v11, 0
	v_lshlrev_b32_e32 v10, 4, v0
	v_lshl_add_u64 v[2:3], s[4:5], 0, v[10:11]
	v_add_co_u32_e32 v4, vcc, 0x40000, v2
	s_waitcnt vmcnt(0)
	v_mov_b32_e32 v16, v184
	v_mov_b32_e32 v17, v185
	v_mov_b32_e32 v18, v186
	v_mov_b32_e32 v19, v187
	s_nop 0
	v_addc_co_u32_e32 v5, vcc, 0, v3, vcc
	v_add_co_u32_e32 v6, vcc, 0x80000, v2
	s_add_i32 s4, s0, 0x2000
	s_nop 0
	v_addc_co_u32_e32 v7, vcc, 0, v3, vcc
	v_add_co_u32_e32 v2, vcc, 0xc0000, v2
	v_mov_b32_e32 v20, v188
	v_mov_b32_e32 v21, v189
	v_mov_b32_e32 v22, v190
	v_mov_b32_e32 v23, v191
	v_mov_b32_e32 v24, v192
	v_mov_b32_e32 v25, v193
	v_mov_b32_e32 v26, v194
	v_mov_b32_e32 v27, v195
	v_addc_co_u32_e32 v3, vcc, 0, v3, vcc
	v_mov_b32_e32 v28, v196
	v_mov_b32_e32 v29, v197
	v_mov_b32_e32 v30, v198
	v_mov_b32_e32 v31, v199
	s_ashr_i32 s5, s4, 31
	s_lshl_b64 s[0:1], s[4:5], 12
	v_readlane_b32 s10, v254, 54
	v_readlane_b32 s11, v254, 55
	s_add_u32 s0, s10, s0
	s_addc_u32 s1, s11, s1
	v_lshlrev_b32_e32 v14, 3, v0
	v_mov_b32_e32 v6, v174
	v_mov_b32_e32 v7, v175
	v_mov_b32_e32 v8, v176
	v_mov_b32_e32 v9, v177
	v_mov_b32_e32 v2, v170
	v_mov_b32_e32 v3, v171
	v_mov_b32_e32 v4, v172
	v_mov_b32_e32 v5, v173
	v_mov_b32_e32 v12, v180
	v_mov_b32_e32 v13, v181
	v_mov_b32_e32 v1, v11
	v_mov_b32_e32 v10, v11
	v_mov_b32_e32 v15, v11
	v_lshl_add_u64 v[14:15], s[0:1], 0, v[14:15]
	v_cmp_eq_u32_e32 vcc, 0, v166
	s_waitcnt vmcnt(5)
	v_pk_add_f32 v[18:19], v[18:19], v[22:23]
	v_pk_add_f32 v[20:21], v[16:17], v[20:21]
	s_waitcnt vmcnt(3)
	v_pk_add_f32 v[16:17], v[26:27], v[30:31]
	v_pk_add_f32 v[22:23], v[24:25], v[28:29]
	v_pk_add_f32 v[16:17], v[18:19], v[16:17]
	v_pk_add_f32 v[18:19], v[20:21], v[22:23]
	v_mul_f32_e32 v21, v17, v17
	v_mul_f32_e32 v20, v19, v19
	v_fmac_f32_e32 v20, v18, v18
	v_fmac_f32_e32 v21, v16, v16
	v_add_f32_e32 v20, v20, v21
	s_nop 1
	v_add_f32_dpp v20, v20, v20 quad_perm:[1,0,3,2] row_mask:0xf bank_mask:0xf bound_ctrl:1
	s_nop 1
	v_add_f32_dpp v20, v20, v20 quad_perm:[2,3,0,1] row_mask:0xf bank_mask:0xf bound_ctrl:1
	s_nop 1
	v_add_f32_dpp v20, v20, v20 row_half_mirror row_mask:0xf bank_mask:0xf bound_ctrl:1
	s_nop 1
	v_add_f32_dpp v20, v20, v20 row_mirror row_mask:0xf bank_mask:0xf bound_ctrl:1
	s_nop 1
	v_mov_b32_dpp v1, v20 row_bcast:15 row_mask:0xa bank_mask:0xf
	v_add_f32_e32 v1, v20, v1
	s_nop 1
	v_mov_b32_dpp v10, v1 row_bcast:31 row_mask:0xc bank_mask:0xf
	v_add_f32_e32 v1, v1, v10
	s_nop 0
	v_readlane_b32 s6, v1, 63
	s_and_saveexec_b64 s[0:1], vcc
	s_lshl_b32 s7, s96, 2
	s_add_i32 s7, s7, 0
	v_mov_b32_e32 v1, s7
	v_mov_b32_e32 v10, s6
	ds_write_b32 v1, v10
	s_or_b64 exec, exec, s[0:1]
	s_waitcnt lgkmcnt(0)
	s_barrier
	ds_read_b128 v[20:23], v11
	ds_read_b128 v[24:27], v11 offset:16
	s_waitcnt vmcnt(2)
	v_pk_mul_f32 v[8:9], v[8:9], v[16:17]
	v_pk_mul_f32 v[6:7], v[6:7], v[18:19]
	s_waitcnt lgkmcnt(1)
	v_add_f32_e32 v1, 0, v20
	v_add_f32_e32 v1, v1, v21
	v_add_f32_e32 v1, v1, v22
	v_add_f32_e32 v1, v1, v23
	s_waitcnt lgkmcnt(0)
	v_add_f32_e32 v1, v1, v24
	v_add_f32_e32 v1, v1, v25
	v_add_f32_e32 v1, v1, v26
	v_add_f32_e32 v10, v1, v27
	v_mov_b32_e32 v1, 0x358637bd
	v_fmamk_f32 v10, v10, 0x3a000000, v1
	v_rsq_f32_e32 v10, v10
	s_waitcnt vmcnt(0)
	v_cvt_f32_f16_sdwa v21, v12 dst_sel:DWORD dst_unused:UNUSED_PAD src0_sel:WORD_1
	v_cvt_f32_f16_e32 v20, v12
	v_cvt_f32_f16_sdwa v23, v13 dst_sel:DWORD dst_unused:UNUSED_PAD src0_sel:WORD_1
	v_cvt_f32_f16_e32 v22, v13
	v_mul_f32_e32 v10, 0.5, v10
	v_pk_fma_f32 v[6:7], v[6:7], v[10:11], v[20:21] op_sel_hi:[1,0,1]
	v_pk_fma_f32 v[8:9], v[8:9], v[10:11], v[22:23] op_sel_hi:[1,0,1]
	v_cvt_f16_f32_e32 v10, v6
	v_cvt_f16_f32_sdwa v12, v7 dst_sel:WORD_1 dst_unused:UNUSED_PAD src0_sel:DWORD
	v_cvt_f16_f32_e32 v13, v8
	v_cvt_f16_f32_sdwa v16, v9 dst_sel:WORD_1 dst_unused:UNUSED_PAD src0_sel:DWORD
	v_or_b32_e32 v12, v12, v10
	v_mul_f32_e32 v10, v7, v7
	v_or_b32_e32 v13, v16, v13
	global_store_dwordx2 v[14:15], v[12:13], off sc1
	v_mul_f32_e32 v12, v9, v9
	v_fmac_f32_e32 v10, v6, v6
	v_fmac_f32_e32 v12, v8, v8
	v_add_f32_e32 v10, v10, v12
	v_mov_b32_e32 v12, 0
	s_nop 0
	v_add_f32_dpp v10, v10, v10 quad_perm:[1,0,3,2] row_mask:0xf bank_mask:0xf bound_ctrl:1
	s_nop 1
	v_add_f32_dpp v10, v10, v10 quad_perm:[2,3,0,1] row_mask:0xf bank_mask:0xf bound_ctrl:1
	s_nop 1
	v_add_f32_dpp v10, v10, v10 row_half_mirror row_mask:0xf bank_mask:0xf bound_ctrl:1
	s_nop 1
	v_add_f32_dpp v10, v10, v10 row_mirror row_mask:0xf bank_mask:0xf bound_ctrl:1
	s_nop 1
	v_mov_b32_dpp v12, v10 row_bcast:15 row_mask:0xa bank_mask:0xf
	v_add_f32_e32 v10, v10, v12
	s_nop 1
	v_mov_b32_dpp v11, v10 row_bcast:31 row_mask:0xc bank_mask:0xf
	v_add_f32_e32 v10, v10, v11
	s_nop 0
	v_readlane_b32 s6, v10, 63
	s_and_saveexec_b64 s[0:1], vcc
	s_lshl_b32 s7, s96, 2
	s_add_i32 s7, s7, 0
	v_mov_b32_e32 v10, s7
	v_mov_b32_e32 v11, s6
	ds_write_b32 v10, v11 offset:32
	s_or_b64 exec, exec, s[0:1]
	v_mov_b32_e32 v10, 0
	s_waitcnt lgkmcnt(0)
	s_barrier
	ds_read_b128 v[12:15], v10 offset:32
	ds_read_b128 v[16:19], v10 offset:48
	v_pk_mul_f32 v[4:5], v[4:5], v[8:9]
	v_pk_mul_f32 v[6:7], v[2:3], v[6:7]
	s_waitcnt lgkmcnt(1)
	v_add_f32_e32 v11, 0, v12
	v_add_f32_e32 v11, v11, v13
	v_add_f32_e32 v11, v11, v14
	v_add_f32_e32 v11, v11, v15
	s_waitcnt lgkmcnt(0)
	v_add_f32_e32 v11, v11, v16
	v_add_f32_e32 v11, v11, v17
	v_add_f32_e32 v11, v11, v18
	v_add_f32_e32 v11, v11, v19
	v_fmac_f32_e32 v1, 0x3a000000, v11
	v_rsq_f32_e32 v12, v1
	s_nop 0
	v_pk_mul_f32 v[2:3], v[4:5], v[12:13] op_sel_hi:[1,0]
	v_pk_mul_f32 v[4:5], v[6:7], v[12:13] op_sel_hi:[1,0]
	v_max_f32_e64 v1, |v2|, |v3|
	v_max3_f32 v1, |v4|, |v5|, v1
	v_mov_b32_e32 v6, 0
	s_nop 1
	v_mov_b32_dpp v6, v1 quad_perm:[1,0,3,2] row_mask:0xf bank_mask:0xf
	v_max_f32_e32 v6, v6, v6
	v_max_f32_e32 v1, v1, v6
	v_mov_b32_e32 v6, 0
	s_nop 1
	v_mov_b32_dpp v6, v1 quad_perm:[2,3,0,1] row_mask:0xf bank_mask:0xf
	v_max_f32_e32 v6, v6, v6
	v_max_f32_e32 v1, v1, v6
	v_mov_b32_e32 v6, 0
	s_nop 1
	v_mov_b32_dpp v6, v1 row_half_mirror row_mask:0xf bank_mask:0xf
	v_max_f32_e32 v6, v6, v6
	v_max_f32_e32 v1, v1, v6
	v_mov_b32_e32 v6, 0
	s_nop 1
	v_mov_b32_dpp v6, v1 row_mirror row_mask:0xf bank_mask:0xf
	v_max_f32_e32 v6, v6, v6
	v_max_f32_e32 v1, v1, v6
	v_mov_b32_e32 v6, 0
	s_nop 1
	v_mov_b32_dpp v6, v1 row_bcast:15 row_mask:0xa bank_mask:0xf
	v_max_f32_e32 v6, v6, v6
	v_max_f32_e32 v1, v1, v6
	v_mov_b32_e32 v6, 0
	s_nop 1
	v_mov_b32_dpp v6, v1 row_bcast:31 row_mask:0xc bank_mask:0xf
	v_max_f32_e32 v6, v6, v6
	v_max_f32_e32 v1, v1, v6
	s_nop 0
	v_readlane_b32 s6, v1, 63
	s_and_saveexec_b64 s[0:1], vcc
	s_lshl_b32 s7, s96, 2
	s_add_i32 s7, s7, 0
	v_mov_b32_e32 v1, s7
	v_mov_b32_e32 v6, s6
	ds_write_b32 v1, v6 offset:64
	s_or_b64 exec, exec, s[0:1]
	s_waitcnt lgkmcnt(0)
	s_barrier
	ds_read_b128 v[6:9], v10 offset:64
	ds_read_b128 v[10:13], v10 offset:80
	s_lshl_b64 s[6:7], s[4:5], 11
	s_waitcnt lgkmcnt(1)
	v_max3_f32 v1, v6, 0, v7
	v_max3_f32 v1, v1, v8, v9
	s_waitcnt lgkmcnt(0)
	v_max3_f32 v1, v1, v10, v11
	v_max3_f32 v1, v1, v12, v13
	v_cmp_lt_f32_e64 s[0:1], 0, v1
	s_mov_b64 s[8:9], exec
	v_readlane_b32 s10, v254, 36
	v_readlane_b32 s11, v254, 37
	s_and_b64 s[10:11], s[8:9], s[10:11]
	s_mov_b64 exec, s[10:11]
	s_cbranch_execz .LBB0_2665
	s_lshl_b64 s[4:5], s[4:5], 2
	v_mul_f32_e32 v6, 0x3c010204, v1
	s_add_u32 s4, s86, s4
	v_cndmask_b32_e64 v6, 1.0, v6, s[0:1]
	s_addc_u32 s5, s87, s5
	v_mov_b32_e32 v7, 0
	global_store_dword v7, v6, s[4:5]

.LBB0_2913:
	v_lshlrev_b32_e32 v134, 16, v126
	v_and_b32_e32 v135, 0xffff0000, v126
	v_lshlrev_b32_e32 v126, 16, v127
	v_and_b32_e32 v127, 0xffff0000, v127
	v_pk_mul_f32 v[136:137], v[126:127], v[126:127]
	v_lshlrev_b32_e32 v138, 16, v128
	v_pk_fma_f32 v[136:137], v[134:135], v[134:135], v[136:137]
	v_and_b32_e32 v139, 0xffff0000, v128
	v_pk_fma_f32 v[136:137], v[138:139], v[138:139], v[136:137]
	v_lshlrev_b32_e32 v128, 16, v129
	v_and_b32_e32 v129, 0xffff0000, v129
	v_pk_fma_f32 v[136:137], v[128:129], v[128:129], v[136:137]
	v_lshlrev_b32_e32 v140, 16, v122
	v_and_b32_e32 v141, 0xffff0000, v122
	v_pk_fma_f32 v[136:137], v[140:141], v[140:141], v[136:137]
	v_lshlrev_b32_e32 v122, 16, v123
	v_and_b32_e32 v123, 0xffff0000, v123
	v_pk_fma_f32 v[136:137], v[122:123], v[122:123], v[136:137]
	v_lshlrev_b32_e32 v142, 16, v124
	v_and_b32_e32 v143, 0xffff0000, v124
	v_pk_fma_f32 v[136:137], v[142:143], v[142:143], v[136:137]
	v_lshlrev_b32_e32 v124, 16, v125
	v_and_b32_e32 v125, 0xffff0000, v125
	v_pk_fma_f32 v[136:137], v[124:125], v[124:125], v[136:137]
	v_lshlrev_b32_e32 v144, 16, v118
	v_and_b32_e32 v145, 0xffff0000, v118
	v_pk_fma_f32 v[136:137], v[144:145], v[144:145], v[136:137]
	v_lshlrev_b32_e32 v118, 16, v119
	v_and_b32_e32 v119, 0xffff0000, v119
	v_pk_fma_f32 v[136:137], v[118:119], v[118:119], v[136:137]
	v_lshlrev_b32_e32 v146, 16, v120
	v_and_b32_e32 v147, 0xffff0000, v120
	v_pk_fma_f32 v[136:137], v[146:147], v[146:147], v[136:137]
	v_lshlrev_b32_e32 v120, 16, v121
	v_and_b32_e32 v121, 0xffff0000, v121
	v_pk_fma_f32 v[136:137], v[120:121], v[120:121], v[136:137]
	v_lshlrev_b32_e32 v148, 16, v114
	v_and_b32_e32 v149, 0xffff0000, v114
	v_pk_fma_f32 v[136:137], v[148:149], v[148:149], v[136:137]
	v_lshlrev_b32_e32 v114, 16, v115
	v_and_b32_e32 v115, 0xffff0000, v115
	v_pk_fma_f32 v[136:137], v[114:115], v[114:115], v[136:137]
	v_lshlrev_b32_e32 v150, 16, v116
	v_and_b32_e32 v151, 0xffff0000, v116
	v_pk_fma_f32 v[136:137], v[150:151], v[150:151], v[136:137]
	v_lshlrev_b32_e32 v116, 16, v117
	v_and_b32_e32 v117, 0xffff0000, v117
	v_pk_fma_f32 v[136:137], v[116:117], v[116:117], v[136:137]
	v_cvt_f32_f16_sdwa v153, v110 dst_sel:DWORD dst_unused:UNUSED_PAD src0_sel:WORD_1
	v_add_f32_e32 v133, v136, v137
	v_mov_b32_e32 v136, 0
	v_cvt_f32_f16_e32 v152, v110
	v_add_f32_dpp v133, v133, v133 quad_perm:[1,0,3,2] row_mask:0xf bank_mask:0xf bound_ctrl:1
	v_cvt_f32_f16_sdwa v155, v111 dst_sel:DWORD dst_unused:UNUSED_PAD src0_sel:WORD_1
	v_cvt_f32_f16_e32 v154, v111
	v_add_f32_dpp v133, v133, v133 quad_perm:[2,3,0,1] row_mask:0xf bank_mask:0xf bound_ctrl:1
	v_pk_mul_f32 v[110:111], v[6:7], v[134:135]
	v_cvt_f32_f16_sdwa v135, v112 dst_sel:DWORD dst_unused:UNUSED_PAD src0_sel:WORD_1
	v_add_f32_dpp v133, v133, v133 row_half_mirror row_mask:0xf bank_mask:0xf bound_ctrl:1
	v_cvt_f32_f16_e32 v134, v112
	v_pk_mul_f32 v[122:123], v[16:17], v[122:123]
	v_add_f32_dpp v133, v133, v133 row_mirror row_mask:0xf bank_mask:0xf bound_ctrl:1
	v_pk_mul_f32 v[124:125], v[12:13], v[124:125]
	v_pk_mul_f32 v[126:127], v[8:9], v[126:127]
	v_mov_b32_dpp v136, v133 row_bcast:15 row_mask:0xa bank_mask:0xf
	v_add_f32_e32 v133, v133, v136
	v_mov_b32_e32 v136, 0
	v_pk_mul_f32 v[118:119], v[24:25], v[118:119]
	v_pk_mul_f32 v[128:129], v[4:5], v[128:129]
	v_mov_b32_dpp v136, v133 row_bcast:31 row_mask:0xc bank_mask:0xf
	v_add_f32_e32 v133, v133, v136
	v_pk_mul_f32 v[120:121], v[20:21], v[120:121]
	v_readlane_b32 s11, v133, 63
	s_nop 1
	v_fma_f32 v133, s11, v132, v1
	v_rsq_f32_e32 v133, v133
	s_nop 0
	v_mul_f32_e32 v136, 0.5, v133
	v_pk_fma_f32 v[110:111], v[110:111], v[136:137], v[152:153] op_sel_hi:[1,0,1]
	v_cvt_f32_f16_sdwa v153, v113 dst_sel:DWORD dst_unused:UNUSED_PAD src0_sel:WORD_1
	v_cvt_f32_f16_e32 v152, v113
	v_pk_mul_f32 v[112:113], v[2:3], v[138:139]
	v_cvt_f32_f16_sdwa v139, v107 dst_sel:DWORD dst_unused:UNUSED_PAD src0_sel:WORD_1
	v_pk_fma_f32 v[112:113], v[112:113], v[136:137], v[134:135] op_sel_hi:[1,0,1]
	v_cvt_f32_f16_sdwa v135, v106 dst_sel:DWORD dst_unused:UNUSED_PAD src0_sel:WORD_1
	v_cvt_f32_f16_e32 v134, v106
	v_cvt_f32_f16_e32 v138, v107
	v_pk_mul_f32 v[106:107], v[14:15], v[140:141]
	v_pk_fma_f32 v[126:127], v[126:127], v[136:137], v[154:155] op_sel_hi:[1,0,1]
	v_pk_fma_f32 v[106:107], v[106:107], v[136:137], v[134:135] op_sel_hi:[1,0,1]
	v_cvt_f32_f16_sdwa v135, v108 dst_sel:DWORD dst_unused:UNUSED_PAD src0_sel:WORD_1
	v_cvt_f32_f16_e32 v134, v108
	v_pk_fma_f32 v[122:123], v[122:123], v[136:137], v[138:139] op_sel_hi:[1,0,1]
	v_cvt_f32_f16_sdwa v139, v109 dst_sel:DWORD dst_unused:UNUSED_PAD src0_sel:WORD_1
	v_cvt_f32_f16_e32 v138, v109
	v_pk_mul_f32 v[108:109], v[10:11], v[142:143]
	v_pk_mul_f32 v[142:143], v[126:127], v[126:127]
	v_pk_fma_f32 v[108:109], v[108:109], v[136:137], v[134:135] op_sel_hi:[1,0,1]
	v_cvt_f32_f16_sdwa v135, v102 dst_sel:DWORD dst_unused:UNUSED_PAD src0_sel:WORD_1
	v_cvt_f32_f16_e32 v134, v102
	v_pk_fma_f32 v[124:125], v[124:125], v[136:137], v[138:139] op_sel_hi:[1,0,1]
	v_cvt_f32_f16_sdwa v139, v103 dst_sel:DWORD dst_unused:UNUSED_PAD src0_sel:WORD_1
	v_cvt_f32_f16_e32 v138, v103
	v_pk_mul_f32 v[102:103], v[22:23], v[144:145]
	v_pk_fma_f32 v[142:143], v[110:111], v[110:111], v[142:143]
	v_pk_fma_f32 v[102:103], v[102:103], v[136:137], v[134:135] op_sel_hi:[1,0,1]
	v_cvt_f32_f16_sdwa v135, v104 dst_sel:DWORD dst_unused:UNUSED_PAD src0_sel:WORD_1
	v_cvt_f32_f16_e32 v134, v104
	v_pk_fma_f32 v[118:119], v[118:119], v[136:137], v[138:139] op_sel_hi:[1,0,1]
	v_cvt_f32_f16_sdwa v139, v105 dst_sel:DWORD dst_unused:UNUSED_PAD src0_sel:WORD_1
	v_cvt_f32_f16_e32 v138, v105
	v_pk_fma_f32 v[128:129], v[128:129], v[136:137], v[152:153] op_sel_hi:[1,0,1]
	v_pk_fma_f32 v[142:143], v[112:113], v[112:113], v[142:143]
	v_pk_mul_f32 v[104:105], v[18:19], v[146:147]
	v_pk_fma_f32 v[142:143], v[128:129], v[128:129], v[142:143]
	v_pk_fma_f32 v[104:105], v[104:105], v[136:137], v[134:135] op_sel_hi:[1,0,1]
	v_cvt_f32_f16_sdwa v135, v98 dst_sel:DWORD dst_unused:UNUSED_PAD src0_sel:WORD_1
	v_cvt_f32_f16_e32 v134, v98
	v_pk_fma_f32 v[142:143], v[106:107], v[106:107], v[142:143]
	v_pk_fma_f32 v[120:121], v[120:121], v[136:137], v[138:139] op_sel_hi:[1,0,1]
	v_cvt_f32_f16_sdwa v139, v99 dst_sel:DWORD dst_unused:UNUSED_PAD src0_sel:WORD_1
	v_cvt_f32_f16_e32 v138, v99
	v_pk_fma_f32 v[142:143], v[122:123], v[122:123], v[142:143]
	v_pk_mul_f32 v[98:99], v[30:31], v[148:149]
	v_pk_fma_f32 v[142:143], v[108:109], v[108:109], v[142:143]
	v_pk_fma_f32 v[134:135], v[98:99], v[136:137], v[134:135] op_sel_hi:[1,0,1]
	v_pk_fma_f32 v[142:143], v[124:125], v[124:125], v[142:143]
	v_pk_mul_f32 v[98:99], v[32:33], v[114:115]
	v_pk_fma_f32 v[142:143], v[102:103], v[102:103], v[142:143]
	v_pk_fma_f32 v[114:115], v[98:99], v[136:137], v[138:139] op_sel_hi:[1,0,1]
	v_cvt_f32_f16_sdwa v99, v100 dst_sel:DWORD dst_unused:UNUSED_PAD src0_sel:WORD_1
	v_cvt_f32_f16_e32 v98, v100
	v_pk_fma_f32 v[142:143], v[118:119], v[118:119], v[142:143]
	v_cvt_f32_f16_sdwa v139, v101 dst_sel:DWORD dst_unused:UNUSED_PAD src0_sel:WORD_1
	v_cvt_f32_f16_e32 v138, v101
	v_pk_fma_f32 v[142:143], v[104:105], v[104:105], v[142:143]
	v_pk_mul_f32 v[100:101], v[26:27], v[150:151]
	v_pk_fma_f32 v[142:143], v[120:121], v[120:121], v[142:143]
	v_pk_fma_f32 v[140:141], v[100:101], v[136:137], v[98:99] op_sel_hi:[1,0,1]
	v_pk_fma_f32 v[142:143], v[134:135], v[134:135], v[142:143]
	v_pk_mul_f32 v[98:99], v[28:29], v[116:117]
	v_pk_fma_f32 v[142:143], v[114:115], v[114:115], v[142:143]
	v_pk_fma_f32 v[116:117], v[98:99], v[136:137], v[138:139] op_sel_hi:[1,0,1]
	v_pk_fma_f32 v[142:143], v[140:141], v[140:141], v[142:143]
	v_lshl_add_u64 v[136:137], s[12:13], 0, v[130:131]
	v_pk_fma_f32 v[142:143], v[116:117], v[116:117], v[142:143]
	v_add_co_u32_e32 v138, vcc, s9, v136
	v_add_f32_e32 v133, v142, v143
	v_mov_b32_e32 v142, 0
	v_cvt_pk_f16_f32 v98, v110, v111
	v_add_f32_dpp v133, v133, v133 quad_perm:[1,0,3,2] row_mask:0xf bank_mask:0xf bound_ctrl:1
	v_cvt_pk_f16_f32 v99, v126, v127
	v_cvt_pk_f16_f32 v100, v112, v113
	v_add_f32_dpp v133, v133, v133 quad_perm:[2,3,0,1] row_mask:0xf bank_mask:0xf bound_ctrl:1
	v_cvt_pk_f16_f32 v101, v128, v129
	v_addc_co_u32_e32 v139, vcc, 0, v137, vcc
	v_add_f32_dpp v133, v133, v133 row_half_mirror row_mask:0xf bank_mask:0xf bound_ctrl:1
	global_store_dwordx4 v[138:139], v[98:101], off offset:1024 sc1
	s_add_u32 s12, s12, s14
	v_add_f32_dpp v133, v133, v133 row_mirror row_mask:0xf bank_mask:0xf bound_ctrl:1
	v_cvt_pk_f16_f32 v98, v106, v107
	v_cvt_pk_f16_f32 v99, v122, v123
	v_mov_b32_dpp v142, v133 row_bcast:15 row_mask:0xa bank_mask:0xf
	v_add_f32_e32 v133, v133, v142
	v_mov_b32_e32 v142, 0
	v_cvt_pk_f16_f32 v100, v108, v109
	v_cvt_pk_f16_f32 v101, v124, v125
	v_mov_b32_dpp v142, v133 row_bcast:31 row_mask:0xc bank_mask:0xf
	v_add_f32_e32 v133, v133, v142
	global_store_dwordx4 v[138:139], v[98:101], off offset:2048 sc1
	v_readlane_b32 s11, v133, 63
	s_addc_u32 s13, s13, s15
	v_cvt_pk_f16_f32 v98, v102, v103
	v_fma_f32 v133, s11, v132, v1
	v_cvt_pk_f16_f32 v99, v118, v119
	v_cvt_pk_f16_f32 v100, v104, v105
	v_cvt_pk_f16_f32 v101, v120, v121
	v_rsq_f32_e32 v142, v133
	global_store_dwordx4 v[138:139], v[98:101], off offset:3072 sc1
	v_add_co_u32_e32 v138, vcc, s22, v136
	s_nop 0
	v_cvt_pk_f16_f32 v98, v134, v135
	v_cvt_pk_f16_f32 v99, v114, v115
	v_cvt_pk_f16_f32 v100, v140, v141
	v_cvt_pk_f16_f32 v101, v116, v117
	v_addc_co_u32_e32 v139, vcc, 0, v137, vcc
	global_store_dwordx4 v[138:139], v[98:101], off sc1
	s_add_u32 s16, s16, s14
	s_addc_u32 s17, s17, s15
	v_pk_mul_f32 v[98:99], v[40:41], v[126:127]
	s_nop 0
	v_pk_mul_f32 v[100:101], v[98:99], v[142:143] op_sel_hi:[1,0]
	v_pk_mul_f32 v[98:99], v[38:39], v[110:111]
	v_pk_mul_f32 v[110:111], v[36:37], v[128:129]
	v_pk_mul_f32 v[98:99], v[98:99], v[142:143] op_sel_hi:[1,0]
	v_pk_mul_f32 v[110:111], v[110:111], v[142:143] op_sel_hi:[1,0]
	v_cvt_pk_bf16_f32 v98, v98, v99
	v_cvt_pk_bf16_f32 v99, v100, v101
	v_pk_mul_f32 v[100:101], v[34:35], v[112:113]
	s_waitcnt vmcnt(9)
	v_mov_b64_e32 v[128:129], v[76:77]
	v_pk_mul_f32 v[100:101], v[100:101], v[142:143] op_sel_hi:[1,0]
	v_mov_b64_e32 v[126:127], v[74:75]
	v_cvt_pk_bf16_f32 v100, v100, v101
	v_cvt_pk_bf16_f32 v101, v110, v111
	v_add_co_u32_e32 v110, vcc, s23, v136
	s_nop 1
	v_addc_co_u32_e32 v111, vcc, 0, v137, vcc
	global_store_dwordx4 v[110:111], v[98:101], off sc1
	s_andn2_b64 vcc, exec, s[20:21]
	s_nop 0
	v_pk_mul_f32 v[98:99], v[46:47], v[106:107]
	v_pk_mul_f32 v[100:101], v[48:49], v[122:123]
	v_pk_mul_f32 v[98:99], v[98:99], v[142:143] op_sel_hi:[1,0]
	v_pk_mul_f32 v[100:101], v[100:101], v[142:143] op_sel_hi:[1,0]
	v_cvt_pk_bf16_f32 v98, v98, v99
	v_pk_mul_f32 v[106:107], v[44:45], v[124:125]
	v_cvt_pk_bf16_f32 v99, v100, v101
	v_pk_mul_f32 v[100:101], v[42:43], v[108:109]
	v_pk_mul_f32 v[106:107], v[106:107], v[142:143] op_sel_hi:[1,0]
	v_pk_mul_f32 v[100:101], v[100:101], v[142:143] op_sel_hi:[1,0]
	s_waitcnt vmcnt(8)
	v_mov_b64_e32 v[124:125], v[84:85]
	v_cvt_pk_bf16_f32 v100, v100, v101
	v_cvt_pk_bf16_f32 v101, v106, v107
	global_store_dwordx4 v[110:111], v[98:101], off offset:1024 sc1
	v_mov_b64_e32 v[108:109], v[72:73]
	v_mov_b64_e32 v[122:123], v[82:83]
	v_pk_mul_f32 v[98:99], v[54:55], v[102:103]
	v_pk_mul_f32 v[100:101], v[56:57], v[118:119]
	v_pk_mul_f32 v[98:99], v[98:99], v[142:143] op_sel_hi:[1,0]
	v_pk_mul_f32 v[100:101], v[100:101], v[142:143] op_sel_hi:[1,0]
	v_cvt_pk_bf16_f32 v98, v98, v99
	v_pk_mul_f32 v[102:103], v[52:53], v[120:121]
	v_cvt_pk_bf16_f32 v99, v100, v101
	v_pk_mul_f32 v[100:101], v[50:51], v[104:105]
	v_pk_mul_f32 v[102:103], v[102:103], v[142:143] op_sel_hi:[1,0]
	v_pk_mul_f32 v[100:101], v[100:101], v[142:143] op_sel_hi:[1,0]
	s_waitcnt vmcnt(8)
	v_mov_b64_e32 v[120:121], v[88:89]
	v_cvt_pk_bf16_f32 v100, v100, v101
	v_cvt_pk_bf16_f32 v101, v102, v103
	global_store_dwordx4 v[110:111], v[98:101], off offset:2048 sc1
	s_waitcnt vmcnt(8)
	v_pk_mul_f32 v[102:103], v[60:61], v[116:117]
	v_mov_b64_e32 v[118:119], v[86:87]
	s_waitcnt vmcnt(7)
	v_pk_mul_f32 v[98:99], v[62:63], v[134:135]
	v_pk_mul_f32 v[100:101], v[64:65], v[114:115]
	v_pk_mul_f32 v[98:99], v[98:99], v[142:143] op_sel_hi:[1,0]
	v_pk_mul_f32 v[100:101], v[100:101], v[142:143] op_sel_hi:[1,0]
	v_cvt_pk_bf16_f32 v98, v98, v99
	v_pk_mul_f32 v[102:103], v[102:103], v[142:143] op_sel_hi:[1,0]
	v_cvt_pk_bf16_f32 v99, v100, v101
	v_pk_mul_f32 v[100:101], v[58:59], v[140:141]
	v_mov_b64_e32 v[116:117], v[92:93]
	v_pk_mul_f32 v[100:101], v[100:101], v[142:143] op_sel_hi:[1,0]
	v_mov_b64_e32 v[114:115], v[90:91]
	v_cvt_pk_bf16_f32 v100, v100, v101
	v_cvt_pk_bf16_f32 v101, v102, v103
	global_store_dwordx4 v[110:111], v[98:101], off offset:3072 sc1
	v_mov_b64_e32 v[112:113], v[68:69]
	v_mov_b64_e32 v[104:105], v[80:81]
	v_mov_b64_e32 v[100:101], v[96:97]
	v_mov_b64_e32 v[110:111], v[66:67]
	v_mov_b64_e32 v[106:107], v[70:71]
	v_mov_b64_e32 v[102:103], v[78:79]
	v_mov_b64_e32 v[98:99], v[94:95]
	s_cbranch_vccz .LBB0_2916

.LBB0_2919:
	s_cmp_gt_i32 s6, 31
	s_cbranch_scc1 .LBB0_2921
	s_ashr_i32 s7, s6, 31
	s_lshl_b64 s[8:9], s[6:7], 13
	v_readlane_b32 s10, v254, 58
	v_readlane_b32 s11, v254, 59
	s_add_u32 s8, s10, s8
	s_addc_u32 s9, s11, s9
	s_add_u32 s10, s8, 0x40000
	s_addc_u32 s11, s9, 0
	v_lshlrev_b32_e32 v148, 4, v166
	s_add_u32 s12, s8, 0x80000
	v_or_b32_e32 v150, 0x400, v148
	v_or_b32_e32 v151, 0x800, v148
	v_or_b32_e32 v152, 0xc00, v148
	s_addc_u32 s13, s9, 0
	global_load_dwordx4 v[16:19], v148, s[8:9]
	global_load_dwordx4 v[20:23], v148, s[8:9] offset:1024
	global_load_dwordx4 v[28:31], v148, s[8:9] offset:2048
	global_load_dwordx4 v[32:35], v148, s[8:9] offset:3072
	v_or_b32_e32 v149, 0x1000, v148
	global_load_dwordx4 v[36:39], v148, s[10:11]
	global_load_dwordx4 v[40:43], v150, s[10:11]
	global_load_dwordx4 v[44:47], v151, s[10:11]
	global_load_dwordx4 v[48:51], v152, s[10:11]
	global_load_dwordx4 v[52:55], v149, s[8:9]
	global_load_dwordx4 v[56:59], v149, s[10:11]
	global_load_dwordx4 v[60:63], v148, s[12:13]
	s_add_u32 s14, s8, 0xc0000
	s_addc_u32 s15, s9, 0
	v_or_b32_e32 v153, 0x1400, v148
	v_or_b32_e32 v154, 0x1800, v148
	v_or_b32_e32 v155, 0x1c00, v148
	global_load_dwordx4 v[64:67], v148, s[14:15]
	global_load_dwordx4 v[68:71], v150, s[12:13]
	global_load_dwordx4 v[72:75], v150, s[14:15]
	global_load_dwordx4 v[76:79], v151, s[12:13]
	global_load_dwordx4 v[80:83], v151, s[14:15]
	global_load_dwordx4 v[84:87], v152, s[12:13]
	global_load_dwordx4 v[88:91], v152, s[14:15]
	global_load_dwordx4 v[92:95], v149, s[12:13]
	global_load_dwordx4 v[96:99], v149, s[14:15]
	global_load_dwordx4 v[100:103], v153, s[8:9]
	global_load_dwordx4 v[104:107], v153, s[10:11]
	global_load_dwordx4 v[108:111], v153, s[12:13]
	global_load_dwordx4 v[112:115], v153, s[14:15]
	global_load_dwordx4 v[116:119], v154, s[8:9]
	global_load_dwordx4 v[120:123], v154, s[10:11]
	global_load_dwordx4 v[124:127], v154, s[12:13]
	global_load_dwordx4 v[128:131], v154, s[14:15]
	global_load_dwordx4 v[132:135], v155, s[8:9]
	global_load_dwordx4 v[136:139], v155, s[10:11]
	global_load_dwordx4 v[140:143], v155, s[12:13]
	global_load_dwordx4 v[144:147], v155, s[14:15]
	s_lshl_b64 s[6:7], s[6:7], 12
	s_add_u32 s8, s6, 0x2000000
	s_addc_u32 s9, s7, 0
	v_readlane_b32 s6, v254, 54
	v_readlane_b32 s7, v254, 55
	s_add_u32 s6, s6, s8
	v_lshlrev_b32_e32 v1, 3, v166
	s_addc_u32 s7, s7, s9
	s_nop 1
	global_load_dwordx2 v[26:27], v1, s[6:7]
	global_load_dwordx2 v[14:15], v1, s[6:7] offset:512
	global_load_dwordx2 v[12:13], v1, s[6:7] offset:1024
	global_load_dwordx2 v[10:11], v1, s[6:7] offset:1536
	global_load_dwordx2 v[8:9], v1, s[6:7] offset:2048
	global_load_dwordx2 v[6:7], v1, s[6:7] offset:2560
	global_load_dwordx2 v[4:5], v1, s[6:7] offset:3072
	global_load_dwordx2 v[2:3], v1, s[6:7] offset:3584
	s_waitcnt vmcnt(35)
	v_pk_add_f32 v[18:19], v[18:19], v[38:39]
	s_waitcnt vmcnt(34)
	v_pk_add_f32 v[20:21], v[20:21], v[40:41]
	s_waitcnt vmcnt(33)
	v_pk_add_f32 v[30:31], v[30:31], v[46:47]
	v_pk_add_f32 v[28:29], v[28:29], v[44:45]
	s_waitcnt vmcnt(32)
	v_pk_add_f32 v[34:35], v[34:35], v[50:51]
	s_waitcnt vmcnt(30)
	v_pk_add_f32 v[40:41], v[52:53], v[56:57]
	s_waitcnt vmcnt(28)
	v_pk_add_f32 v[24:25], v[62:63], v[66:67]
	s_waitcnt vmcnt(26)
	v_pk_add_f32 v[44:45], v[68:69], v[72:73]
	s_waitcnt vmcnt(24)
	v_pk_add_f32 v[50:51], v[78:79], v[82:83]
	v_pk_add_f32 v[52:53], v[76:77], v[80:81]
	v_pk_add_f32 v[16:17], v[16:17], v[36:37]
	v_pk_add_f32 v[22:23], v[22:23], v[42:43]
	v_pk_add_f32 v[32:33], v[32:33], v[48:49]
	v_pk_add_f32 v[36:37], v[54:55], v[58:59]
	v_pk_add_f32 v[38:39], v[60:61], v[64:65]
	v_pk_add_f32 v[42:43], v[70:71], v[74:75]
	s_waitcnt vmcnt(22)
	v_pk_add_f32 v[54:55], v[86:87], v[90:91]
	v_pk_add_f32 v[56:57], v[84:85], v[88:89]
	v_pk_add_f32 v[46:47], v[18:19], v[24:25]
	v_pk_add_f32 v[24:25], v[20:21], v[44:45]
	v_pk_add_f32 v[18:19], v[30:31], v[50:51]
	v_pk_add_f32 v[20:21], v[28:29], v[52:53]
	global_load_dwordx4 v[50:53], v148, s[0:1]
	s_waitcnt vmcnt(21)
	v_pk_add_f32 v[58:59], v[94:95], v[98:99]
	v_pk_add_f32 v[48:49], v[16:17], v[38:39]
	v_pk_add_f32 v[22:23], v[22:23], v[42:43]
	v_pk_add_f32 v[16:17], v[34:35], v[54:55]
	v_pk_add_f32 v[38:39], v[32:33], v[56:57]
	s_waitcnt vmcnt(11)
	v_pk_add_f32 v[54:55], v[132:133], v[136:137]
	s_waitcnt vmcnt(9)
	v_pk_add_f32 v[56:57], v[140:141], v[144:145]
	v_pk_add_f32 v[30:31], v[36:37], v[58:59]
	v_pk_add_f32 v[58:59], v[54:55], v[56:57]
	v_mul_f32_e32 v54, v25, v25
	v_mul_f32_e32 v55, v23, v23
	v_pk_add_f32 v[60:61], v[92:93], v[96:97]
	v_fmac_f32_e32 v54, v24, v24
	v_fmac_f32_e32 v55, v22, v22
	v_pk_add_f32 v[32:33], v[40:41], v[60:61]
	v_add_f32_e32 v60, v54, v55
	global_load_dwordx4 v[54:57], v150, s[0:1]
	v_mul_f32_e32 v61, v21, v21
	v_mul_f32_e32 v62, v19, v19
	v_fmac_f32_e32 v61, v20, v20
	v_fmac_f32_e32 v62, v18, v18
	v_add_f32_e32 v61, v61, v62
	v_mul_f32_e32 v66, v39, v39
	v_mul_f32_e32 v67, v17, v17
	global_load_dwordx4 v[62:65], v151, s[0:1]
	v_fmac_f32_e32 v66, v38, v38
	v_fmac_f32_e32 v67, v16, v16
	v_add_f32_e32 v86, v66, v67
	v_mul_f32_e32 v66, v33, v33
	v_mul_f32_e32 v67, v31, v31
	v_fmac_f32_e32 v66, v32, v32
	v_fmac_f32_e32 v67, v30, v30
	v_pk_add_f32 v[28:29], v[102:103], v[106:107]
	v_pk_add_f32 v[36:37], v[100:101], v[104:105]
	v_pk_add_f32 v[34:35], v[110:111], v[114:115]
	v_pk_add_f32 v[40:41], v[108:109], v[112:113]
	v_add_f32_e32 v87, v66, v67
	global_load_dwordx4 v[66:69], v152, s[0:1]
	v_pk_add_f32 v[34:35], v[28:29], v[34:35]
	v_pk_add_f32 v[36:37], v[36:37], v[40:41]
	v_mul_f32_e32 v71, v35, v35
	v_mul_f32_e32 v70, v37, v37
	v_fmac_f32_e32 v70, v36, v36
	v_fmac_f32_e32 v71, v34, v34
	v_pk_add_f32 v[28:29], v[118:119], v[122:123]
	v_pk_add_f32 v[42:43], v[116:117], v[120:121]
	v_pk_add_f32 v[40:41], v[126:127], v[130:131]
	v_pk_add_f32 v[44:45], v[124:125], v[128:129]
	v_add_f32_e32 v88, v70, v71
	global_load_dwordx4 v[70:73], v149, s[0:1]
	v_pk_add_f32 v[40:41], v[28:29], v[40:41]
	v_pk_add_f32 v[42:43], v[42:43], v[44:45]
	v_pk_add_f32 v[28:29], v[134:135], v[138:139]
	v_pk_add_f32 v[44:45], v[142:143], v[146:147]
	v_mul_f32_e32 v74, v43, v43
	v_mul_f32_e32 v75, v41, v41
	v_pk_add_f32 v[44:45], v[28:29], v[44:45]
	v_fmac_f32_e32 v74, v42, v42
	v_fmac_f32_e32 v75, v40, v40
	v_add_f32_e32 v89, v74, v75
	v_mul_f32_e32 v74, v59, v59
	v_mul_f32_e32 v75, v45, v45
	v_fmac_f32_e32 v74, v58, v58
	v_fmac_f32_e32 v75, v44, v44
	v_add_f32_e32 v90, v74, v75
	global_load_dwordx4 v[74:77], v153, s[0:1]
	global_load_dwordx4 v[78:81], v154, s[0:1]
	global_load_dwordx4 v[82:85], v155, s[0:1]
	v_mul_f32_e32 v28, v49, v49
	v_mul_f32_e32 v29, v47, v47
	v_fmac_f32_e32 v29, v46, v46
	v_fmac_f32_e32 v28, v48, v48
	v_add_f32_e32 v28, v28, v29
	v_add_f32_e32 v28, v28, v60
	v_add_f32_e32 v28, v28, v61
	v_add_f32_e32 v28, v28, v86
	v_add_f32_e32 v28, v28, v87
	v_add_f32_e32 v28, v28, v88
	v_add_f32_e32 v28, v28, v89
	v_add_f32_e32 v28, v28, v90
	v_mov_b32_e32 v29, 0
	v_mov_b32_e32 v91, 0x358637bd
	v_add_f32_dpp v28, v28, v28 quad_perm:[1,0,3,2] row_mask:0xf bank_mask:0xf bound_ctrl:1
	v_mov_b32_e32 v98, 0x3a000000
	s_waitcnt vmcnt(15)
	v_cvt_f32_f16_e32 v60, v27
	v_add_f32_dpp v28, v28, v28 quad_perm:[2,3,0,1] row_mask:0xf bank_mask:0xf bound_ctrl:1
	v_cvt_f32_f16_sdwa v61, v27 dst_sel:DWORD dst_unused:UNUSED_PAD src0_sel:WORD_1
	s_waitcnt vmcnt(7)
	v_pk_mul_f32 v[46:47], v[46:47], v[52:53]
	v_add_f32_dpp v28, v28, v28 row_half_mirror row_mask:0xf bank_mask:0xf bound_ctrl:1
	v_cvt_f32_f16_e32 v86, v26
	v_cvt_f32_f16_sdwa v87, v26 dst_sel:DWORD dst_unused:UNUSED_PAD src0_sel:WORD_1
	v_add_f32_dpp v28, v28, v28 row_mirror row_mask:0xf bank_mask:0xf bound_ctrl:1
	v_pk_mul_f32 v[48:49], v[48:49], v[50:51]
	v_mov_b32_e32 v99, 0
	v_mov_b32_dpp v29, v28 row_bcast:15 row_mask:0xa bank_mask:0xf
	v_add_f32_e32 v28, v28, v29
	v_mov_b32_e32 v29, 0
	s_waitcnt vmcnt(6)
	v_pk_mul_f32 v[22:23], v[22:23], v[56:57]
	v_mov_b32_dpp v29, v28 row_bcast:31 row_mask:0xc bank_mask:0xf
	v_add_f32_e32 v28, v28, v29
	v_pk_mul_f32 v[24:25], v[24:25], v[54:55]
	v_readlane_b32 s10, v28, 63
	s_waitcnt vmcnt(5)
	v_pk_mul_f32 v[18:19], v[18:19], v[64:65]
	v_fma_f32 v28, s10, v98, v91
	v_rsq_f32_e32 v28, v28
	v_pk_mul_f32 v[20:21], v[20:21], v[62:63]
	v_mul_f32_e32 v90, 0.5, v28
	v_pk_fma_f32 v[60:61], v[46:47], v[90:91], v[60:61] op_sel_hi:[1,0,1]
	v_cvt_f32_f16_e32 v46, v14
	v_cvt_f32_f16_sdwa v47, v14 dst_sel:DWORD dst_unused:UNUSED_PAD src0_sel:WORD_1
	v_cvt_f32_f16_e32 v14, v15
	v_cvt_f32_f16_sdwa v15, v15 dst_sel:DWORD dst_unused:UNUSED_PAD src0_sel:WORD_1
	v_pk_fma_f32 v[92:93], v[48:49], v[90:91], v[86:87] op_sel_hi:[1,0,1]
	global_load_dwordx4 v[26:29], v148, s[4:5]
	v_pk_fma_f32 v[96:97], v[24:25], v[90:91], v[46:47] op_sel_hi:[1,0,1]
	v_pk_fma_f32 v[94:95], v[22:23], v[90:91], v[14:15] op_sel_hi:[1,0,1]
	v_cvt_f32_f16_e32 v14, v12
	v_cvt_f32_f16_sdwa v15, v12 dst_sel:DWORD dst_unused:UNUSED_PAD src0_sel:WORD_1
	v_cvt_f32_f16_e32 v12, v13
	v_cvt_f32_f16_sdwa v13, v13 dst_sel:DWORD dst_unused:UNUSED_PAD src0_sel:WORD_1
	global_load_dwordx4 v[86:89], v150, s[4:5]
	global_load_dwordx4 v[22:25], v151, s[4:5]
	v_pk_fma_f32 v[62:63], v[20:21], v[90:91], v[14:15] op_sel_hi:[1,0,1]
	v_pk_fma_f32 v[56:57], v[18:19], v[90:91], v[12:13] op_sel_hi:[1,0,1]
	v_cvt_f32_f16_e32 v12, v10
	v_cvt_f32_f16_sdwa v13, v10 dst_sel:DWORD dst_unused:UNUSED_PAD src0_sel:WORD_1
	v_cvt_f32_f16_e32 v10, v11
	v_cvt_f32_f16_sdwa v11, v11 dst_sel:DWORD dst_unused:UNUSED_PAD src0_sel:WORD_1
	s_waitcnt vmcnt(7)
	v_pk_mul_f32 v[14:15], v[16:17], v[68:69]
	v_pk_mul_f32 v[16:17], v[38:39], v[66:67]
	global_load_dwordx4 v[18:21], v152, s[4:5]
	v_pk_fma_f32 v[52:53], v[14:15], v[90:91], v[10:11] op_sel_hi:[1,0,1]
	v_cvt_f32_f16_e32 v10, v8
	v_cvt_f32_f16_sdwa v11, v8 dst_sel:DWORD dst_unused:UNUSED_PAD src0_sel:WORD_1
	v_cvt_f32_f16_e32 v8, v9
	v_cvt_f32_f16_sdwa v9, v9 dst_sel:DWORD dst_unused:UNUSED_PAD src0_sel:WORD_1
	v_pk_fma_f32 v[54:55], v[16:17], v[90:91], v[12:13] op_sel_hi:[1,0,1]
	s_waitcnt vmcnt(7)
	v_pk_mul_f32 v[12:13], v[30:31], v[72:73]
	v_pk_mul_f32 v[30:31], v[32:33], v[70:71]
	v_pk_fma_f32 v[48:49], v[12:13], v[90:91], v[8:9] op_sel_hi:[1,0,1]
	v_cvt_f32_f16_e32 v8, v6
	v_cvt_f32_f16_sdwa v9, v6 dst_sel:DWORD dst_unused:UNUSED_PAD src0_sel:WORD_1
	v_cvt_f32_f16_e32 v6, v7
	v_cvt_f32_f16_sdwa v7, v7 dst_sel:DWORD dst_unused:UNUSED_PAD src0_sel:WORD_1
	v_pk_fma_f32 v[50:51], v[30:31], v[90:91], v[10:11] op_sel_hi:[1,0,1]
	s_waitcnt vmcnt(6)
	v_pk_mul_f32 v[30:31], v[34:35], v[76:77]
	v_pk_mul_f32 v[32:33], v[36:37], v[74:75]
	v_pk_fma_f32 v[38:39], v[30:31], v[90:91], v[6:7] op_sel_hi:[1,0,1]
	v_cvt_f32_f16_e32 v30, v4
	v_cvt_f32_f16_sdwa v31, v4 dst_sel:DWORD dst_unused:UNUSED_PAD src0_sel:WORD_1
	v_cvt_f32_f16_e32 v4, v5
	v_cvt_f32_f16_sdwa v5, v5 dst_sel:DWORD dst_unused:UNUSED_PAD src0_sel:WORD_1
	v_pk_fma_f32 v[46:47], v[32:33], v[90:91], v[8:9] op_sel_hi:[1,0,1]
	s_waitcnt vmcnt(5)
	v_pk_mul_f32 v[32:33], v[40:41], v[80:81]
	v_pk_mul_f32 v[34:35], v[42:43], v[78:79]
	global_load_dwordx4 v[14:17], v149, s[4:5]
	global_load_dwordx4 v[10:13], v153, s[4:5]
	global_load_dwordx4 v[6:9], v154, s[4:5]
	v_pk_fma_f32 v[32:33], v[32:33], v[90:91], v[4:5] op_sel_hi:[1,0,1]
	v_pk_fma_f32 v[36:37], v[34:35], v[90:91], v[30:31] op_sel_hi:[1,0,1]
	v_cvt_f32_f16_e32 v34, v2
	v_cvt_f32_f16_sdwa v35, v2 dst_sel:DWORD dst_unused:UNUSED_PAD src0_sel:WORD_1
	v_cvt_f32_f16_e32 v30, v3
	v_cvt_f32_f16_sdwa v31, v3 dst_sel:DWORD dst_unused:UNUSED_PAD src0_sel:WORD_1
	global_load_dwordx4 v[2:5], v155, s[4:5]
	s_waitcnt vmcnt(8)
	v_pk_mul_f32 v[40:41], v[44:45], v[84:85]
	v_cvt_f16_f32_e32 v44, v92
	v_cvt_f16_f32_sdwa v45, v93 dst_sel:WORD_1 dst_unused:UNUSED_PAD src0_sel:DWORD
	v_pk_mul_f32 v[42:43], v[58:59], v[82:83]
	v_pk_fma_f32 v[30:31], v[40:41], v[90:91], v[30:31] op_sel_hi:[1,0,1]
	v_pk_fma_f32 v[34:35], v[42:43], v[90:91], v[34:35] op_sel_hi:[1,0,1]
	v_cvt_f16_f32_e32 v41, v60
	v_cvt_f16_f32_sdwa v42, v61 dst_sel:WORD_1 dst_unused:UNUSED_PAD src0_sel:DWORD
	v_or_b32_e32 v40, v45, v44
	v_cvt_f16_f32_e32 v43, v96
	v_cvt_f16_f32_sdwa v44, v97 dst_sel:WORD_1 dst_unused:UNUSED_PAD src0_sel:DWORD
	v_cvt_f16_f32_e32 v45, v94
	v_cvt_f16_f32_sdwa v58, v95 dst_sel:WORD_1 dst_unused:UNUSED_PAD src0_sel:DWORD
	v_or_b32_e32 v41, v42, v41
	global_store_dwordx2 v1, v[40:41], s[6:7] sc1
	v_or_b32_e32 v40, v44, v43
	v_or_b32_e32 v41, v58, v45
	global_store_dwordx2 v1, v[40:41], s[6:7] offset:512 sc1
	v_cvt_f16_f32_e32 v40, v62
	v_cvt_f16_f32_sdwa v41, v63 dst_sel:WORD_1 dst_unused:UNUSED_PAD src0_sel:DWORD
	v_cvt_f16_f32_e32 v42, v56
	v_cvt_f16_f32_sdwa v43, v57 dst_sel:WORD_1 dst_unused:UNUSED_PAD src0_sel:DWORD
	v_cvt_f16_f32_e32 v44, v54
	v_cvt_f16_f32_sdwa v45, v55 dst_sel:WORD_1 dst_unused:UNUSED_PAD src0_sel:DWORD
	v_or_b32_e32 v40, v41, v40
	v_or_b32_e32 v41, v43, v42
	global_store_dwordx2 v1, v[40:41], s[6:7] offset:1024 sc1
	v_cvt_f16_f32_e32 v41, v52
	v_cvt_f16_f32_sdwa v42, v53 dst_sel:WORD_1 dst_unused:UNUSED_PAD src0_sel:DWORD
	v_or_b32_e32 v40, v45, v44
	v_cvt_f16_f32_e32 v43, v50
	v_cvt_f16_f32_sdwa v44, v51 dst_sel:WORD_1 dst_unused:UNUSED_PAD src0_sel:DWORD
	v_cvt_f16_f32_e32 v45, v48
	v_cvt_f16_f32_sdwa v58, v49 dst_sel:WORD_1 dst_unused:UNUSED_PAD src0_sel:DWORD
	v_or_b32_e32 v41, v42, v41
	global_store_dwordx2 v1, v[40:41], s[6:7] offset:1536 sc1
	v_or_b32_e32 v40, v44, v43
	v_or_b32_e32 v41, v58, v45
	global_store_dwordx2 v1, v[40:41], s[6:7] offset:2048 sc1
	v_cvt_f16_f32_e32 v40, v46
	v_cvt_f16_f32_sdwa v41, v47 dst_sel:WORD_1 dst_unused:UNUSED_PAD src0_sel:DWORD
	v_cvt_f16_f32_e32 v42, v38
	v_cvt_f16_f32_sdwa v43, v39 dst_sel:WORD_1 dst_unused:UNUSED_PAD src0_sel:DWORD
	v_cvt_f16_f32_e32 v44, v36
	v_cvt_f16_f32_sdwa v45, v37 dst_sel:WORD_1 dst_unused:UNUSED_PAD src0_sel:DWORD
	v_or_b32_e32 v40, v41, v40
	v_or_b32_e32 v41, v43, v42
	global_store_dwordx2 v1, v[40:41], s[6:7] offset:2560 sc1
	v_cvt_f16_f32_e32 v41, v32
	v_cvt_f16_f32_sdwa v42, v33 dst_sel:WORD_1 dst_unused:UNUSED_PAD src0_sel:DWORD
	v_or_b32_e32 v40, v45, v44
	v_cvt_f16_f32_e32 v43, v34
	v_cvt_f16_f32_sdwa v44, v35 dst_sel:WORD_1 dst_unused:UNUSED_PAD src0_sel:DWORD
	v_cvt_f16_f32_e32 v45, v30
	v_cvt_f16_f32_sdwa v58, v31 dst_sel:WORD_1 dst_unused:UNUSED_PAD src0_sel:DWORD
	v_or_b32_e32 v41, v42, v41
	global_store_dwordx2 v1, v[40:41], s[6:7] offset:3072 sc1
	v_or_b32_e32 v40, v44, v43
	v_or_b32_e32 v41, v58, v45
	v_mov_b32_e32 v42, v93
	v_mov_b32_e32 v43, v97
	global_store_dwordx2 v1, v[40:41], s[6:7] offset:3584 sc1
	v_mov_b32_e32 v40, v92
	v_mov_b32_e32 v41, v96
	v_pk_mul_f32 v[42:43], v[42:43], v[42:43]
	v_mov_b32_e32 v44, v61
	v_mov_b32_e32 v45, v95
	v_pk_fma_f32 v[40:41], v[40:41], v[40:41], v[42:43]
	v_mov_b32_e32 v42, v60
	v_mov_b32_e32 v43, v94
	v_pk_mul_f32 v[44:45], v[44:45], v[44:45]
	s_waitcnt vmcnt(15)
	v_pk_mul_f32 v[26:27], v[26:27], v[92:93]
	v_pk_fma_f32 v[42:43], v[42:43], v[42:43], v[44:45]
	v_pk_mul_f32 v[44:45], v[62:63], v[62:63]
	v_pk_add_f32 v[40:41], v[40:41], v[42:43]
	v_pk_mul_f32 v[42:43], v[56:57], v[56:57]
	v_pk_add_f32 v[40:41], v[40:41], v[40:41] op_sel_hi:[0,1]
	v_pk_mov_b32 v[58:59], v[44:45], v[42:43] op_sel:[1,0]
	v_mov_b32_e32 v45, v43
	v_mul_f32_e32 v40, v54, v54
	v_pk_add_f32 v[42:43], v[58:59], v[44:45]
	v_pk_fma_f32 v[44:45], v[54:55], v[54:55], v[40:41] op_sel_hi:[1,1,0]
	v_mul_f32_e32 v40, v52, v52
	v_pk_add_f32 v[42:43], v[42:43], v[42:43] op_sel_hi:[0,1]
	v_pk_fma_f32 v[58:59], v[52:53], v[52:53], v[40:41] op_sel_hi:[1,1,0]
	v_mul_f32_e32 v44, v50, v50
	v_mul_f32_e32 v58, v51, v51
	v_mul_f32_e32 v42, v48, v48
	v_mul_f32_e32 v40, v49, v49
	v_pk_add_f32 v[44:45], v[44:45], v[58:59]
	v_pk_add_f32 v[40:41], v[42:43], v[40:41]
	v_pk_mul_f32 v[42:43], v[38:39], v[38:39]
	v_pk_add_f32 v[40:41], v[44:45], v[40:41]
	v_pk_mul_f32 v[44:45], v[46:47], v[46:47]
	v_pk_add_f32 v[40:41], v[40:41], v[40:41] op_sel_hi:[0,1]
	v_pk_mov_b32 v[58:59], v[44:45], v[42:43] op_sel:[1,0]
	v_mov_b32_e32 v45, v43
	v_mul_f32_e32 v40, v36, v36
	v_pk_add_f32 v[42:43], v[58:59], v[44:45]
	v_pk_fma_f32 v[44:45], v[36:37], v[36:37], v[40:41] op_sel_hi:[1,1,0]
	v_mul_f32_e32 v40, v32, v32
	v_pk_add_f32 v[42:43], v[42:43], v[42:43] op_sel_hi:[0,1]
	v_pk_fma_f32 v[58:59], v[32:33], v[32:33], v[40:41] op_sel_hi:[1,1,0]
	v_mul_f32_e32 v44, v34, v34
	v_mul_f32_e32 v58, v35, v35
	v_mul_f32_e32 v42, v30, v30
	v_mul_f32_e32 v40, v31, v31
	v_pk_add_f32 v[44:45], v[44:45], v[58:59]
	v_pk_add_f32 v[40:41], v[42:43], v[40:41]
	v_pk_mul_f32 v[28:29], v[28:29], v[60:61]
	v_pk_add_f32 v[40:41], v[44:45], v[40:41]
	s_waitcnt vmcnt(13)
	v_pk_mul_f32 v[22:23], v[22:23], v[62:63]
	v_add_f32_e32 v40, v40, v41
	v_mov_b32_e32 v41, 0
	s_waitcnt vmcnt(12)
	v_pk_mul_f32 v[18:19], v[18:19], v[54:55]
	v_add_f32_dpp v40, v40, v40 quad_perm:[1,0,3,2] row_mask:0xf bank_mask:0xf bound_ctrl:1
	s_waitcnt vmcnt(11)
	v_pk_mul_f32 v[14:15], v[14:15], v[50:51]
	s_waitcnt vmcnt(10)
	v_pk_mul_f32 v[10:11], v[10:11], v[46:47]
	v_add_f32_dpp v40, v40, v40 quad_perm:[2,3,0,1] row_mask:0xf bank_mask:0xf bound_ctrl:1
	s_waitcnt vmcnt(9)
	v_pk_mul_f32 v[6:7], v[6:7], v[36:37]
	s_waitcnt vmcnt(8)
	v_pk_mul_f32 v[2:3], v[34:35], v[2:3]
	v_add_f32_dpp v40, v40, v40 row_half_mirror row_mask:0xf bank_mask:0xf bound_ctrl:1
	v_pk_mul_f32 v[42:43], v[86:87], v[96:97]
	v_pk_mul_f32 v[44:45], v[88:89], v[94:95]
	v_add_f32_dpp v40, v40, v40 row_mirror row_mask:0xf bank_mask:0xf bound_ctrl:1
	v_pk_mul_f32 v[24:25], v[24:25], v[56:57]
	v_pk_mul_f32 v[20:21], v[20:21], v[52:53]
	v_mov_b32_dpp v41, v40 row_bcast:15 row_mask:0xa bank_mask:0xf
	v_add_f32_e32 v40, v40, v41
	v_pk_mul_f32 v[16:17], v[16:17], v[48:49]
	v_pk_mul_f32 v[12:13], v[12:13], v[38:39]
	v_mov_b32_dpp v99, v40 row_bcast:31 row_mask:0xc bank_mask:0xf
	v_add_f32_e32 v40, v40, v99
	v_pk_mul_f32 v[8:9], v[8:9], v[32:33]
	v_readlane_b32 s6, v40, 63
	v_pk_mul_f32 v[4:5], v[30:31], v[4:5]
	s_nop 0
	v_fmac_f32_e32 v91, s6, v98
	v_rsq_f32_e32 v40, v91
	v_readlane_b32 s6, v254, 60
	v_readlane_b32 s7, v254, 61
	s_add_u32 s6, s6, s8
	v_pk_mul_f32 v[26:27], v[26:27], v[40:41] op_sel_hi:[1,0]
	s_addc_u32 s7, s7, s9
	v_pk_mul_f32 v[28:29], v[28:29], v[40:41] op_sel_hi:[1,0]
	v_cvt_pk_bf16_f32 v26, v26, v27
	v_pk_mul_f32 v[22:23], v[22:23], v[40:41] op_sel_hi:[1,0]
	v_cvt_pk_bf16_f32 v27, v28, v29
	v_pk_mul_f32 v[18:19], v[18:19], v[40:41] op_sel_hi:[1,0]
	v_pk_mul_f32 v[14:15], v[14:15], v[40:41] op_sel_hi:[1,0]
	v_pk_mul_f32 v[10:11], v[10:11], v[40:41] op_sel_hi:[1,0]
	v_pk_mul_f32 v[6:7], v[6:7], v[40:41] op_sel_hi:[1,0]
	v_pk_mul_f32 v[2:3], v[2:3], v[40:41] op_sel_hi:[1,0]
	v_pk_mul_f32 v[44:45], v[44:45], v[40:41] op_sel_hi:[1,0]
	v_pk_mul_f32 v[42:43], v[42:43], v[40:41] op_sel_hi:[1,0]
	global_store_dwordx2 v1, v[26:27], s[6:7] sc1
	v_cvt_pk_bf16_f32 v26, v42, v43
	v_cvt_pk_bf16_f32 v27, v44, v45
	global_store_dwordx2 v1, v[26:27], s[6:7] offset:512 sc1
	v_pk_mul_f32 v[24:25], v[24:25], v[40:41] op_sel_hi:[1,0]
	v_cvt_pk_bf16_f32 v22, v22, v23
	v_pk_mul_f32 v[20:21], v[20:21], v[40:41] op_sel_hi:[1,0]
	v_cvt_pk_bf16_f32 v23, v24, v25
	global_store_dwordx2 v1, v[22:23], s[6:7] offset:1024 sc1
	v_cvt_pk_bf16_f32 v18, v18, v19
	v_cvt_pk_bf16_f32 v19, v20, v21
	global_store_dwordx2 v1, v[18:19], s[6:7] offset:1536 sc1
	v_pk_mul_f32 v[16:17], v[16:17], v[40:41] op_sel_hi:[1,0]
	v_cvt_pk_bf16_f32 v14, v14, v15
	v_pk_mul_f32 v[12:13], v[12:13], v[40:41] op_sel_hi:[1,0]
	v_cvt_pk_bf16_f32 v15, v16, v17
	global_store_dwordx2 v1, v[14:15], s[6:7] offset:2048 sc1
	v_cvt_pk_bf16_f32 v10, v10, v11
	v_cvt_pk_bf16_f32 v11, v12, v13
	global_store_dwordx2 v1, v[10:11], s[6:7] offset:2560 sc1
	v_pk_mul_f32 v[8:9], v[8:9], v[40:41] op_sel_hi:[1,0]
	v_cvt_pk_bf16_f32 v6, v6, v7
	v_pk_mul_f32 v[4:5], v[4:5], v[40:41] op_sel_hi:[1,0]
	v_cvt_pk_bf16_f32 v7, v8, v9
	global_store_dwordx2 v1, v[6:7], s[6:7] offset:3072 sc1
	v_cvt_pk_bf16_f32 v2, v2, v3
	v_cvt_pk_bf16_f32 v3, v4, v5
	global_store_dwordx2 v1, v[2:3], s[6:7] offset:3584 sc1

.LBB0_2922:
	s_cbranch_execz .LBB0_2929
	s_ashr_i32 s7, s90, 5
	s_abs_i32 s6, s7
	v_cvt_f32_u32_e32 v1, s6
	s_sub_i32 s10, 0, s6
	s_abs_i32 s8, s62
	s_xor_b32 s9, s62, s7
	v_rcp_iflag_f32_e32 v1, v1
	s_ashr_i32 s9, s9, 31
	v_mul_f32_e32 v1, 0x4f7ffffe, v1
	v_cvt_u32_f32_e32 v1, v1
	s_nop 0
	v_readfirstlane_b32 s11, v1
	s_mul_i32 s10, s10, s11
	s_mul_hi_u32 s10, s11, s10
	s_add_i32 s11, s11, s10
	s_mul_hi_u32 s10, s8, s11
	s_mul_i32 s11, s10, s6
	s_sub_i32 s8, s8, s11
	s_add_i32 s12, s10, 1
	s_sub_i32 s11, s8, s6
	s_cmp_ge_u32 s8, s6
	s_cselect_b32 s10, s12, s10
	s_cselect_b32 s8, s11, s8
	s_add_i32 s11, s10, 1
	s_cmp_ge_u32 s8, s6
	s_cselect_b32 s6, s11, s10
	s_xor_b32 s6, s6, s9
	s_sub_i32 s6, s6, s9
	s_mul_i32 s7, s6, s7
	s_sub_i32 s7, s62, s7
	s_cmp_lg_u32 s7, 0
	s_cbranch_scc1 .LBB0_2929
	s_ashr_i32 s7, s6, 31
	s_lshl_b64 s[8:9], s[6:7], 13
	v_readlane_b32 s10, v254, 58
	v_readlane_b32 s11, v254, 59
	s_add_u32 s8, s10, s8
	s_addc_u32 s9, s11, s9
	v_mov_b32_e32 v13, 0
	v_lshlrev_b32_e32 v12, 4, v0
	v_lshl_add_u64 v[2:3], s[8:9], 0, v[12:13]
	v_add_co_u32_e32 v4, vcc, 0x40000, v2
	s_waitcnt vmcnt(0)
	v_mov_b32_e32 v18, v186
	v_mov_b32_e32 v19, v187
	v_mov_b32_e32 v20, v188
	v_mov_b32_e32 v21, v189
	s_nop 0
	v_addc_co_u32_e32 v5, vcc, 0, v3, vcc
	v_add_co_u32_e32 v6, vcc, 0x80000, v2
	s_addk_i32 s6, 0x2000
	s_nop 0
	v_addc_co_u32_e32 v7, vcc, 0, v3, vcc
	v_add_co_u32_e32 v2, vcc, 0xc0000, v2
	v_mov_b32_e32 v22, v190
	v_mov_b32_e32 v23, v191
	v_mov_b32_e32 v24, v192
	v_mov_b32_e32 v25, v193
	v_mov_b32_e32 v26, v194
	v_mov_b32_e32 v27, v195
	v_mov_b32_e32 v28, v196
	v_mov_b32_e32 v29, v197
	v_addc_co_u32_e32 v3, vcc, 0, v3, vcc
	v_mov_b32_e32 v30, v198
	v_mov_b32_e32 v31, v199
	v_mov_b32_e32 v32, v200
	v_mov_b32_e32 v33, v201
	s_ashr_i32 s7, s6, 31
	s_lshl_b64 s[8:9], s[6:7], 12
	v_readlane_b32 s10, v254, 54
	v_readlane_b32 s11, v254, 55
	s_add_u32 s8, s10, s8
	s_addc_u32 s9, s11, s9
	v_lshlrev_b32_e32 v10, 3, v0
	v_mov_b32_e32 v6, v174
	v_mov_b32_e32 v7, v175
	v_mov_b32_e32 v8, v176
	v_mov_b32_e32 v9, v177
	v_mov_b32_e32 v2, v170
	v_mov_b32_e32 v3, v171
	v_mov_b32_e32 v4, v172
	v_mov_b32_e32 v5, v173
	v_mov_b32_e32 v14, v182
	v_mov_b32_e32 v15, v183
	v_mov_b32_e32 v11, v13
	v_lshl_add_u64 v[16:17], s[8:9], 0, v[10:11]
	v_mov_b32_e32 v1, v13
	v_mov_b32_e32 v12, v13
	v_cmp_eq_u32_e32 vcc, 0, v166
	s_waitcnt vmcnt(5)
	v_pk_add_f32 v[20:21], v[20:21], v[24:25]
	v_pk_add_f32 v[22:23], v[18:19], v[22:23]
	s_waitcnt vmcnt(3)
	v_pk_add_f32 v[18:19], v[28:29], v[32:33]
	v_pk_add_f32 v[24:25], v[26:27], v[30:31]
	v_pk_add_f32 v[18:19], v[20:21], v[18:19]
	v_pk_add_f32 v[20:21], v[22:23], v[24:25]
	v_mul_f32_e32 v22, v19, v19
	v_mul_f32_e32 v11, v21, v21
	v_fmac_f32_e32 v11, v20, v20
	v_fmac_f32_e32 v22, v18, v18
	v_add_f32_e32 v11, v11, v22
	s_nop 1
	v_add_f32_dpp v11, v11, v11 quad_perm:[1,0,3,2] row_mask:0xf bank_mask:0xf bound_ctrl:1
	s_nop 1
	v_add_f32_dpp v11, v11, v11 quad_perm:[2,3,0,1] row_mask:0xf bank_mask:0xf bound_ctrl:1
	s_nop 1
	v_add_f32_dpp v11, v11, v11 row_half_mirror row_mask:0xf bank_mask:0xf bound_ctrl:1
	s_nop 1
	v_add_f32_dpp v11, v11, v11 row_mirror row_mask:0xf bank_mask:0xf bound_ctrl:1
	s_nop 1
	v_mov_b32_dpp v1, v11 row_bcast:15 row_mask:0xa bank_mask:0xf
	v_add_f32_e32 v1, v11, v1
	s_nop 1
	v_mov_b32_dpp v12, v1 row_bcast:31 row_mask:0xc bank_mask:0xf
	v_add_f32_e32 v1, v1, v12
	s_nop 0
	v_readlane_b32 s4, v1, 63
	s_and_saveexec_b64 s[0:1], vcc
	s_lshl_b32 s5, s96, 2
	s_add_i32 s5, s5, 0
	v_mov_b32_e32 v1, s5
	v_mov_b32_e32 v11, s4
	ds_write_b32 v1, v11
	s_or_b64 exec, exec, s[0:1]
	s_waitcnt lgkmcnt(0)
	s_barrier
	ds_read_b128 v[22:25], v13
	ds_read_b128 v[26:29], v13 offset:16
	s_waitcnt vmcnt(2)
	v_pk_mul_f32 v[6:7], v[6:7], v[20:21]
	v_pk_mul_f32 v[8:9], v[8:9], v[18:19]
	s_lshl_b64 s[0:1], s[6:7], 11
	s_waitcnt lgkmcnt(1)
	v_add_f32_e32 v1, 0, v22
	v_add_f32_e32 v1, v1, v23
	v_add_f32_e32 v1, v1, v24
	v_add_f32_e32 v1, v1, v25
	s_waitcnt lgkmcnt(0)
	v_add_f32_e32 v1, v1, v26
	v_add_f32_e32 v1, v1, v27
	v_add_f32_e32 v1, v1, v28
	v_add_f32_e32 v11, v1, v29
	v_mov_b32_e32 v1, 0x358637bd
	v_fmamk_f32 v11, v11, 0x3a000000, v1
	v_rsq_f32_e32 v11, v11
	s_waitcnt vmcnt(0)
	v_cvt_f32_f16_sdwa v23, v14 dst_sel:DWORD dst_unused:UNUSED_PAD src0_sel:WORD_1
	v_cvt_f32_f16_e32 v22, v14
	v_cvt_f32_f16_sdwa v25, v15 dst_sel:DWORD dst_unused:UNUSED_PAD src0_sel:WORD_1
	v_cvt_f32_f16_e32 v24, v15
	v_mul_f32_e32 v12, 0.5, v11
	v_pk_fma_f32 v[6:7], v[6:7], v[12:13], v[22:23] op_sel_hi:[1,0,1]
	v_pk_fma_f32 v[8:9], v[8:9], v[12:13], v[24:25] op_sel_hi:[1,0,1]
	v_cvt_f16_f32_e32 v11, v6
	v_cvt_f16_f32_sdwa v12, v7 dst_sel:WORD_1 dst_unused:UNUSED_PAD src0_sel:DWORD
	v_cvt_f16_f32_e32 v15, v8
	v_cvt_f16_f32_sdwa v18, v9 dst_sel:WORD_1 dst_unused:UNUSED_PAD src0_sel:DWORD
	v_or_b32_e32 v14, v12, v11
	v_mul_f32_e32 v11, v7, v7
	v_mul_f32_e32 v12, v9, v9
	v_fmac_f32_e32 v11, v6, v6
	v_fmac_f32_e32 v12, v8, v8
	v_add_f32_e32 v11, v11, v12
	v_mov_b32_e32 v12, 0
	v_or_b32_e32 v15, v18, v15
	v_add_f32_dpp v11, v11, v11 quad_perm:[1,0,3,2] row_mask:0xf bank_mask:0xf bound_ctrl:1
	global_store_dwordx2 v[16:17], v[14:15], off sc1
	s_nop 0
	v_add_f32_dpp v11, v11, v11 quad_perm:[2,3,0,1] row_mask:0xf bank_mask:0xf bound_ctrl:1
	s_nop 1
	v_add_f32_dpp v11, v11, v11 row_half_mirror row_mask:0xf bank_mask:0xf bound_ctrl:1
	s_nop 1
	v_add_f32_dpp v11, v11, v11 row_mirror row_mask:0xf bank_mask:0xf bound_ctrl:1
	s_nop 1
	v_mov_b32_dpp v12, v11 row_bcast:15 row_mask:0xa bank_mask:0xf
	v_add_f32_e32 v11, v11, v12
	s_nop 1
	v_mov_b32_dpp v13, v11 row_bcast:31 row_mask:0xc bank_mask:0xf
	v_add_f32_e32 v11, v11, v13
	s_nop 0
	v_readlane_b32 s6, v11, 63
	s_and_saveexec_b64 s[4:5], vcc
	s_lshl_b32 s7, s96, 2
	s_add_i32 s7, s7, 0
	v_mov_b32_e32 v11, s7
	v_mov_b32_e32 v12, s6
	ds_write_b32 v11, v12 offset:32
	s_or_b64 exec, exec, s[4:5]
	v_mov_b32_e32 v11, 0
	s_waitcnt lgkmcnt(0)
	s_barrier
	ds_read_b128 v[12:15], v11 offset:32
	ds_read_b128 v[16:19], v11 offset:48
	s_lshl_b64 s[0:1], s[0:1], 1
	v_readlane_b32 s4, v254, 60
	v_pk_mul_f32 v[2:3], v[2:3], v[6:7]
	s_waitcnt lgkmcnt(1)
	v_add_f32_e32 v11, 0, v12
	v_add_f32_e32 v11, v11, v13
	v_add_f32_e32 v11, v11, v14
	v_add_f32_e32 v11, v11, v15
	s_waitcnt lgkmcnt(0)
	v_add_f32_e32 v11, v11, v16
	v_add_f32_e32 v11, v11, v17
	v_add_f32_e32 v11, v11, v18
	v_add_f32_e32 v11, v11, v19
	v_fmac_f32_e32 v1, 0x3a000000, v11
	v_rsq_f32_e32 v12, v1
	v_readlane_b32 s5, v254, 61
	s_add_u32 s0, s4, s0
	v_pk_mul_f32 v[4:5], v[4:5], v[8:9]
	v_pk_mul_f32 v[2:3], v[2:3], v[12:13] op_sel_hi:[1,0]
	s_addc_u32 s1, s5, s1
	v_pk_mul_f32 v[4:5], v[4:5], v[12:13] op_sel_hi:[1,0]
	v_cvt_pk_bf16_f32 v2, v2, v3
	s_nop 0
	v_cvt_pk_bf16_f32 v3, v4, v5
	global_store_dwordx2 v10, v[2:3], s[0:1] sc1
	s_barrier

.LBB0_3288:
	s_or_b64 exec, exec, s[24:25]
	v_div_scale_f32 v140, s[24:25], s15, s15, v139
	v_rcp_f32_e32 v141, v140
	v_mov_b32_e32 v142, s15
	v_div_scale_f32 v142, vcc, s28, v142, s28
	v_fma_f32 v143, -v140, v141, 1.0
	v_fmac_f32_e32 v141, v143, v141
	v_mul_f32_e32 v143, v142, v141
	v_fma_f32 v144, -v140, v143, v142
	v_fmac_f32_e32 v143, v144, v141
	v_fma_f32 v140, -v140, v143, v142
	v_div_fmas_f32 v140, v140, v141, v143
	v_div_fixup_f32 v140, v140, s15, v139
	v_cndmask_b32_e64 v140, 0, v140, s[4:5]
	v_fmaak_f32 v128, v128, v140, 0x4b400000
	v_fmaak_f32 v129, v129, v140, 0x4b400000
	v_fmaak_f32 v122, v122, v140, 0x4b400000
	v_perm_b32 v128, v129, v128, s29
	v_fmaak_f32 v123, v123, v140, 0x4b400000
	v_perm_b32 v122, v122, v128, s30
	v_perm_b32 v122, v123, v122, s31
	v_fmaak_f32 v123, v124, v140, 0x4b400000
	v_fmaak_f32 v124, v125, v140, 0x4b400000
	v_fmaak_f32 v114, v114, v140, 0x4b400000
	v_fmaak_f32 v115, v115, v140, 0x4b400000
	v_fmaak_f32 v106, v106, v140, 0x4b400000
	v_fmaak_f32 v107, v107, v140, 0x4b400000
	v_fmaak_f32 v98, v98, v140, 0x4b400000
	v_fmaak_f32 v99, v99, v140, 0x4b400000
	v_fmaak_f32 v125, v126, v140, 0x4b400000
	v_perm_b32 v123, v124, v123, s29
	v_perm_b32 v114, v115, v114, s29
	v_fmaak_f32 v115, v116, v140, 0x4b400000
	v_fmaak_f32 v116, v117, v140, 0x4b400000
	v_perm_b32 v106, v107, v106, s29
	v_fmaak_f32 v107, v108, v140, 0x4b400000
	v_fmaak_f32 v108, v109, v140, 0x4b400000
	v_perm_b32 v98, v99, v98, s29
	v_fmaak_f32 v99, v100, v140, 0x4b400000
	v_fmaak_f32 v100, v101, v140, 0x4b400000
	v_perm_b32 v123, v125, v123, s30
	v_lshl_add_u64 v[124:125], s[94:95], 0, v[130:131]
	v_fmaak_f32 v118, v118, v140, 0x4b400000
	v_fmaak_f32 v117, v120, v140, 0x4b400000
	v_perm_b32 v115, v116, v115, s29
	v_fmaak_f32 v110, v110, v140, 0x4b400000
	v_fmaak_f32 v109, v112, v140, 0x4b400000
	v_perm_b32 v107, v108, v107, s29
	v_fmaak_f32 v102, v102, v140, 0x4b400000
	v_fmaak_f32 v101, v104, v140, 0x4b400000
	v_perm_b32 v99, v100, v99, s29
	v_fmaak_f32 v126, v127, v140, 0x4b400000
	v_add_co_u32_e32 v124, vcc, s34, v124
	v_fmaak_f32 v119, v119, v140, 0x4b400000
	v_perm_b32 v114, v118, v114, s30
	v_fmaak_f32 v118, v121, v140, 0x4b400000
	v_perm_b32 v115, v117, v115, s30
	v_fmaak_f32 v111, v111, v140, 0x4b400000
	v_perm_b32 v106, v110, v106, s30
	v_fmaak_f32 v110, v113, v140, 0x4b400000
	v_perm_b32 v107, v109, v107, s30
	v_fmaak_f32 v103, v103, v140, 0x4b400000
	v_perm_b32 v98, v102, v98, s30
	v_fmaak_f32 v102, v105, v140, 0x4b400000
	v_perm_b32 v99, v101, v99, s30
	v_perm_b32 v123, v126, v123, s31
	v_addc_co_u32_e32 v125, vcc, 0, v125, vcc
	v_perm_b32 v114, v119, v114, s31
	v_perm_b32 v115, v118, v115, s31
	v_perm_b32 v106, v111, v106, s31
	v_perm_b32 v107, v110, v107, s31
	v_perm_b32 v98, v103, v98, s31
	v_perm_b32 v99, v102, v99, s31
	global_store_dwordx2 v[124:125], v[122:123], off sc1
	global_store_dwordx2 v[124:125], v[114:115], off offset:512 sc1
	global_store_dwordx2 v[124:125], v[106:107], off offset:1024 sc1
	global_store_dwordx2 v[124:125], v[98:99], off offset:1536 sc1
	s_add_u32 s13, s13, s16
	v_mov_b64_e32 v[128:129], v[76:77]
	v_mov_b64_e32 v[124:125], v[84:85]
	v_mov_b64_e32 v[120:121], v[88:89]
	v_mov_b64_e32 v[116:117], v[92:93]
	v_mov_b64_e32 v[112:113], v[68:69]
	v_mov_b64_e32 v[108:109], v[72:73]
	v_mov_b64_e32 v[104:105], v[80:81]
	v_mov_b64_e32 v[100:101], v[96:97]
	s_addc_u32 s35, s35, s17
	v_lshl_add_u64 v[130:131], v[130:131], 0, s[18:19]
	v_lshl_add_u64 v[132:133], v[132:133], 0, s[20:21]
	v_lshl_add_u64 v[134:135], v[134:135], 0, s[20:21]
	s_andn2_b64 vcc, exec, s[22:23]
	v_mov_b64_e32 v[126:127], v[74:75]
	v_mov_b64_e32 v[122:123], v[82:83]
	v_mov_b64_e32 v[118:119], v[86:87]
	v_mov_b64_e32 v[114:115], v[90:91]
	v_mov_b64_e32 v[110:111], v[66:67]
	v_mov_b64_e32 v[106:107], v[70:71]
	v_mov_b64_e32 v[102:103], v[78:79]
	v_mov_b64_e32 v[98:99], v[94:95]
	s_cbranch_vccz .LBB0_3293

.LBB0_3296:
	s_cmp_gt_i32 s10, 31
	s_cbranch_scc1 .LBB0_3300
	s_ashr_i32 s11, s10, 31
	s_lshl_b64 s[0:1], s[10:11], 13
	v_readlane_b32 s4, v254, 58
	v_readlane_b32 s5, v254, 59
	s_add_u32 s0, s4, s0
	s_addc_u32 s1, s5, s1
	s_add_u32 s4, s0, 0x40000
	s_addc_u32 s5, s1, 0
	v_lshlrev_b32_e32 v57, 4, v166
	s_add_u32 s12, s0, 0x80000
	v_or_b32_e32 v149, 0x400, v57
	v_or_b32_e32 v150, 0x800, v57
	v_or_b32_e32 v151, 0xc00, v57
	s_addc_u32 s13, s1, 0
	global_load_dwordx4 v[2:5], v57, s[0:1]
	global_load_dwordx4 v[6:9], v57, s[0:1] offset:1024
	global_load_dwordx4 v[24:27], v57, s[0:1] offset:2048
	global_load_dwordx4 v[28:31], v57, s[0:1] offset:3072
	v_or_b32_e32 v148, 0x1000, v57
	global_load_dwordx4 v[32:35], v57, s[4:5]
	global_load_dwordx4 v[36:39], v149, s[4:5]
	global_load_dwordx4 v[40:43], v150, s[4:5]
	global_load_dwordx4 v[44:47], v151, s[4:5]
	global_load_dwordx4 v[48:51], v148, s[0:1]
	global_load_dwordx4 v[52:55], v148, s[4:5]
	global_load_dwordx4 v[58:61], v57, s[12:13]
	s_add_u32 s14, s0, 0xc0000
	s_addc_u32 s15, s1, 0
	global_load_dwordx4 v[62:65], v57, s[14:15]
	global_load_dwordx4 v[66:69], v149, s[12:13]
	global_load_dwordx4 v[70:73], v149, s[14:15]
	global_load_dwordx4 v[74:77], v150, s[12:13]
	global_load_dwordx4 v[78:81], v150, s[14:15]
	global_load_dwordx4 v[82:85], v151, s[12:13]
	global_load_dwordx4 v[86:89], v151, s[14:15]
	global_load_dwordx4 v[90:93], v148, s[12:13]
	global_load_dwordx4 v[94:97], v148, s[14:15]
	v_or_b32_e32 v152, 0x1400, v57
	global_load_dwordx4 v[98:101], v152, s[0:1]
	global_load_dwordx4 v[102:105], v152, s[4:5]
	global_load_dwordx4 v[106:109], v152, s[12:13]
	global_load_dwordx4 v[110:113], v152, s[14:15]
	v_or_b32_e32 v153, 0x1800, v57
	global_load_dwordx4 v[114:117], v153, s[0:1]
	global_load_dwordx4 v[118:121], v153, s[4:5]
	global_load_dwordx4 v[122:125], v153, s[12:13]
	global_load_dwordx4 v[126:129], v153, s[14:15]
	v_or_b32_e32 v154, 0x1c00, v57
	global_load_dwordx4 v[130:133], v154, s[0:1]
	global_load_dwordx4 v[134:137], v154, s[4:5]
	global_load_dwordx4 v[138:141], v154, s[12:13]
	global_load_dwordx4 v[142:145], v154, s[14:15]
	s_add_i32 s4, s10, 0x2000
	s_ashr_i32 s5, s4, 31
	s_lshl_b64 s[0:1], s[4:5], 12
	v_readlane_b32 s10, v254, 54
	v_readlane_b32 s11, v254, 55
	s_add_u32 s0, s10, s0
	v_lshlrev_b32_e32 v56, 3, v166
	s_addc_u32 s1, s11, s1
	global_load_dwordx2 v[146:147], v56, s[0:1]
	global_load_dwordx2 v[22:23], v56, s[0:1] offset:512
	global_load_dwordx2 v[20:21], v56, s[0:1] offset:1024
	global_load_dwordx2 v[18:19], v56, s[0:1] offset:1536
	global_load_dwordx2 v[16:17], v56, s[0:1] offset:2048
	global_load_dwordx2 v[14:15], v56, s[0:1] offset:2560
	global_load_dwordx2 v[12:13], v56, s[0:1] offset:3072
	global_load_dwordx2 v[10:11], v56, s[0:1] offset:3584
	v_mov_b32_e32 v1, 0
	v_cmp_eq_u32_e32 vcc, 0, v166
	s_waitcnt vmcnt(35)
	v_pk_add_f32 v[4:5], v[4:5], v[34:35]
	v_pk_add_f32 v[2:3], v[2:3], v[32:33]
	s_waitcnt vmcnt(32)
	v_pk_add_f32 v[30:31], v[30:31], v[46:47]
	v_pk_add_f32 v[28:29], v[28:29], v[44:45]
	s_waitcnt vmcnt(28)
	v_pk_add_f32 v[32:33], v[60:61], v[64:65]
	v_pk_add_f32 v[34:35], v[58:59], v[62:63]
	s_waitcnt vmcnt(22)
	v_pk_add_f32 v[58:59], v[84:85], v[88:89]
	v_pk_add_f32 v[60:61], v[82:83], v[86:87]
	v_pk_add_f32 v[8:9], v[8:9], v[38:39]
	v_pk_add_f32 v[6:7], v[6:7], v[36:37]
	v_pk_add_f32 v[36:37], v[50:51], v[54:55]
	v_pk_add_f32 v[38:39], v[48:49], v[52:53]
	v_pk_add_f32 v[52:53], v[4:5], v[32:33]
	v_pk_add_f32 v[54:55], v[2:3], v[34:35]
	v_pk_add_f32 v[32:33], v[30:31], v[58:59]
	v_pk_add_f32 v[34:35], v[28:29], v[60:61]
	global_load_dwordx4 v[58:61], v57, s[6:7]
	v_pk_add_f32 v[26:27], v[26:27], v[42:43]
	v_pk_add_f32 v[24:25], v[24:25], v[40:41]
	v_pk_add_f32 v[42:43], v[66:67], v[70:71]
	v_pk_add_f32 v[46:47], v[74:75], v[78:79]
	s_waitcnt vmcnt(21)
	v_pk_add_f32 v[62:63], v[92:93], v[96:97]
	v_pk_add_f32 v[50:51], v[6:7], v[42:43]
	v_pk_add_f32 v[42:43], v[24:25], v[46:47]
	v_pk_add_f32 v[24:25], v[36:37], v[62:63]
	global_load_dwordx4 v[62:65], v149, s[6:7]
	v_pk_add_f32 v[40:41], v[68:69], v[72:73]
	v_pk_add_f32 v[44:45], v[76:77], v[80:81]
	v_pk_add_f32 v[2:3], v[90:91], v[94:95]
	v_pk_add_f32 v[48:49], v[8:9], v[40:41]
	v_pk_add_f32 v[40:41], v[26:27], v[44:45]
	v_pk_add_f32 v[26:27], v[38:39], v[2:3]
	s_waitcnt vmcnt(20)
	v_pk_add_f32 v[2:3], v[100:101], v[104:105]
	v_pk_add_f32 v[4:5], v[98:99], v[102:103]
	s_waitcnt vmcnt(18)
	v_pk_add_f32 v[6:7], v[108:109], v[112:113]
	v_pk_add_f32 v[8:9], v[106:107], v[110:111]
	v_pk_add_f32 v[28:29], v[2:3], v[6:7]
	v_pk_add_f32 v[30:31], v[4:5], v[8:9]
	s_waitcnt vmcnt(16)
	v_pk_add_f32 v[2:3], v[116:117], v[120:121]
	v_pk_add_f32 v[4:5], v[114:115], v[118:119]
	s_waitcnt vmcnt(14)
	v_pk_add_f32 v[6:7], v[124:125], v[128:129]
	v_pk_add_f32 v[8:9], v[122:123], v[126:127]
	v_pk_add_f32 v[36:37], v[2:3], v[6:7]
	v_pk_add_f32 v[38:39], v[4:5], v[8:9]
	s_waitcnt vmcnt(12)
	v_pk_add_f32 v[2:3], v[132:133], v[136:137]
	v_pk_add_f32 v[4:5], v[130:131], v[134:135]
	s_waitcnt vmcnt(10)
	v_pk_add_f32 v[6:7], v[140:141], v[144:145]
	v_pk_add_f32 v[8:9], v[138:139], v[142:143]
	v_pk_add_f32 v[46:47], v[2:3], v[6:7]
	v_pk_add_f32 v[44:45], v[4:5], v[8:9]
	v_pk_mul_f32 v[2:3], v[40:41], v[40:41]
	v_pk_mul_f32 v[4:5], v[42:43], v[42:43]
	v_mov_b32_e32 v90, v53
	v_pk_mov_b32 v[6:7], v[4:5], v[2:3] op_sel:[1,0]
	v_mov_b32_e32 v5, v3
	v_pk_add_f32 v[6:7], v[6:7], v[4:5]
	v_pk_mul_f32 v[2:3], v[28:29], v[28:29]
	v_pk_mul_f32 v[4:5], v[30:31], v[30:31]
	v_mov_b32_e32 v91, v49
	v_pk_mov_b32 v[8:9], v[4:5], v[2:3] op_sel:[1,0]
	v_mov_b32_e32 v5, v3
	v_pk_add_f32 v[8:9], v[8:9], v[4:5]
	global_load_dwordx4 v[66:69], v150, s[6:7]
	global_load_dwordx4 v[70:73], v151, s[6:7]
	global_load_dwordx4 v[74:77], v148, s[6:7]
	global_load_dwordx4 v[78:81], v152, s[6:7]
	global_load_dwordx4 v[82:85], v153, s[6:7]
	global_load_dwordx4 v[2:5], v154, s[6:7]
	v_mov_b32_e32 v86, v55
	v_mov_b32_e32 v87, v51
	v_mov_b32_e32 v88, v52
	v_mov_b32_e32 v89, v48
	v_pk_mul_f32 v[90:91], v[90:91], v[90:91]
	v_pk_mul_f32 v[86:87], v[86:87], v[86:87]
	v_pk_fma_f32 v[88:89], v[88:89], v[88:89], v[90:91]
	v_mov_b32_e32 v90, v54
	v_mov_b32_e32 v91, v50
	v_pk_fma_f32 v[86:87], v[90:91], v[90:91], v[86:87]
	v_mul_f32_e32 v90, v33, v33
	v_pk_add_f32 v[86:87], v[86:87], v[88:89]
	v_mul_f32_e32 v88, v35, v35
	v_mul_f32_e32 v92, v26, v26
	v_mul_f32_e32 v93, v27, v27
	v_mul_f32_e32 v94, v24, v24
	v_mul_f32_e32 v95, v25, v25
	v_pk_fma_f32 v[88:89], v[34:35], v[34:35], v[88:89] op_sel_hi:[1,1,0]
	v_pk_fma_f32 v[90:91], v[32:33], v[32:33], v[90:91] op_sel_hi:[1,1,0]
	v_pk_add_f32 v[86:87], v[86:87], v[86:87] op_sel:[0,1] op_sel_hi:[1,0]
	v_pk_add_f32 v[6:7], v[6:7], v[6:7] op_sel:[0,1] op_sel_hi:[1,0]
	v_mov_b32_e32 v89, v94
	v_mov_b32_e32 v91, v95
	v_mov_b32_e32 v87, v92
	v_mov_b32_e32 v7, v93
	v_pk_add_f32 v[88:89], v[88:89], v[90:91]
	v_pk_add_f32 v[6:7], v[86:87], v[6:7]
	v_mul_f32_e32 v86, v39, v39
	v_pk_add_f32 v[6:7], v[6:7], v[88:89]
	v_mul_f32_e32 v88, v37, v37
	v_mul_f32_e32 v96, v44, v44
	v_mul_f32_e32 v97, v45, v45
	v_mul_f32_e32 v98, v46, v46
	v_mul_f32_e32 v99, v47, v47
	v_pk_fma_f32 v[86:87], v[38:39], v[38:39], v[86:87] op_sel_hi:[1,1,0]
	v_pk_fma_f32 v[88:89], v[36:37], v[36:37], v[88:89] op_sel_hi:[1,1,0]
	v_pk_add_f32 v[6:7], v[6:7], v[6:7] op_sel:[0,1] op_sel_hi:[1,0]
	v_pk_add_f32 v[8:9], v[8:9], v[8:9] op_sel:[0,1] op_sel_hi:[1,0]
	v_mov_b32_e32 v87, v98
	v_mov_b32_e32 v89, v99
	v_mov_b32_e32 v7, v96
	v_mov_b32_e32 v9, v97
	v_pk_add_f32 v[86:87], v[86:87], v[88:89]
	v_pk_add_f32 v[6:7], v[6:7], v[8:9]
	v_mov_b32_e32 v96, 0x3a000000
	v_pk_add_f32 v[6:7], v[6:7], v[86:87]
	v_mov_b32_e32 v87, 0x358637bd
	v_add_f32_e32 v6, v6, v7
	v_mov_b32_e32 v7, 0
	s_waitcnt vmcnt(7)
	v_pk_mul_f32 v[54:55], v[54:55], v[58:59]
	v_add_f32_dpp v6, v6, v6 quad_perm:[1,0,3,2] row_mask:0xf bank_mask:0xf bound_ctrl:1
	v_cvt_f32_f16_e32 v58, v22
	v_cvt_f32_f16_sdwa v59, v22 dst_sel:DWORD dst_unused:UNUSED_PAD src0_sel:WORD_1
	v_add_f32_dpp v6, v6, v6 quad_perm:[2,3,0,1] row_mask:0xf bank_mask:0xf bound_ctrl:1
	v_cvt_f32_f16_e32 v22, v23
	v_cvt_f32_f16_sdwa v23, v23 dst_sel:DWORD dst_unused:UNUSED_PAD src0_sel:WORD_1
	v_add_f32_dpp v6, v6, v6 row_half_mirror row_mask:0xf bank_mask:0xf bound_ctrl:1
	s_waitcnt vmcnt(6)
	v_pk_mul_f32 v[48:49], v[48:49], v[64:65]
	v_cvt_f32_f16_e32 v88, v146
	v_add_f32_dpp v6, v6, v6 row_mirror row_mask:0xf bank_mask:0xf bound_ctrl:1
	v_cvt_f32_f16_sdwa v89, v146 dst_sel:DWORD dst_unused:UNUSED_PAD src0_sel:WORD_1
	v_cvt_f32_f16_e32 v90, v147
	v_mov_b32_dpp v7, v6 row_bcast:15 row_mask:0xa bank_mask:0xf
	v_add_f32_e32 v6, v6, v7
	v_mov_b32_e32 v7, 0
	v_cvt_f32_f16_sdwa v91, v147 dst_sel:DWORD dst_unused:UNUSED_PAD src0_sel:WORD_1
	v_pk_mul_f32 v[52:53], v[52:53], v[60:61]
	v_mov_b32_dpp v7, v6 row_bcast:31 row_mask:0xc bank_mask:0xf
	v_add_f32_e32 v6, v6, v7
	v_pk_mul_f32 v[50:51], v[50:51], v[62:63]
	v_readlane_b32 s10, v6, 63
	global_load_dwordx4 v[62:65], v153, s[8:9]
	s_waitcnt vmcnt(6)
	v_pk_mul_f32 v[42:43], v[42:43], v[66:67]
	v_fma_f32 v6, s10, v96, v87
	v_rsq_f32_e32 v86, v6
	global_load_dwordx4 v[6:9], v57, s[8:9]
	v_pk_mul_f32 v[40:41], v[40:41], v[68:69]
	s_waitcnt vmcnt(6)
	v_pk_mul_f32 v[32:33], v[32:33], v[72:73]
	v_pk_fma_f32 v[92:93], v[48:49], v[86:87], v[22:23] op_sel_hi:[1,0,1]
	v_cvt_f32_f16_e32 v48, v20
	v_cvt_f32_f16_sdwa v49, v20 dst_sel:DWORD dst_unused:UNUSED_PAD src0_sel:WORD_1
	v_pk_fma_f32 v[90:91], v[52:53], v[86:87], v[90:91] op_sel_hi:[1,0,1]
	v_pk_fma_f32 v[88:89], v[54:55], v[86:87], v[88:89] op_sel_hi:[1,0,1]
	global_load_dwordx4 v[52:55], v149, s[8:9]
	v_pk_fma_f32 v[68:69], v[42:43], v[86:87], v[48:49] op_sel_hi:[1,0,1]
	v_cvt_f32_f16_e32 v48, v18
	v_cvt_f32_f16_sdwa v49, v18 dst_sel:DWORD dst_unused:UNUSED_PAD src0_sel:WORD_1
	v_cvt_f32_f16_e32 v18, v19
	v_cvt_f32_f16_sdwa v19, v19 dst_sel:DWORD dst_unused:UNUSED_PAD src0_sel:WORD_1
	v_pk_fma_f32 v[94:95], v[50:51], v[86:87], v[58:59] op_sel_hi:[1,0,1]
	v_cvt_f32_f16_e32 v50, v21
	v_cvt_f32_f16_sdwa v51, v21 dst_sel:DWORD dst_unused:UNUSED_PAD src0_sel:WORD_1
	global_load_dwordx4 v[20:23], v150, s[8:9]
	v_pk_fma_f32 v[18:19], v[32:33], v[86:87], v[18:19] op_sel_hi:[1,0,1]
	v_cvt_f32_f16_e32 v32, v16
	v_cvt_f32_f16_sdwa v33, v16 dst_sel:DWORD dst_unused:UNUSED_PAD src0_sel:WORD_1
	v_cvt_f32_f16_e32 v16, v17
	v_cvt_f32_f16_sdwa v17, v17 dst_sel:DWORD dst_unused:UNUSED_PAD src0_sel:WORD_1
	v_pk_fma_f32 v[66:67], v[40:41], v[86:87], v[50:51] op_sel_hi:[1,0,1]
	global_load_dwordx4 v[40:43], v151, s[8:9]
	global_load_dwordx4 v[58:61], v152, s[8:9]
	v_pk_mul_f32 v[34:35], v[34:35], v[70:71]
	s_waitcnt vmcnt(9)
	v_pk_mul_f32 v[24:25], v[24:25], v[76:77]
	v_pk_fma_f32 v[70:71], v[34:35], v[86:87], v[48:49] op_sel_hi:[1,0,1]
	global_load_dwordx4 v[48:51], v148, s[8:9]
	v_pk_fma_f32 v[16:17], v[24:25], v[86:87], v[16:17] op_sel_hi:[1,0,1]
	v_cvt_f32_f16_e32 v24, v14
	v_cvt_f32_f16_sdwa v25, v14 dst_sel:DWORD dst_unused:UNUSED_PAD src0_sel:WORD_1
	v_cvt_f32_f16_e32 v14, v15
	v_cvt_f32_f16_sdwa v15, v15 dst_sel:DWORD dst_unused:UNUSED_PAD src0_sel:WORD_1
	v_pk_mul_f32 v[26:27], v[26:27], v[74:75]
	s_waitcnt vmcnt(7)
	v_pk_mul_f32 v[4:5], v[46:47], v[4:5]
	v_pk_fma_f32 v[72:73], v[26:27], v[86:87], v[32:33] op_sel_hi:[1,0,1]
	v_pk_mul_f32 v[26:27], v[28:29], v[80:81]
	v_pk_mul_f32 v[28:29], v[30:31], v[78:79]
	v_pk_fma_f32 v[74:75], v[26:27], v[86:87], v[14:15] op_sel_hi:[1,0,1]
	v_cvt_f32_f16_e32 v14, v12
	v_cvt_f32_f16_sdwa v15, v12 dst_sel:DWORD dst_unused:UNUSED_PAD src0_sel:WORD_1
	v_cvt_f32_f16_e32 v12, v13
	v_cvt_f32_f16_sdwa v13, v13 dst_sel:DWORD dst_unused:UNUSED_PAD src0_sel:WORD_1
	v_pk_fma_f32 v[76:77], v[28:29], v[86:87], v[24:25] op_sel_hi:[1,0,1]
	v_pk_mul_f32 v[24:25], v[36:37], v[84:85]
	global_load_dwordx4 v[34:37], v154, s[8:9]
	v_pk_mul_f32 v[26:27], v[38:39], v[82:83]
	v_pk_fma_f32 v[38:39], v[24:25], v[86:87], v[12:13] op_sel_hi:[1,0,1]
	v_cvt_f32_f16_e32 v12, v10
	v_cvt_f32_f16_sdwa v13, v10 dst_sel:DWORD dst_unused:UNUSED_PAD src0_sel:WORD_1
	v_cvt_f32_f16_e32 v10, v11
	v_cvt_f32_f16_sdwa v11, v11 dst_sel:DWORD dst_unused:UNUSED_PAD src0_sel:WORD_1
	v_pk_fma_f32 v[78:79], v[26:27], v[86:87], v[14:15] op_sel_hi:[1,0,1]
	v_cvt_f16_f32_e32 v14, v88
	v_cvt_f16_f32_sdwa v15, v89 dst_sel:WORD_1 dst_unused:UNUSED_PAD src0_sel:DWORD
	v_pk_mul_f32 v[2:3], v[44:45], v[2:3]
	v_pk_fma_f32 v[4:5], v[4:5], v[86:87], v[10:11] op_sel_hi:[1,0,1]
	v_pk_fma_f32 v[2:3], v[2:3], v[86:87], v[12:13] op_sel_hi:[1,0,1]
	v_cvt_f16_f32_e32 v11, v90
	v_cvt_f16_f32_sdwa v12, v91 dst_sel:WORD_1 dst_unused:UNUSED_PAD src0_sel:DWORD
	v_or_b32_e32 v10, v15, v14
	v_cvt_f16_f32_e32 v13, v94
	v_cvt_f16_f32_sdwa v14, v95 dst_sel:WORD_1 dst_unused:UNUSED_PAD src0_sel:DWORD
	v_cvt_f16_f32_e32 v15, v92
	v_cvt_f16_f32_sdwa v24, v93 dst_sel:WORD_1 dst_unused:UNUSED_PAD src0_sel:DWORD
	v_or_b32_e32 v11, v12, v11
	global_store_dwordx2 v56, v[10:11], s[0:1] sc1
	v_or_b32_e32 v10, v14, v13
	v_or_b32_e32 v11, v24, v15
	global_store_dwordx2 v56, v[10:11], s[0:1] offset:512 sc1
	v_cvt_f16_f32_e32 v10, v68
	v_cvt_f16_f32_sdwa v11, v69 dst_sel:WORD_1 dst_unused:UNUSED_PAD src0_sel:DWORD
	v_cvt_f16_f32_e32 v12, v66
	v_cvt_f16_f32_sdwa v13, v67 dst_sel:WORD_1 dst_unused:UNUSED_PAD src0_sel:DWORD
	v_cvt_f16_f32_e32 v14, v70
	v_cvt_f16_f32_sdwa v15, v71 dst_sel:WORD_1 dst_unused:UNUSED_PAD src0_sel:DWORD
	v_or_b32_e32 v10, v11, v10
	v_or_b32_e32 v11, v13, v12
	global_store_dwordx2 v56, v[10:11], s[0:1] offset:1024 sc1
	v_cvt_f16_f32_e32 v11, v18
	v_cvt_f16_f32_sdwa v12, v19 dst_sel:WORD_1 dst_unused:UNUSED_PAD src0_sel:DWORD
	v_or_b32_e32 v10, v15, v14
	v_cvt_f16_f32_e32 v13, v72
	v_cvt_f16_f32_sdwa v14, v73 dst_sel:WORD_1 dst_unused:UNUSED_PAD src0_sel:DWORD
	v_cvt_f16_f32_e32 v15, v16
	v_cvt_f16_f32_sdwa v24, v17 dst_sel:WORD_1 dst_unused:UNUSED_PAD src0_sel:DWORD
	v_or_b32_e32 v11, v12, v11
	global_store_dwordx2 v56, v[10:11], s[0:1] offset:1536 sc1
	v_or_b32_e32 v10, v14, v13
	v_or_b32_e32 v11, v24, v15
	global_store_dwordx2 v56, v[10:11], s[0:1] offset:2048 sc1
	v_cvt_f16_f32_e32 v10, v76
	v_cvt_f16_f32_sdwa v11, v77 dst_sel:WORD_1 dst_unused:UNUSED_PAD src0_sel:DWORD
	v_cvt_f16_f32_e32 v12, v74
	v_cvt_f16_f32_sdwa v13, v75 dst_sel:WORD_1 dst_unused:UNUSED_PAD src0_sel:DWORD
	v_cvt_f16_f32_e32 v14, v78
	v_cvt_f16_f32_sdwa v15, v79 dst_sel:WORD_1 dst_unused:UNUSED_PAD src0_sel:DWORD
	v_or_b32_e32 v10, v11, v10
	v_or_b32_e32 v11, v13, v12
	global_store_dwordx2 v56, v[10:11], s[0:1] offset:2560 sc1
	v_cvt_f16_f32_e32 v11, v38
	v_cvt_f16_f32_sdwa v12, v39 dst_sel:WORD_1 dst_unused:UNUSED_PAD src0_sel:DWORD
	v_or_b32_e32 v10, v15, v14
	v_cvt_f16_f32_e32 v13, v2
	v_cvt_f16_f32_sdwa v14, v3 dst_sel:WORD_1 dst_unused:UNUSED_PAD src0_sel:DWORD
	v_cvt_f16_f32_e32 v15, v4
	v_cvt_f16_f32_sdwa v24, v5 dst_sel:WORD_1 dst_unused:UNUSED_PAD src0_sel:DWORD
	v_or_b32_e32 v11, v12, v11
	global_store_dwordx2 v56, v[10:11], s[0:1] offset:3072 sc1
	v_or_b32_e32 v10, v14, v13
	v_or_b32_e32 v11, v24, v15
	v_mov_b32_e32 v12, v89
	v_mov_b32_e32 v13, v95
	global_store_dwordx2 v56, v[10:11], s[0:1] offset:3584 sc1
	v_mov_b32_e32 v10, v88
	v_mov_b32_e32 v11, v94
	v_pk_mul_f32 v[12:13], v[12:13], v[12:13]
	v_mov_b32_e32 v14, v91
	v_mov_b32_e32 v15, v93
	v_pk_fma_f32 v[10:11], v[10:11], v[10:11], v[12:13]
	v_mov_b32_e32 v12, v90
	v_mov_b32_e32 v13, v92
	v_pk_mul_f32 v[14:15], v[14:15], v[14:15]
	s_waitcnt vmcnt(14)
	v_pk_mul_f32 v[8:9], v[8:9], v[90:91]
	v_pk_fma_f32 v[12:13], v[12:13], v[12:13], v[14:15]
	v_pk_mul_f32 v[14:15], v[68:69], v[68:69]
	v_pk_add_f32 v[10:11], v[10:11], v[12:13]
	v_pk_mul_f32 v[12:13], v[66:67], v[66:67]
	v_pk_add_f32 v[10:11], v[10:11], v[10:11] op_sel_hi:[0,1]
	v_pk_mov_b32 v[24:25], v[14:15], v[12:13] op_sel:[1,0]
	v_mov_b32_e32 v15, v13
	v_mul_f32_e32 v10, v70, v70
	v_pk_add_f32 v[12:13], v[24:25], v[14:15]
	v_pk_fma_f32 v[14:15], v[70:71], v[70:71], v[10:11] op_sel_hi:[1,1,0]
	v_mul_f32_e32 v10, v18, v18
	v_pk_add_f32 v[12:13], v[12:13], v[12:13] op_sel_hi:[0,1]
	v_pk_fma_f32 v[24:25], v[18:19], v[18:19], v[10:11] op_sel_hi:[1,1,0]
	v_mul_f32_e32 v14, v72, v72
	v_mul_f32_e32 v24, v73, v73
	v_mul_f32_e32 v12, v16, v16
	v_mul_f32_e32 v10, v17, v17
	v_pk_add_f32 v[14:15], v[14:15], v[24:25]
	v_pk_add_f32 v[10:11], v[12:13], v[10:11]
	v_pk_mul_f32 v[12:13], v[74:75], v[74:75]
	v_pk_add_f32 v[10:11], v[14:15], v[10:11]
	v_pk_mul_f32 v[14:15], v[76:77], v[76:77]
	v_pk_add_f32 v[10:11], v[10:11], v[10:11] op_sel_hi:[0,1]
	v_pk_mov_b32 v[24:25], v[14:15], v[12:13] op_sel:[1,0]
	v_mov_b32_e32 v15, v13
	v_mul_f32_e32 v10, v78, v78
	v_pk_add_f32 v[12:13], v[24:25], v[14:15]
	v_pk_fma_f32 v[14:15], v[78:79], v[78:79], v[10:11] op_sel_hi:[1,1,0]
	v_mul_f32_e32 v10, v38, v38
	v_pk_add_f32 v[12:13], v[12:13], v[12:13] op_sel_hi:[0,1]
	v_pk_fma_f32 v[24:25], v[38:39], v[38:39], v[10:11] op_sel_hi:[1,1,0]
	v_mul_f32_e32 v14, v2, v2
	v_mul_f32_e32 v24, v3, v3
	v_mul_f32_e32 v12, v4, v4
	v_mul_f32_e32 v10, v5, v5
	v_pk_add_f32 v[14:15], v[14:15], v[24:25]
	v_pk_add_f32 v[10:11], v[12:13], v[10:11]
	s_waitcnt vmcnt(13)
	v_pk_mul_f32 v[12:13], v[54:55], v[92:93]
	v_pk_add_f32 v[10:11], v[14:15], v[10:11]
	v_pk_mul_f32 v[6:7], v[6:7], v[88:89]
	v_add_f32_e32 v10, v10, v11
	v_mov_b32_e32 v11, 0
	s_waitcnt vmcnt(8)
	v_pk_mul_f32 v[34:35], v[2:3], v[34:35]
	v_add_f32_dpp v10, v10, v10 quad_perm:[1,0,3,2] row_mask:0xf bank_mask:0xf bound_ctrl:1
	v_pk_mul_f32 v[2:3], v[4:5], v[36:37]
	s_nop 0
	v_add_f32_dpp v10, v10, v10 quad_perm:[2,3,0,1] row_mask:0xf bank_mask:0xf bound_ctrl:1
	s_nop 1
	v_add_f32_dpp v10, v10, v10 row_half_mirror row_mask:0xf bank_mask:0xf bound_ctrl:1
	s_nop 1
	v_add_f32_dpp v10, v10, v10 row_mirror row_mask:0xf bank_mask:0xf bound_ctrl:1
	s_nop 1
	v_mov_b32_dpp v11, v10 row_bcast:15 row_mask:0xa bank_mask:0xf
	v_add_f32_e32 v10, v10, v11
	v_mov_b32_e32 v11, 0
	s_nop 1
	v_mov_b32_dpp v11, v10 row_bcast:31 row_mask:0xc bank_mask:0xf
	v_add_f32_e32 v10, v10, v11
	s_nop 0
	v_readlane_b32 s0, v10, 63
	v_pk_mul_f32 v[10:11], v[52:53], v[94:95]
	s_nop 0
	v_fmac_f32_e32 v87, s0, v96
	v_rsq_f32_e32 v44, v87
	s_nop 0
	v_pk_mul_f32 v[24:25], v[12:13], v[44:45] op_sel_hi:[1,0]
	v_pk_mul_f32 v[30:31], v[8:9], v[44:45] op_sel_hi:[1,0]
	v_pk_mul_f32 v[28:29], v[10:11], v[44:45] op_sel_hi:[1,0]
	v_pk_mul_f32 v[32:33], v[6:7], v[44:45] op_sel_hi:[1,0]
	v_max_f32_e64 v6, |v30|, |v31|
	v_max_f32_e64 v7, |v24|, |v25|
	v_max3_f32 v6, |v32|, |v33|, v6
	v_max3_f32 v7, |v28|, |v29|, v7
	v_pk_mul_f32 v[8:9], v[22:23], v[66:67]
	v_max3_f32 v10, v6, 0, v7
	v_pk_mul_f32 v[6:7], v[20:21], v[68:69]
	v_pk_mul_f32 v[22:23], v[8:9], v[44:45] op_sel_hi:[1,0]
	v_pk_mul_f32 v[26:27], v[6:7], v[44:45] op_sel_hi:[1,0]
	v_max_f32_e64 v6, |v22|, |v23|
	v_pk_mul_f32 v[8:9], v[42:43], v[18:19]
	v_max3_f32 v11, |v26|, |v27|, v6
	v_pk_mul_f32 v[6:7], v[40:41], v[70:71]
	v_pk_mul_f32 v[18:19], v[8:9], v[44:45] op_sel_hi:[1,0]
	v_pk_mul_f32 v[20:21], v[6:7], v[44:45] op_sel_hi:[1,0]
	v_max_f32_e64 v6, |v18|, |v19|
	v_max3_f32 v6, |v20|, |v21|, v6
	v_pk_mul_f32 v[8:9], v[50:51], v[16:17]
	v_max3_f32 v40, v10, v11, v6
	v_pk_mul_f32 v[6:7], v[48:49], v[72:73]
	v_pk_mul_f32 v[14:15], v[8:9], v[44:45] op_sel_hi:[1,0]
	v_pk_mul_f32 v[16:17], v[6:7], v[44:45] op_sel_hi:[1,0]
	v_max_f32_e64 v6, |v14|, |v15|
	v_pk_mul_f32 v[8:9], v[60:61], v[74:75]
	v_max3_f32 v41, |v16|, |v17|, v6
	v_pk_mul_f32 v[6:7], v[58:59], v[76:77]
	v_pk_mul_f32 v[10:11], v[8:9], v[44:45] op_sel_hi:[1,0]
	v_pk_mul_f32 v[12:13], v[6:7], v[44:45] op_sel_hi:[1,0]
	v_max_f32_e64 v6, |v10|, |v11|
	v_max3_f32 v6, |v12|, |v13|, v6
	v_max3_f32 v40, v40, v41, v6
	v_pk_mul_f32 v[6:7], v[38:39], v[64:65]
	v_pk_mul_f32 v[8:9], v[78:79], v[62:63]
	v_pk_mul_f32 v[6:7], v[6:7], v[44:45] op_sel_hi:[1,0]
	v_pk_mul_f32 v[2:3], v[2:3], v[44:45] op_sel_hi:[1,0]
	v_pk_mul_f32 v[8:9], v[8:9], v[44:45] op_sel_hi:[1,0]
	v_max_f32_e64 v38, |v6|, |v7|
	v_pk_mul_f32 v[4:5], v[34:35], v[44:45] op_sel_hi:[1,0]
	v_max_f32_e64 v34, |v2|, |v3|
	v_max3_f32 v38, |v8|, |v9|, v38
	v_max3_f32 v34, |v4|, |v5|, v34
	v_max3_f32 v34, v40, v38, v34
	v_mov_b32_e32 v35, 0
	s_nop 1
	v_mov_b32_dpp v35, v34 quad_perm:[1,0,3,2] row_mask:0xf bank_mask:0xf
	v_max_f32_e32 v35, v35, v35
	v_max_f32_e32 v34, v34, v35
	v_mov_b32_e32 v35, 0
	s_nop 1
	v_mov_b32_dpp v35, v34 quad_perm:[2,3,0,1] row_mask:0xf bank_mask:0xf
	v_max_f32_e32 v35, v35, v35
	v_max_f32_e32 v34, v34, v35
	v_mov_b32_e32 v35, 0
	s_nop 1
	v_mov_b32_dpp v35, v34 row_half_mirror row_mask:0xf bank_mask:0xf
	v_max_f32_e32 v35, v35, v35
	v_max_f32_e32 v34, v34, v35
	v_mov_b32_e32 v35, 0
	s_nop 1
	v_mov_b32_dpp v35, v34 row_mirror row_mask:0xf bank_mask:0xf
	v_max_f32_e32 v35, v35, v35
	v_max_f32_e32 v34, v34, v35
	v_mov_b32_e32 v35, 0
	s_nop 1
	v_mov_b32_dpp v35, v34 row_bcast:15 row_mask:0xa bank_mask:0xf
	v_max_f32_e32 v35, v35, v35
	v_max_f32_e32 v34, v34, v35
	v_mov_b32_e32 v35, 0
	s_nop 1
	v_mov_b32_dpp v35, v34 row_bcast:31 row_mask:0xc bank_mask:0xf
	v_max_f32_e32 v35, v35, v35
	v_max_f32_e32 v34, v34, v35
	s_nop 0
	v_readlane_b32 s12, v34, 63
	s_nop 1
	v_cmp_gt_f32_e64 s[0:1], s12, 0
	s_and_saveexec_b64 s[10:11], vcc
	s_cbranch_execz .LBB0_3299
	s_lshl_b64 s[14:15], s[4:5], 2
	v_mov_b32_e32 v34, 0x3c010204
	s_add_u32 s14, s86, s14
	v_mul_f32_e32 v34, s12, v34
	s_addc_u32 s15, s87, s15
	v_cndmask_b32_e64 v34, 1.0, v34, s[0:1]
	global_store_dword v1, v34, s[14:15]

.LBB0_3301:
	s_cbranch_execz .LBB0_3312
	s_ashr_i32 s1, s90, 5
	s_abs_i32 s0, s1
	v_cvt_f32_u32_e32 v1, s0
	s_sub_i32 s10, 0, s0
	s_abs_i32 s4, s62
	s_xor_b32 s5, s62, s1
	v_rcp_iflag_f32_e32 v1, v1
	s_ashr_i32 s5, s5, 31
	v_mul_f32_e32 v1, 0x4f7ffffe, v1
	v_cvt_u32_f32_e32 v1, v1
	s_nop 0
	v_readfirstlane_b32 s11, v1
	s_mul_i32 s10, s10, s11
	s_mul_hi_u32 s10, s11, s10
	s_add_i32 s11, s11, s10
	s_mul_hi_u32 s10, s4, s11
	s_mul_i32 s11, s10, s0
	s_sub_i32 s4, s4, s11
	s_add_i32 s12, s10, 1
	s_sub_i32 s11, s4, s0
	s_cmp_ge_u32 s4, s0
	s_cselect_b32 s10, s12, s10
	s_cselect_b32 s4, s11, s4
	s_add_i32 s11, s10, 1
	s_cmp_ge_u32 s4, s0
	s_cselect_b32 s0, s11, s10
	s_xor_b32 s0, s0, s5
	s_sub_i32 s0, s0, s5
	s_mul_i32 s1, s0, s1
	s_sub_i32 s1, s62, s1
	s_cmp_lg_u32 s1, 0
	s_cbranch_scc1 .LBB0_3312
	s_ashr_i32 s1, s0, 31
	s_lshl_b64 s[4:5], s[0:1], 13
	v_readlane_b32 s10, v254, 58
	v_readlane_b32 s11, v254, 59
	s_add_u32 s4, s10, s4
	s_addc_u32 s5, s11, s5
	v_mov_b32_e32 v11, 0
	v_lshlrev_b32_e32 v10, 4, v0
	v_lshl_add_u64 v[2:3], s[4:5], 0, v[10:11]
	v_add_co_u32_e32 v4, vcc, 0x40000, v2
	s_waitcnt vmcnt(0)
	v_mov_b32_e32 v16, v184
	v_mov_b32_e32 v17, v185
	v_mov_b32_e32 v18, v186
	v_mov_b32_e32 v19, v187
	s_nop 0
	v_addc_co_u32_e32 v5, vcc, 0, v3, vcc
	v_add_co_u32_e32 v6, vcc, 0x80000, v2
	s_add_i32 s4, s0, 0x2000
	s_nop 0
	v_addc_co_u32_e32 v7, vcc, 0, v3, vcc
	v_add_co_u32_e32 v2, vcc, 0xc0000, v2
	v_mov_b32_e32 v20, v188
	v_mov_b32_e32 v21, v189
	v_mov_b32_e32 v22, v190
	v_mov_b32_e32 v23, v191
	v_mov_b32_e32 v24, v192
	v_mov_b32_e32 v25, v193
	v_mov_b32_e32 v26, v194
	v_mov_b32_e32 v27, v195
	v_addc_co_u32_e32 v3, vcc, 0, v3, vcc
	v_mov_b32_e32 v28, v196
	v_mov_b32_e32 v29, v197
	v_mov_b32_e32 v30, v198
	v_mov_b32_e32 v31, v199
	s_ashr_i32 s5, s4, 31
	s_lshl_b64 s[0:1], s[4:5], 12
	v_readlane_b32 s10, v254, 54
	v_readlane_b32 s11, v254, 55
	s_add_u32 s0, s10, s0
	s_addc_u32 s1, s11, s1
	v_lshlrev_b32_e32 v14, 3, v0
	v_mov_b32_e32 v6, v174
	v_mov_b32_e32 v7, v175
	v_mov_b32_e32 v8, v176
	v_mov_b32_e32 v9, v177
	v_mov_b32_e32 v2, v170
	v_mov_b32_e32 v3, v171
	v_mov_b32_e32 v4, v172
	v_mov_b32_e32 v5, v173
	v_mov_b32_e32 v12, v180
	v_mov_b32_e32 v13, v181
	v_mov_b32_e32 v1, v11
	v_mov_b32_e32 v10, v11
	v_mov_b32_e32 v15, v11
	v_lshl_add_u64 v[14:15], s[0:1], 0, v[14:15]
	v_cmp_eq_u32_e32 vcc, 0, v166
	s_waitcnt vmcnt(5)
	v_pk_add_f32 v[18:19], v[18:19], v[22:23]
	v_pk_add_f32 v[20:21], v[16:17], v[20:21]
	s_waitcnt vmcnt(3)
	v_pk_add_f32 v[16:17], v[26:27], v[30:31]
	v_pk_add_f32 v[22:23], v[24:25], v[28:29]
	v_pk_add_f32 v[16:17], v[18:19], v[16:17]
	v_pk_add_f32 v[18:19], v[20:21], v[22:23]
	v_mul_f32_e32 v21, v17, v17
	v_mul_f32_e32 v20, v19, v19
	v_fmac_f32_e32 v20, v18, v18
	v_fmac_f32_e32 v21, v16, v16
	v_add_f32_e32 v20, v20, v21
	s_nop 1
	v_add_f32_dpp v20, v20, v20 quad_perm:[1,0,3,2] row_mask:0xf bank_mask:0xf bound_ctrl:1
	s_nop 1
	v_add_f32_dpp v20, v20, v20 quad_perm:[2,3,0,1] row_mask:0xf bank_mask:0xf bound_ctrl:1
	s_nop 1
	v_add_f32_dpp v20, v20, v20 row_half_mirror row_mask:0xf bank_mask:0xf bound_ctrl:1
	s_nop 1
	v_add_f32_dpp v20, v20, v20 row_mirror row_mask:0xf bank_mask:0xf bound_ctrl:1
	s_nop 1
	v_mov_b32_dpp v1, v20 row_bcast:15 row_mask:0xa bank_mask:0xf
	v_add_f32_e32 v1, v20, v1
	s_nop 1
	v_mov_b32_dpp v10, v1 row_bcast:31 row_mask:0xc bank_mask:0xf
	v_add_f32_e32 v1, v1, v10
	s_nop 0
	v_readlane_b32 s6, v1, 63
	s_and_saveexec_b64 s[0:1], vcc
	s_lshl_b32 s7, s96, 2
	s_add_i32 s7, s7, 0
	v_mov_b32_e32 v1, s7
	v_mov_b32_e32 v10, s6
	ds_write_b32 v1, v10
	s_or_b64 exec, exec, s[0:1]
	s_waitcnt lgkmcnt(0)
	s_barrier
	ds_read_b128 v[20:23], v11
	ds_read_b128 v[24:27], v11 offset:16
	s_waitcnt vmcnt(2)
	v_pk_mul_f32 v[8:9], v[8:9], v[16:17]
	v_pk_mul_f32 v[6:7], v[6:7], v[18:19]
	s_waitcnt lgkmcnt(1)
	v_add_f32_e32 v1, 0, v20
	v_add_f32_e32 v1, v1, v21
	v_add_f32_e32 v1, v1, v22
	v_add_f32_e32 v1, v1, v23
	s_waitcnt lgkmcnt(0)
	v_add_f32_e32 v1, v1, v24
	v_add_f32_e32 v1, v1, v25
	v_add_f32_e32 v1, v1, v26
	v_add_f32_e32 v10, v1, v27
	v_mov_b32_e32 v1, 0x358637bd
	v_fmamk_f32 v10, v10, 0x3a000000, v1
	v_rsq_f32_e32 v10, v10
	s_waitcnt vmcnt(0)
	v_cvt_f32_f16_sdwa v21, v12 dst_sel:DWORD dst_unused:UNUSED_PAD src0_sel:WORD_1
	v_cvt_f32_f16_e32 v20, v12
	v_cvt_f32_f16_sdwa v23, v13 dst_sel:DWORD dst_unused:UNUSED_PAD src0_sel:WORD_1
	v_cvt_f32_f16_e32 v22, v13
	v_pk_fma_f32 v[6:7], v[6:7], v[10:11], v[20:21] op_sel_hi:[1,0,1]
	s_nop 0
	v_cvt_f16_f32_sdwa v12, v7 dst_sel:WORD_1 dst_unused:UNUSED_PAD src0_sel:DWORD
	v_pk_fma_f32 v[8:9], v[8:9], v[10:11], v[22:23] op_sel_hi:[1,0,1]
	v_cvt_f16_f32_e32 v10, v6
	v_cvt_f16_f32_e32 v13, v8
	v_cvt_f16_f32_sdwa v16, v9 dst_sel:WORD_1 dst_unused:UNUSED_PAD src0_sel:DWORD
	v_or_b32_e32 v12, v12, v10
	v_mul_f32_e32 v10, v7, v7
	v_or_b32_e32 v13, v16, v13
	global_store_dwordx2 v[14:15], v[12:13], off sc1
	v_mul_f32_e32 v12, v9, v9
	v_fmac_f32_e32 v10, v6, v6
	v_fmac_f32_e32 v12, v8, v8
	v_add_f32_e32 v10, v10, v12
	v_mov_b32_e32 v12, 0
	s_nop 0
	v_add_f32_dpp v10, v10, v10 quad_perm:[1,0,3,2] row_mask:0xf bank_mask:0xf bound_ctrl:1
	s_nop 1
	v_add_f32_dpp v10, v10, v10 quad_perm:[2,3,0,1] row_mask:0xf bank_mask:0xf bound_ctrl:1
	s_nop 1
	v_add_f32_dpp v10, v10, v10 row_half_mirror row_mask:0xf bank_mask:0xf bound_ctrl:1
	s_nop 1
	v_add_f32_dpp v10, v10, v10 row_mirror row_mask:0xf bank_mask:0xf bound_ctrl:1
	s_nop 1
	v_mov_b32_dpp v12, v10 row_bcast:15 row_mask:0xa bank_mask:0xf
	v_add_f32_e32 v10, v10, v12
	s_nop 1
	v_mov_b32_dpp v11, v10 row_bcast:31 row_mask:0xc bank_mask:0xf
	v_add_f32_e32 v10, v10, v11
	s_nop 0
	v_readlane_b32 s6, v10, 63
	s_and_saveexec_b64 s[0:1], vcc
	s_lshl_b32 s7, s96, 2
	s_add_i32 s7, s7, 0
	v_mov_b32_e32 v10, s7
	v_mov_b32_e32 v11, s6
	ds_write_b32 v10, v11 offset:32
	s_or_b64 exec, exec, s[0:1]
	v_mov_b32_e32 v10, 0
	s_waitcnt lgkmcnt(0)
	s_barrier
	ds_read_b128 v[12:15], v10 offset:32
	ds_read_b128 v[16:19], v10 offset:48
	v_pk_mul_f32 v[4:5], v[4:5], v[8:9]
	v_pk_mul_f32 v[6:7], v[2:3], v[6:7]
	s_waitcnt lgkmcnt(1)
	v_add_f32_e32 v11, 0, v12
	v_add_f32_e32 v11, v11, v13
	v_add_f32_e32 v11, v11, v14
	v_add_f32_e32 v11, v11, v15
	s_waitcnt lgkmcnt(0)
	v_add_f32_e32 v11, v11, v16
	v_add_f32_e32 v11, v11, v17
	v_add_f32_e32 v11, v11, v18
	v_add_f32_e32 v11, v11, v19
	v_fmac_f32_e32 v1, 0x3a000000, v11
	v_rsq_f32_e32 v12, v1
	s_nop 0
	v_pk_mul_f32 v[2:3], v[4:5], v[12:13] op_sel_hi:[1,0]
	v_pk_mul_f32 v[4:5], v[6:7], v[12:13] op_sel_hi:[1,0]
	v_max_f32_e64 v1, |v2|, |v3|
	v_max3_f32 v1, |v4|, |v5|, v1
	v_mov_b32_e32 v6, 0
	s_nop 1
	v_mov_b32_dpp v6, v1 quad_perm:[1,0,3,2] row_mask:0xf bank_mask:0xf
	v_max_f32_e32 v6, v6, v6
	v_max_f32_e32 v1, v1, v6
	v_mov_b32_e32 v6, 0
	s_nop 1
	v_mov_b32_dpp v6, v1 quad_perm:[2,3,0,1] row_mask:0xf bank_mask:0xf
	v_max_f32_e32 v6, v6, v6
	v_max_f32_e32 v1, v1, v6
	v_mov_b32_e32 v6, 0
	s_nop 1
	v_mov_b32_dpp v6, v1 row_half_mirror row_mask:0xf bank_mask:0xf
	v_max_f32_e32 v6, v6, v6
	v_max_f32_e32 v1, v1, v6
	v_mov_b32_e32 v6, 0
	s_nop 1
	v_mov_b32_dpp v6, v1 row_mirror row_mask:0xf bank_mask:0xf
	v_max_f32_e32 v6, v6, v6
	v_max_f32_e32 v1, v1, v6
	v_mov_b32_e32 v6, 0
	s_nop 1
	v_mov_b32_dpp v6, v1 row_bcast:15 row_mask:0xa bank_mask:0xf
	v_max_f32_e32 v6, v6, v6
	v_max_f32_e32 v1, v1, v6
	v_mov_b32_e32 v6, 0
	s_nop 1
	v_mov_b32_dpp v6, v1 row_bcast:31 row_mask:0xc bank_mask:0xf
	v_max_f32_e32 v6, v6, v6
	v_max_f32_e32 v1, v1, v6
	s_nop 0
	v_readlane_b32 s6, v1, 63
	s_and_saveexec_b64 s[0:1], vcc
	s_lshl_b32 s7, s96, 2
	s_add_i32 s7, s7, 0
	v_mov_b32_e32 v1, s7
	v_mov_b32_e32 v6, s6
	ds_write_b32 v1, v6 offset:64
	s_or_b64 exec, exec, s[0:1]
	s_waitcnt lgkmcnt(0)
	s_barrier
	ds_read_b128 v[6:9], v10 offset:64
	ds_read_b128 v[10:13], v10 offset:80
	s_lshl_b64 s[6:7], s[4:5], 11
	s_waitcnt lgkmcnt(1)
	v_max3_f32 v1, v6, 0, v7
	v_max3_f32 v1, v1, v8, v9
	s_waitcnt lgkmcnt(0)
	v_max3_f32 v1, v1, v10, v11
	v_max3_f32 v1, v1, v12, v13
	v_cmp_lt_f32_e64 s[0:1], 0, v1
	s_mov_b64 s[8:9], exec
	v_readlane_b32 s10, v254, 36
	v_readlane_b32 s11, v254, 37
	s_and_b64 s[10:11], s[8:9], s[10:11]
	s_mov_b64 exec, s[10:11]
	s_cbranch_execz .LBB0_3311
	s_lshl_b64 s[4:5], s[4:5], 2
	v_mul_f32_e32 v6, 0x3c010204, v1
	s_add_u32 s4, s86, s4
	v_cndmask_b32_e64 v6, 1.0, v6, s[0:1]
	s_addc_u32 s5, s87, s5
	v_mov_b32_e32 v7, 0
	global_store_dword v7, v6, s[4:5]

.LBB0_3560:
	v_lshlrev_b32_e32 v104, 16, v94
	v_and_b32_e32 v105, 0xffff0000, v94
	v_lshlrev_b32_e32 v94, 16, v95
	v_and_b32_e32 v95, 0xffff0000, v95
	v_pk_mul_f32 v[106:107], v[94:95], v[94:95]
	v_lshlrev_b32_e32 v108, 16, v96
	v_pk_fma_f32 v[106:107], v[104:105], v[104:105], v[106:107]
	v_and_b32_e32 v109, 0xffff0000, v96
	v_pk_fma_f32 v[106:107], v[108:109], v[108:109], v[106:107]
	v_lshlrev_b32_e32 v96, 16, v97
	v_and_b32_e32 v97, 0xffff0000, v97
	v_pk_fma_f32 v[106:107], v[96:97], v[96:97], v[106:107]
	v_lshlrev_b32_e32 v110, 16, v90
	v_and_b32_e32 v111, 0xffff0000, v90
	v_pk_fma_f32 v[106:107], v[110:111], v[110:111], v[106:107]
	v_lshlrev_b32_e32 v90, 16, v91
	v_and_b32_e32 v91, 0xffff0000, v91
	v_pk_fma_f32 v[106:107], v[90:91], v[90:91], v[106:107]
	v_lshlrev_b32_e32 v112, 16, v92
	v_and_b32_e32 v113, 0xffff0000, v92
	v_pk_fma_f32 v[106:107], v[112:113], v[112:113], v[106:107]
	v_lshlrev_b32_e32 v92, 16, v93
	v_and_b32_e32 v93, 0xffff0000, v93
	v_pk_fma_f32 v[106:107], v[92:93], v[92:93], v[106:107]
	v_lshlrev_b32_e32 v114, 16, v86
	v_and_b32_e32 v115, 0xffff0000, v86
	v_pk_fma_f32 v[106:107], v[114:115], v[114:115], v[106:107]
	v_lshlrev_b32_e32 v86, 16, v87
	v_and_b32_e32 v87, 0xffff0000, v87
	v_pk_fma_f32 v[106:107], v[86:87], v[86:87], v[106:107]
	v_lshlrev_b32_e32 v116, 16, v88
	v_and_b32_e32 v117, 0xffff0000, v88
	v_pk_fma_f32 v[106:107], v[116:117], v[116:117], v[106:107]
	v_lshlrev_b32_e32 v88, 16, v89
	v_and_b32_e32 v89, 0xffff0000, v89
	v_pk_fma_f32 v[106:107], v[88:89], v[88:89], v[106:107]
	v_lshlrev_b32_e32 v118, 16, v82
	v_and_b32_e32 v119, 0xffff0000, v82
	v_pk_fma_f32 v[106:107], v[118:119], v[118:119], v[106:107]
	v_lshlrev_b32_e32 v82, 16, v83
	v_and_b32_e32 v83, 0xffff0000, v83
	v_pk_fma_f32 v[106:107], v[82:83], v[82:83], v[106:107]
	v_lshlrev_b32_e32 v120, 16, v84
	v_and_b32_e32 v121, 0xffff0000, v84
	v_pk_fma_f32 v[106:107], v[120:121], v[120:121], v[106:107]
	v_lshlrev_b32_e32 v84, 16, v85
	v_and_b32_e32 v85, 0xffff0000, v85
	v_pk_fma_f32 v[106:107], v[84:85], v[84:85], v[106:107]
	v_cvt_f32_f16_sdwa v123, v78 dst_sel:DWORD dst_unused:UNUSED_PAD src0_sel:WORD_1
	v_add_f32_e32 v103, v106, v107
	v_mov_b32_e32 v106, 0
	v_cvt_f32_f16_e32 v122, v78
	v_add_f32_dpp v103, v103, v103 quad_perm:[1,0,3,2] row_mask:0xf bank_mask:0xf bound_ctrl:1
	v_cvt_f32_f16_sdwa v125, v79 dst_sel:DWORD dst_unused:UNUSED_PAD src0_sel:WORD_1
	v_cvt_f32_f16_e32 v124, v79
	v_add_f32_dpp v103, v103, v103 quad_perm:[2,3,0,1] row_mask:0xf bank_mask:0xf bound_ctrl:1
	v_cvt_f32_f16_sdwa v79, v80 dst_sel:DWORD dst_unused:UNUSED_PAD src0_sel:WORD_1
	v_cvt_f32_f16_e32 v78, v80
	v_add_f32_dpp v103, v103, v103 row_half_mirror row_mask:0xf bank_mask:0xf bound_ctrl:1
	v_cvt_f32_f16_sdwa v127, v81 dst_sel:DWORD dst_unused:UNUSED_PAD src0_sel:WORD_1
	v_cvt_f32_f16_e32 v126, v81
	v_add_f32_dpp v103, v103, v103 row_mirror row_mask:0xf bank_mask:0xf bound_ctrl:1
	v_cvt_f32_f16_sdwa v81, v74 dst_sel:DWORD dst_unused:UNUSED_PAD src0_sel:WORD_1
	v_cvt_f32_f16_e32 v80, v74
	v_mov_b32_dpp v106, v103 row_bcast:15 row_mask:0xa bank_mask:0xf
	v_add_f32_e32 v103, v103, v106
	v_mov_b32_e32 v106, 0
	v_cvt_f32_f16_sdwa v129, v75 dst_sel:DWORD dst_unused:UNUSED_PAD src0_sel:WORD_1
	v_cvt_f32_f16_e32 v128, v75
	v_mov_b32_dpp v106, v103 row_bcast:31 row_mask:0xc bank_mask:0xf
	v_add_f32_e32 v103, v103, v106
	v_cvt_f32_f16_sdwa v75, v76 dst_sel:DWORD dst_unused:UNUSED_PAD src0_sel:WORD_1
	v_readlane_b32 s5, v103, 63
	v_cvt_f32_f16_e32 v74, v76
	v_cvt_f32_f16_sdwa v131, v77 dst_sel:DWORD dst_unused:UNUSED_PAD src0_sel:WORD_1
	v_fma_f32 v103, s5, v102, v1
	v_rsq_f32_e32 v103, v103
	v_cvt_f32_f16_e32 v130, v77
	v_cvt_f32_f16_sdwa v77, v70 dst_sel:DWORD dst_unused:UNUSED_PAD src0_sel:WORD_1
	v_cvt_f32_f16_e32 v76, v70
	v_mul_f32_e32 v106, 0.5, v103
	v_cvt_f32_f16_sdwa v133, v71 dst_sel:DWORD dst_unused:UNUSED_PAD src0_sel:WORD_1
	v_cvt_f32_f16_e32 v132, v71
	v_cvt_f32_f16_sdwa v71, v72 dst_sel:DWORD dst_unused:UNUSED_PAD src0_sel:WORD_1
	v_cvt_f32_f16_e32 v70, v72
	v_cvt_f32_f16_sdwa v135, v73 dst_sel:DWORD dst_unused:UNUSED_PAD src0_sel:WORD_1
	v_cvt_f32_f16_e32 v134, v73
	v_cvt_f32_f16_sdwa v73, v66 dst_sel:DWORD dst_unused:UNUSED_PAD src0_sel:WORD_1
	v_cvt_f32_f16_e32 v72, v66
	v_cvt_f32_f16_sdwa v137, v67 dst_sel:DWORD dst_unused:UNUSED_PAD src0_sel:WORD_1
	v_cvt_f32_f16_e32 v136, v67
	v_cvt_f32_f16_sdwa v139, v68 dst_sel:DWORD dst_unused:UNUSED_PAD src0_sel:WORD_1
	v_cvt_f32_f16_e32 v138, v68
	v_cvt_f32_f16_sdwa v141, v69 dst_sel:DWORD dst_unused:UNUSED_PAD src0_sel:WORD_1
	v_cvt_f32_f16_e32 v140, v69
	v_pk_mul_f32 v[66:67], v[6:7], v[104:105]
	v_pk_mul_f32 v[68:69], v[8:9], v[94:95]
	v_pk_fma_f32 v[66:67], v[66:67], v[106:107], v[122:123] op_sel_hi:[1,0,1]
	v_pk_fma_f32 v[68:69], v[68:69], v[106:107], v[124:125] op_sel_hi:[1,0,1]
	global_store_dwordx4 v[100:101], v[66:69], off offset:-4096 sc1
	v_lshl_add_u64 v[98:99], v[98:99], 0, s[8:9]
	s_andn2_b64 vcc, exec, s[12:13]
	v_pk_mul_f32 v[66:67], v[2:3], v[108:109]
	v_pk_mul_f32 v[68:69], v[4:5], v[96:97]
	v_pk_fma_f32 v[66:67], v[66:67], v[106:107], v[78:79] op_sel_hi:[1,0,1]
	v_pk_fma_f32 v[68:69], v[68:69], v[106:107], v[126:127] op_sel_hi:[1,0,1]
	global_store_dwordx4 v[100:101], v[66:69], off offset:-4080 sc1
	s_waitcnt vmcnt(7)
	v_mov_b64_e32 v[96:97], v[44:45]
	v_mov_b64_e32 v[94:95], v[42:43]
	v_pk_mul_f32 v[66:67], v[14:15], v[110:111]
	v_pk_mul_f32 v[68:69], v[16:17], v[90:91]
	v_pk_fma_f32 v[66:67], v[66:67], v[106:107], v[80:81] op_sel_hi:[1,0,1]
	v_pk_fma_f32 v[68:69], v[68:69], v[106:107], v[128:129] op_sel_hi:[1,0,1]
	global_store_dwordx4 v[100:101], v[66:69], off offset:-2048 sc1
	v_mov_b64_e32 v[80:81], v[36:37]
	v_mov_b64_e32 v[78:79], v[34:35]
	v_pk_mul_f32 v[66:67], v[10:11], v[112:113]
	v_pk_mul_f32 v[68:69], v[12:13], v[92:93]
	v_pk_fma_f32 v[66:67], v[66:67], v[106:107], v[74:75] op_sel_hi:[1,0,1]
	v_pk_fma_f32 v[68:69], v[68:69], v[106:107], v[130:131] op_sel_hi:[1,0,1]
	global_store_dwordx4 v[100:101], v[66:69], off offset:-2032 sc1
	s_waitcnt vmcnt(8)
	v_mov_b64_e32 v[92:93], v[48:49]
	v_mov_b64_e32 v[90:91], v[46:47]
	v_pk_mul_f32 v[66:67], v[22:23], v[114:115]
	v_pk_mul_f32 v[68:69], v[24:25], v[86:87]
	v_pk_fma_f32 v[66:67], v[66:67], v[106:107], v[76:77] op_sel_hi:[1,0,1]
	v_pk_fma_f32 v[68:69], v[68:69], v[106:107], v[132:133] op_sel_hi:[1,0,1]
	global_store_dwordx4 v[100:101], v[66:69], off sc1
	v_mov_b64_e32 v[76:77], v[40:41]
	v_mov_b64_e32 v[74:75], v[38:39]
	v_pk_mul_f32 v[66:67], v[18:19], v[116:117]
	v_pk_mul_f32 v[68:69], v[20:21], v[88:89]
	v_pk_fma_f32 v[66:67], v[66:67], v[106:107], v[70:71] op_sel_hi:[1,0,1]
	v_pk_fma_f32 v[68:69], v[68:69], v[106:107], v[134:135] op_sel_hi:[1,0,1]
	global_store_dwordx4 v[100:101], v[66:69], off offset:16 sc1
	s_waitcnt vmcnt(7)
	v_mov_b64_e32 v[88:89], v[56:57]
	v_mov_b64_e32 v[86:87], v[54:55]
	s_waitcnt vmcnt(6)
	v_pk_mul_f32 v[66:67], v[30:31], v[118:119]
	v_pk_mul_f32 v[68:69], v[32:33], v[82:83]
	v_pk_fma_f32 v[66:67], v[66:67], v[106:107], v[72:73] op_sel_hi:[1,0,1]
	v_pk_fma_f32 v[68:69], v[68:69], v[106:107], v[136:137] op_sel_hi:[1,0,1]
	global_store_dwordx4 v[100:101], v[66:69], off offset:2048 sc1
	v_mov_b64_e32 v[72:73], v[52:53]
	v_mov_b64_e32 v[70:71], v[50:51]
	v_pk_mul_f32 v[66:67], v[26:27], v[120:121]
	v_pk_mul_f32 v[68:69], v[28:29], v[84:85]
	v_pk_fma_f32 v[66:67], v[66:67], v[106:107], v[138:139] op_sel_hi:[1,0,1]
	v_pk_fma_f32 v[68:69], v[68:69], v[106:107], v[140:141] op_sel_hi:[1,0,1]
	global_store_dwordx4 v[100:101], v[66:69], off offset:2064 sc1
	v_mov_b64_e32 v[84:85], v[64:65]
	v_lshl_add_u64 v[100:101], v[100:101], 0, s[10:11]
	v_mov_b64_e32 v[68:69], v[60:61]
	v_mov_b64_e32 v[82:83], v[62:63]
	v_mov_b64_e32 v[66:67], v[58:59]
	s_cbranch_vccz .LBB0_3563

.LBB0_3566:
	s_cmp_gt_i32 s2, 31
	s_cbranch_scc1 .LBB0_3568
	s_ashr_i32 s3, s2, 31
	s_lshl_b64 s[4:5], s[2:3], 13
	v_readlane_b32 s6, v254, 58
	v_readlane_b32 s7, v254, 59
	s_add_u32 s4, s6, s4
	s_addc_u32 s5, s7, s5
	s_add_u32 s6, s4, 0x40000
	v_lshlrev_b32_e32 v1, 4, v166
	s_addc_u32 s7, s5, 0
	v_or_b32_e32 v134, 0x400, v1
	v_or_b32_e32 v138, 0x800, v1
	s_add_u32 s8, s4, 0x80000
	global_load_dwordx4 v[10:13], v1, s[4:5]
	global_load_dwordx4 v[6:9], v1, s[4:5] offset:1024
	global_load_dwordx4 v[2:5], v1, s[4:5] offset:2048
	global_load_dwordx4 v[14:17], v1, s[4:5] offset:3072
	global_load_dwordx4 v[18:21], v1, s[6:7]
	global_load_dwordx4 v[22:25], v134, s[6:7]
	global_load_dwordx4 v[26:29], v138, s[6:7]
	s_addc_u32 s9, s5, 0
	v_or_b32_e32 v142, 0xc00, v1
	s_add_u32 s10, s4, 0xc0000
	global_load_dwordx4 v[30:33], v142, s[6:7]
	s_addc_u32 s11, s5, 0
	global_load_dwordx4 v[50:53], v1, s[8:9]
	global_load_dwordx4 v[54:57], v1, s[10:11]
	global_load_dwordx4 v[58:61], v134, s[8:9]
	global_load_dwordx4 v[62:65], v134, s[10:11]
	global_load_dwordx4 v[66:69], v138, s[8:9]
	global_load_dwordx4 v[70:73], v138, s[10:11]
	global_load_dwordx4 v[74:77], v142, s[8:9]
	global_load_dwordx4 v[78:81], v142, s[10:11]
	v_or_b32_e32 v162, 0x1000, v1
	global_load_dwordx4 v[82:85], v162, s[4:5]
	global_load_dwordx4 v[86:89], v162, s[6:7]
	global_load_dwordx4 v[90:93], v162, s[8:9]
	global_load_dwordx4 v[94:97], v162, s[10:11]
	v_or_b32_e32 v163, 0x1400, v1
	global_load_dwordx4 v[98:101], v163, s[4:5]
	global_load_dwordx4 v[102:105], v163, s[6:7]
	global_load_dwordx4 v[106:109], v163, s[8:9]
	global_load_dwordx4 v[110:113], v163, s[10:11]
	v_or_b32_e32 v164, 0x1800, v1
	global_load_dwordx4 v[114:117], v164, s[4:5]
	global_load_dwordx4 v[118:121], v164, s[6:7]
	global_load_dwordx4 v[122:125], v164, s[8:9]
	global_load_dwordx4 v[126:129], v164, s[10:11]
	v_or_b32_e32 v165, 0x1c00, v1
	global_load_dwordx4 v[34:37], v165, s[4:5]
	global_load_dwordx4 v[42:45], v165, s[6:7]
	global_load_dwordx4 v[38:41], v165, s[8:9]
	global_load_dwordx4 v[46:49], v165, s[10:11]
	s_addk_i32 s2, 0x2000
	s_ashr_i32 s3, s2, 31
	s_lshl_b64 s[4:5], s[2:3], 12
	v_readlane_b32 s6, v254, 54
	v_readlane_b32 s7, v254, 55
	s_add_u32 s4, s6, s4
	v_lshlrev_b32_e32 v160, 3, v166
	global_load_dwordx4 v[130:133], v1, s[0:1]
	s_nop 0
	global_load_dwordx4 v[134:137], v134, s[0:1]
	s_nop 0
	global_load_dwordx4 v[138:141], v138, s[0:1]
	s_nop 0
	global_load_dwordx4 v[142:145], v142, s[0:1]
	s_addc_u32 s5, s7, s5
	global_load_dwordx2 v[146:147], v160, s[4:5]
	global_load_dwordx2 v[148:149], v160, s[4:5] offset:512
	global_load_dwordx2 v[150:151], v160, s[4:5] offset:1024
	global_load_dwordx2 v[152:153], v160, s[4:5] offset:1536
	global_load_dwordx2 v[154:155], v160, s[4:5] offset:2048
	global_load_dwordx2 v[156:157], v160, s[4:5] offset:2560
	global_load_dwordx2 v[158:159], v160, s[4:5] offset:3072
	s_nop 0
	global_load_dwordx2 v[160:161], v160, s[4:5] offset:3584
	s_lshl_b64 s[2:3], s[2:3], 13
	s_add_u32 s2, s92, s2
	s_addc_u32 s3, s93, s3
	s_waitcnt vmcnt(39)
	v_pk_add_f32 v[12:13], v[12:13], v[20:21]
	v_pk_add_f32 v[10:11], v[10:11], v[18:19]
	s_waitcnt vmcnt(37)
	v_pk_add_f32 v[4:5], v[4:5], v[28:29]
	v_pk_add_f32 v[2:3], v[2:3], v[26:27]
	v_pk_add_f32 v[8:9], v[8:9], v[24:25]
	v_pk_add_f32 v[6:7], v[6:7], v[22:23]
	s_waitcnt vmcnt(30)
	v_pk_add_f32 v[26:27], v[68:69], v[72:73]
	v_pk_add_f32 v[28:29], v[66:67], v[70:71]
	v_pk_add_f32 v[26:27], v[4:5], v[26:27]
	v_pk_add_f32 v[28:29], v[2:3], v[28:29]
	global_load_dwordx4 v[2:5], v162, s[0:1]
	v_pk_add_f32 v[18:19], v[52:53], v[56:57]
	v_pk_add_f32 v[20:21], v[50:51], v[54:55]
	v_pk_add_f32 v[22:23], v[60:61], v[64:65]
	v_pk_add_f32 v[24:25], v[58:59], v[62:63]
	v_pk_add_f32 v[18:19], v[12:13], v[18:19]
	v_pk_add_f32 v[20:21], v[10:11], v[20:21]
	v_pk_add_f32 v[22:23], v[8:9], v[22:23]
	v_pk_add_f32 v[24:25], v[6:7], v[24:25]
	s_waitcnt vmcnt(27)
	v_pk_add_f32 v[6:7], v[84:85], v[88:89]
	v_pk_add_f32 v[8:9], v[82:83], v[86:87]
	s_waitcnt vmcnt(25)
	v_pk_add_f32 v[10:11], v[92:93], v[96:97]
	v_pk_add_f32 v[12:13], v[90:91], v[94:95]
	v_pk_add_f32 v[50:51], v[6:7], v[10:11]
	v_pk_add_f32 v[52:53], v[8:9], v[12:13]
	global_load_dwordx4 v[6:9], v163, s[0:1]
	v_pk_add_f32 v[16:17], v[16:17], v[32:33]
	v_pk_add_f32 v[14:15], v[14:15], v[30:31]
	v_pk_add_f32 v[30:31], v[76:77], v[80:81]
	v_pk_add_f32 v[32:33], v[74:75], v[78:79]
	v_pk_add_f32 v[30:31], v[16:17], v[30:31]
	v_pk_add_f32 v[32:33], v[14:15], v[32:33]
	s_waitcnt vmcnt(24)
	v_pk_add_f32 v[10:11], v[100:101], v[104:105]
	v_pk_add_f32 v[12:13], v[98:99], v[102:103]
	s_waitcnt vmcnt(22)
	v_pk_add_f32 v[14:15], v[108:109], v[112:113]
	v_pk_add_f32 v[16:17], v[106:107], v[110:111]
	v_pk_add_f32 v[54:55], v[10:11], v[14:15]
	v_pk_add_f32 v[56:57], v[12:13], v[16:17]
	global_load_dwordx4 v[10:13], v164, s[0:1]
	s_waitcnt vmcnt(21)
	v_pk_add_f32 v[14:15], v[116:117], v[120:121]
	v_pk_add_f32 v[16:17], v[114:115], v[118:119]
	s_waitcnt vmcnt(19)
	v_pk_add_f32 v[58:59], v[124:125], v[128:129]
	v_pk_add_f32 v[60:61], v[122:123], v[126:127]
	v_pk_add_f32 v[58:59], v[14:15], v[58:59]
	v_pk_add_f32 v[60:61], v[16:17], v[60:61]
	global_load_dwordx4 v[14:17], v165, s[0:1]
	s_waitcnt vmcnt(18)
	v_pk_add_f32 v[36:37], v[36:37], v[44:45]
	s_waitcnt vmcnt(16)
	v_pk_add_f32 v[40:41], v[40:41], v[48:49]
	v_pk_add_f32 v[34:35], v[34:35], v[42:43]
	v_pk_add_f32 v[36:37], v[36:37], v[40:41]
	v_mul_f32_e32 v40, v25, v25
	v_mul_f32_e32 v41, v23, v23
	v_fmac_f32_e32 v40, v24, v24
	v_fmac_f32_e32 v41, v22, v22
	v_add_f32_e32 v40, v40, v41
	v_mul_f32_e32 v41, v29, v29
	v_mul_f32_e32 v42, v27, v27
	v_fmac_f32_e32 v41, v28, v28
	v_fmac_f32_e32 v42, v26, v26
	v_add_f32_e32 v41, v41, v42
	v_mul_f32_e32 v42, v33, v33
	v_mul_f32_e32 v43, v31, v31
	v_pk_add_f32 v[38:39], v[38:39], v[46:47]
	v_fmac_f32_e32 v42, v32, v32
	v_fmac_f32_e32 v43, v30, v30
	v_pk_add_f32 v[34:35], v[34:35], v[38:39]
	v_mul_f32_e32 v38, v21, v21
	v_mul_f32_e32 v39, v19, v19
	v_add_f32_e32 v42, v42, v43
	v_mul_f32_e32 v43, v53, v53
	v_mul_f32_e32 v44, v51, v51
	v_fmac_f32_e32 v39, v18, v18
	v_fmac_f32_e32 v43, v52, v52
	v_fmac_f32_e32 v44, v50, v50
	v_fmac_f32_e32 v38, v20, v20
	v_add_f32_e32 v43, v43, v44
	v_mul_f32_e32 v44, v57, v57
	v_mul_f32_e32 v45, v55, v55
	v_add_f32_e32 v38, v38, v39
	v_fmac_f32_e32 v44, v56, v56
	v_fmac_f32_e32 v45, v54, v54
	v_add_f32_e32 v38, v38, v40
	v_add_f32_e32 v44, v44, v45
	v_mul_f32_e32 v45, v61, v61
	v_mul_f32_e32 v46, v59, v59
	v_add_f32_e32 v38, v38, v41
	v_fmac_f32_e32 v45, v60, v60
	v_fmac_f32_e32 v46, v58, v58
	v_add_f32_e32 v38, v38, v42
	v_add_f32_e32 v45, v45, v46
	v_mul_f32_e32 v46, v35, v35
	v_mul_f32_e32 v47, v37, v37
	v_add_f32_e32 v38, v38, v43
	v_fmac_f32_e32 v46, v34, v34
	v_fmac_f32_e32 v47, v36, v36
	v_add_f32_e32 v38, v38, v44
	v_add_f32_e32 v46, v46, v47
	v_add_f32_e32 v38, v38, v45
	v_add_f32_e32 v38, v38, v46
	v_mov_b32_e32 v40, 0
	v_mov_b32_e32 v39, 0
	v_add_f32_dpp v38, v38, v38 quad_perm:[1,0,3,2] row_mask:0xf bank_mask:0xf bound_ctrl:1
	s_waitcnt vmcnt(11)
	v_cvt_f32_f16_sdwa v41, v146 dst_sel:DWORD dst_unused:UNUSED_PAD src0_sel:WORD_1
	v_cvt_f32_f16_e32 v42, v147
	v_add_f32_dpp v38, v38, v38 quad_perm:[2,3,0,1] row_mask:0xf bank_mask:0xf bound_ctrl:1
	v_cvt_f32_f16_sdwa v43, v147 dst_sel:DWORD dst_unused:UNUSED_PAD src0_sel:WORD_1
	v_pk_mul_f32 v[18:19], v[18:19], v[132:133]
	v_add_f32_dpp v38, v38, v38 row_half_mirror row_mask:0xf bank_mask:0xf bound_ctrl:1
	v_pk_mul_f32 v[44:45], v[20:21], v[130:131]
	v_pk_mul_f32 v[22:23], v[22:23], v[136:137]
	v_add_f32_dpp v38, v38, v38 row_mirror row_mask:0xf bank_mask:0xf bound_ctrl:1
	v_pk_mul_f32 v[26:27], v[26:27], v[140:141]
	v_pk_mul_f32 v[30:31], v[30:31], v[144:145]
	v_mov_b32_dpp v40, v38 row_bcast:15 row_mask:0xa bank_mask:0xf
	v_add_f32_e32 v38, v38, v40
	v_cvt_f32_f16_e32 v40, v146
	s_waitcnt vmcnt(3)
	v_pk_mul_f32 v[4:5], v[50:51], v[4:5]
	v_mov_b32_dpp v39, v38 row_bcast:31 row_mask:0xc bank_mask:0xf
	v_add_f32_e32 v38, v38, v39
	v_mov_b32_e32 v39, 0x3a000000
	v_readlane_b32 s4, v38, 63
	v_mov_b32_e32 v38, 0x358637bd
	v_pk_mul_f32 v[2:3], v[52:53], v[2:3]
	v_fmac_f32_e32 v38, s4, v39
	v_rsq_f32_e32 v38, v38
	s_waitcnt vmcnt(2)
	v_pk_mul_f32 v[8:9], v[54:55], v[8:9]
	v_pk_mul_f32 v[6:7], v[56:57], v[6:7]
	s_waitcnt vmcnt(1)
	v_pk_mul_f32 v[12:13], v[58:59], v[12:13]
	v_mul_f32_e32 v38, 0.5, v38
	v_pk_fma_f32 v[20:21], v[18:19], v[38:39], v[42:43] op_sel_hi:[1,0,1]
	v_pk_fma_f32 v[18:19], v[44:45], v[38:39], v[40:41] op_sel_hi:[1,0,1]
	v_cvt_f32_f16_e32 v40, v148
	v_cvt_f32_f16_e32 v42, v149
	v_cvt_f32_f16_sdwa v43, v149 dst_sel:DWORD dst_unused:UNUSED_PAD src0_sel:WORD_1
	v_cvt_f32_f16_sdwa v41, v148 dst_sel:DWORD dst_unused:UNUSED_PAD src0_sel:WORD_1
	v_pk_mul_f32 v[44:45], v[24:25], v[134:135]
	v_pk_mul_f32 v[10:11], v[60:61], v[10:11]
	v_pk_fma_f32 v[24:25], v[22:23], v[38:39], v[42:43] op_sel_hi:[1,0,1]
	v_pk_fma_f32 v[22:23], v[44:45], v[38:39], v[40:41] op_sel_hi:[1,0,1]
	v_cvt_f32_f16_e32 v40, v150
	v_cvt_f32_f16_e32 v42, v151
	v_cvt_f32_f16_sdwa v43, v151 dst_sel:DWORD dst_unused:UNUSED_PAD src0_sel:WORD_1
	v_cvt_f32_f16_sdwa v41, v150 dst_sel:DWORD dst_unused:UNUSED_PAD src0_sel:WORD_1
	v_pk_mul_f32 v[44:45], v[28:29], v[138:139]
	s_waitcnt vmcnt(0)
	v_pk_mul_f32 v[16:17], v[36:37], v[16:17]
	v_pk_fma_f32 v[28:29], v[26:27], v[38:39], v[42:43] op_sel_hi:[1,0,1]
	v_pk_fma_f32 v[26:27], v[44:45], v[38:39], v[40:41] op_sel_hi:[1,0,1]
	v_cvt_f32_f16_e32 v40, v152
	v_cvt_f32_f16_e32 v42, v153
	v_cvt_f32_f16_sdwa v43, v153 dst_sel:DWORD dst_unused:UNUSED_PAD src0_sel:WORD_1
	v_cvt_f32_f16_sdwa v41, v152 dst_sel:DWORD dst_unused:UNUSED_PAD src0_sel:WORD_1
	v_pk_mul_f32 v[44:45], v[32:33], v[142:143]
	v_pk_mul_f32 v[14:15], v[34:35], v[14:15]
	v_pk_fma_f32 v[32:33], v[30:31], v[38:39], v[42:43] op_sel_hi:[1,0,1]
	v_pk_fma_f32 v[30:31], v[44:45], v[38:39], v[40:41] op_sel_hi:[1,0,1]
	v_cvt_f32_f16_e32 v40, v154
	v_cvt_f32_f16_e32 v42, v155
	v_cvt_f32_f16_sdwa v43, v155 dst_sel:DWORD dst_unused:UNUSED_PAD src0_sel:WORD_1
	v_cvt_f32_f16_sdwa v41, v154 dst_sel:DWORD dst_unused:UNUSED_PAD src0_sel:WORD_1
	v_pk_fma_f32 v[4:5], v[4:5], v[38:39], v[42:43] op_sel_hi:[1,0,1]
	v_pk_fma_f32 v[2:3], v[2:3], v[38:39], v[40:41] op_sel_hi:[1,0,1]
	v_cvt_f32_f16_e32 v40, v156
	v_cvt_f32_f16_e32 v42, v157
	v_cvt_f32_f16_sdwa v43, v157 dst_sel:DWORD dst_unused:UNUSED_PAD src0_sel:WORD_1
	v_cvt_f32_f16_sdwa v41, v156 dst_sel:DWORD dst_unused:UNUSED_PAD src0_sel:WORD_1
	v_pk_fma_f32 v[8:9], v[8:9], v[38:39], v[42:43] op_sel_hi:[1,0,1]
	v_pk_fma_f32 v[6:7], v[6:7], v[38:39], v[40:41] op_sel_hi:[1,0,1]
	v_cvt_f32_f16_e32 v40, v158
	v_cvt_f32_f16_e32 v42, v159
	v_cvt_f32_f16_sdwa v43, v159 dst_sel:DWORD dst_unused:UNUSED_PAD src0_sel:WORD_1
	v_cvt_f32_f16_sdwa v41, v158 dst_sel:DWORD dst_unused:UNUSED_PAD src0_sel:WORD_1
	v_pk_fma_f32 v[12:13], v[12:13], v[38:39], v[42:43] op_sel_hi:[1,0,1]
	v_pk_fma_f32 v[10:11], v[10:11], v[38:39], v[40:41] op_sel_hi:[1,0,1]
	v_cvt_f32_f16_e32 v40, v160
	v_cvt_f32_f16_e32 v42, v161
	v_cvt_f32_f16_sdwa v43, v161 dst_sel:DWORD dst_unused:UNUSED_PAD src0_sel:WORD_1
	v_cvt_f32_f16_sdwa v41, v160 dst_sel:DWORD dst_unused:UNUSED_PAD src0_sel:WORD_1
	v_pk_fma_f32 v[16:17], v[16:17], v[38:39], v[42:43] op_sel_hi:[1,0,1]
	v_pk_fma_f32 v[14:15], v[14:15], v[38:39], v[40:41] op_sel_hi:[1,0,1]
	global_store_dwordx4 v1, v[18:21], s[2:3] sc1
	global_store_dwordx4 v1, v[22:25], s[2:3] offset:1024 sc1
	global_store_dwordx4 v1, v[26:29], s[2:3] offset:2048 sc1
	global_store_dwordx4 v1, v[30:33], s[2:3] offset:3072 sc1
	global_store_dwordx4 v162, v[2:5], s[2:3] sc1
	global_store_dwordx4 v163, v[6:9], s[2:3] sc1
	global_store_dwordx4 v164, v[10:13], s[2:3] sc1
	global_store_dwordx4 v165, v[14:17], s[2:3] sc1

.LBB0_3569:
	s_cbranch_execz .LBB0_3574
	s_ashr_i32 s3, s90, 5
	s_abs_i32 s2, s3
	v_cvt_f32_u32_e32 v1, s2
	s_sub_i32 s6, 0, s2
	s_abs_i32 s4, s62
	s_xor_b32 s5, s62, s3
	v_rcp_iflag_f32_e32 v1, v1
	s_ashr_i32 s5, s5, 31
	v_mul_f32_e32 v1, 0x4f7ffffe, v1
	v_cvt_u32_f32_e32 v1, v1
	s_nop 0
	v_readfirstlane_b32 s7, v1
	s_mul_i32 s6, s6, s7
	s_mul_hi_u32 s6, s7, s6
	s_add_i32 s7, s7, s6
	s_mul_hi_u32 s6, s4, s7
	s_mul_i32 s7, s6, s2
	s_sub_i32 s4, s4, s7
	s_add_i32 s8, s6, 1
	s_sub_i32 s7, s4, s2
	s_cmp_ge_u32 s4, s2
	s_cselect_b32 s6, s8, s6
	s_cselect_b32 s4, s7, s4
	s_add_i32 s7, s6, 1
	s_cmp_ge_u32 s4, s2
	s_cselect_b32 s2, s7, s6
	s_xor_b32 s2, s2, s5
	s_sub_i32 s2, s2, s5
	s_mul_i32 s3, s2, s3
	s_sub_i32 s3, s62, s3
	s_cmp_lg_u32 s3, 0
	s_cbranch_scc1 .LBB0_3574
	s_ashr_i32 s3, s2, 31
	s_lshl_b64 s[4:5], s[2:3], 13
	v_readlane_b32 s6, v254, 58
	v_readlane_b32 s7, v254, 59
	s_add_u32 s4, s6, s4
	s_addc_u32 s5, s7, s5
	v_mov_b32_e32 v5, 0
	v_lshlrev_b32_e32 v4, 4, v0
	v_lshl_add_u64 v[2:3], s[4:5], 0, v[4:5]
	v_add_co_u32_e32 v6, vcc, 0x40000, v2
	global_load_dwordx4 v[8:11], v4, s[4:5]
	s_nop 0
	v_addc_co_u32_e32 v7, vcc, 0, v3, vcc
	v_add_co_u32_e32 v20, vcc, 0x80000, v2
	s_add_i32 s4, s2, 0x2000
	s_nop 0
	v_addc_co_u32_e32 v21, vcc, 0, v3, vcc
	v_add_co_u32_e32 v2, vcc, 0xc0000, v2
	global_load_dwordx4 v[12:15], v[6:7], off
	global_load_dwordx4 v[16:19], v[20:21], off
	v_addc_co_u32_e32 v3, vcc, 0, v3, vcc
	global_load_dwordx4 v[20:23], v[2:3], off
	s_ashr_i32 s5, s4, 31
	s_lshl_b64 s[2:3], s[4:5], 11
	s_lshl_b64 s[4:5], s[4:5], 12
	v_readlane_b32 s6, v254, 54
	v_readlane_b32 s7, v254, 55
	s_add_u32 s4, s6, s4
	s_addc_u32 s5, s7, s5
	v_lshlrev_b32_e32 v24, 3, v0
	global_load_dwordx4 v[0:3], v4, s[0:1]
	global_load_dwordx2 v[6:7], v24, s[4:5]
	v_mov_b32_e32 v24, v5
	v_mov_b32_e32 v25, v5
	v_cmp_eq_u32_e32 vcc, 0, v166
	s_waitcnt vmcnt(4)
	v_pk_add_f32 v[10:11], v[10:11], v[14:15]
	v_pk_add_f32 v[12:13], v[8:9], v[12:13]
	s_waitcnt vmcnt(2)
	v_pk_add_f32 v[8:9], v[18:19], v[22:23]
	v_pk_add_f32 v[14:15], v[16:17], v[20:21]
	v_pk_add_f32 v[8:9], v[10:11], v[8:9]
	v_pk_add_f32 v[10:11], v[12:13], v[14:15]
	v_mul_f32_e32 v13, v9, v9
	v_mul_f32_e32 v12, v11, v11
	v_fmac_f32_e32 v12, v10, v10
	v_fmac_f32_e32 v13, v8, v8
	v_add_f32_e32 v12, v12, v13
	s_nop 1
	v_add_f32_dpp v12, v12, v12 quad_perm:[1,0,3,2] row_mask:0xf bank_mask:0xf bound_ctrl:1
	s_nop 1
	v_add_f32_dpp v12, v12, v12 quad_perm:[2,3,0,1] row_mask:0xf bank_mask:0xf bound_ctrl:1
	s_nop 1
	v_add_f32_dpp v12, v12, v12 row_half_mirror row_mask:0xf bank_mask:0xf bound_ctrl:1
	s_nop 1
	v_add_f32_dpp v12, v12, v12 row_mirror row_mask:0xf bank_mask:0xf bound_ctrl:1
	s_nop 1
	v_mov_b32_dpp v24, v12 row_bcast:15 row_mask:0xa bank_mask:0xf
	v_add_f32_e32 v12, v12, v24
	s_nop 1
	v_mov_b32_dpp v25, v12 row_bcast:31 row_mask:0xc bank_mask:0xf
	v_add_f32_e32 v12, v12, v25
	s_nop 0
	v_readlane_b32 s4, v12, 63
	s_and_saveexec_b64 s[0:1], vcc
	s_lshl_b32 s5, s96, 2
	s_add_i32 s5, s5, 0
	v_mov_b32_e32 v12, s5
	v_mov_b32_e32 v13, s4
	ds_write_b32 v12, v13
	s_or_b64 exec, exec, s[0:1]
	s_waitcnt lgkmcnt(0)
	s_barrier
	ds_read_b128 v[12:15], v5
	ds_read_b128 v[16:19], v5 offset:16
	s_lshl_b64 s[0:1], s[2:3], 2
	s_waitcnt vmcnt(1)
	v_pk_mul_f32 v[2:3], v[8:9], v[2:3]
	v_pk_mul_f32 v[0:1], v[10:11], v[0:1]
	s_waitcnt lgkmcnt(1)
	v_add_f32_e32 v5, 0, v12
	v_add_f32_e32 v5, v5, v13
	v_add_f32_e32 v5, v5, v14
	v_add_f32_e32 v5, v5, v15
	s_waitcnt lgkmcnt(0)
	v_add_f32_e32 v5, v5, v16
	v_add_f32_e32 v5, v5, v17
	v_add_f32_e32 v5, v5, v18
	v_add_f32_e32 v5, v5, v19
	v_mov_b32_e32 v12, 0x358637bd
	v_fmac_f32_e32 v12, 0x3a000000, v5
	v_rsq_f32_e32 v5, v12
	s_waitcnt vmcnt(0)
	v_cvt_f32_f16_sdwa v13, v6 dst_sel:DWORD dst_unused:UNUSED_PAD src0_sel:WORD_1
	v_cvt_f32_f16_e32 v12, v6
	v_cvt_f32_f16_sdwa v15, v7 dst_sel:DWORD dst_unused:UNUSED_PAD src0_sel:WORD_1
	v_cvt_f32_f16_e32 v14, v7
	v_mul_f32_e32 v6, 0.5, v5
	s_add_u32 s0, s92, s0
	v_pk_fma_f32 v[0:1], v[0:1], v[6:7], v[12:13] op_sel_hi:[1,0,1]
	v_pk_fma_f32 v[2:3], v[2:3], v[6:7], v[14:15] op_sel_hi:[1,0,1]
	s_addc_u32 s1, s93, s1
	global_store_dwordx4 v4, v[0:3], s[0:1] sc1
	s_barrier
